# token mixer: hand-written attention stage (batched K/V LDS fragment reads, static window masks, permlane-swap row reductions, packed f32 q-prep, prefetched chunk inputs)
# speedup vs baseline: 1.0394x; 1.0064x over previous
; __device__ __forceinline__ void p2_block(LAS unsigned char* lds, const bf16_t* __restrict__ PROJ, bf16_t* __restrict__ ATT, bf16_t* __restrict__ SGU, const float* __restrict__ qn, const float* __restrict__ kn, ...
;     ...
;     const int b = item >> 6, n = (item >> 2) & 15, kvh = item & 3;
;     const int lane = tid & 63, w = __builtin_amdgcn_readfirstlane(tid >> 6), fr = lane & 15, fq = lane >> 4;
;     LAS unsigned char* KS = lds; LAS unsigned char* VT = lds + KS_BYTES;
;     const int g = w >> 1, rbase = (w & 1) * 64, hq = kvh * 4 + g;
;     const int kk = tid >> 1, h = tid & 1, s = n * 128 - 128 + kk, sc = s < 0 ? 0 : s;
;     const bf16_t* rowp = PROJ + (size_t)(b * pg8::SEQ + sc) * pg8::IN_W;
;     const bf16_t* kp = rowp + pg8::C_K + kvh * 64 + 16 * h;
;     const u32x4 ka = *(const u32x4*)kp, kb = *(const u32x4*)(kp + 8), kc = *(const u32x4*)(kp + 32), kd = *(const u32x4*)(kp + 40);
;     const bf16_t* vp = rowp + pg8::C_V + kvh * 64 + 32 * h;
;     u32x4 vv[4];
; #pragma unroll
;     for (int c4 = 0; c4 < 4; ++c4) vv[c4] = *(const u32x4*)(vp + 8 * c4);
;     const int sp_ = tid >> 2, q4 = tid & 3;
;     u32x4 sv[2][4];
;     const bf16_t* svsrc = PROJ + ((size_t)b * pg8::SEQ + n * 128 + sp_) * pg8::IN_W + pg8::C_VS + (2 * kvh) * 128 + 32 * q4;
; #pragma unroll
;     for (int c4 = 0; c4 < 4; ++c4) sv[0][c4] = *(const u32x4*)(svsrc + 8 * c4);
;     u32x4 qa[4], qb[4];
; #pragma unroll
;     for (int c = 0; c < 2; ++c) { const bf16_t* qp = PROJ + ((size_t)b * pg8::SEQ + n * 128 + rbase + 16 * c + fr) * pg8::IN_W + hq * 64 + 8 * fq; qa[c] = *(const u32x4*)qp; qb[c] = *(const u32x4*)(qp + 32); }
;     {
;         const float valid = s < 0 ? 0.f : 1.f;
;         float x1[16], x2[16]; unpack8(ka, x1); unpack8(kb, x1 + 8); unpack8(kc, x2); unpack8(kd, x2 + 8);
;         float ss = 0.f;
; #pragma unroll
;         for (int j = 0; j < 16; ++j) ss += x1[j] * x1[j] + x2[j] * x2[j];
;         ss += __shfl_xor(ss, 1);
;         const float rinv = rsqrtf(ss * (1.0f / 64.0f) + pg8::EPS) * valid;
;         const float* cp = COS + sc * 32 + 16 * h; const float* sp = SIN + sc * 32 + 16 * h;
;         float o1[16], o2[16];
; #pragma unroll
;         for (int j = 0; j < 16; ++j) { const float a1 = x1[j] * rinv * kn[16 * h + j], a2 = x2[j] * rinv * kn[32 + 16 * h + j], c = cp[j], sn = sp[j]; o1[j] = a1 * c - a2 * sn; o2[j] = a2 * c + a1 * sn; }
.LBB0_330:
	s_bfe_u32 s27, s2, 0x40002
	v_mov_b32_e32 v160, v204
	s_lshl_b32 s17, s27, 7
	s_add_i32 s4, s17, 0xffffff80
	v_ashrrev_i32_e32 v167, 1, v160
	v_add_u32_e32 v22, s4, v167
	s_ashr_i32 s6, s2, 6
	v_max_i32_e32 v66, 0, v22
	s_and_b32 s73, s2, 3
	v_lshl_add_u32 v0, s6, 11, v66
	s_waitcnt lgkmcnt(0)
	v_mov_b64_e32 v[2:3], s[10:11]
	v_and_b32_e32 v166, 1, v160
	v_mad_i64_i32 v[4:5], s[24:25], v0, s83, v[2:3]
	s_lshl_b32 s4, s73, 7
	v_lshl_add_u64 v[4:5], v[4:5], 0, s[4:5]
	v_lshlrev_b32_e32 v0, 5, v166
	v_lshl_add_u64 v[6:7], v[4:5], 0, v[0:1]
	global_load_dwordx4 v[50:53], v[6:7], off offset:2048
	global_load_dwordx4 v[58:61], v[6:7], off offset:2064
	global_load_dwordx4 v[54:57], v[6:7], off offset:2112
	global_load_dwordx4 v[62:65], v[6:7], off offset:2128
	v_readfirstlane_b32 s16, v160
	s_ashr_i32 s77, s16, 7
	s_lshl_b32 s7, s73, 2
	s_add_i32 s42, s77, s7
	s_ashr_i32 s7, s6, 31
	v_lshlrev_b32_e32 v74, 6, v166
	v_mov_b32_e32 v75, v1
	v_ashrrev_i32_e32 v136, 2, v160
	s_lshl_b64 s[48:49], s[6:7], 11
	v_lshl_add_u64 v[4:5], v[4:5], 0, v[74:75]
	s_or_b32 s24, s48, s17
	s_mov_b32 s25, s49
	v_ashrrev_i32_e32 v137, 31, v136
	s_waitcnt lgkmcnt(0)
	global_load_dwordx4 v[18:21], v[4:5], off offset:2560
	global_load_dwordx4 v[14:17], v[4:5], off offset:2576
	global_load_dwordx4 v[10:13], v[4:5], off offset:2592
	global_load_dwordx4 v[6:9], v[4:5], off offset:2608
	v_lshl_add_u64 v[4:5], s[24:25], 0, v[136:137]
	v_mad_u64_u32 v[2:3], s[6:7], v4, s83, v[2:3]
	v_lshlrev_b32_e32 v4, 5, v160
	v_mad_i32_i24 v3, v5, s83, v3
	s_lshl_b32 s4, s73, 9
	v_and_b32_e32 v165, 0x60, v4
	v_lshl_add_u64 v[2:3], v[2:3], 0, s[4:5]
	v_lshlrev_b32_e32 v4, 1, v165
	v_mov_b32_e32 v5, v1
	v_lshl_add_u64 v[2:3], v[2:3], 0, v[4:5]
	s_mov_b64 s[6:7], 0x1400
	v_lshl_add_u64 v[138:139], v[2:3], 0, s[6:7]
	s_lshl_b32 s6, s42, 6
	s_ashr_i32 s7, s6, 31
	s_and_b32 s26, s16, 64
	s_lshl_b64 s[6:7], s[6:7], 1
	v_bfe_u32 v162, v160, 4, 2
	s_add_u32 s28, s10, s6
	s_movk_i32 s4, 0x1000
	v_and_b32_e32 v137, 15, v160
	s_addc_u32 s29, s11, s7
	v_lshlrev_b32_e32 v132, 4, v162
	v_mov_b32_e32 v133, v1
	v_and_b32_e32 v68, 64, v211
	v_add_co_u32_e32 v2, vcc, s4, v2
	v_or_b32_e32 v161, s26, v137
	v_lshl_add_u64 v[134:135], s[28:29], 0, v[132:133]
	v_xor_b32_e32 v67, 1, v211
	v_add_u32_e32 v133, 64, v68
	v_addc_co_u32_e32 v3, vcc, 0, v3, vcc
	v_or_b32_e32 v163, s24, v161
	v_cmp_lt_i32_e64 s[40:41], v67, v133
	v_cmp_gt_i32_e32 vcc, 0, v22
	v_mad_u64_u32 v[22:23], s[28:29], v163, s83, v[134:135]
	v_cndmask_b32_e64 v67, v211, v67, s[40:41]
	v_mad_i32_i24 v23, s49, v212, v23
	v_lshlrev_b32_e32 v164, 2, v67
	v_lshlrev_b32_e32 v66, 5, v66
	v_mov_b32_e32 v67, v1
	v_readlane_b32 s44, v250, 36
	v_readlane_b32 s46, v250, 38
	global_load_dwordx4 v[46:49], v[2:3], off offset:1024
	global_load_dwordx4 v[34:37], v[138:139], off offset:48
	global_load_dwordx4 v[38:41], v[138:139], off offset:32
	global_load_dwordx4 v[42:45], v[138:139], off offset:16
	s_nop 0
	global_load_dwordx4 v[2:5], v[22:23], off
	global_load_dwordx4 v[30:33], v[22:23], off offset:64
	v_or_b32_e32 v22, 16, v163
	v_lshlrev_b64 v[66:67], 2, v[66:67]
	v_readlane_b32 s45, v250, 37
	v_readlane_b32 s47, v250, 39
	v_mad_u64_u32 v[26:27], s[28:29], v22, s83, v[134:135]
	v_lshl_add_u64 v[68:69], s[44:45], 0, v[66:67]
	v_lshl_add_u64 v[66:67], s[46:47], 0, v[66:67]
	v_mad_i32_i24 v27, s49, v212, v27
	v_lshl_add_u64 v[86:87], v[68:69], 0, v[74:75]
	v_lshl_add_u64 v[126:127], v[66:67], 0, v[74:75]
	global_load_dwordx4 v[22:25], v[26:27], off
	s_nop 0
	global_load_dwordx4 v[26:29], v[26:27], off offset:64
	s_nop 0
	global_load_dwordx4 v[66:69], v74, s[0:1] offset:48
	global_load_dwordx4 v[78:81], v74, s[0:1] offset:32
	global_load_dwordx4 v[94:97], v74, s[0:1] offset:16
	global_load_dwordx4 v[106:109], v74, s[0:1]
	global_load_dwordx4 v[70:73], v74, s[0:1] offset:176
	global_load_dwordx4 v[82:85], v74, s[0:1] offset:160
	global_load_dwordx4 v[98:101], v74, s[0:1] offset:144
	global_load_dwordx4 v[110:113], v74, s[0:1] offset:128
	s_nop 0
	global_load_dwordx4 v[74:77], v[86:87], off offset:48
	global_load_dwordx4 v[90:93], v[86:87], off offset:32
	global_load_dwordx4 v[102:105], v[86:87], off offset:16
	global_load_dwordx4 v[114:117], v[86:87], off
	s_nop 0
	global_load_dwordx4 v[86:89], v[126:127], off offset:48
	global_load_dwordx4 v[118:121], v[126:127], off offset:32
	global_load_dwordx4 v[122:125], v[126:127], off offset:16
	s_nop 0
	global_load_dwordx4 v[126:129], v[126:127], off
	v_cndmask_b32_e64 v180, 1.0, 0, vcc
	s_lshl_b32 s4, s73, 10
	s_waitcnt vmcnt(0)
; __device__ __forceinline__ void unpack8(const u32x4 w, float* f) { f[0] = bf_lo(w.x); f[1] = bf_hi(w.x); f[2] = bf_lo(w.y); f[3] = bf_hi(w.y); f[4] = bf_lo(w.z); f[5] = bf_hi(w.z); f[6] = bf_lo(w.w); f[7] = bf_hi(w.w); }
; __device__ __forceinline__ void p2_block(LAS unsigned char* lds, const bf16_t* __restrict__ PROJ, bf16_t* __restrict__ ATT, bf16_t* __restrict__ SGU, const float* __restrict__ qn, const float* __restrict__ kn, ...
;     ...
;         float x1[16], x2[16]; unpack8(ka, x1); unpack8(kb, x1 + 8); unpack8(kc, x2); unpack8(kd, x2 + 8);
;         float ss = 0.f;
; #pragma unroll
;         for (int j = 0; j < 16; ++j) ss += x1[j] * x1[j] + x2[j] * x2[j];
;         ss += __shfl_xor(ss, 1);
;         const float rinv = rsqrtf(ss * (1.0f / 64.0f) + pg8::EPS) * valid;
;         const float* cp = COS + sc * 32 + 16 * h; const float* sp = SIN + sc * 32 + 16 * h;
;         float o1[16], o2[16];
; #pragma unroll
;         for (int j = 0; j < 16; ++j) { const float a1 = x1[j] * rinv * kn[16 * h + j], a2 = x2[j] * rinv * kn[32 + 16 * h + j], c = cp[j], sn = sp[j]; o1[j] = a1 * c - a2 * sn; o2[j] = a2 * c + a1 * sn; }
	v_lshlrev_b32_e32 v226, 16, v51
	v_lshlrev_b32_e32 v142, 16, v61
	v_and_b32_e32 v140, 0xffff0000, v61
	v_lshlrev_b32_e32 v143, 16, v65
	v_and_b32_e32 v141, 0xffff0000, v65
	v_mov_b32_e32 v150, v141
	v_mov_b32_e32 v151, v143
	v_mov_b32_e32 v148, v140
	v_mov_b32_e32 v149, v142
	v_pk_mul_f32 v[150:151], v[150:151], v[150:151]
	v_and_b32_e32 v61, 0xffff0000, v64
	v_pk_fma_f32 v[182:183], v[148:149], v[148:149], v[150:151]
	v_lshlrev_b32_e32 v149, 16, v64
	v_lshlrev_b32_e32 v148, 16, v60
	v_and_b32_e32 v60, 0xffff0000, v60
	v_mov_b32_e32 v154, v61
	v_mov_b32_e32 v155, v149
	v_mov_b32_e32 v64, v60
	v_mov_b32_e32 v65, v148
	v_pk_mul_f32 v[154:155], v[154:155], v[154:155]
	v_and_b32_e32 v201, 0xffff0000, v57
	v_pk_fma_f32 v[184:185], v[64:65], v[64:65], v[154:155]
	v_lshlrev_b32_e32 v155, 16, v63
	v_and_b32_e32 v65, 0xffff0000, v63
	v_lshlrev_b32_e32 v154, 16, v59
	v_and_b32_e32 v64, 0xffff0000, v59
	v_mov_b32_e32 v188, v65
	v_mov_b32_e32 v189, v155
	v_mov_b32_e32 v186, v64
	v_mov_b32_e32 v187, v154
	v_pk_mul_f32 v[188:189], v[188:189], v[188:189]
	v_and_b32_e32 v59, 0xffff0000, v62
	v_pk_fma_f32 v[186:187], v[186:187], v[186:187], v[188:189]
	v_lshlrev_b32_e32 v189, 16, v62
	v_lshlrev_b32_e32 v188, 16, v58
	v_and_b32_e32 v58, 0xffff0000, v58
	v_mov_b32_e32 v194, v59
	v_mov_b32_e32 v195, v189
	v_mov_b32_e32 v62, v58
	v_mov_b32_e32 v63, v188
	v_pk_mul_f32 v[194:195], v[194:195], v[194:195]
	v_and_b32_e32 v234, 0xffff0000, v51
	v_pk_fma_f32 v[62:63], v[62:63], v[62:63], v[194:195]
	v_lshlrev_b32_e32 v195, 16, v57
	v_lshlrev_b32_e32 v239, 16, v54
	v_lshlrev_b32_e32 v238, 16, v50
	v_and_b32_e32 v51, 0xffff0000, v54
	v_and_b32_e32 v50, 0xffff0000, v50
	v_lshlrev_b32_e32 v194, 16, v53
	v_and_b32_e32 v200, 0xffff0000, v53
	v_mov_b32_e32 v218, v201
	v_mov_b32_e32 v219, v195
	v_lshlrev_b32_e32 v227, 16, v55
	v_and_b32_e32 v235, 0xffff0000, v55
	v_pk_mul_f32 v[240:241], v[238:239], v[238:239]
	v_pk_mul_f32 v[54:55], v[50:51], v[50:51]
	v_mov_b32_e32 v202, v200
	v_mov_b32_e32 v203, v194
	v_pk_mul_f32 v[218:219], v[218:219], v[218:219]
	v_pk_mul_f32 v[228:229], v[226:227], v[226:227]
	v_add_f32_e32 v54, v54, v55
	v_add_f32_e32 v55, v240, v241
	v_pk_fma_f32 v[202:203], v[202:203], v[202:203], v[218:219]
	v_lshlrev_b32_e32 v219, 16, v56
	v_lshlrev_b32_e32 v218, 16, v52
	v_pk_mul_f32 v[236:237], v[234:235], v[234:235]
	v_add_f32_e32 v54, v55, v54
	v_add_f32_e32 v55, v228, v229
	v_mov_b32_e32 v150, v66
	v_pk_mul_f32 v[220:221], v[218:219], v[218:219]
	v_and_b32_e32 v53, 0xffff0000, v56
	v_and_b32_e32 v52, 0xffff0000, v52
	v_add_f32_e32 v66, v236, v237
	v_add_f32_e32 v54, v55, v54
	v_pk_mul_f32 v[56:57], v[52:53], v[52:53]
	v_add_f32_e32 v54, v66, v54
	v_add_f32_e32 v55, v220, v221
	v_add_f32_e32 v54, v55, v54
	v_add_f32_e32 v55, v56, v57
	v_add_f32_e32 v54, v55, v54
	v_add_f32_e32 v54, v203, v54
	v_add_f32_e32 v54, v202, v54
	v_add_f32_e32 v54, v63, v54
	v_add_f32_e32 v54, v62, v54
	v_add_f32_e32 v54, v187, v54
	v_add_f32_e32 v54, v186, v54
	v_add_f32_e32 v54, v185, v54
	v_add_f32_e32 v54, v184, v54
	v_add_f32_e32 v54, v183, v54
	v_add_f32_e32 v54, v182, v54
	ds_bpermute_b32 v55, v164, v54
	v_mov_b32_e32 v242, v106
	v_mov_b32_e32 v243, v110
	v_mov_b32_e32 v244, v114
	v_mov_b32_e32 v245, v126
	s_waitcnt lgkmcnt(0)
	v_add_f32_e32 v54, v54, v55
	v_fmamk_f32 v54, v54, 0x3c800000, v209
	v_cmp_gt_f32_e64 s[40:41], s82, v54
	v_mul_f32_e32 v55, 0x4b800000, v54
	v_mov_b32_e32 v110, v107
	v_cndmask_b32_e64 v54, v54, v55, s[40:41]
	v_rsq_f32_e32 v54, v54
	v_mov_b32_e32 v230, v108
	v_mov_b32_e32 v231, v112
	v_mov_b32_e32 v232, v116
	v_mul_f32_e32 v55, 0x45800000, v54
	v_cndmask_b32_e64 v54, v54, v55, s[40:41]
	v_mul_f32_e32 v54, v180, v54
	v_pk_mul_f32 v[56:57], v[54:55], v[238:239] op_sel_hi:[0,1]
	v_pk_mul_f32 v[56:57], v[242:243], v[56:57]
	v_mov_b32_e32 v233, v128
	v_pk_mul_f32 v[62:63], v[244:245], v[56:57]
	v_mov_b32_e32 v144, v68
	v_sub_f32_e32 v55, v62, v63
	v_mov_b32_e32 v62, v126
	v_mov_b32_e32 v63, v114
	v_pk_mul_f32 v[50:51], v[54:55], v[50:51] op_sel_hi:[0,1]
	v_pk_mul_f32 v[56:57], v[62:63], v[56:57]
	v_pk_mul_f32 v[50:51], v[110:111], v[50:51]
	v_mov_b32_e32 v126, v115
	v_mov_b32_e32 v114, v127
	v_add_f32_e32 v62, v57, v56
	v_pk_mul_f32 v[56:57], v[126:127], v[50:51]
	v_pk_mul_f32 v[50:51], v[114:115], v[50:51]
	v_sub_f32_e32 v63, v56, v57
	v_add_f32_e32 v66, v51, v50
	v_pk_mul_f32 v[50:51], v[54:55], v[226:227] op_sel_hi:[0,1]
	v_pk_mul_f32 v[50:51], v[230:231], v[50:51]
	v_mov_b32_e32 v190, v78
	v_pk_mul_f32 v[56:57], v[232:233], v[50:51]
	v_mov_b32_e32 v112, v109
	v_sub_f32_e32 v68, v56, v57
	v_mov_b32_e32 v56, v128
	v_mov_b32_e32 v57, v116
	v_pk_mul_f32 v[50:51], v[56:57], v[50:51]
	v_mov_b32_e32 v128, v117
	v_add_f32_e32 v78, v51, v50
	v_pk_mul_f32 v[50:51], v[54:55], v[234:235] op_sel_hi:[0,1]
	v_pk_mul_f32 v[50:51], v[112:113], v[50:51]
	v_mov_b32_e32 v116, v129
	v_pk_mul_f32 v[56:57], v[128:129], v[50:51]
	v_pk_mul_f32 v[50:51], v[116:117], v[50:51]
	v_mov_b32_e32 v222, v94
	v_mov_b32_e32 v223, v98
	v_add_f32_e32 v94, v51, v50
	v_pk_mul_f32 v[50:51], v[54:55], v[218:219] op_sel_hi:[0,1]
	v_mov_b32_e32 v224, v102
	v_mov_b32_e32 v225, v122
	v_pk_mul_f32 v[50:51], v[50:51], v[222:223]
	v_mov_b32_e32 v156, v80
	v_sub_f32_e32 v80, v56, v57
	v_pk_mul_f32 v[56:57], v[50:51], v[224:225]
	v_mov_b32_e32 v196, v96
	v_sub_f32_e32 v96, v56, v57
	v_mov_b32_e32 v56, v122
	v_mov_b32_e32 v57, v102
	v_pk_mul_f32 v[50:51], v[50:51], v[56:57]
	v_mov_b32_e32 v98, v95
	v_add_f32_e32 v106, v51, v50
	v_pk_mul_f32 v[50:51], v[54:55], v[52:53] op_sel_hi:[0,1]
	v_pk_mul_f32 v[50:51], v[50:51], v[98:99]
	v_mov_b32_e32 v122, v103
	v_mov_b32_e32 v102, v123
; __device__ __forceinline__ unsigned cvt_pk_bf16(float lo, float hi) { unsigned r; asm volatile("v_cvt_pk_bf16_f32 %0, %1, %2" : "=v"(r) : "v"(lo), "v"(hi)); return r; }
; #define LAS __attribute__((address_space(3)))
; __device__ __forceinline__ void p2_block(LAS unsigned char* lds, const bf16_t* __restrict__ PROJ, bf16_t* __restrict__ ATT, bf16_t* __restrict__ SGU, const float* __restrict__ qn, const float* __restrict__ kn, ...
;     ...
;         for (int j = 0; j < 16; ++j) { const float a1 = x1[j] * rinv * kn[16 * h + j], a2 = x2[j] * rinv * kn[32 + 16 * h + j], c = cp[j], sn = sp[j]; o1[j] = a1 * c - a2 * sn; o2[j] = a2 * c + a1 * sn; }
;         LAS unsigned char* kdst = KS + kk * KS_STRIDE + 32 * h;
;         u32x4 w0, w1;
;         w0.x = cvt_pk_bf16(o1[0], o1[1]); w0.y = cvt_pk_bf16(o1[2], o1[3]); w0.z = cvt_pk_bf16(o1[4], o1[5]); w0.w = cvt_pk_bf16(o1[6], o1[7]);
;         w1.x = cvt_pk_bf16(o1[8], o1[9]); w1.y = cvt_pk_bf16(o1[10], o1[11]); w1.z = cvt_pk_bf16(o1[12], o1[13]); w1.w = cvt_pk_bf16(o1[14], o1[15]);
;         *(LAS u32x4*)kdst = w0; *(LAS u32x4*)(kdst + 16) = w1;
;         w0.x = cvt_pk_bf16(o2[0], o2[1]); w0.y = cvt_pk_bf16(o2[2], o2[3]); w0.z = cvt_pk_bf16(o2[4], o2[5]); w0.w = cvt_pk_bf16(o2[6], o2[7]);
;         w1.x = cvt_pk_bf16(o2[8], o2[9]); w1.y = cvt_pk_bf16(o2[10], o2[11]); w1.z = cvt_pk_bf16(o2[12], o2[13]); w1.w = cvt_pk_bf16(o2[14], o2[15]);
;         *(LAS u32x4*)(kdst + 64) = w0; *(LAS u32x4*)(kdst + 80) = w1;
;     ...
;         const float* gp = lng + gg * 128 + 32 * q4; const float* bp = lnb + gg * 128 + 32 * q4;
	v_pk_mul_f32 v[52:53], v[50:51], v[122:123]
	v_pk_mul_f32 v[50:51], v[50:51], v[102:103]
	v_mov_b32_e32 v197, v100
	v_add_f32_e32 v95, v51, v50
	v_pk_mul_f32 v[50:51], v[54:55], v[194:195] op_sel_hi:[0,1]
	v_mov_b32_e32 v198, v104
	v_mov_b32_e32 v199, v124
	v_pk_mul_f32 v[50:51], v[50:51], v[196:197]
	v_sub_f32_e32 v56, v52, v53
	v_pk_mul_f32 v[52:53], v[50:51], v[198:199]
	v_mov_b32_e32 v100, v97
	v_sub_f32_e32 v57, v52, v53
	v_mov_b32_e32 v52, v124
	v_mov_b32_e32 v53, v104
	v_pk_mul_f32 v[50:51], v[50:51], v[52:53]
	v_mov_b32_e32 v124, v105
	v_add_f32_e32 v98, v51, v50
	v_pk_mul_f32 v[50:51], v[54:55], v[200:201] op_sel_hi:[0,1]
	v_pk_mul_f32 v[50:51], v[50:51], v[100:101]
	v_mov_b32_e32 v104, v125
	v_pk_mul_f32 v[52:53], v[50:51], v[124:125]
	v_pk_mul_f32 v[50:51], v[50:51], v[104:105]
	v_mov_b32_e32 v191, v82
	v_add_f32_e32 v99, v51, v50
	v_pk_mul_f32 v[50:51], v[54:55], v[188:189] op_sel_hi:[0,1]
	v_mov_b32_e32 v192, v90
	v_mov_b32_e32 v193, v118
	v_pk_mul_f32 v[50:51], v[50:51], v[190:191]
	v_sub_f32_e32 v97, v52, v53
	v_pk_mul_f32 v[52:53], v[50:51], v[192:193]
	v_mov_b32_e32 v82, v79
	v_sub_f32_e32 v100, v52, v53
	v_mov_b32_e32 v52, v118
	v_mov_b32_e32 v53, v90
	v_pk_mul_f32 v[50:51], v[50:51], v[52:53]
	v_mov_b32_e32 v118, v91
	v_add_f32_e32 v101, v51, v50
	v_pk_mul_f32 v[50:51], v[54:55], v[58:59] op_sel_hi:[0,1]
	v_pk_mul_f32 v[50:51], v[50:51], v[82:83]
	v_mov_b32_e32 v90, v119
	v_pk_mul_f32 v[52:53], v[50:51], v[118:119]
	v_pk_mul_f32 v[50:51], v[50:51], v[90:91]
	v_mov_b32_e32 v157, v84
	v_add_f32_e32 v59, v51, v50
	v_pk_mul_f32 v[50:51], v[54:55], v[154:155] op_sel_hi:[0,1]
	v_mov_b32_e32 v158, v92
	v_mov_b32_e32 v159, v120
	v_pk_mul_f32 v[50:51], v[50:51], v[156:157]
	v_sub_f32_e32 v58, v52, v53
	v_pk_mul_f32 v[52:53], v[50:51], v[158:159]
	v_mov_b32_e32 v84, v81
	v_sub_f32_e32 v79, v52, v53
	v_mov_b32_e32 v52, v120
	v_mov_b32_e32 v53, v92
	v_pk_mul_f32 v[50:51], v[50:51], v[52:53]
	v_mov_b32_e32 v120, v93
	v_add_f32_e32 v82, v51, v50
	v_pk_mul_f32 v[50:51], v[54:55], v[64:65] op_sel_hi:[0,1]
	v_pk_mul_f32 v[50:51], v[50:51], v[84:85]
	v_mov_b32_e32 v92, v121
	v_pk_mul_f32 v[52:53], v[50:51], v[120:121]
	v_pk_mul_f32 v[50:51], v[50:51], v[92:93]
	v_mov_b32_e32 v151, v70
	v_add_f32_e32 v65, v51, v50
	v_pk_mul_f32 v[50:51], v[54:55], v[148:149] op_sel_hi:[0,1]
	v_mov_b32_e32 v152, v74
	v_mov_b32_e32 v153, v86
	v_pk_mul_f32 v[50:51], v[50:51], v[150:151]
	v_sub_f32_e32 v64, v52, v53
	v_pk_mul_f32 v[52:53], v[50:51], v[152:153]
	v_mov_b32_e32 v70, v67
	v_sub_f32_e32 v81, v52, v53
	v_mov_b32_e32 v52, v86
	v_mov_b32_e32 v53, v74
	v_pk_mul_f32 v[50:51], v[50:51], v[52:53]
	v_mov_b32_e32 v86, v75
	v_add_f32_e32 v83, v51, v50
	v_pk_mul_f32 v[50:51], v[54:55], v[60:61] op_sel_hi:[0,1]
	v_pk_mul_f32 v[50:51], v[50:51], v[70:71]
	v_mov_b32_e32 v74, v87
	v_pk_mul_f32 v[52:53], v[50:51], v[86:87]
	v_pk_mul_f32 v[50:51], v[50:51], v[74:75]
	v_mov_b32_e32 v145, v72
	v_add_f32_e32 v61, v51, v50
	v_pk_mul_f32 v[50:51], v[54:55], v[142:143] op_sel_hi:[0,1]
	v_mov_b32_e32 v146, v76
	v_mov_b32_e32 v147, v88
	v_pk_mul_f32 v[50:51], v[50:51], v[144:145]
	v_sub_f32_e32 v60, v52, v53
	v_pk_mul_f32 v[52:53], v[50:51], v[146:147]
	v_mov_b32_e32 v72, v69
	v_lshl_add_u32 v182, v165, 2, s4
	global_load_dwordx4 v[144:147], v182, s[36:37] offset:0
	global_load_dwordx4 v[148:151], v182, s[36:37] offset:16
	global_load_dwordx4 v[152:155], v182, s[36:37] offset:32
	global_load_dwordx4 v[156:159], v182, s[36:37] offset:48
	global_load_dwordx4 v[184:187], v182, s[36:37] offset:64
	global_load_dwordx4 v[188:191], v182, s[36:37] offset:80
	global_load_dwordx4 v[192:195], v182, s[36:37] offset:96
	global_load_dwordx4 v[196:199], v182, s[36:37] offset:112
	global_load_dwordx4 v[218:221], v182, s[18:19] offset:0
	global_load_dwordx4 v[222:225], v182, s[18:19] offset:16
	global_load_dwordx4 v[226:229], v182, s[18:19] offset:32
	global_load_dwordx4 v[230:233], v182, s[18:19] offset:48
	global_load_dwordx4 v[234:237], v182, s[18:19] offset:64
	global_load_dwordx4 v[238:241], v182, s[18:19] offset:80
	global_load_dwordx4 v[242:245], v182, s[18:19] offset:96
	global_load_dwordx4 v[200:203], v182, s[18:19] offset:112
	v_sub_f32_e32 v67, v52, v53
	v_mov_b32_e32 v52, v88
	v_mov_b32_e32 v53, v76
	v_pk_mul_f32 v[50:51], v[50:51], v[52:53]
	v_mov_b32_e32 v88, v77
	v_add_f32_e32 v70, v51, v50
	v_pk_mul_f32 v[50:51], v[54:55], v[140:141] op_sel_hi:[0,1]
	v_pk_mul_f32 v[50:51], v[50:51], v[72:73]
	v_mov_b32_e32 v76, v89
	v_pk_mul_f32 v[52:53], v[50:51], v[88:89]
	v_pk_mul_f32 v[50:51], v[50:51], v[76:77]
	v_sub_f32_e32 v69, v52, v53
	v_add_f32_e32 v71, v51, v50
	v_mul_lo_u32 v50, v167, s59
	v_add3_u32 v0, 0, v50, v0
	v_cvt_pk_bf16_f32 v50, v55, v63
	v_cvt_pk_bf16_f32 v51, v68, v80
	v_cvt_pk_bf16_f32 v52, v96, v56
	v_cvt_pk_bf16_f32 v53, v57, v97
	v_cvt_pk_bf16_f32 v54, v100, v58
	v_cvt_pk_bf16_f32 v55, v79, v64
	v_cvt_pk_bf16_f32 v56, v81, v60
	v_cvt_pk_bf16_f32 v57, v67, v69
	v_lshlrev_b32_e32 v73, 16, v46
	ds_write_b128 v0, v[50:53]
	ds_write_b128 v0, v[54:57] offset:16
	v_cvt_pk_bf16_f32 v50, v62, v66
	v_cvt_pk_bf16_f32 v51, v78, v94
	v_cvt_pk_bf16_f32 v52, v106, v95
	v_cvt_pk_bf16_f32 v53, v98, v99
	v_cvt_pk_bf16_f32 v54, v101, v59
	v_cvt_pk_bf16_f32 v55, v82, v65
	v_cvt_pk_bf16_f32 v56, v83, v61
	v_cvt_pk_bf16_f32 v57, v70, v71
	v_lshlrev_b32_e32 v70, 16, v48
	v_and_b32_e32 v69, 0xffff0000, v48
	v_lshlrev_b32_e32 v68, 16, v49
	v_and_b32_e32 v67, 0xffff0000, v49
	v_lshlrev_b32_e32 v66, 16, v42
	v_and_b32_e32 v65, 0xffff0000, v42
	v_lshlrev_b32_e32 v64, 16, v43
	v_and_b32_e32 v63, 0xffff0000, v43
	v_lshlrev_b32_e32 v62, 16, v44
	v_and_b32_e32 v61, 0xffff0000, v44
; __device__ __forceinline__ float gelu_f(float x) { const float y2 = 1.5957691216057308f * x * (1.0f + 0.044715f * x * x); return x * sigmoid_f(y2); }
; __device__ __forceinline__ void unpack8(const u32x4 w, float* f) { f[0] = bf_lo(w.x); f[1] = bf_hi(w.x); f[2] = bf_lo(w.y); f[3] = bf_hi(w.y); f[4] = bf_lo(w.z); f[5] = bf_hi(w.z); f[6] = bf_lo(w.w); f[7] = bf_hi(w.w); }
; __device__ __forceinline__ float sigmoid_f(float v) { return __builtin_amdgcn_rcpf(1.0f + __expf(-v)); }
; __device__ __forceinline__ void p2_block(LAS unsigned char* lds, const bf16_t* __restrict__ PROJ, bf16_t* __restrict__ ATT, bf16_t* __restrict__ SGU, const float* __restrict__ qn, const float* __restrict__ kn, ...
;     ...
;         for (int c4 = 0; c4 < 4; ++c4) unpack8(sv[gi][c4], v + 8 * c4);
;         float sm = 0.f;
; #pragma unroll
;         for (int j = 0; j < 32; ++j) { v[j] = gelu_f(v[j]); sm += v[j]; }
	v_lshlrev_b32_e32 v60, 16, v45
	v_and_b32_e32 v59, 0xffff0000, v45
	v_lshlrev_b32_e32 v49, 16, v40
	v_and_b32_e32 v48, 0xffff0000, v40
	v_lshlrev_b32_e32 v45, 16, v41
	v_and_b32_e32 v44, 0xffff0000, v41
	v_lshlrev_b32_e32 v43, 16, v34
	v_and_b32_e32 v42, 0xffff0000, v34
	v_lshlrev_b32_e32 v41, 16, v35
	v_and_b32_e32 v40, 0xffff0000, v35
	v_lshlrev_b32_e32 v35, 16, v37
	v_and_b32_e32 v34, 0xffff0000, v37
	v_mul_f32_e32 v37, 0x3d372713, v73
	ds_write_b128 v0, v[50:53] offset:64
	ds_write_b128 v0, v[54:57] offset:80
	v_lshlrev_b32_e32 v58, 16, v38
	v_and_b32_e32 v57, 0xffff0000, v38
	v_lshlrev_b32_e32 v56, 16, v39
	v_and_b32_e32 v55, 0xffff0000, v39
	v_lshlrev_b32_e32 v39, 16, v36
	v_and_b32_e32 v38, 0xffff0000, v36
	v_mul_f32_e32 v36, 0x3fcc422a, v73
	v_fma_f32 v37, v37, v73, 1.0
	v_mul_f32_e32 v36, v36, v37
	v_mul_f32_e32 v36, 0xbfb8aa3b, v36
	v_exp_f32_e32 v36, v36
	v_and_b32_e32 v74, 0xffff0000, v46
	v_mul_f32_e32 v37, 0x3d372713, v74
	v_fma_f32 v37, v37, v74, 1.0
	v_add_f32_e32 v36, 1.0, v36
	v_rcp_f32_e32 v75, v36
	v_mul_f32_e32 v36, 0x3fcc422a, v74
	v_mul_f32_e32 v36, v36, v37
	v_mul_f32_e32 v36, 0xbfb8aa3b, v36
	v_exp_f32_e32 v36, v36
	v_lshlrev_b32_e32 v72, 16, v47
	v_mul_f32_e32 v37, 0x3d372713, v72
	v_fma_f32 v37, v37, v72, 1.0
	v_add_f32_e32 v36, 1.0, v36
	v_rcp_f32_e32 v76, v36
	v_mul_f32_e32 v36, 0x3fcc422a, v72
	v_mul_f32_e32 v36, v36, v37
	v_mul_f32_e32 v36, 0xbfb8aa3b, v36
	v_exp_f32_e32 v36, v36
	v_and_b32_e32 v71, 0xffff0000, v47
	v_mul_f32_e32 v37, 0x3d372713, v71
	v_fma_f32 v37, v37, v71, 1.0
	v_add_f32_e32 v36, 1.0, v36
	v_rcp_f32_e32 v77, v36
	v_mul_f32_e32 v36, 0x3fcc422a, v71
	v_mul_f32_e32 v36, v36, v37
	v_mul_f32_e32 v36, 0xbfb8aa3b, v36
	v_exp_f32_e32 v36, v36
	v_mul_f32_e32 v37, 0x3d372713, v70
	v_fma_f32 v37, v37, v70, 1.0
	v_fma_f32 v46, v75, v73, 0
	v_add_f32_e32 v36, 1.0, v36
	v_rcp_f32_e32 v78, v36
	v_mul_f32_e32 v36, 0x3fcc422a, v70
	v_mul_f32_e32 v36, v36, v37
	v_mul_f32_e32 v36, 0xbfb8aa3b, v36
	v_exp_f32_e32 v36, v36
	v_mul_f32_e32 v37, 0x3d372713, v69
	v_fma_f32 v37, v37, v69, 1.0
	v_fmac_f32_e32 v46, v76, v74
	v_add_f32_e32 v36, 1.0, v36
	v_rcp_f32_e32 v79, v36
	v_mul_f32_e32 v36, 0x3fcc422a, v69
	v_mul_f32_e32 v36, v36, v37
	v_mul_f32_e32 v36, 0xbfb8aa3b, v36
	v_exp_f32_e32 v36, v36
	v_mul_f32_e32 v37, 0x3d372713, v68
	v_fma_f32 v37, v37, v68, 1.0
	v_fmac_f32_e32 v46, v77, v72
	v_add_f32_e32 v36, 1.0, v36
	v_rcp_f32_e32 v80, v36
	v_mul_f32_e32 v36, 0x3fcc422a, v68
	v_mul_f32_e32 v36, v36, v37
	v_mul_f32_e32 v36, 0xbfb8aa3b, v36
	v_exp_f32_e32 v36, v36
	v_mul_f32_e32 v37, 0x3d372713, v67
	v_fma_f32 v37, v37, v67, 1.0
	v_fmac_f32_e32 v46, v78, v71
	v_add_f32_e32 v36, 1.0, v36
	v_rcp_f32_e32 v81, v36
	v_mul_f32_e32 v36, 0x3fcc422a, v67
	v_mul_f32_e32 v36, v36, v37
	v_mul_f32_e32 v36, 0xbfb8aa3b, v36
	v_exp_f32_e32 v36, v36
	v_mul_f32_e32 v37, 0x3d372713, v66
	v_fma_f32 v37, v37, v66, 1.0
	v_fmac_f32_e32 v46, v79, v70
	v_add_f32_e32 v36, 1.0, v36
	v_rcp_f32_e32 v82, v36
	v_mul_f32_e32 v36, 0x3fcc422a, v66
	v_mul_f32_e32 v36, v36, v37
	v_mul_f32_e32 v36, 0xbfb8aa3b, v36
	v_exp_f32_e32 v36, v36
	v_mul_f32_e32 v37, 0x3d372713, v65
	v_fma_f32 v37, v37, v65, 1.0
	v_fmac_f32_e32 v46, v80, v69
	v_add_f32_e32 v36, 1.0, v36
	v_rcp_f32_e32 v84, v36
	v_mul_f32_e32 v36, 0x3fcc422a, v65
	v_mul_f32_e32 v36, v36, v37
	v_mul_f32_e32 v36, 0xbfb8aa3b, v36
	v_exp_f32_e32 v36, v36
	v_mul_f32_e32 v37, 0x3d372713, v64
	v_fma_f32 v37, v37, v64, 1.0
	v_fmac_f32_e32 v46, v81, v68
	v_add_f32_e32 v36, 1.0, v36
	v_rcp_f32_e32 v85, v36
	v_mul_f32_e32 v36, 0x3fcc422a, v64
	v_mul_f32_e32 v36, v36, v37
	v_mul_f32_e32 v36, 0xbfb8aa3b, v36
	v_exp_f32_e32 v36, v36
	v_mul_f32_e32 v37, 0x3d372713, v63
	v_fma_f32 v37, v37, v63, 1.0
	v_fmac_f32_e32 v46, v82, v67
	v_add_f32_e32 v36, 1.0, v36
	v_rcp_f32_e32 v86, v36
	v_mul_f32_e32 v36, 0x3fcc422a, v63
	v_mul_f32_e32 v36, v36, v37
	v_mul_f32_e32 v36, 0xbfb8aa3b, v36
	v_exp_f32_e32 v36, v36
	v_mul_f32_e32 v37, 0x3d372713, v62
	v_fma_f32 v37, v37, v62, 1.0
	v_fmac_f32_e32 v46, v84, v66
	v_add_f32_e32 v36, 1.0, v36
	v_rcp_f32_e32 v87, v36
	v_mul_f32_e32 v36, 0x3fcc422a, v62
	v_mul_f32_e32 v36, v36, v37
	v_mul_f32_e32 v36, 0xbfb8aa3b, v36
	v_exp_f32_e32 v36, v36
	v_mul_f32_e32 v37, 0x3d372713, v61
	v_fma_f32 v37, v37, v61, 1.0
	v_fmac_f32_e32 v46, v85, v65
	v_add_f32_e32 v36, 1.0, v36
	v_rcp_f32_e32 v88, v36
	v_mul_f32_e32 v36, 0x3fcc422a, v61
	v_mul_f32_e32 v36, v36, v37
	v_mul_f32_e32 v36, 0xbfb8aa3b, v36
	v_exp_f32_e32 v36, v36
	v_mul_f32_e32 v37, 0x3d372713, v60
	v_fma_f32 v37, v37, v60, 1.0
	v_fmac_f32_e32 v46, v86, v64
	v_add_f32_e32 v36, 1.0, v36
	v_rcp_f32_e32 v89, v36
	v_mul_f32_e32 v36, 0x3fcc422a, v60
	v_mul_f32_e32 v36, v36, v37
	v_mul_f32_e32 v36, 0xbfb8aa3b, v36
	v_exp_f32_e32 v36, v36
	v_mul_f32_e32 v37, 0x3d372713, v59
	v_fma_f32 v37, v37, v59, 1.0
	v_mul_f32_e32 v47, 0x3d372713, v42
	v_add_f32_e32 v36, 1.0, v36
	v_rcp_f32_e32 v90, v36
	v_mul_f32_e32 v36, 0x3fcc422a, v59
	v_mul_f32_e32 v36, v36, v37
	v_mul_f32_e32 v36, 0xbfb8aa3b, v36
	v_exp_f32_e32 v36, v36
	v_mul_f32_e32 v37, 0x3d372713, v58
	v_fma_f32 v37, v37, v58, 1.0
	v_fmac_f32_e32 v46, v87, v63
	v_add_f32_e32 v36, 1.0, v36
	v_rcp_f32_e32 v91, v36
	v_mul_f32_e32 v36, 0x3fcc422a, v58
	v_mul_f32_e32 v36, v36, v37
	v_mul_f32_e32 v36, 0xbfb8aa3b, v36
	v_exp_f32_e32 v36, v36
	v_mul_f32_e32 v37, 0x3d372713, v57
	v_fma_f32 v37, v37, v57, 1.0
	v_fma_f32 v47, v47, v42, 1.0
	v_add_f32_e32 v36, 1.0, v36
	v_rcp_f32_e32 v98, v36
	v_mul_f32_e32 v36, 0x3fcc422a, v57
	v_mul_f32_e32 v36, v36, v37
	v_mul_f32_e32 v36, 0xbfb8aa3b, v36
	v_exp_f32_e32 v36, v36
	v_mul_f32_e32 v37, 0x3d372713, v56
	v_fma_f32 v37, v37, v56, 1.0
	v_fmac_f32_e32 v46, v88, v62
; __device__ __forceinline__ float gelu_f(float x) { const float y2 = 1.5957691216057308f * x * (1.0f + 0.044715f * x * x); return x * sigmoid_f(y2); }
; #define LAS __attribute__((address_space(3)))
; __device__ __forceinline__ void p2_block(LAS unsigned char* lds, const bf16_t* __restrict__ PROJ, bf16_t* __restrict__ ATT, bf16_t* __restrict__ SGU, const float* __restrict__ qn, const float* __restrict__ kn, ...
;     ...
; #pragma unroll
;         for (int c4 = 0; c4 < 4; ++c4) { u32x4 t = vv[c4]; if (s < 0) t = (u32x4){0u, 0u, 0u, 0u};
;             LAS unsigned char* vd = VT + (32 * h + 8 * c4) * VT_STRIDE + kk * 2;
;             *(LAS unsigned short*)(vd + 0 * VT_STRIDE) = (unsigned short)(t.x & 0xffffu); *(LAS unsigned short*)(vd + 1 * VT_STRIDE) = (unsigned short)(t.x >> 16);
;             *(LAS unsigned short*)(vd + 2 * VT_STRIDE) = (unsigned short)(t.y & 0xffffu); *(LAS unsigned short*)(vd + 3 * VT_STRIDE) = (unsigned short)(t.y >> 16);
;             *(LAS unsigned short*)(vd + 4 * VT_STRIDE) = (unsigned short)(t.z & 0xffffu); *(LAS unsigned short*)(vd + 5 * VT_STRIDE) = (unsigned short)(t.z >> 16);
;             *(LAS unsigned short*)(vd + 6 * VT_STRIDE) = (unsigned short)(t.w & 0xffffu); *(LAS unsigned short*)(vd + 7 * VT_STRIDE) = (unsigned short)(t.w >> 16); }
;     ...
;         for (int j = 0; j < 32; ++j) { v[j] = gelu_f(v[j]); sm += v[j]; }
;         sm += __shfl_xor(sm, 1); sm += __shfl_xor(sm, 2);
	v_add_f32_e32 v36, 1.0, v36
	v_rcp_f32_e32 v99, v36
	v_mul_f32_e32 v36, 0x3fcc422a, v56
	v_mul_f32_e32 v36, v36, v37
	v_mul_f32_e32 v36, 0xbfb8aa3b, v36
	v_exp_f32_e32 v36, v36
	v_mul_f32_e32 v37, 0x3d372713, v55
	v_fma_f32 v37, v37, v55, 1.0
	v_fmac_f32_e32 v46, v89, v61
	v_add_f32_e32 v36, 1.0, v36
	v_rcp_f32_e32 v100, v36
	v_mul_f32_e32 v36, 0x3fcc422a, v55
	v_mul_f32_e32 v36, v36, v37
	v_mul_f32_e32 v36, 0xbfb8aa3b, v36
	v_exp_f32_e32 v36, v36
	v_mul_f32_e32 v37, 0x3d372713, v49
	v_fma_f32 v37, v37, v49, 1.0
	v_fmac_f32_e32 v46, v90, v60
	v_add_f32_e32 v36, 1.0, v36
	v_rcp_f32_e32 v101, v36
	v_mul_f32_e32 v36, 0x3fcc422a, v49
	v_mul_f32_e32 v36, v36, v37
	v_mul_f32_e32 v36, 0xbfb8aa3b, v36
	v_exp_f32_e32 v36, v36
	v_mul_f32_e32 v37, 0x3d372713, v48
	v_fma_f32 v37, v37, v48, 1.0
	v_fmac_f32_e32 v46, v91, v59
	v_add_f32_e32 v36, 1.0, v36
	v_rcp_f32_e32 v102, v36
	v_mul_f32_e32 v36, 0x3fcc422a, v48
	v_mul_f32_e32 v36, v36, v37
	v_mul_f32_e32 v36, 0xbfb8aa3b, v36
	v_exp_f32_e32 v36, v36
	v_mul_f32_e32 v37, 0x3d372713, v45
	v_fma_f32 v37, v37, v45, 1.0
	v_fmac_f32_e32 v46, v98, v58
	v_add_f32_e32 v36, 1.0, v36
	v_rcp_f32_e32 v103, v36
	v_mul_f32_e32 v36, 0x3fcc422a, v45
	v_mul_f32_e32 v36, v36, v37
	v_mul_f32_e32 v36, 0xbfb8aa3b, v36
	v_exp_f32_e32 v36, v36
	v_mul_f32_e32 v37, 0x3d372713, v44
	v_fma_f32 v37, v37, v44, 1.0
	v_fmac_f32_e32 v46, v99, v57
	v_add_f32_e32 v36, 1.0, v36
	v_rcp_f32_e32 v104, v36
	v_mul_f32_e32 v36, 0x3fcc422a, v44
	v_mul_f32_e32 v36, v36, v37
	v_mul_f32_e32 v36, 0xbfb8aa3b, v36
	v_exp_f32_e32 v36, v36
	v_mul_f32_e32 v37, 0x3d372713, v43
	v_fma_f32 v37, v37, v43, 1.0
	v_fmac_f32_e32 v46, v100, v56
	v_add_f32_e32 v36, 1.0, v36
	v_rcp_f32_e32 v105, v36
	v_mul_f32_e32 v36, 0x3fcc422a, v43
	v_mul_f32_e32 v36, v36, v37
	v_mul_f32_e32 v36, 0xbfb8aa3b, v36
	v_exp_f32_e32 v36, v36
	v_fmac_f32_e32 v46, v101, v55
	v_fmac_f32_e32 v46, v102, v49
	v_fmac_f32_e32 v46, v103, v48
	v_add_f32_e32 v36, 1.0, v36
	v_rcp_f32_e32 v37, v36
	v_mul_f32_e32 v36, 0x3fcc422a, v42
	v_mul_f32_e32 v36, v36, v47
	v_mul_f32_e32 v36, 0xbfb8aa3b, v36
	v_exp_f32_e32 v36, v36
	v_fmac_f32_e32 v46, v104, v45
	v_fmac_f32_e32 v46, v105, v44
	v_mul_f32_e32 v47, 0x3d372713, v41
	v_add_f32_e32 v36, 1.0, v36
	v_rcp_f32_e32 v36, v36
	v_fma_f32 v47, v47, v41, 1.0
	v_mul_f32_e32 v94, 0x3d372713, v38
	v_fma_f32 v94, v94, v38, 1.0
	v_pk_mul_f32 v[92:93], v[36:37], v[42:43]
	v_mul_f32_e32 v96, 0x3d372713, v34
	v_add_f32_e32 v46, v93, v46
	v_add_f32_e32 v83, v92, v46
	v_mul_f32_e32 v46, 0x3fcc422a, v41
	v_mul_f32_e32 v46, v46, v47
	v_mul_f32_e32 v46, 0xbfb8aa3b, v46
	v_exp_f32_e32 v46, v46
	v_mul_f32_e32 v92, 0x3d372713, v40
	v_fma_f32 v92, v92, v40, 1.0
	v_fma_f32 v96, v96, v34, 1.0
	v_add_f32_e32 v46, 1.0, v46
	v_rcp_f32_e32 v47, v46
	v_mul_f32_e32 v46, 0x3fcc422a, v40
	v_mul_f32_e32 v46, v46, v92
	v_mul_f32_e32 v46, 0xbfb8aa3b, v46
	v_exp_f32_e32 v46, v46
	v_and_b32_e32 v0, -2, v160
	v_mul_u32_u24_e32 v50, 0x4200, v166
	v_cndmask_b32_e64 v18, v18, 0, vcc
	v_add_f32_e32 v46, 1.0, v46
	v_rcp_f32_e32 v46, v46
	v_add3_u32 v0, 0, v0, v50
	v_cndmask_b32_e64 v14, v14, 0, vcc
	v_cndmask_b32_e64 v10, v10, 0, vcc
	v_pk_mul_f32 v[92:93], v[46:47], v[40:41]
	v_cndmask_b32_e64 v6, v6, 0, vcc
	v_add_f32_e32 v83, v93, v83
	v_mul_f32_e32 v93, 0x3d372713, v39
	v_add_f32_e32 v83, v92, v83
	v_mul_f32_e32 v92, 0x3fcc422a, v39
	v_fma_f32 v93, v93, v39, 1.0
	v_mul_f32_e32 v92, v92, v93
	v_mul_f32_e32 v92, 0xbfb8aa3b, v92
	v_exp_f32_e32 v92, v92
	v_cndmask_b32_e64 v21, v21, 0, vcc
	v_cndmask_b32_e64 v20, v20, 0, vcc
	v_cndmask_b32_e64 v19, v19, 0, vcc
	v_add_f32_e32 v92, 1.0, v92
	v_rcp_f32_e32 v93, v92
	v_mul_f32_e32 v92, 0x3fcc422a, v38
	v_mul_f32_e32 v92, v92, v94
	v_mul_f32_e32 v92, 0xbfb8aa3b, v92
	v_exp_f32_e32 v92, v92
	ds_write_b16 v0, v18 offset:36864
	ds_write_b16_d16_hi v0, v18 offset:37392
	ds_write_b16 v0, v19 offset:37920
	ds_write_b16_d16_hi v0, v19 offset:38448
	ds_write_b16 v0, v20 offset:38976
	ds_write_b16_d16_hi v0, v20 offset:39504
	ds_write_b16 v0, v21 offset:40032
	ds_write_b16_d16_hi v0, v21 offset:40560
	v_cndmask_b32_e64 v17, v17, 0, vcc
	v_cndmask_b32_e64 v16, v16, 0, vcc
	v_add_f32_e32 v92, 1.0, v92
	v_rcp_f32_e32 v92, v92
	v_cndmask_b32_e64 v15, v15, 0, vcc
	ds_write_b16 v0, v14 offset:41088
	ds_write_b16_d16_hi v0, v14 offset:41616
	ds_write_b16 v0, v15 offset:42144
	ds_write_b16_d16_hi v0, v15 offset:42672
	ds_write_b16 v0, v16 offset:43200
	ds_write_b16_d16_hi v0, v16 offset:43728
	ds_write_b16 v0, v17 offset:44256
	ds_write_b16_d16_hi v0, v17 offset:44784
	v_cndmask_b32_e64 v13, v13, 0, vcc
	v_pk_mul_f32 v[94:95], v[92:93], v[38:39]
	v_cndmask_b32_e64 v12, v12, 0, vcc
	v_add_f32_e32 v83, v95, v83
	v_mul_f32_e32 v95, 0x3d372713, v35
	v_add_f32_e32 v83, v94, v83
	v_mul_f32_e32 v94, 0x3fcc422a, v35
	v_fma_f32 v95, v95, v35, 1.0
	v_mul_f32_e32 v94, v94, v95
	v_mul_f32_e32 v94, 0xbfb8aa3b, v94
	v_exp_f32_e32 v94, v94
	v_cndmask_b32_e64 v11, v11, 0, vcc
	ds_write_b16 v0, v10 offset:45312
	ds_write_b16_d16_hi v0, v10 offset:45840
	ds_write_b16 v0, v11 offset:46368
	ds_write_b16_d16_hi v0, v11 offset:46896
	ds_write_b16 v0, v12 offset:47424
	ds_write_b16_d16_hi v0, v12 offset:47952
	ds_write_b16 v0, v13 offset:48480
	ds_write_b16_d16_hi v0, v13 offset:49008
	v_cndmask_b32_e64 v9, v9, 0, vcc
	v_add_f32_e32 v94, 1.0, v94
	v_rcp_f32_e32 v95, v94
	v_mul_f32_e32 v94, 0x3fcc422a, v34
	v_mul_f32_e32 v94, v94, v96
	v_mul_f32_e32 v94, 0xbfb8aa3b, v94
	v_exp_f32_e32 v94, v94
	v_cndmask_b32_e64 v8, v8, 0, vcc
	v_cndmask_b32_e64 v7, v7, 0, vcc
	ds_write_b16 v0, v6 offset:49536
	ds_write_b16_d16_hi v0, v6 offset:50064
	ds_write_b16 v0, v7 offset:50592
	ds_write_b16_d16_hi v0, v7 offset:51120
	ds_write_b16 v0, v8 offset:51648
	ds_write_b16_d16_hi v0, v8 offset:52176
	ds_write_b16 v0, v9 offset:52704
	ds_write_b16_d16_hi v0, v9 offset:53232
	v_add_f32_e32 v94, 1.0, v94
	v_rcp_f32_e32 v94, v94
	v_xor_b32_e32 v0, 2, v211
	v_cmp_lt_i32_e32 vcc, v0, v133
	v_lshlrev_b32_e32 v6, 1, v136
	v_pk_mul_f32 v[96:97], v[94:95], v[34:35]
	v_cndmask_b32_e32 v0, v211, v0, vcc
	v_add_f32_e32 v83, v97, v83
	v_add_f32_e32 v83, v96, v83
	ds_bpermute_b32 v96, v164, v83
	v_lshlrev_b32_e32 v54, 2, v0
	v_lshlrev_b32_e32 v0, 2, v165
	v_lshl_add_u64 v[50:51], s[36:37], 0, v[0:1]
	v_lshl_add_u64 v[52:53], s[18:19], 0, v[0:1]
	s_waitcnt lgkmcnt(0)
; __device__ __forceinline__ unsigned cvt_pk_bf16(float lo, float hi) { unsigned r; asm volatile("v_cvt_pk_bf16_f32 %0, %1, %2" : "=v"(r) : "v"(lo), "v"(hi)); return r; }
; __device__ __forceinline__ float gelu_f(float x) { const float y2 = 1.5957691216057308f * x * (1.0f + 0.044715f * x * x); return x * sigmoid_f(y2); }
; #define LAS __attribute__((address_space(3)))
; __device__ __forceinline__ void unpack8(const u32x4 w, float* f) { f[0] = bf_lo(w.x); f[1] = bf_hi(w.x); f[2] = bf_lo(w.y); f[3] = bf_hi(w.y); f[4] = bf_lo(w.z); f[5] = bf_hi(w.z); f[6] = bf_lo(w.w); f[7] = bf_hi(w.w); }
; __device__ __forceinline__ void p2_block(LAS unsigned char* lds, const bf16_t* __restrict__ PROJ, bf16_t* __restrict__ ATT, bf16_t* __restrict__ SGU, const float* __restrict__ qn, const float* __restrict__ kn, ...
;     ...
;             for (int c4 = 0; c4 < 4; ++c4) sv[1][c4] = *(const u32x4*)(svsrc + 128 + 8 * c4); }
;         float v[32];
; #pragma unroll
;         for (int c4 = 0; c4 < 4; ++c4) unpack8(sv[gi][c4], v + 8 * c4);
;         float sm = 0.f;
; #pragma unroll
;         for (int j = 0; j < 32; ++j) { v[j] = gelu_f(v[j]); sm += v[j]; }
;         sm += __shfl_xor(sm, 1); sm += __shfl_xor(sm, 2);
;         const float mu = sm * (1.0f / 128.0f); float q = 0.f;
; #pragma unroll
;         for (int j = 0; j < 32; ++j) { v[j] -= mu; q += v[j] * v[j]; }
;         q += __shfl_xor(q, 1); q += __shfl_xor(q, 2);
;         const float rstd = rsqrtf(q * (1.0f / 128.0f) + pg8::EPS);
;         const float* gp = lng + gg * 128 + 32 * q4; const float* bp = lnb + gg * 128 + 32 * q4;
;         LAS unsigned char* dst = lds + (gi ? VN_OFF1 : VN_OFF0) + (32 * q4) * VN_STRIDE + sp_ * 2;
; #pragma unroll
;         for (int j = 0; j < 32; j += 2) { const unsigned pk = cvt_pk_bf16(v[j] * rstd * gp[j] + bp[j], v[j + 1] * rstd * gp[j + 1] + bp[j + 1]);
;             *(LAS unsigned short*)(dst + j * VN_STRIDE) = (unsigned short)(pk & 0xffffu); *(LAS unsigned short*)(dst + (j + 1) * VN_STRIDE) = (unsigned short)(pk >> 16); }
	v_add_f32_e32 v83, v83, v96
	ds_bpermute_b32 v96, v54, v83
	v_mul_u32_u24_e32 v0, 0x110, v165
	v_add3_u32 v0, 0, v0, v6
	global_load_dwordx4 v[6:9], v[138:139], off offset:304
	global_load_dwordx4 v[10:13], v[138:139], off offset:288
	global_load_dwordx4 v[14:17], v[138:139], off offset:272
	global_load_dwordx4 v[18:21], v[138:139], off offset:256
	s_ashr_i32 s43, s42, 31
	s_waitcnt lgkmcnt(0)
	v_add_f32_e32 v83, v83, v96
	v_mul_f32_e32 v96, 0x3c000000, v83
	v_fma_f32 v83, v76, v74, -v96
	v_fma_f32 v97, v75, v73, -v96
	v_mul_f32_e32 v106, v83, v83
	v_fmac_f32_e32 v106, v97, v97
	v_fma_f32 v77, v77, v72, -v96
	v_fmac_f32_e32 v106, v77, v77
	v_fma_f32 v76, v78, v71, -v96
	v_fmac_f32_e32 v106, v76, v76
	v_fma_f32 v75, v79, v70, -v96
	v_fmac_f32_e32 v106, v75, v75
	v_fma_f32 v74, v80, v69, -v96
	v_fmac_f32_e32 v106, v74, v74
	v_fma_f32 v73, v81, v68, -v96
	v_fmac_f32_e32 v106, v73, v73
	v_fma_f32 v72, v82, v67, -v96
	v_fmac_f32_e32 v106, v72, v72
	v_fma_f32 v71, v84, v66, -v96
	v_fmac_f32_e32 v106, v71, v71
	v_fma_f32 v70, v85, v65, -v96
	v_fmac_f32_e32 v106, v70, v70
	v_fma_f32 v69, v86, v64, -v96
	v_fmac_f32_e32 v106, v69, v69
	v_fma_f32 v68, v87, v63, -v96
	v_fmac_f32_e32 v106, v68, v68
	v_fma_f32 v67, v88, v62, -v96
	v_fmac_f32_e32 v106, v67, v67
	v_fma_f32 v66, v89, v61, -v96
	v_fmac_f32_e32 v106, v66, v66
	v_fma_f32 v65, v90, v60, -v96
	v_fmac_f32_e32 v106, v65, v65
	v_fma_f32 v64, v91, v59, -v96
	v_fmac_f32_e32 v106, v64, v64
	v_fma_f32 v63, v98, v58, -v96
	v_fmac_f32_e32 v106, v63, v63
	v_fma_f32 v62, v99, v57, -v96
	v_fmac_f32_e32 v106, v62, v62
	v_fma_f32 v61, v100, v56, -v96
	v_fmac_f32_e32 v106, v61, v61
	v_fma_f32 v60, v101, v55, -v96
	v_fmac_f32_e32 v106, v60, v60
	v_fma_f32 v59, v102, v49, -v96
	v_fmac_f32_e32 v106, v59, v59
	v_fma_f32 v58, v103, v48, -v96
	v_fmac_f32_e32 v106, v58, v58
	v_fma_f32 v57, v104, v45, -v96
	v_fmac_f32_e32 v106, v57, v57
	v_fma_f32 v56, v105, v44, -v96
	v_pk_fma_f32 v[44:45], v[36:37], v[42:43], v[96:97] op_sel_hi:[1,1,0] neg_lo:[0,0,1] neg_hi:[0,0,1]
	v_fmac_f32_e32 v106, v56, v56
	v_pk_mul_f32 v[36:37], v[44:45], v[44:45]
	v_pk_fma_f32 v[42:43], v[46:47], v[40:41], v[96:97] op_sel_hi:[1,1,0] neg_lo:[0,0,1] neg_hi:[0,0,1]
	v_add_f32_e32 v37, v37, v106
	v_add_f32_e32 v48, v36, v37
	v_pk_mul_f32 v[36:37], v[42:43], v[42:43]
	v_pk_fma_f32 v[40:41], v[92:93], v[38:39], v[96:97] op_sel_hi:[1,1,0] neg_lo:[0,0,1] neg_hi:[0,0,1]
	v_add_f32_e32 v37, v37, v48
	v_add_f32_e32 v46, v36, v37
	v_pk_mul_f32 v[36:37], v[40:41], v[40:41]
	v_pk_fma_f32 v[38:39], v[94:95], v[34:35], v[96:97] op_sel_hi:[1,1,0] neg_lo:[0,0,1] neg_hi:[0,0,1]
	v_add_f32_e32 v37, v37, v46
	v_add_f32_e32 v36, v36, v37
	v_pk_mul_f32 v[34:35], v[38:39], v[38:39]
	v_lshlrev_b32_e32 v105, 16, v3
	v_add_f32_e32 v35, v35, v36
	v_add_f32_e32 v34, v34, v35
	ds_bpermute_b32 v35, v164, v34
	v_lshl_add_u64 v[36:37], v[52:53], 0, s[4:5]
	v_and_b32_e32 v109, 0xffff0000, v3
	v_lshlrev_b32_e32 v113, 16, v2
	v_lshlrev_b32_e32 v112, 16, v30
	s_waitcnt lgkmcnt(0)
	v_add_f32_e32 v34, v34, v35
	ds_bpermute_b32 v35, v54, v34
	v_and_b32_e32 v3, 0xffff0000, v2
	v_and_b32_e32 v2, 0xffff0000, v30
	v_and_b32_e32 v96, 0xffff0000, v33
	s_waitcnt vmcnt(1)
	v_lshlrev_b32_e32 v53, 16, v14
	s_waitcnt lgkmcnt(0)
	v_add_f32_e32 v34, v34, v35
	v_fmamk_f32 v34, v34, 0x3c000000, v209
	v_cmp_gt_f32_e32 vcc, s82, v34
	v_mul_f32_e32 v35, 0x4b800000, v34
	v_and_b32_e32 v52, 0xffff0000, v14
	v_cndmask_b32_e32 v34, v34, v35, vcc
	v_rsq_f32_e32 v34, v34
	v_and_b32_e32 v14, 0xffff0000, v6
	v_lshlrev_b32_e32 v104, 16, v31
	v_and_b32_e32 v108, 0xffff0000, v31
	v_mul_f32_e32 v35, 0x45800000, v34
	v_cndmask_b32_e32 v55, v34, v35, vcc
	v_lshl_add_u64 v[34:35], v[50:51], 0, s[4:5]
	v_mov_b64_e32 v[46:47], v[144:145]
	v_mov_b64_e32 v[48:49], v[218:219]
	v_mul_f32_e32 v51, v97, v55
	v_add_u32_e32 v50, 0x11800, v0
	v_mul_f32_e32 v45, v45, v55
	v_mul_f32_e32 v44, v44, v55
	v_mul_f32_e32 v43, v43, v55
	v_mul_f32_e32 v42, v42, v55
	v_mul_f32_e32 v41, v41, v55
	v_mul_f32_e32 v40, v40, v55
	v_mul_f32_e32 v39, v39, v55
	v_mul_f32_e32 v38, v38, v55
	v_mov_b32_e32 v116, v112
	v_mov_b32_e32 v117, v2
	v_and_b32_e32 v97, 0xffff0000, v5
	v_mov_b32_e32 v110, v108
	v_mov_b32_e32 v111, v104
	v_mov_b32_e32 v30, v113
	v_mov_b32_e32 v31, v3
	v_pk_mul_f32 v[116:117], v[116:117], v[116:117]
	v_lshlrev_b32_e32 v101, 16, v4
	v_lshlrev_b32_e32 v100, 16, v32
	v_pk_mul_f32 v[110:111], v[110:111], v[110:111]
	v_pk_fma_f32 v[30:31], v[30:31], v[30:31], v[116:117]
	v_lshlrev_b32_e32 v130, 3, v162
	v_mov_b32_e32 v131, v1
	s_mov_b32 s4, s5
	s_mov_b32 s52, 0xf149f2ca
	s_waitcnt vmcnt(0)
	v_fma_f32 v46, v46, v51, v48
	v_mul_f32_e32 v48, v83, v55
	v_fmac_f32_e32 v49, v47, v48
	v_add_u32_e32 v47, 0x11910, v0
	v_cvt_pk_bf16_f32 v46, v46, v49
	ds_write_b16 v50, v46
	ds_write_b16_d16_hi v47, v46
	v_mov_b64_e32 v[46:47], v[146:147]
	v_mov_b64_e32 v[48:49], v[220:221]
	v_mul_f32_e32 v50, v77, v55
	v_lshlrev_b32_e32 v51, 16, v15
	s_waitcnt vmcnt(0)
	v_fma_f32 v46, v46, v50, v48
	v_mul_f32_e32 v48, v76, v55
	v_fmac_f32_e32 v49, v47, v48
	v_add_u32_e32 v47, 0x11a20, v0
	v_cvt_pk_bf16_f32 v46, v46, v49
	ds_write_b16 v47, v46
	v_add_u32_e32 v47, 0x11b30, v0
	ds_write_b16_d16_hi v47, v46
	v_mov_b64_e32 v[46:47], v[148:149]
	v_mov_b64_e32 v[48:49], v[222:223]
	v_mul_f32_e32 v50, v75, v55
	s_waitcnt vmcnt(0)
	v_fma_f32 v46, v46, v50, v48
	v_mul_f32_e32 v48, v74, v55
	v_fmac_f32_e32 v49, v47, v48
	v_add_u32_e32 v47, 0x11c40, v0
	v_cvt_pk_bf16_f32 v46, v46, v49
	ds_write_b16 v47, v46
	v_add_u32_e32 v47, 0x11d50, v0
	ds_write_b16_d16_hi v47, v46
	v_mov_b64_e32 v[46:47], v[150:151]
	v_mov_b64_e32 v[48:49], v[224:225]
	v_mul_f32_e32 v50, v73, v55
	s_waitcnt vmcnt(0)
; __device__ __forceinline__ unsigned cvt_pk_bf16(float lo, float hi) { unsigned r; asm volatile("v_cvt_pk_bf16_f32 %0, %1, %2" : "=v"(r) : "v"(lo), "v"(hi)); return r; }
; __device__ __forceinline__ float gelu_f(float x) { const float y2 = 1.5957691216057308f * x * (1.0f + 0.044715f * x * x); return x * sigmoid_f(y2); }
; #define LAS __attribute__((address_space(3)))
; __device__ __forceinline__ void unpack8(const u32x4 w, float* f) { f[0] = bf_lo(w.x); f[1] = bf_hi(w.x); f[2] = bf_lo(w.y); f[3] = bf_hi(w.y); f[4] = bf_lo(w.z); f[5] = bf_hi(w.z); f[6] = bf_lo(w.w); f[7] = bf_hi(w.w); }
; __device__ __forceinline__ void p2_block(LAS unsigned char* lds, const bf16_t* __restrict__ PROJ, bf16_t* __restrict__ ATT, bf16_t* __restrict__ SGU, const float* __restrict__ qn, const float* __restrict__ kn, ...
;     ...
;         for (int c4 = 0; c4 < 4; ++c4) unpack8(sv[gi][c4], v + 8 * c4);
;         float sm = 0.f;
; #pragma unroll
;         for (int j = 0; j < 32; ++j) { v[j] = gelu_f(v[j]); sm += v[j]; }
;         sm += __shfl_xor(sm, 1); sm += __shfl_xor(sm, 2);
;         const float mu = sm * (1.0f / 128.0f); float q = 0.f;
; #pragma unroll
;         for (int j = 0; j < 32; ++j) { v[j] -= mu; q += v[j] * v[j]; }
;         q += __shfl_xor(q, 1); q += __shfl_xor(q, 2);
;         const float rstd = rsqrtf(q * (1.0f / 128.0f) + pg8::EPS);
;         const float* gp = lng + gg * 128 + 32 * q4; const float* bp = lnb + gg * 128 + 32 * q4;
;         LAS unsigned char* dst = lds + (gi ? VN_OFF1 : VN_OFF0) + (32 * q4) * VN_STRIDE + sp_ * 2;
; #pragma unroll
;         for (int j = 0; j < 32; j += 2) { const unsigned pk = cvt_pk_bf16(v[j] * rstd * gp[j] + bp[j], v[j + 1] * rstd * gp[j + 1] + bp[j + 1]);
;             *(LAS unsigned short*)(dst + j * VN_STRIDE) = (unsigned short)(pk & 0xffffu); *(LAS unsigned short*)(dst + (j + 1) * VN_STRIDE) = (unsigned short)(pk >> 16); }
	v_fma_f32 v46, v46, v50, v48
	v_mul_f32_e32 v48, v72, v55
	v_fmac_f32_e32 v49, v47, v48
	v_add_u32_e32 v47, 0x11e60, v0
	v_cvt_pk_bf16_f32 v46, v46, v49
	ds_write_b16 v47, v46
	v_add_u32_e32 v47, 0x11f70, v0
	ds_write_b16_d16_hi v47, v46
	v_mov_b64_e32 v[46:47], v[152:153]
	v_mov_b64_e32 v[48:49], v[226:227]
	v_mul_f32_e32 v50, v71, v55
	s_waitcnt vmcnt(0)
	v_fma_f32 v46, v46, v50, v48
	v_mul_f32_e32 v48, v70, v55
	v_fmac_f32_e32 v49, v47, v48
	v_add_u32_e32 v47, 0x12080, v0
	v_cvt_pk_bf16_f32 v46, v46, v49
	ds_write_b16 v47, v46
	v_add_u32_e32 v47, 0x12190, v0
	ds_write_b16_d16_hi v47, v46
	v_mov_b64_e32 v[46:47], v[154:155]
	v_mov_b64_e32 v[48:49], v[228:229]
	v_mul_f32_e32 v50, v69, v55
	s_waitcnt vmcnt(0)
	v_fma_f32 v46, v46, v50, v48
	v_mul_f32_e32 v48, v68, v55
	v_fmac_f32_e32 v49, v47, v48
	v_add_u32_e32 v47, 0x122a0, v0
	v_cvt_pk_bf16_f32 v46, v46, v49
	ds_write_b16 v47, v46
	v_add_u32_e32 v47, 0x123b0, v0
	ds_write_b16_d16_hi v47, v46
	v_mov_b64_e32 v[46:47], v[156:157]
	v_mov_b64_e32 v[48:49], v[230:231]
	v_mul_f32_e32 v50, v67, v55
	s_waitcnt vmcnt(0)
	v_fma_f32 v46, v46, v50, v48
	v_mul_f32_e32 v48, v66, v55
	v_fmac_f32_e32 v49, v48, v47
	v_add_u32_e32 v47, 0x124c0, v0
	v_cvt_pk_bf16_f32 v46, v46, v49
	ds_write_b16 v47, v46
	v_add_u32_e32 v47, 0x125d0, v0
	ds_write_b16_d16_hi v47, v46
	v_mov_b64_e32 v[46:47], v[158:159]
	v_mov_b64_e32 v[48:49], v[232:233]
	v_mul_f32_e32 v50, v65, v55
	s_waitcnt vmcnt(0)
	v_fma_f32 v46, v50, v46, v48
	v_mul_f32_e32 v48, v64, v55
	v_fmac_f32_e32 v49, v48, v47
	v_add_u32_e32 v47, 0x126e0, v0
	v_cvt_pk_bf16_f32 v46, v46, v49
	ds_write_b16 v47, v46
	v_add_u32_e32 v47, 0x127f0, v0
	ds_write_b16_d16_hi v47, v46
	v_mov_b64_e32 v[46:47], v[184:185]
	v_mov_b64_e32 v[48:49], v[234:235]
	v_mul_f32_e32 v50, v63, v55
	s_waitcnt vmcnt(0)
	v_fma_f32 v46, v50, v46, v48
	v_mul_f32_e32 v48, v62, v55
	v_fmac_f32_e32 v49, v48, v47
	v_add_u32_e32 v47, 0x12900, v0
	v_cvt_pk_bf16_f32 v46, v46, v49
	ds_write_b16 v47, v46
	v_add_u32_e32 v47, 0x12a10, v0
	ds_write_b16_d16_hi v47, v46
	v_mov_b64_e32 v[46:47], v[186:187]
	v_mov_b64_e32 v[48:49], v[236:237]
	v_mul_f32_e32 v50, v61, v55
	v_lshlrev_b32_e32 v61, 16, v18
	v_and_b32_e32 v62, 0xffff0000, v18
	s_waitcnt vmcnt(0)
	v_fma_f32 v46, v50, v46, v48
	v_mul_f32_e32 v48, v60, v55
	v_fmac_f32_e32 v49, v48, v47
	v_add_u32_e32 v47, 0x12b20, v0
	v_cvt_pk_bf16_f32 v46, v46, v49
	ds_write_b16 v47, v46
	v_add_u32_e32 v47, 0x12c30, v0
	ds_write_b16_d16_hi v47, v46
	v_mov_b64_e32 v[46:47], v[188:189]
	v_mov_b64_e32 v[48:49], v[238:239]
	v_mul_f32_e32 v50, v59, v55
	v_lshlrev_b32_e32 v60, 16, v19
	v_and_b32_e32 v59, 0xffff0000, v19
	s_waitcnt vmcnt(0)
	v_fma_f32 v46, v50, v46, v48
	v_mul_f32_e32 v48, v58, v55
	v_fmac_f32_e32 v49, v48, v47
	v_add_u32_e32 v47, 0x12d40, v0
	v_cvt_pk_bf16_f32 v46, v46, v49
	ds_write_b16 v47, v46
	v_add_u32_e32 v47, 0x12e50, v0
	ds_write_b16_d16_hi v47, v46
	v_mov_b64_e32 v[46:47], v[190:191]
	v_mov_b64_e32 v[48:49], v[240:241]
	v_mul_f32_e32 v50, v57, v55
	v_lshlrev_b32_e32 v58, 16, v20
	v_and_b32_e32 v57, 0xffff0000, v20
	s_waitcnt vmcnt(0)
	v_fma_f32 v46, v50, v46, v48
	v_mul_f32_e32 v48, v56, v55
	v_fmac_f32_e32 v49, v48, v47
	v_add_u32_e32 v47, 0x12f60, v0
	v_cvt_pk_bf16_f32 v46, v46, v49
	ds_write_b16 v47, v46
	v_add_u32_e32 v47, 0x13070, v0
	ds_write_b16_d16_hi v47, v46
	v_mov_b64_e32 v[46:47], v[192:193]
	v_mov_b64_e32 v[48:49], v[242:243]
	v_and_b32_e32 v50, 0xffff0000, v15
	v_lshlrev_b32_e32 v15, 16, v6
	v_and_b32_e32 v6, 0xffff0000, v9
	v_lshlrev_b32_e32 v56, 16, v21
	v_and_b32_e32 v55, 0xffff0000, v21
	v_mul_f32_e32 v88, 0x3d372713, v6
	v_fma_f32 v88, v88, v6, 1.0
	s_waitcnt vmcnt(0)
	v_fma_f32 v45, v45, v46, v48
	v_fmac_f32_e32 v49, v44, v47
	v_cvt_pk_bf16_f32 v44, v45, v49
	v_add_u32_e32 v45, 0x13180, v0
	ds_write_b16 v45, v44
	v_add_u32_e32 v45, 0x13290, v0
	ds_write_b16_d16_hi v45, v44
	v_mov_b64_e32 v[44:45], v[194:195]
	v_mov_b64_e32 v[46:47], v[244:245]
	v_lshlrev_b32_e32 v49, 16, v16
	v_and_b32_e32 v48, 0xffff0000, v16
	s_waitcnt vmcnt(0)
	v_fma_f32 v43, v43, v44, v46
	v_fmac_f32_e32 v47, v42, v45
	v_cvt_pk_bf16_f32 v42, v43, v47
	v_add_u32_e32 v43, 0x133a0, v0
	ds_write_b16 v43, v42
	v_add_u32_e32 v43, 0x134b0, v0
	ds_write_b16_d16_hi v43, v42
	v_mov_b64_e32 v[42:43], v[196:197]
	v_mov_b64_e32 v[44:45], v[200:201]
	v_lshlrev_b32_e32 v47, 16, v17
	v_and_b32_e32 v46, 0xffff0000, v17
	v_mul_f32_e32 v17, 0x3d372713, v14
	v_fma_f32 v17, v17, v14, 1.0
	s_waitcnt vmcnt(0)
	v_fma_f32 v41, v41, v42, v44
	v_fmac_f32_e32 v45, v40, v43
	v_cvt_pk_bf16_f32 v40, v41, v45
	v_add_u32_e32 v41, 0x135c0, v0
	ds_write_b16 v41, v40
	v_add_u32_e32 v41, 0x136d0, v0
	ds_write_b16_d16_hi v41, v40
	v_mov_b64_e32 v[40:41], v[198:199]
	v_mov_b64_e32 v[42:43], v[202:203]
	v_lshlrev_b32_e32 v45, 16, v10
	v_and_b32_e32 v44, 0xffff0000, v10
	v_and_b32_e32 v10, 0xffff0000, v8
	s_waitcnt vmcnt(0)
; __device__ __forceinline__ float gelu_f(float x) { const float y2 = 1.5957691216057308f * x * (1.0f + 0.044715f * x * x); return x * sigmoid_f(y2); }
; __device__ __forceinline__ void unpack8(const u32x4 w, float* f) { f[0] = bf_lo(w.x); f[1] = bf_hi(w.x); f[2] = bf_lo(w.y); f[3] = bf_hi(w.y); f[4] = bf_lo(w.z); f[5] = bf_hi(w.z); f[6] = bf_lo(w.w); f[7] = bf_hi(w.w); }
; __device__ __forceinline__ void p2_block(LAS unsigned char* lds, const bf16_t* __restrict__ PROJ, bf16_t* __restrict__ ATT, bf16_t* __restrict__ SGU, const float* __restrict__ qn, const float* __restrict__ kn, ...
;     ...
;         for (int c4 = 0; c4 < 4; ++c4) unpack8(sv[gi][c4], v + 8 * c4);
;         float sm = 0.f;
; #pragma unroll
;         for (int j = 0; j < 32; ++j) { v[j] = gelu_f(v[j]); sm += v[j]; }
;         sm += __shfl_xor(sm, 1); sm += __shfl_xor(sm, 2);
;         const float mu = sm * (1.0f / 128.0f); float q = 0.f;
; #pragma unroll
;         for (int j = 0; j < 32; ++j) { v[j] -= mu; q += v[j] * v[j]; }
;         q += __shfl_xor(q, 1); q += __shfl_xor(q, 2);
;         const float rstd = rsqrtf(q * (1.0f / 128.0f) + pg8::EPS);
;         const float* gp = lng + gg * 128 + 32 * q4; const float* bp = lnb + gg * 128 + 32 * q4;
	global_load_dwordx4 v[144:147], v182, s[36:37] offset:512
	global_load_dwordx4 v[148:151], v182, s[36:37] offset:528
	global_load_dwordx4 v[152:155], v182, s[36:37] offset:544
	global_load_dwordx4 v[156:159], v182, s[36:37] offset:560
	global_load_dwordx4 v[184:187], v182, s[36:37] offset:576
	global_load_dwordx4 v[188:191], v182, s[36:37] offset:592
	global_load_dwordx4 v[192:195], v182, s[36:37] offset:608
	global_load_dwordx4 v[196:199], v182, s[36:37] offset:624
	global_load_dwordx4 v[218:221], v182, s[18:19] offset:512
	global_load_dwordx4 v[222:225], v182, s[18:19] offset:528
	global_load_dwordx4 v[226:229], v182, s[18:19] offset:544
	global_load_dwordx4 v[230:233], v182, s[18:19] offset:560
	global_load_dwordx4 v[234:237], v182, s[18:19] offset:576
	global_load_dwordx4 v[238:241], v182, s[18:19] offset:592
	global_load_dwordx4 v[242:245], v182, s[18:19] offset:608
	global_load_dwordx4 v[200:203], v182, s[18:19] offset:624
	v_fma_f32 v39, v39, v40, v42
	v_fmac_f32_e32 v43, v38, v41
	v_cvt_pk_bf16_f32 v38, v39, v43
	v_add_u32_e32 v39, 0x137e0, v0
	ds_write_b16 v39, v38
	v_add_u32_e32 v39, 0x138f0, v0
	ds_write_b16_d16_hi v39, v38
	v_lshlrev_b32_e32 v41, 16, v12
	v_and_b32_e32 v40, 0xffff0000, v12
	v_lshlrev_b32_e32 v39, 16, v13
	v_and_b32_e32 v38, 0xffff0000, v13
	v_lshlrev_b32_e32 v13, 16, v7
	v_and_b32_e32 v12, 0xffff0000, v7
	v_lshlrev_b32_e32 v7, 16, v9
	v_mul_f32_e32 v9, 0x3d372713, v61
	v_lshlrev_b32_e32 v43, 16, v11
	v_and_b32_e32 v42, 0xffff0000, v11
	v_lshlrev_b32_e32 v11, 16, v8
	v_mul_f32_e32 v8, 0x3fcc422a, v61
	v_fma_f32 v9, v9, v61, 1.0
	v_mul_f32_e32 v8, v8, v9
	v_mul_f32_e32 v8, 0xbfb8aa3b, v8
	v_exp_f32_e32 v8, v8
	v_mul_f32_e32 v9, 0x3d372713, v62
	v_fma_f32 v9, v9, v62, 1.0
	v_add_f32_e32 v8, 1.0, v8
	v_rcp_f32_e32 v63, v8
	v_mul_f32_e32 v8, 0x3fcc422a, v62
	v_mul_f32_e32 v8, v8, v9
	v_mul_f32_e32 v8, 0xbfb8aa3b, v8
	v_exp_f32_e32 v8, v8
	v_mul_f32_e32 v9, 0x3d372713, v60
	v_fma_f32 v9, v9, v60, 1.0
	v_fma_f32 v16, v63, v61, 0
	v_add_f32_e32 v8, 1.0, v8
	v_rcp_f32_e32 v64, v8
	v_mul_f32_e32 v8, 0x3fcc422a, v60
	v_mul_f32_e32 v8, v8, v9
	v_mul_f32_e32 v8, 0xbfb8aa3b, v8
	v_exp_f32_e32 v8, v8
	v_mul_f32_e32 v9, 0x3d372713, v59
	v_fma_f32 v9, v9, v59, 1.0
	v_fmac_f32_e32 v16, v64, v62
	v_add_f32_e32 v8, 1.0, v8
	v_rcp_f32_e32 v65, v8
	v_mul_f32_e32 v8, 0x3fcc422a, v59
	v_mul_f32_e32 v8, v8, v9
	v_mul_f32_e32 v8, 0xbfb8aa3b, v8
	v_exp_f32_e32 v8, v8
	v_mul_f32_e32 v9, 0x3d372713, v58
	v_fma_f32 v9, v9, v58, 1.0
	v_fmac_f32_e32 v16, v65, v60
	v_add_f32_e32 v8, 1.0, v8
	v_rcp_f32_e32 v66, v8
	v_mul_f32_e32 v8, 0x3fcc422a, v58
	v_mul_f32_e32 v8, v8, v9
	v_mul_f32_e32 v8, 0xbfb8aa3b, v8
	v_exp_f32_e32 v8, v8
	v_mul_f32_e32 v9, 0x3d372713, v57
	v_fma_f32 v9, v9, v57, 1.0
	v_fmac_f32_e32 v16, v66, v59
	v_add_f32_e32 v8, 1.0, v8
	v_rcp_f32_e32 v67, v8
	v_mul_f32_e32 v8, 0x3fcc422a, v57
	v_mul_f32_e32 v8, v8, v9
	v_mul_f32_e32 v8, 0xbfb8aa3b, v8
	v_exp_f32_e32 v8, v8
	v_mul_f32_e32 v9, 0x3d372713, v56
	v_fma_f32 v9, v9, v56, 1.0
	v_fmac_f32_e32 v16, v67, v58
	v_add_f32_e32 v8, 1.0, v8
	v_rcp_f32_e32 v68, v8
	v_mul_f32_e32 v8, 0x3fcc422a, v56
	v_mul_f32_e32 v8, v8, v9
	v_mul_f32_e32 v8, 0xbfb8aa3b, v8
	v_exp_f32_e32 v8, v8
	v_mul_f32_e32 v9, 0x3d372713, v55
	v_fma_f32 v9, v9, v55, 1.0
	v_fmac_f32_e32 v16, v68, v57
	v_add_f32_e32 v8, 1.0, v8
	v_rcp_f32_e32 v69, v8
	v_mul_f32_e32 v8, 0x3fcc422a, v55
	v_mul_f32_e32 v8, v8, v9
	v_mul_f32_e32 v8, 0xbfb8aa3b, v8
	v_exp_f32_e32 v8, v8
	v_mul_f32_e32 v9, 0x3d372713, v53
	v_fma_f32 v9, v9, v53, 1.0
	v_fmac_f32_e32 v16, v69, v56
	v_add_f32_e32 v8, 1.0, v8
	v_rcp_f32_e32 v70, v8
	v_mul_f32_e32 v8, 0x3fcc422a, v53
	v_mul_f32_e32 v8, v8, v9
	v_mul_f32_e32 v8, 0xbfb8aa3b, v8
	v_exp_f32_e32 v8, v8
	v_mul_f32_e32 v9, 0x3d372713, v52
	v_fma_f32 v9, v9, v52, 1.0
	v_fmac_f32_e32 v16, v70, v55
	v_add_f32_e32 v8, 1.0, v8
	v_rcp_f32_e32 v71, v8
	v_mul_f32_e32 v8, 0x3fcc422a, v52
	v_mul_f32_e32 v8, v8, v9
	v_mul_f32_e32 v8, 0xbfb8aa3b, v8
	v_exp_f32_e32 v8, v8
	v_mul_f32_e32 v9, 0x3d372713, v51
	v_fma_f32 v9, v9, v51, 1.0
	v_fmac_f32_e32 v16, v71, v53
	v_add_f32_e32 v8, 1.0, v8
	v_rcp_f32_e32 v72, v8
	v_mul_f32_e32 v8, 0x3fcc422a, v51
	v_mul_f32_e32 v8, v8, v9
	v_mul_f32_e32 v8, 0xbfb8aa3b, v8
	v_exp_f32_e32 v8, v8
	v_mul_f32_e32 v9, 0x3d372713, v50
	v_fma_f32 v9, v9, v50, 1.0
	v_fmac_f32_e32 v16, v72, v52
	v_add_f32_e32 v8, 1.0, v8
	v_rcp_f32_e32 v73, v8
	v_mul_f32_e32 v8, 0x3fcc422a, v50
	v_mul_f32_e32 v8, v8, v9
	v_mul_f32_e32 v8, 0xbfb8aa3b, v8
	v_exp_f32_e32 v8, v8
	v_mul_f32_e32 v9, 0x3d372713, v49
	v_fma_f32 v9, v9, v49, 1.0
	v_fmac_f32_e32 v16, v73, v51
	v_add_f32_e32 v8, 1.0, v8
	v_rcp_f32_e32 v74, v8
	v_mul_f32_e32 v8, 0x3fcc422a, v49
	v_mul_f32_e32 v8, v8, v9
	v_mul_f32_e32 v8, 0xbfb8aa3b, v8
	v_exp_f32_e32 v8, v8
	v_mul_f32_e32 v9, 0x3d372713, v48
	v_fma_f32 v9, v9, v48, 1.0
	v_fmac_f32_e32 v16, v74, v50
	v_add_f32_e32 v8, 1.0, v8
	v_rcp_f32_e32 v75, v8
	v_mul_f32_e32 v8, 0x3fcc422a, v48
	v_mul_f32_e32 v8, v8, v9
	v_mul_f32_e32 v8, 0xbfb8aa3b, v8
	v_exp_f32_e32 v8, v8
	v_mul_f32_e32 v9, 0x3d372713, v47
	v_fma_f32 v9, v9, v47, 1.0
	v_fmac_f32_e32 v16, v75, v49
	v_add_f32_e32 v8, 1.0, v8
	v_rcp_f32_e32 v76, v8
	v_mul_f32_e32 v8, 0x3fcc422a, v47
	v_mul_f32_e32 v8, v8, v9
	v_mul_f32_e32 v8, 0xbfb8aa3b, v8
	v_exp_f32_e32 v8, v8
	v_mul_f32_e32 v9, 0x3d372713, v46
	v_fma_f32 v9, v9, v46, 1.0
	v_fmac_f32_e32 v16, v76, v48
	v_add_f32_e32 v8, 1.0, v8
	v_rcp_f32_e32 v77, v8
	v_mul_f32_e32 v8, 0x3fcc422a, v46
	v_mul_f32_e32 v8, v8, v9
	v_mul_f32_e32 v8, 0xbfb8aa3b, v8
	v_exp_f32_e32 v8, v8
	v_mul_f32_e32 v9, 0x3d372713, v45
	v_fma_f32 v9, v9, v45, 1.0
	v_fmac_f32_e32 v16, v77, v47
	v_add_f32_e32 v8, 1.0, v8
; __device__ __forceinline__ float gelu_f(float x) { const float y2 = 1.5957691216057308f * x * (1.0f + 0.044715f * x * x); return x * sigmoid_f(y2); }
; __device__ __forceinline__ float sigmoid_f(float v) { return __builtin_amdgcn_rcpf(1.0f + __expf(-v)); }
; __device__ __forceinline__ void p2_block(LAS unsigned char* lds, const bf16_t* __restrict__ PROJ, bf16_t* __restrict__ ATT, bf16_t* __restrict__ SGU, const float* __restrict__ qn, const float* __restrict__ kn, ...
;     ...
;         for (int j = 0; j < 32; ++j) { v[j] = gelu_f(v[j]); sm += v[j]; }
;         sm += __shfl_xor(sm, 1); sm += __shfl_xor(sm, 2);
	v_rcp_f32_e32 v78, v8
	v_mul_f32_e32 v8, 0x3fcc422a, v45
	v_mul_f32_e32 v8, v8, v9
	v_mul_f32_e32 v8, 0xbfb8aa3b, v8
	v_exp_f32_e32 v8, v8
	v_mul_f32_e32 v9, 0x3d372713, v44
	v_fma_f32 v9, v9, v44, 1.0
	v_fmac_f32_e32 v16, v78, v46
	v_add_f32_e32 v8, 1.0, v8
	v_rcp_f32_e32 v79, v8
	v_mul_f32_e32 v8, 0x3fcc422a, v44
	v_mul_f32_e32 v8, v8, v9
	v_mul_f32_e32 v8, 0xbfb8aa3b, v8
	v_exp_f32_e32 v8, v8
	v_mul_f32_e32 v9, 0x3d372713, v43
	v_fma_f32 v9, v9, v43, 1.0
	v_fmac_f32_e32 v16, v79, v45
	v_add_f32_e32 v8, 1.0, v8
	v_rcp_f32_e32 v80, v8
	v_mul_f32_e32 v8, 0x3fcc422a, v43
	v_mul_f32_e32 v8, v8, v9
	v_mul_f32_e32 v8, 0xbfb8aa3b, v8
	v_exp_f32_e32 v8, v8
	v_mul_f32_e32 v9, 0x3d372713, v42
	v_fma_f32 v9, v9, v42, 1.0
	v_fmac_f32_e32 v16, v80, v44
	v_add_f32_e32 v8, 1.0, v8
	v_rcp_f32_e32 v81, v8
	v_mul_f32_e32 v8, 0x3fcc422a, v42
	v_mul_f32_e32 v8, v8, v9
	v_mul_f32_e32 v8, 0xbfb8aa3b, v8
	v_exp_f32_e32 v8, v8
	v_mul_f32_e32 v9, 0x3d372713, v41
	v_fma_f32 v9, v9, v41, 1.0
	v_fmac_f32_e32 v16, v81, v43
	v_add_f32_e32 v8, 1.0, v8
	v_rcp_f32_e32 v82, v8
	v_mul_f32_e32 v8, 0x3fcc422a, v41
	v_mul_f32_e32 v8, v8, v9
	v_mul_f32_e32 v8, 0xbfb8aa3b, v8
	v_exp_f32_e32 v8, v8
	v_mul_f32_e32 v9, 0x3d372713, v40
	v_fma_f32 v9, v9, v40, 1.0
	v_fmac_f32_e32 v16, v82, v42
	v_add_f32_e32 v8, 1.0, v8
	v_rcp_f32_e32 v83, v8
	v_mul_f32_e32 v8, 0x3fcc422a, v40
	v_mul_f32_e32 v8, v8, v9
	v_mul_f32_e32 v8, 0xbfb8aa3b, v8
	v_exp_f32_e32 v8, v8
	v_mul_f32_e32 v9, 0x3d372713, v39
	v_fma_f32 v9, v9, v39, 1.0
	v_fmac_f32_e32 v16, v83, v41
	v_add_f32_e32 v8, 1.0, v8
	v_rcp_f32_e32 v84, v8
	v_mul_f32_e32 v8, 0x3fcc422a, v39
	v_mul_f32_e32 v8, v8, v9
	v_mul_f32_e32 v8, 0xbfb8aa3b, v8
	v_exp_f32_e32 v8, v8
	v_mul_f32_e32 v9, 0x3d372713, v38
	v_fma_f32 v9, v9, v38, 1.0
	v_fmac_f32_e32 v16, v84, v40
	v_add_f32_e32 v8, 1.0, v8
	v_rcp_f32_e32 v85, v8
	v_mul_f32_e32 v8, 0x3fcc422a, v38
	v_mul_f32_e32 v8, v8, v9
	v_mul_f32_e32 v8, 0xbfb8aa3b, v8
	v_exp_f32_e32 v8, v8
	v_mul_f32_e32 v9, 0x3d372713, v15
	v_fma_f32 v9, v9, v15, 1.0
	v_fmac_f32_e32 v16, v85, v39
	v_add_f32_e32 v8, 1.0, v8
	v_rcp_f32_e32 v86, v8
	v_mul_f32_e32 v8, 0x3fcc422a, v15
	v_mul_f32_e32 v8, v8, v9
	v_mul_f32_e32 v8, 0xbfb8aa3b, v8
	v_exp_f32_e32 v8, v8
	v_fmac_f32_e32 v16, v86, v38
	v_add_f32_e32 v8, 1.0, v8
	v_rcp_f32_e32 v9, v8
	v_mul_f32_e32 v8, 0x3fcc422a, v14
	v_mul_f32_e32 v8, v8, v17
	v_mul_f32_e32 v8, 0xbfb8aa3b, v8
	v_exp_f32_e32 v8, v8
	v_mul_f32_e32 v17, 0x3d372713, v13
	v_fma_f32 v17, v17, v13, 1.0
	v_add_f32_e32 v8, 1.0, v8
	v_rcp_f32_e32 v8, v8
	s_nop 0
	v_pk_mul_f32 v[18:19], v[8:9], v[14:15]
	s_nop 0
	v_add_f32_e32 v16, v19, v16
	v_add_f32_e32 v20, v18, v16
	v_mul_f32_e32 v16, 0x3fcc422a, v13
	v_mul_f32_e32 v16, v16, v17
	v_mul_f32_e32 v16, 0xbfb8aa3b, v16
	v_exp_f32_e32 v16, v16
	v_mul_f32_e32 v18, 0x3d372713, v12
	v_fma_f32 v18, v18, v12, 1.0
	v_add_f32_e32 v16, 1.0, v16
	v_rcp_f32_e32 v17, v16
	v_mul_f32_e32 v16, 0x3fcc422a, v12
	v_mul_f32_e32 v16, v16, v18
	v_mul_f32_e32 v16, 0xbfb8aa3b, v16
	v_exp_f32_e32 v16, v16
	s_nop 0
	v_add_f32_e32 v16, 1.0, v16
	v_rcp_f32_e32 v16, v16
	s_nop 0
	v_pk_mul_f32 v[18:19], v[16:17], v[12:13]
	s_nop 0
	v_add_f32_e32 v19, v19, v20
	v_add_f32_e32 v87, v18, v19
	v_mul_f32_e32 v19, 0x3d372713, v11
	v_mul_f32_e32 v18, 0x3fcc422a, v11
	v_fma_f32 v19, v19, v11, 1.0
	v_mul_f32_e32 v18, v18, v19
	v_mul_f32_e32 v18, 0xbfb8aa3b, v18
	v_exp_f32_e32 v18, v18
	v_mul_f32_e32 v20, 0x3d372713, v10
	v_fma_f32 v20, v20, v10, 1.0
	v_add_f32_e32 v18, 1.0, v18
	v_rcp_f32_e32 v19, v18
	v_mul_f32_e32 v18, 0x3fcc422a, v10
	v_mul_f32_e32 v18, v18, v20
	v_mul_f32_e32 v18, 0xbfb8aa3b, v18
	v_exp_f32_e32 v18, v18
	s_nop 0
	v_add_f32_e32 v18, 1.0, v18
	v_rcp_f32_e32 v18, v18
	s_nop 0
	v_pk_mul_f32 v[20:21], v[18:19], v[10:11]
	s_nop 0
	v_add_f32_e32 v21, v21, v87
	v_add_f32_e32 v87, v20, v21
	v_mul_f32_e32 v21, 0x3d372713, v7
	v_mul_f32_e32 v20, 0x3fcc422a, v7
	v_fma_f32 v21, v21, v7, 1.0
	v_mul_f32_e32 v20, v20, v21
	v_mul_f32_e32 v20, 0xbfb8aa3b, v20
	v_exp_f32_e32 v20, v20
	s_nop 0
	v_add_f32_e32 v20, 1.0, v20
	v_rcp_f32_e32 v21, v20
	v_mul_f32_e32 v20, 0x3fcc422a, v6
	v_mul_f32_e32 v20, v20, v88
	v_mul_f32_e32 v20, 0xbfb8aa3b, v20
	v_exp_f32_e32 v20, v20
	s_nop 0
	v_add_f32_e32 v20, 1.0, v20
	v_rcp_f32_e32 v20, v20
	s_nop 0
	v_pk_mul_f32 v[88:89], v[20:21], v[6:7]
	s_nop 0
	v_add_f32_e32 v87, v89, v87
	v_add_f32_e32 v87, v88, v87
	ds_bpermute_b32 v88, v164, v87
	s_waitcnt lgkmcnt(0)
	v_add_f32_e32 v87, v87, v88
	ds_bpermute_b32 v88, v54, v87
	s_waitcnt lgkmcnt(0)
; __device__ __forceinline__ unsigned cvt_pk_bf16(float lo, float hi) { unsigned r; asm volatile("v_cvt_pk_bf16_f32 %0, %1, %2" : "=v"(r) : "v"(lo), "v"(hi)); return r; }
; #define LAS __attribute__((address_space(3)))
; __device__ __forceinline__ void p2_block(LAS unsigned char* lds, const bf16_t* __restrict__ PROJ, bf16_t* __restrict__ ATT, bf16_t* __restrict__ SGU, const float* __restrict__ qn, const float* __restrict__ kn, ...
;     ...
;         const float mu = sm * (1.0f / 128.0f); float q = 0.f;
; #pragma unroll
;         for (int j = 0; j < 32; ++j) { v[j] -= mu; q += v[j] * v[j]; }
;         q += __shfl_xor(q, 1); q += __shfl_xor(q, 2);
;         const float rstd = rsqrtf(q * (1.0f / 128.0f) + pg8::EPS);
;         const float* gp = lng + gg * 128 + 32 * q4; const float* bp = lnb + gg * 128 + 32 * q4;
;         LAS unsigned char* dst = lds + (gi ? VN_OFF1 : VN_OFF0) + (32 * q4) * VN_STRIDE + sp_ * 2;
; #pragma unroll
;         for (int j = 0; j < 32; j += 2) { const unsigned pk = cvt_pk_bf16(v[j] * rstd * gp[j] + bp[j], v[j + 1] * rstd * gp[j + 1] + bp[j + 1]);
;             *(LAS unsigned short*)(dst + j * VN_STRIDE) = (unsigned short)(pk & 0xffffu); *(LAS unsigned short*)(dst + (j + 1) * VN_STRIDE) = (unsigned short)(pk >> 16); }
	v_add_f32_e32 v87, v87, v88
	v_mul_f32_e32 v88, 0x3c000000, v87
	v_fma_f32 v63, v63, v61, -v88
	v_fma_f32 v61, v64, v62, -v88
	v_mul_f32_e32 v62, v61, v61
	v_fmac_f32_e32 v62, v63, v63
	v_fma_f32 v60, v65, v60, -v88
	v_fmac_f32_e32 v62, v60, v60
	v_fma_f32 v59, v66, v59, -v88
	v_fmac_f32_e32 v62, v59, v59
	v_fma_f32 v58, v67, v58, -v88
	v_fmac_f32_e32 v62, v58, v58
	v_fma_f32 v57, v68, v57, -v88
	v_fmac_f32_e32 v62, v57, v57
	v_fma_f32 v56, v69, v56, -v88
	v_fmac_f32_e32 v62, v56, v56
	v_fma_f32 v55, v70, v55, -v88
	v_fmac_f32_e32 v62, v55, v55
	v_fma_f32 v53, v71, v53, -v88
	v_fmac_f32_e32 v62, v53, v53
	v_fma_f32 v52, v72, v52, -v88
	v_fmac_f32_e32 v62, v52, v52
	v_fma_f32 v51, v73, v51, -v88
	v_fmac_f32_e32 v62, v51, v51
	v_fma_f32 v50, v74, v50, -v88
	v_fmac_f32_e32 v62, v50, v50
	v_fma_f32 v49, v75, v49, -v88
	v_fmac_f32_e32 v62, v49, v49
	v_fma_f32 v48, v76, v48, -v88
	v_fmac_f32_e32 v62, v48, v48
	v_fma_f32 v47, v77, v47, -v88
	v_fmac_f32_e32 v62, v47, v47
	v_fma_f32 v46, v78, v46, -v88
	v_fmac_f32_e32 v62, v46, v46
	v_fma_f32 v45, v79, v45, -v88
	v_fmac_f32_e32 v62, v45, v45
	v_fma_f32 v44, v80, v44, -v88
	v_fmac_f32_e32 v62, v44, v44
	v_fma_f32 v43, v81, v43, -v88
	v_fmac_f32_e32 v62, v43, v43
	v_fma_f32 v42, v82, v42, -v88
	v_fmac_f32_e32 v62, v42, v42
	v_fma_f32 v41, v83, v41, -v88
	v_fmac_f32_e32 v62, v41, v41
	v_fma_f32 v40, v84, v40, -v88
	v_fmac_f32_e32 v62, v40, v40
	v_fma_f32 v39, v85, v39, -v88
	v_fmac_f32_e32 v62, v39, v39
	v_fma_f32 v38, v86, v38, -v88
	v_pk_fma_f32 v[14:15], v[8:9], v[14:15], v[88:89] op_sel_hi:[1,1,0] neg_lo:[0,0,1] neg_hi:[0,0,1]
	v_fmac_f32_e32 v62, v38, v38
	v_pk_mul_f32 v[8:9], v[14:15], v[14:15]
	v_pk_fma_f32 v[12:13], v[16:17], v[12:13], v[88:89] op_sel_hi:[1,1,0] neg_lo:[0,0,1] neg_hi:[0,0,1]
	v_add_f32_e32 v9, v9, v62
	v_add_f32_e32 v62, v8, v9
	v_pk_mul_f32 v[8:9], v[12:13], v[12:13]
	v_pk_fma_f32 v[6:7], v[20:21], v[6:7], v[88:89] op_sel_hi:[1,1,0] neg_lo:[0,0,1] neg_hi:[0,0,1]
	v_add_f32_e32 v9, v9, v62
	v_add_f32_e32 v16, v8, v9
	v_pk_fma_f32 v[8:9], v[18:19], v[10:11], v[88:89] op_sel_hi:[1,1,0] neg_lo:[0,0,1] neg_hi:[0,0,1]
	v_add_u32_e32 v19, 0x1a000, v0
	v_pk_mul_f32 v[10:11], v[8:9], v[8:9]
	v_lshlrev_b32_e32 v78, 16, v33
	v_add_f32_e32 v11, v11, v16
	v_add_f32_e32 v16, v10, v11
	v_pk_mul_f32 v[10:11], v[6:7], v[6:7]
	v_lshlrev_b32_e32 v79, 16, v5
	v_add_f32_e32 v11, v11, v16
	v_add_f32_e32 v10, v10, v11
	ds_bpermute_b32 v11, v164, v10
	v_and_b32_e32 v5, 0xffff0000, v4
	v_and_b32_e32 v4, 0xffff0000, v32
	v_mov_b32_e32 v32, v5
	v_mov_b32_e32 v33, v101
	s_waitcnt lgkmcnt(0)
	v_add_f32_e32 v10, v10, v11
	ds_bpermute_b32 v11, v54, v10
	v_mov_b32_e32 v54, v96
	v_add_u32_e32 v81, 0, v132
	v_lshlrev_b32_e32 v73, 2, v162
	v_sub_u32_e32 v74, v81, v130
	s_waitcnt lgkmcnt(0)
	v_add_f32_e32 v10, v10, v11
	v_fmamk_f32 v10, v10, 0x3c000000, v209
	v_cmp_gt_f32_e32 vcc, s82, v10
	v_mul_f32_e32 v11, 0x4b800000, v10
	v_or_b32_e32 v71, 2, v130
	v_cndmask_b32_e32 v10, v10, v11, vcc
	v_rsq_f32_e32 v10, v10
	v_or_b32_e32 v70, 3, v130
	v_or_b32_e32 v72, 4, v130
	v_mul_f32_e32 v11, 0x45800000, v10
	v_cndmask_b32_e32 v18, v10, v11, vcc
	s_waitcnt vmcnt(0)
	v_mov_b64_e32 v[10:11], v[144:145]
	v_mov_b64_e32 v[16:17], v[218:219]
	v_mul_f32_e32 v20, v63, v18
	v_mul_f32_e32 v15, v15, v18
	v_mul_f32_e32 v14, v14, v18
	v_mul_f32_e32 v13, v13, v18
	v_mul_f32_e32 v12, v12, v18
	v_mul_f32_e32 v9, v9, v18
	v_mul_f32_e32 v8, v8, v18
	v_mul_f32_e32 v7, v7, v18
	v_mul_f32_e32 v6, v6, v18
	s_waitcnt vmcnt(0)
	v_fma_f32 v10, v10, v20, v16
	v_mul_f32_e32 v16, v61, v18
	v_fmac_f32_e32 v17, v11, v16
	v_add_u32_e32 v11, 0x1a110, v0
	v_cvt_pk_bf16_f32 v10, v10, v17
	ds_write_b16 v19, v10
	ds_write_b16_d16_hi v11, v10
	v_mov_b64_e32 v[10:11], v[146:147]
	v_mov_b64_e32 v[16:17], v[220:221]
	v_mul_f32_e32 v19, v60, v18
	s_waitcnt vmcnt(0)
	v_fma_f32 v10, v10, v19, v16
	v_mul_f32_e32 v16, v59, v18
	v_fmac_f32_e32 v17, v11, v16
	v_add_u32_e32 v11, 0x1a220, v0
	v_cvt_pk_bf16_f32 v10, v10, v17
	ds_write_b16 v11, v10
	v_add_u32_e32 v11, 0x1a330, v0
	ds_write_b16_d16_hi v11, v10
	v_mov_b64_e32 v[10:11], v[148:149]
	v_mov_b64_e32 v[16:17], v[222:223]
	v_mul_f32_e32 v19, v58, v18
	s_waitcnt vmcnt(0)
	v_fma_f32 v10, v10, v19, v16
	v_mul_f32_e32 v16, v57, v18
	v_fmac_f32_e32 v17, v11, v16
	v_add_u32_e32 v11, 0x1a440, v0
	v_cvt_pk_bf16_f32 v10, v10, v17
	ds_write_b16 v11, v10
	v_add_u32_e32 v11, 0x1a550, v0
	ds_write_b16_d16_hi v11, v10
	v_mov_b64_e32 v[10:11], v[150:151]
	v_mov_b64_e32 v[16:17], v[224:225]
	v_mul_f32_e32 v19, v56, v18
	v_mov_b32_e32 v56, v109
	v_mov_b32_e32 v57, v105
	v_pk_fma_f32 v[110:111], v[56:57], v[56:57], v[110:111]
	s_waitcnt vmcnt(0)
	v_fma_f32 v10, v10, v19, v16
	v_mul_f32_e32 v16, v55, v18
	v_fmac_f32_e32 v17, v11, v16
	v_add_u32_e32 v11, 0x1a660, v0
	v_cvt_pk_bf16_f32 v10, v10, v17
	ds_write_b16 v11, v10
	v_add_u32_e32 v11, 0x1a770, v0
	ds_write_b16_d16_hi v11, v10
	v_mov_b64_e32 v[10:11], v[152:153]
	v_mov_b64_e32 v[16:17], v[226:227]
	v_mul_f32_e32 v19, v53, v18
	v_mov_b32_e32 v55, v78
	v_pk_mul_f32 v[54:55], v[54:55], v[54:55]
	s_waitcnt vmcnt(0)
	v_fma_f32 v10, v10, v19, v16
	v_mul_f32_e32 v16, v52, v18
	v_fmac_f32_e32 v17, v11, v16
	v_add_u32_e32 v11, 0x1a880, v0
	v_cvt_pk_bf16_f32 v10, v10, v17
	ds_write_b16 v11, v10
	v_add_u32_e32 v11, 0x1a990, v0
	ds_write_b16_d16_hi v11, v10
	v_mov_b64_e32 v[10:11], v[154:155]
	v_mov_b64_e32 v[16:17], v[228:229]
	v_mul_f32_e32 v19, v51, v18
	s_waitcnt vmcnt(0)
	v_fma_f32 v10, v10, v19, v16
	v_mul_f32_e32 v16, v50, v18
	v_fmac_f32_e32 v17, v11, v16
	v_add_u32_e32 v11, 0x1aaa0, v0
	v_cvt_pk_bf16_f32 v10, v10, v17
	ds_write_b16 v11, v10
	v_add_u32_e32 v11, 0x1abb0, v0
	ds_write_b16_d16_hi v11, v10
	v_mov_b64_e32 v[10:11], v[156:157]
	v_mov_b64_e32 v[16:17], v[230:231]
	v_mul_f32_e32 v19, v49, v18
	s_waitcnt vmcnt(0)
; #define LAS __attribute__((address_space(3)))
; __device__ __forceinline__ void p2_block(LAS unsigned char* lds, const bf16_t* __restrict__ PROJ, bf16_t* __restrict__ ATT, bf16_t* __restrict__ SGU, const float* __restrict__ qn, const float* __restrict__ kn, ...
;     ...
;         for (int j = 0; j < 32; j += 2) { const unsigned pk = cvt_pk_bf16(v[j] * rstd * gp[j] + bp[j], v[j + 1] * rstd * gp[j + 1] + bp[j + 1]);
;             *(LAS unsigned short*)(dst + j * VN_STRIDE) = (unsigned short)(pk & 0xffffu); *(LAS unsigned short*)(dst + (j + 1) * VN_STRIDE) = (unsigned short)(pk >> 16); }
;     }
;     __syncthreads();
; #pragma unroll
;     for (int c = 2; c < 4; ++c) { const bf16_t* qp = PROJ + ((size_t)b * pg8::SEQ + n * 128 + rbase + 16 * c + fr) * pg8::IN_W + hq * 64 + 8 * fq; qa[c] = *(const u32x4*)qp; qb[c] = *(const u32x4*)(qp + 32); }
;     const float sink = sinks[hq];
;     ...
;         const int i0 = rbase + 16 * c, irow = i0 + fr, pos = n * 128 + irow; const size_t grow = (size_t)b * pg8::SEQ + pos;
;         bf16x8 qf0, qf1;
;         {
;             float x1[8], x2[8]; unpack8(qa[c], x1); unpack8(qb[c], x2);
;             float ss = 0.f;
; #pragma unroll
;             for (int j = 0; j < 8; ++j) ss += x1[j] * x1[j] + x2[j] * x2[j];
;             ss += __shfl_xor(ss, 16); ss += __shfl_xor(ss, 32);
;             const float rinv = rsqrtf(ss * (1.0f / 64.0f) + pg8::EPS) * 0.125f;
;             const float* cp = COS + pos * 32 + 8 * fq; const float* sp = SIN + pos * 32 + 8 * fq;
;             float o1[8], o2[8];
; #pragma unroll
;             for (int j = 0; j < 8; ++j) { const float a1 = x1[j] * rinv * qn[8 * fq + j], a2 = x2[j] * rinv * qn[32 + 8 * fq + j], cc = cp[j], sn = sp[j]; o1[j] = a1 * cc - a2 * sn; o2[j] = a2 * cc + a1 * sn; }
;             u32x4 w0, w1;
;             w0.x = cvt_pk_bf16(o1[0], o1[1]); w0.y = cvt_pk_bf16(o1[2], o1[3]); w0.z = cvt_pk_bf16(o1[4], o1[5]); w0.w = cvt_pk_bf16(o1[6], o1[7]);
;             w1.x = cvt_pk_bf16(o2[0], o2[1]); w1.y = cvt_pk_bf16(o2[2], o2[3]); w1.z = cvt_pk_bf16(o2[4], o2[5]); w1.w = cvt_pk_bf16(o2[6], o2[7]);
;             qf0 = __builtin_bit_cast(bf16x8, w0); qf1 = __builtin_bit_cast(bf16x8, w1);
;         }
;         const int t0 = (i0 >> 4) < 6 ? (i0 >> 4) : 6;
;         f32x4 sc_[10];
;         const LAS unsigned char* kbase = KS + (16 * t0 + fr) * KS_STRIDE + 16 * fq;
	v_fma_f32 v10, v10, v19, v16
	v_mul_f32_e32 v16, v48, v18
	v_fmac_f32_e32 v17, v16, v11
	v_add_u32_e32 v11, 0x1acc0, v0
	v_cvt_pk_bf16_f32 v10, v10, v17
	ds_write_b16 v11, v10
	v_add_u32_e32 v11, 0x1add0, v0
	ds_write_b16_d16_hi v11, v10
	v_mov_b64_e32 v[10:11], v[158:159]
	v_mov_b64_e32 v[16:17], v[232:233]
	v_mul_f32_e32 v19, v47, v18
	s_waitcnt vmcnt(0)
	v_fma_f32 v10, v19, v10, v16
	v_mul_f32_e32 v16, v46, v18
	v_fmac_f32_e32 v17, v16, v11
	v_add_u32_e32 v11, 0x1aee0, v0
	v_cvt_pk_bf16_f32 v10, v10, v17
	ds_write_b16 v11, v10
	v_add_u32_e32 v11, 0x1aff0, v0
	ds_write_b16_d16_hi v11, v10
	v_mov_b64_e32 v[10:11], v[184:185]
	v_mov_b64_e32 v[16:17], v[234:235]
	v_mul_f32_e32 v19, v45, v18
	s_waitcnt vmcnt(0)
	v_fma_f32 v10, v19, v10, v16
	v_mul_f32_e32 v16, v44, v18
	v_fmac_f32_e32 v17, v16, v11
	v_add_u32_e32 v11, 0x1b100, v0
	v_cvt_pk_bf16_f32 v10, v10, v17
	ds_write_b16 v11, v10
	v_add_u32_e32 v11, 0x1b210, v0
	ds_write_b16_d16_hi v11, v10
	v_mov_b64_e32 v[10:11], v[186:187]
	v_mov_b64_e32 v[16:17], v[236:237]
	v_mul_f32_e32 v19, v43, v18
	v_or_b32_e32 v44, s17, v161
	s_waitcnt vmcnt(0)
	v_fma_f32 v10, v19, v10, v16
	v_mul_f32_e32 v16, v42, v18
	v_fmac_f32_e32 v17, v16, v11
	v_add_u32_e32 v11, 0x1b320, v0
	v_cvt_pk_bf16_f32 v10, v10, v17
	ds_write_b16 v11, v10
	v_add_u32_e32 v11, 0x1b430, v0
	ds_write_b16_d16_hi v11, v10
	v_mov_b64_e32 v[10:11], v[188:189]
	v_mov_b64_e32 v[16:17], v[238:239]
	v_mul_f32_e32 v19, v41, v18
	s_waitcnt vmcnt(0)
	v_fma_f32 v10, v19, v10, v16
	v_mul_f32_e32 v16, v40, v18
	v_fmac_f32_e32 v17, v16, v11
	v_add_u32_e32 v11, 0x1b540, v0
	v_cvt_pk_bf16_f32 v10, v10, v17
	ds_write_b16 v11, v10
	v_add_u32_e32 v11, 0x1b650, v0
	ds_write_b16_d16_hi v11, v10
	v_mov_b64_e32 v[10:11], v[190:191]
	v_mov_b64_e32 v[16:17], v[240:241]
	v_mul_f32_e32 v19, v39, v18
	s_waitcnt vmcnt(0)
	v_fma_f32 v10, v19, v10, v16
	v_mul_f32_e32 v16, v38, v18
	v_fmac_f32_e32 v17, v16, v11
	v_add_u32_e32 v11, 0x1b760, v0
	v_cvt_pk_bf16_f32 v10, v10, v17
	ds_write_b16 v11, v10
	v_add_u32_e32 v11, 0x1b870, v0
	ds_write_b16_d16_hi v11, v10
	v_mov_b64_e32 v[10:11], v[192:193]
	v_mov_b64_e32 v[16:17], v[242:243]
	s_waitcnt vmcnt(0)
	v_fma_f32 v10, v15, v10, v16
	v_fmac_f32_e32 v17, v14, v11
	v_add_u32_e32 v11, 0x1b980, v0
	v_cvt_pk_bf16_f32 v10, v10, v17
	ds_write_b16 v11, v10
	v_add_u32_e32 v11, 0x1ba90, v0
	ds_write_b16_d16_hi v11, v10
	v_mov_b64_e32 v[10:11], v[194:195]
	v_mov_b64_e32 v[14:15], v[244:245]
	s_waitcnt vmcnt(0)
	v_fma_f32 v10, v13, v10, v14
	v_fmac_f32_e32 v15, v12, v11
	v_add_u32_e32 v11, 0x1bba0, v0
	v_cvt_pk_bf16_f32 v10, v10, v15
	ds_write_b16 v11, v10
	v_add_u32_e32 v11, 0x1bcb0, v0
	ds_write_b16_d16_hi v11, v10
	v_mov_b64_e32 v[10:11], v[196:197]
	v_mov_b64_e32 v[12:13], v[200:201]
	v_lshlrev_b32_e32 v14, 7, v44
	v_mov_b32_e32 v15, v1
	v_or_b32_e32 v44, s48, v44
	s_waitcnt vmcnt(0)
	v_fma_f32 v9, v9, v10, v12
	v_fmac_f32_e32 v13, v8, v11
	v_cvt_pk_bf16_f32 v8, v9, v13
	v_add_u32_e32 v9, 0x1bdc0, v0
	ds_write_b16 v9, v8
	v_add_u32_e32 v9, 0x1bed0, v0
	ds_write_b16_d16_hi v9, v8
	v_mov_b64_e32 v[8:9], v[198:199]
	v_mov_b64_e32 v[10:11], v[202:203]
	s_waitcnt vmcnt(0)
	v_fma_f32 v7, v7, v8, v10
	v_fmac_f32_e32 v11, v6, v9
	v_cvt_pk_bf16_f32 v6, v7, v11
	v_add_u32_e32 v7, 0x1bfe0, v0
	v_add_u32_e32 v0, 0x1c0f0, v0
	ds_write_b16_d16_hi v0, v6
	v_or_b32_e32 v0, 32, v163
	ds_write_b16 v7, v6
	v_mad_u64_u32 v[6:7], s[28:29], v0, s83, v[134:135]
	v_mad_i32_i24 v7, s49, v212, v7
	v_or_b32_e32 v0, 48, v163
	v_readfirstlane_b32 s16, v204
	v_and_b32_e32 v43, 15, v204
	v_bfe_u32 v44, v204, 4, 2
	s_and_b32 s24, s2, 3
	s_lshr_b32 s16, s16, 6
	s_bfe_u32 s27, s2, 0x40002
	s_lshr_b32 s17, s16, 1
	s_and_b32 s25, s16, 1
	s_lshl_b32 s25, s25, 6
	s_lshl_b32 s26, s24, 2
	s_add_i32 s26, s26, s17
	s_and_b32 s28, s2, -4
	s_lshl_b32 s28, s28, 5
	s_lshl_b32 s29, s27, 7
	s_add_i32 s28, s28, s25
	s_add_i32 s29, s29, s25
	s_lshl_b32 s4, s26, 7
	v_add_u32_e32 v166, s28, v43
	v_mul_u32_u24_e32 v46, 0x3c00, v166
	v_lshl_add_u32 v46, v44, 4, v46
	v_add_u32_e32 v46, s4, v46
	v_lshlrev_b32_e32 v48, 11, v166
	v_lshl_add_u32 v48, v44, 3, v48
	v_add_u32_e32 v48, s4, v48
	v_add_u32_e32 v166, s29, v43
	v_lshlrev_b32_e32 v47, 7, v166
	v_lshl_add_u32 v47, v44, 5, v47
	v_mul_u32_u24_e32 v45, 0x90, v43
	v_lshl_add_u32 v45, v44, 4, v45
	v_mul_u32_u24_e32 v166, 0x210, v43
	v_lshl_add_u32 v166, v44, 3, v166
	v_add_u32_e32 v194, 0x9000, v166
	v_add_u32_e32 v195, 0xb100, v166
	v_add_u32_e32 v196, 0xd200, v166
	v_add_u32_e32 v197, 0xf300, v166
	v_lshlrev_b32_e32 v166, 2, v44
	v_sub_u32_e32 v166, v43, v166
	v_cmp_gt_i32_e64 s[40:41], 0, v166
	v_cmp_gt_i32_e64 s[42:43], 1, v166
	v_cmp_gt_i32_e64 s[44:45], 2, v166
	v_cmp_gt_i32_e64 s[46:47], 3, v166
	v_mov_b32_e32 v49, 0xf149f2ca
	v_lshlrev_b32_e32 v167, 5, v44
	v_mov_b32_e32 v166, s26
	v_lshlrev_b32_e32 v166, 2, v166
	s_mov_b32 s4, s25
	s_mov_b32 vcc_lo, s63
	s_mov_b32 vcc_hi, s78
	s_cmp_lg_u32 s27, 0
	s_cselect_b64 s[28:29], -1, 0
	s_and_b64 s[48:49], s[40:41], s[28:29]
	s_and_b64 s[50:51], s[42:43], s[28:29]
	s_and_b64 s[52:53], s[44:45], s[28:29]
	s_and_b64 s[26:27], s[46:47], s[28:29]
	v_readlane_b32 s6, v250, 36
	v_readlane_b32 s7, v250, 37
	v_readlane_b32 s16, v250, 38
	v_readlane_b32 s17, v250, 39
	v_readlane_b32 s24, v248, 54
	v_readlane_b32 s25, v248, 55
	global_load_dwordx4 v[26:29], v167, s[38:39]
	global_load_dwordx4 v[30:33], v167, s[38:39] offset:16
	global_load_dwordx4 v[34:37], v167, s[38:39] offset:128
	global_load_dwordx4 v[38:41], v167, s[38:39] offset:144
	global_load_dword v42, v166, vcc
	s_nop 1
	global_load_dwordx4 v[2:5], v46, s[10:11]
	global_load_dwordx4 v[6:9], v46, s[10:11] offset:64
	global_load_dwordx4 v[10:13], v47, s[6:7]
	global_load_dwordx4 v[14:17], v47, s[6:7] offset:16
	global_load_dwordx4 v[18:21], v47, s[16:17]
	global_load_dwordx4 v[22:25], v47, s[16:17] offset:16
	v_add_u32_e32 v46, 0x3c000, v46
	v_add_u32_e32 v47, 0x800, v47
	global_load_dwordx4 v[218:221], v46, s[10:11]
	global_load_dwordx4 v[222:225], v46, s[10:11] offset:64
	global_load_dwordx4 v[226:229], v47, s[6:7]
	global_load_dwordx4 v[230:233], v47, s[6:7] offset:16
	global_load_dwordx4 v[234:237], v47, s[16:17]
	global_load_dwordx4 v[238:241], v47, s[16:17] offset:16
	v_add_u32_e32 v46, 0x3c000, v46
	v_add_u32_e32 v47, 0x800, v47
	s_waitcnt lgkmcnt(0)
	s_barrier
	s_cmp_eq_u32 s4, 0
	s_cbranch_scc1 .Latt_r0
; __device__ __forceinline__ unsigned cvt_pk_bf16(float lo, float hi) { unsigned r; asm volatile("v_cvt_pk_bf16_f32 %0, %1, %2" : "=v"(r) : "v"(lo), "v"(hi)); return r; }
; #define LAS __attribute__((address_space(3)))
; #define MFMA16(a, b, c) __builtin_amdgcn_mfma_f32_16x16x32_bf16((a), (b), (c), 0, 0, 0)
; __device__ __forceinline__ void unpack8(const u32x4 w, float* f) { f[0] = bf_lo(w.x); f[1] = bf_hi(w.x); f[2] = bf_lo(w.y); f[3] = bf_hi(w.y); f[4] = bf_lo(w.z); f[5] = bf_hi(w.z); f[6] = bf_lo(w.w); f[7] = bf_hi(w.w); }
; __device__ __forceinline__ void p2_block(LAS unsigned char* lds, const bf16_t* __restrict__ PROJ, bf16_t* __restrict__ ATT, bf16_t* __restrict__ SGU, const float* __restrict__ qn, const float* __restrict__ kn, ...
;     ...
;             float x1[8], x2[8]; unpack8(qa[c], x1); unpack8(qb[c], x2);
;             float ss = 0.f;
; #pragma unroll
;             for (int j = 0; j < 8; ++j) ss += x1[j] * x1[j] + x2[j] * x2[j];
;             ss += __shfl_xor(ss, 16); ss += __shfl_xor(ss, 32);
;             const float rinv = rsqrtf(ss * (1.0f / 64.0f) + pg8::EPS) * 0.125f;
;             const float* cp = COS + pos * 32 + 8 * fq; const float* sp = SIN + pos * 32 + 8 * fq;
;             float o1[8], o2[8];
; #pragma unroll
;             for (int j = 0; j < 8; ++j) { const float a1 = x1[j] * rinv * qn[8 * fq + j], a2 = x2[j] * rinv * qn[32 + 8 * fq + j], cc = cp[j], sn = sp[j]; o1[j] = a1 * cc - a2 * sn; o2[j] = a2 * cc + a1 * sn; }
;             u32x4 w0, w1;
;             w0.x = cvt_pk_bf16(o1[0], o1[1]); w0.y = cvt_pk_bf16(o1[2], o1[3]); w0.z = cvt_pk_bf16(o1[4], o1[5]); w0.w = cvt_pk_bf16(o1[6], o1[7]);
;             w1.x = cvt_pk_bf16(o2[0], o2[1]); w1.y = cvt_pk_bf16(o2[2], o2[3]); w1.z = cvt_pk_bf16(o2[4], o2[5]); w1.w = cvt_pk_bf16(o2[6], o2[7]);
;             qf0 = __builtin_bit_cast(bf16x8, w0); qf1 = __builtin_bit_cast(bf16x8, w1);
;         }
;         const int t0 = (i0 >> 4) < 6 ? (i0 >> 4) : 6;
;         f32x4 sc_[10];
;         const LAS unsigned char* kbase = KS + (16 * t0 + fr) * KS_STRIDE + 16 * fq;
; #pragma unroll
;         for (int t = 0; t < 10; ++t) { const bf16x8 k0 = *(const LAS bf16x8*)(kbase + t * 16 * KS_STRIDE), k1 = *(const LAS bf16x8*)(kbase + t * 16 * KS_STRIDE + 64);
;             f32x4 z = (f32x4){0.f, 0.f, 0.f, 0.f}; z = MFMA16(k0, qf0, z); sc_[t] = MFMA16(k1, qf1, z); }
.Latt_r64:
	ds_read_b128 v[98:101], v45 offset:9216
	ds_read_b128 v[102:105], v45 offset:9280
	ds_read_b128 v[106:109], v45 offset:11520
	ds_read_b128 v[110:113], v45 offset:11584
	ds_read_b128 v[114:117], v45 offset:13824
	ds_read_b128 v[118:121], v45 offset:13888
	ds_read_b128 v[122:125], v45 offset:16128
	ds_read_b128 v[126:129], v45 offset:16192
	ds_read_b128 v[130:133], v45 offset:18432
	ds_read_b128 v[134:137], v45 offset:18496
	ds_read_b128 v[138:141], v45 offset:20736
	ds_read_b128 v[142:145], v45 offset:20800
	ds_read_b128 v[146:149], v45 offset:23040
	ds_read_b128 v[150:153], v45 offset:23104
	s_waitcnt vmcnt(6)
	v_lshlrev_b32_e32 v58, 16, v2
	v_and_b32_e32 v59, 0xffff0000, v2
	v_lshlrev_b32_e32 v66, 16, v6
	v_and_b32_e32 v67, 0xffff0000, v6
	v_lshlrev_b32_e32 v60, 16, v3
	v_and_b32_e32 v61, 0xffff0000, v3
	v_lshlrev_b32_e32 v68, 16, v7
	v_and_b32_e32 v69, 0xffff0000, v7
	v_lshlrev_b32_e32 v62, 16, v4
	v_and_b32_e32 v63, 0xffff0000, v4
	v_lshlrev_b32_e32 v70, 16, v8
	v_and_b32_e32 v71, 0xffff0000, v8
	v_lshlrev_b32_e32 v64, 16, v5
	v_and_b32_e32 v65, 0xffff0000, v5
	v_lshlrev_b32_e32 v72, 16, v9
	v_and_b32_e32 v73, 0xffff0000, v9
	v_pk_mul_f32 v[74:75], v[58:59], v[58:59]
	v_pk_fma_f32 v[74:75], v[60:61], v[60:61], v[74:75]
	v_pk_fma_f32 v[74:75], v[62:63], v[62:63], v[74:75]
	v_pk_fma_f32 v[74:75], v[64:65], v[64:65], v[74:75]
	v_pk_fma_f32 v[74:75], v[66:67], v[66:67], v[74:75]
	v_pk_fma_f32 v[74:75], v[68:69], v[68:69], v[74:75]
	v_pk_fma_f32 v[74:75], v[70:71], v[70:71], v[74:75]
	v_pk_fma_f32 v[74:75], v[72:73], v[72:73], v[74:75]
	v_add_f32_e32 v74, v74, v75
	v_mov_b32_e32 v166, v74
	s_nop 1
	v_permlane16_swap_b32_e32 v74, v166
	v_add_f32_e32 v74, v74, v166
	v_mov_b32_e32 v166, v74
	s_nop 1
	v_permlane32_swap_b32_e32 v74, v166
	v_add_f32_e32 v74, v74, v166
	v_fmamk_f32 v74, v74, 0x3c800000, v209
	v_rsq_f32_e32 v76, v74
	s_nop 0
	v_mul_f32_e32 v76, 0x3e000000, v76
	v_pk_mul_f32 v[58:59], v[58:59], v[76:77] op_sel_hi:[1,0]
	v_pk_mul_f32 v[66:67], v[66:67], v[76:77] op_sel_hi:[1,0]
	v_pk_mul_f32 v[60:61], v[60:61], v[76:77] op_sel_hi:[1,0]
	v_pk_mul_f32 v[68:69], v[68:69], v[76:77] op_sel_hi:[1,0]
	v_pk_mul_f32 v[62:63], v[62:63], v[76:77] op_sel_hi:[1,0]
	v_pk_mul_f32 v[70:71], v[70:71], v[76:77] op_sel_hi:[1,0]
	v_pk_mul_f32 v[64:65], v[64:65], v[76:77] op_sel_hi:[1,0]
	v_pk_mul_f32 v[72:73], v[72:73], v[76:77] op_sel_hi:[1,0]
	v_pk_mul_f32 v[58:59], v[58:59], v[26:27]
	v_pk_mul_f32 v[66:67], v[66:67], v[34:35]
	v_pk_mul_f32 v[60:61], v[60:61], v[28:29]
	v_pk_mul_f32 v[68:69], v[68:69], v[36:37]
	v_pk_mul_f32 v[62:63], v[62:63], v[30:31]
	v_pk_mul_f32 v[70:71], v[70:71], v[38:39]
	v_pk_mul_f32 v[64:65], v[64:65], v[32:33]
	v_pk_mul_f32 v[72:73], v[72:73], v[40:41]
	v_pk_mul_f32 v[78:79], v[66:67], v[18:19]
	v_pk_mul_f32 v[86:87], v[58:59], v[18:19]
	v_pk_mul_f32 v[80:81], v[68:69], v[20:21]
	v_pk_mul_f32 v[88:89], v[60:61], v[20:21]
	v_pk_mul_f32 v[82:83], v[70:71], v[22:23]
	v_pk_mul_f32 v[90:91], v[62:63], v[22:23]
	v_pk_mul_f32 v[84:85], v[72:73], v[24:25]
	v_pk_mul_f32 v[92:93], v[64:65], v[24:25]
	v_pk_fma_f32 v[78:79], v[58:59], v[10:11], v[78:79] neg_lo:[0,0,1] neg_hi:[0,0,1]
	v_pk_fma_f32 v[86:87], v[66:67], v[10:11], v[86:87]
	v_pk_fma_f32 v[80:81], v[60:61], v[12:13], v[80:81] neg_lo:[0,0,1] neg_hi:[0,0,1]
	v_pk_fma_f32 v[88:89], v[68:69], v[12:13], v[88:89]
	v_pk_fma_f32 v[82:83], v[62:63], v[14:15], v[82:83] neg_lo:[0,0,1] neg_hi:[0,0,1]
	v_pk_fma_f32 v[90:91], v[70:71], v[14:15], v[90:91]
	v_pk_fma_f32 v[84:85], v[64:65], v[16:17], v[84:85] neg_lo:[0,0,1] neg_hi:[0,0,1]
	v_pk_fma_f32 v[92:93], v[72:73], v[16:17], v[92:93]
	v_cvt_pk_bf16_f32 v50, v78, v79
	v_cvt_pk_bf16_f32 v54, v86, v87
	v_cvt_pk_bf16_f32 v51, v80, v81
	v_cvt_pk_bf16_f32 v55, v88, v89
	v_cvt_pk_bf16_f32 v52, v82, v83
	v_cvt_pk_bf16_f32 v56, v90, v91
	v_cvt_pk_bf16_f32 v53, v84, v85
	v_cvt_pk_bf16_f32 v57, v92, v93
	global_load_dwordx4 v[2:5], v46, s[10:11]
	global_load_dwordx4 v[6:9], v46, s[10:11] offset:64
	global_load_dwordx4 v[10:13], v47, s[6:7]
	global_load_dwordx4 v[14:17], v47, s[6:7] offset:16
	global_load_dwordx4 v[18:21], v47, s[16:17]
	global_load_dwordx4 v[22:25], v47, s[16:17] offset:16
	v_add_u32_e32 v46, 0x3c000, v46
	v_add_u32_e32 v47, 0x800, v47
	s_nop 1
	s_waitcnt lgkmcnt(13)
	v_mfma_f32_16x16x32_bf16 v[58:61], v[98:101], v[50:53], 0
	s_waitcnt lgkmcnt(12)
	v_mfma_f32_16x16x32_bf16 v[58:61], v[102:105], v[54:57], v[58:61]
	ds_read_b128 v[154:157], v45 offset:25344
	ds_read_b128 v[158:161], v45 offset:25408
	s_waitcnt lgkmcnt(13)
	v_mfma_f32_16x16x32_bf16 v[62:65], v[106:109], v[50:53], 0
	s_waitcnt lgkmcnt(12)
	v_mfma_f32_16x16x32_bf16 v[62:65], v[110:113], v[54:57], v[62:65]
	ds_read_b128 v[162:165], v45 offset:27648
	ds_read_b128 v[182:185], v45 offset:27712
	s_waitcnt lgkmcnt(13)
	v_mfma_f32_16x16x32_bf16 v[66:69], v[114:117], v[50:53], 0
	s_waitcnt lgkmcnt(12)
	v_mfma_f32_16x16x32_bf16 v[66:69], v[118:121], v[54:57], v[66:69]
	s_waitcnt lgkmcnt(11)
	v_mfma_f32_16x16x32_bf16 v[70:73], v[122:125], v[50:53], 0
	s_waitcnt lgkmcnt(10)
	v_mfma_f32_16x16x32_bf16 v[70:73], v[126:129], v[54:57], v[70:73]
	s_waitcnt lgkmcnt(9)
	v_mfma_f32_16x16x32_bf16 v[74:77], v[130:133], v[50:53], 0
	s_waitcnt lgkmcnt(8)
	v_mfma_f32_16x16x32_bf16 v[74:77], v[134:137], v[54:57], v[74:77]
	s_waitcnt lgkmcnt(7)
	v_mfma_f32_16x16x32_bf16 v[78:81], v[138:141], v[50:53], 0
	s_waitcnt lgkmcnt(6)
	v_mfma_f32_16x16x32_bf16 v[78:81], v[142:145], v[54:57], v[78:81]
	s_waitcnt lgkmcnt(5)
	v_mfma_f32_16x16x32_bf16 v[82:85], v[146:149], v[50:53], 0
	s_waitcnt lgkmcnt(4)
	v_mfma_f32_16x16x32_bf16 v[82:85], v[150:153], v[54:57], v[82:85]
	s_waitcnt lgkmcnt(3)
; #define MFMA16(a, b, c) __builtin_amdgcn_mfma_f32_16x16x32_bf16((a), (b), (c), 0, 0, 0)
; __device__ __forceinline__ void p2_block(LAS unsigned char* lds, const bf16_t* __restrict__ PROJ, bf16_t* __restrict__ ATT, bf16_t* __restrict__ SGU, const float* __restrict__ qn, const float* __restrict__ kn, ...
;     ...
;             f32x4 z = (f32x4){0.f, 0.f, 0.f, 0.f}; z = MFMA16(k0, qf0, z); sc_[t] = MFMA16(k1, qf1, z); }
;         float mx = -1e30f;
; #pragma unroll
;         for (int t = 0; t < 10; ++t)
; #pragma unroll
;             for (int e = 0; e < 4; ++e) { const int kx = 16 * (t0 + t) + 4 * fq + e, d = kx - irow; const bool ok = (d >= 1) && (d <= 128) && (n > 0 || kx >= 128);
;                 const float v = ok ? sc_[t][e] : -1e30f; sc_[t][e] = v; mx = fmaxf(mx, v); }
;         mx = fmaxf(mx, __shfl_xor(mx, 16)); mx = fmaxf(mx, __shfl_xor(mx, 32)); mx = fmaxf(mx, sink);
;         float sum = 0.f;
; #pragma unroll
;         for (int t = 0; t < 10; ++t)
; #pragma unroll
;             for (int e = 0; e < 4; ++e) { const float p = __builtin_amdgcn_exp2f((sc_[t][e] - mx) * LOG2E); sc_[t][e] = p; sum += p; }
	v_mfma_f32_16x16x32_bf16 v[86:89], v[154:157], v[50:53], 0
	s_waitcnt lgkmcnt(2)
	v_mfma_f32_16x16x32_bf16 v[86:89], v[158:161], v[54:57], v[86:89]
	s_waitcnt lgkmcnt(1)
	v_mfma_f32_16x16x32_bf16 v[90:93], v[162:165], v[50:53], 0
	s_waitcnt lgkmcnt(0)
	v_mfma_f32_16x16x32_bf16 v[90:93], v[182:185], v[54:57], v[90:93]
	ds_read2_b64 v[98:101], v194 offset0:16 offset1:20
	ds_read2_b64 v[102:105], v195 offset0:16 offset1:20
	ds_read2_b64 v[106:109], v196 offset0:16 offset1:20
	ds_read2_b64 v[110:113], v197 offset0:16 offset1:20
	ds_read2_b64 v[114:117], v194 offset0:24 offset1:28
	ds_read2_b64 v[118:121], v195 offset0:24 offset1:28
	ds_read2_b64 v[122:125], v196 offset0:24 offset1:28
	ds_read2_b64 v[126:129], v197 offset0:24 offset1:28
	ds_read2_b64 v[130:133], v194 offset0:32 offset1:36
	ds_read2_b64 v[134:137], v195 offset0:32 offset1:36
	ds_read2_b64 v[138:141], v196 offset0:32 offset1:36
	ds_read2_b64 v[142:145], v197 offset0:32 offset1:36
	ds_read2_b64 v[146:149], v194 offset0:40 offset1:44
	ds_read2_b64 v[150:153], v195 offset0:40 offset1:44
	ds_read2_b64 v[154:157], v196 offset0:40 offset1:44
	s_nop 4
	v_cndmask_b32_e64 v58, v49, v58, s[48:49]
	v_cndmask_b32_e64 v59, v49, v59, s[50:51]
	v_cndmask_b32_e64 v60, v49, v60, s[52:53]
	v_cndmask_b32_e64 v61, v49, v61, s[26:27]
	v_cndmask_b32_e64 v62, v49, v62, s[28:29]
	v_cndmask_b32_e64 v63, v49, v63, s[28:29]
	v_cndmask_b32_e64 v64, v49, v64, s[28:29]
	v_cndmask_b32_e64 v65, v49, v65, s[28:29]
	v_cndmask_b32_e64 v66, v49, v66, s[28:29]
	v_cndmask_b32_e64 v67, v49, v67, s[28:29]
	v_cndmask_b32_e64 v68, v49, v68, s[28:29]
	v_cndmask_b32_e64 v69, v49, v69, s[28:29]
	v_cndmask_b32_e64 v70, v49, v70, s[28:29]
	v_cndmask_b32_e64 v71, v49, v71, s[28:29]
	v_cndmask_b32_e64 v72, v49, v72, s[28:29]
	v_cndmask_b32_e64 v73, v49, v73, s[28:29]
	v_cndmask_b32_e64 v90, v90, v49, s[40:41]
	v_cndmask_b32_e64 v91, v91, v49, s[42:43]
	v_cndmask_b32_e64 v92, v92, v49, s[44:45]
	v_cndmask_b32_e64 v93, v93, v49, s[46:47]
	v_max_f32_e32 v167, v58, v59
	v_max_f32_e32 v94, v60, v61
	v_max3_f32 v167, v167, v62, v63
	v_max3_f32 v94, v94, v64, v65
	v_max3_f32 v167, v167, v66, v67
	v_max3_f32 v94, v94, v68, v69
	v_max3_f32 v167, v167, v70, v71
	v_max3_f32 v94, v94, v72, v73
	v_max3_f32 v167, v167, v74, v75
	v_max3_f32 v94, v94, v76, v77
	v_max3_f32 v167, v167, v78, v79
	v_max3_f32 v94, v94, v80, v81
	v_max3_f32 v167, v167, v82, v83
	v_max3_f32 v94, v94, v84, v85
	v_max3_f32 v167, v167, v86, v87
	v_max3_f32 v94, v94, v88, v89
	v_max3_f32 v167, v167, v90, v91
	v_max3_f32 v94, v94, v92, v93
	v_max_f32_e32 v167, v167, v94
	v_mov_b32_e32 v166, v167
	s_nop 1
	v_permlane16_swap_b32_e32 v167, v166
	v_max_f32_e32 v167, v167, v166
	v_mov_b32_e32 v166, v167
	s_nop 1
	v_permlane32_swap_b32_e32 v167, v166
	v_max_f32_e32 v167, v167, v166
	v_max_f32_e32 v167, v167, v42
	v_mul_f32_e32 v94, 0xbfb8aa3b, v167
	v_fmamk_f32 v58, v58, 0x3fb8aa3b, v94
	v_fmamk_f32 v59, v59, 0x3fb8aa3b, v94
	v_fmamk_f32 v60, v60, 0x3fb8aa3b, v94
	v_fmamk_f32 v61, v61, 0x3fb8aa3b, v94
	v_fmamk_f32 v62, v62, 0x3fb8aa3b, v94
	v_fmamk_f32 v63, v63, 0x3fb8aa3b, v94
	v_fmamk_f32 v64, v64, 0x3fb8aa3b, v94
	v_fmamk_f32 v65, v65, 0x3fb8aa3b, v94
	v_fmamk_f32 v66, v66, 0x3fb8aa3b, v94
	v_fmamk_f32 v67, v67, 0x3fb8aa3b, v94
	v_fmamk_f32 v68, v68, 0x3fb8aa3b, v94
	v_fmamk_f32 v69, v69, 0x3fb8aa3b, v94
	v_fmamk_f32 v70, v70, 0x3fb8aa3b, v94
	v_fmamk_f32 v71, v71, 0x3fb8aa3b, v94
	v_fmamk_f32 v72, v72, 0x3fb8aa3b, v94
	v_fmamk_f32 v73, v73, 0x3fb8aa3b, v94
	v_fmamk_f32 v74, v74, 0x3fb8aa3b, v94
	v_fmamk_f32 v75, v75, 0x3fb8aa3b, v94
	v_fmamk_f32 v76, v76, 0x3fb8aa3b, v94
	v_fmamk_f32 v77, v77, 0x3fb8aa3b, v94
	v_fmamk_f32 v78, v78, 0x3fb8aa3b, v94
	v_fmamk_f32 v79, v79, 0x3fb8aa3b, v94
	v_fmamk_f32 v80, v80, 0x3fb8aa3b, v94
	v_fmamk_f32 v81, v81, 0x3fb8aa3b, v94
	v_fmamk_f32 v82, v82, 0x3fb8aa3b, v94
	v_fmamk_f32 v83, v83, 0x3fb8aa3b, v94
	v_fmamk_f32 v84, v84, 0x3fb8aa3b, v94
	v_fmamk_f32 v85, v85, 0x3fb8aa3b, v94
	v_fmamk_f32 v86, v86, 0x3fb8aa3b, v94
	v_fmamk_f32 v87, v87, 0x3fb8aa3b, v94
	v_fmamk_f32 v88, v88, 0x3fb8aa3b, v94
	v_fmamk_f32 v89, v89, 0x3fb8aa3b, v94
	v_fmamk_f32 v90, v90, 0x3fb8aa3b, v94
	v_fmamk_f32 v91, v91, 0x3fb8aa3b, v94
	v_fmamk_f32 v92, v92, 0x3fb8aa3b, v94
	v_fmamk_f32 v93, v93, 0x3fb8aa3b, v94
	v_exp_f32_e32 v58, v58
	v_exp_f32_e32 v59, v59
	v_exp_f32_e32 v60, v60
	v_exp_f32_e32 v61, v61
	v_exp_f32_e32 v62, v62
	v_exp_f32_e32 v63, v63
	v_exp_f32_e32 v64, v64
	v_exp_f32_e32 v65, v65
	v_exp_f32_e32 v66, v66
	v_exp_f32_e32 v67, v67
	v_exp_f32_e32 v68, v68
	v_exp_f32_e32 v69, v69
	v_exp_f32_e32 v70, v70
	v_exp_f32_e32 v71, v71
	v_exp_f32_e32 v72, v72
	v_exp_f32_e32 v73, v73
	v_exp_f32_e32 v74, v74
	v_exp_f32_e32 v75, v75
	v_exp_f32_e32 v76, v76
	v_exp_f32_e32 v77, v77
	v_exp_f32_e32 v78, v78
	v_exp_f32_e32 v79, v79
	v_exp_f32_e32 v80, v80
	v_exp_f32_e32 v81, v81
	v_exp_f32_e32 v82, v82
	v_exp_f32_e32 v83, v83
	v_exp_f32_e32 v84, v84
	v_exp_f32_e32 v85, v85
	v_exp_f32_e32 v86, v86
	v_exp_f32_e32 v87, v87
	v_exp_f32_e32 v88, v88
	v_exp_f32_e32 v89, v89
	v_exp_f32_e32 v90, v90
	v_exp_f32_e32 v91, v91
	v_exp_f32_e32 v92, v92
	v_exp_f32_e32 v93, v93
	v_fmamk_f32 v95, v42, 0x3fb8aa3b, v94
	v_exp_f32_e32 v95, v95
	v_add_f32_e32 v167, v58, v59
	v_add_f32_e32 v94, v60, v61
	v_add_f32_e32 v167, v167, v62
	v_add_f32_e32 v94, v94, v63
	v_add_f32_e32 v167, v167, v64
	v_add_f32_e32 v94, v94, v65
	v_add_f32_e32 v167, v167, v66
	v_add_f32_e32 v94, v94, v67
	v_add_f32_e32 v167, v167, v68
	v_add_f32_e32 v94, v94, v69
	v_add_f32_e32 v167, v167, v70
	v_add_f32_e32 v94, v94, v71
	v_add_f32_e32 v167, v167, v72
	v_add_f32_e32 v94, v94, v73
	v_add_f32_e32 v167, v167, v74
; __device__ __forceinline__ unsigned cvt_pk_bf16(float lo, float hi) { unsigned r; asm volatile("v_cvt_pk_bf16_f32 %0, %1, %2" : "=v"(r) : "v"(lo), "v"(hi)); return r; }
; #define LAS __attribute__((address_space(3)))
; #define MFMA16(a, b, c) __builtin_amdgcn_mfma_f32_16x16x32_bf16((a), (b), (c), 0, 0, 0)
; __device__ __forceinline__ void p2_block(LAS unsigned char* lds, const bf16_t* __restrict__ PROJ, bf16_t* __restrict__ ATT, bf16_t* __restrict__ SGU, const float* __restrict__ qn, const float* __restrict__ kn, ...
;     ...
;             for (int e = 0; e < 4; ++e) { const float p = __builtin_amdgcn_exp2f((sc_[t][e] - mx) * LOG2E); sc_[t][e] = p; sum += p; }
;         sum += __shfl_xor(sum, 16); sum += __shfl_xor(sum, 32);
;         const float inv = 1.0f / (sum + __builtin_amdgcn_exp2f((sink - mx) * LOG2E));
;         f32x4 o[4];
; #pragma unroll
;         for (int dt = 0; dt < 4; ++dt) o[dt] = (f32x4){0.f, 0.f, 0.f, 0.f};
; #pragma unroll
;         for (int j = 0; j < 5; ++j) {
;             u32x4 pw; pw.x = cvt_pk_bf16(sc_[2 * j][0], sc_[2 * j][1]); pw.y = cvt_pk_bf16(sc_[2 * j][2], sc_[2 * j][3]); pw.z = cvt_pk_bf16(sc_[2 * j + 1][0], sc_[2 * j + 1][1]); pw.w = cvt_pk_bf16(sc_[2 * j + 1][2], sc_[2 * j + 1][3]);
;             const bf16x8 pf = __builtin_bit_cast(bf16x8, pw);
; #pragma unroll
;             for (int dt = 0; dt < 4; ++dt) { const LAS unsigned char* vb = VT + (16 * dt + fr) * VT_STRIDE + (16 * (t0 + 2 * j) + 4 * fq) * 2;
;                 const u32x2 va = *(const LAS u32x2*)vb, vc = *(const LAS u32x2*)(vb + 32); u32x4 vw; vw.x = va.x; vw.y = va.y; vw.z = vc.x; vw.w = vc.y;
;                 o[dt] = MFMA16(__builtin_bit_cast(bf16x8, vw), pf, o[dt]); }
;         }
;         bf16_t* op = ATT + grow * 1024 + hq * 64 + 4 * fq;
; #pragma unroll
;         for (int dt = 0; dt < 4; ++dt) { u32x2 ow; ow.x = cvt_pk_bf16(o[dt][0] * inv, o[dt][1] * inv); ow.y = cvt_pk_bf16(o[dt][2] * inv, o[dt][3] * inv); *(u32x2*)(op + 16 * dt) = ow; }
	v_add_f32_e32 v94, v94, v75
	v_add_f32_e32 v167, v167, v76
	v_add_f32_e32 v94, v94, v77
	v_add_f32_e32 v167, v167, v78
	v_add_f32_e32 v94, v94, v79
	v_add_f32_e32 v167, v167, v80
	v_add_f32_e32 v94, v94, v81
	v_add_f32_e32 v167, v167, v82
	v_add_f32_e32 v94, v94, v83
	v_add_f32_e32 v167, v167, v84
	v_add_f32_e32 v94, v94, v85
	v_add_f32_e32 v167, v167, v86
	v_add_f32_e32 v94, v94, v87
	v_add_f32_e32 v167, v167, v88
	v_add_f32_e32 v94, v94, v89
	v_add_f32_e32 v167, v167, v90
	v_add_f32_e32 v94, v94, v91
	v_add_f32_e32 v167, v167, v92
	v_add_f32_e32 v94, v94, v93
	v_add_f32_e32 v167, v167, v94
	v_mov_b32_e32 v166, v167
	s_nop 1
	v_permlane16_swap_b32_e32 v167, v166
	v_add_f32_e32 v167, v167, v166
	v_mov_b32_e32 v166, v167
	s_nop 1
	v_permlane32_swap_b32_e32 v167, v166
	v_add_f32_e32 v167, v167, v166
	v_add_f32_e32 v167, v167, v95
	v_rcp_f32_e32 v167, v167
	v_mov_b32_e32 v94, 0
	v_mov_b32_e32 v95, 0
	v_mov_b32_e32 v96, 0
	v_mov_b32_e32 v97, 0
	v_cvt_pk_bf16_f32 v58, v58, v59
	v_cvt_pk_bf16_f32 v59, v60, v61
	v_cvt_pk_bf16_f32 v60, v62, v63
	v_cvt_pk_bf16_f32 v61, v64, v65
	v_cvt_pk_bf16_f32 v66, v66, v67
	v_cvt_pk_bf16_f32 v67, v68, v69
	v_cvt_pk_bf16_f32 v68, v70, v71
	v_cvt_pk_bf16_f32 v69, v72, v73
	v_cvt_pk_bf16_f32 v74, v74, v75
	v_cvt_pk_bf16_f32 v75, v76, v77
	v_cvt_pk_bf16_f32 v76, v78, v79
	v_cvt_pk_bf16_f32 v77, v80, v81
	v_cvt_pk_bf16_f32 v82, v82, v83
	v_cvt_pk_bf16_f32 v83, v84, v85
	v_cvt_pk_bf16_f32 v84, v86, v87
	v_cvt_pk_bf16_f32 v85, v88, v89
	v_cvt_pk_bf16_f32 v90, v90, v91
	v_cvt_pk_bf16_f32 v91, v92, v93
	v_cvt_pk_bf16_f32 v92, v94, v95
	v_cvt_pk_bf16_f32 v93, v96, v97
	s_nop 1
	s_waitcnt lgkmcnt(14)
	v_mfma_f32_16x16x32_bf16 v[62:65], v[98:101], v[58:61], 0
	ds_read2_b64 v[158:161], v197 offset0:40 offset1:44
	s_waitcnt lgkmcnt(14)
	v_mfma_f32_16x16x32_bf16 v[70:73], v[102:105], v[58:61], 0
	ds_read2_b64 v[162:165], v194 offset0:48 offset1:52
	s_waitcnt lgkmcnt(14)
	v_mfma_f32_16x16x32_bf16 v[78:81], v[106:109], v[58:61], 0
	ds_read2_b64 v[182:185], v195 offset0:48 offset1:52
	s_waitcnt lgkmcnt(14)
	v_mfma_f32_16x16x32_bf16 v[86:89], v[110:113], v[58:61], 0
	ds_read2_b64 v[186:189], v196 offset0:48 offset1:52
	s_waitcnt lgkmcnt(14)
	v_mfma_f32_16x16x32_bf16 v[62:65], v[114:117], v[66:69], v[62:65]
	ds_read2_b64 v[190:193], v197 offset0:48 offset1:52
	s_waitcnt lgkmcnt(14)
	v_mfma_f32_16x16x32_bf16 v[70:73], v[118:121], v[66:69], v[70:73]
	s_waitcnt lgkmcnt(13)
	v_mfma_f32_16x16x32_bf16 v[78:81], v[122:125], v[66:69], v[78:81]
	s_waitcnt lgkmcnt(12)
	v_mfma_f32_16x16x32_bf16 v[86:89], v[126:129], v[66:69], v[86:89]
	s_waitcnt lgkmcnt(11)
	v_mfma_f32_16x16x32_bf16 v[62:65], v[130:133], v[74:77], v[62:65]
	s_waitcnt lgkmcnt(10)
	v_mfma_f32_16x16x32_bf16 v[70:73], v[134:137], v[74:77], v[70:73]
	s_waitcnt lgkmcnt(9)
	v_mfma_f32_16x16x32_bf16 v[78:81], v[138:141], v[74:77], v[78:81]
	s_waitcnt lgkmcnt(8)
	v_mfma_f32_16x16x32_bf16 v[86:89], v[142:145], v[74:77], v[86:89]
	s_waitcnt lgkmcnt(7)
	v_mfma_f32_16x16x32_bf16 v[62:65], v[146:149], v[82:85], v[62:65]
	s_waitcnt lgkmcnt(6)
	v_mfma_f32_16x16x32_bf16 v[70:73], v[150:153], v[82:85], v[70:73]
	s_waitcnt lgkmcnt(5)
	v_mfma_f32_16x16x32_bf16 v[78:81], v[154:157], v[82:85], v[78:81]
	s_waitcnt lgkmcnt(4)
	v_mfma_f32_16x16x32_bf16 v[86:89], v[158:161], v[82:85], v[86:89]
	s_waitcnt lgkmcnt(3)
	v_mfma_f32_16x16x32_bf16 v[62:65], v[162:165], v[90:93], v[62:65]
	s_waitcnt lgkmcnt(2)
	v_mfma_f32_16x16x32_bf16 v[70:73], v[182:185], v[90:93], v[70:73]
	s_waitcnt lgkmcnt(1)
	v_mfma_f32_16x16x32_bf16 v[78:81], v[186:189], v[90:93], v[78:81]
	s_waitcnt lgkmcnt(0)
	v_mfma_f32_16x16x32_bf16 v[86:89], v[190:193], v[90:93], v[86:89]
	ds_read_b128 v[98:101], v45 offset:11520
	ds_read_b128 v[102:105], v45 offset:11584
	ds_read_b128 v[106:109], v45 offset:13824
	ds_read_b128 v[110:113], v45 offset:13888
	ds_read_b128 v[114:117], v45 offset:16128
	ds_read_b128 v[118:121], v45 offset:16192
	ds_read_b128 v[122:125], v45 offset:18432
	ds_read_b128 v[126:129], v45 offset:18496
	ds_read_b128 v[130:133], v45 offset:20736
	ds_read_b128 v[134:137], v45 offset:20800
	ds_read_b128 v[138:141], v45 offset:23040
	ds_read_b128 v[142:145], v45 offset:23104
	ds_read_b128 v[146:149], v45 offset:25344
	ds_read_b128 v[150:153], v45 offset:25408
	s_nop 7
	v_mul_f32_e32 v62, v62, v167
	v_mul_f32_e32 v63, v63, v167
	v_mul_f32_e32 v64, v64, v167
	v_mul_f32_e32 v65, v65, v167
	v_mul_f32_e32 v70, v70, v167
	v_mul_f32_e32 v71, v71, v167
	v_mul_f32_e32 v72, v72, v167
	v_mul_f32_e32 v73, v73, v167
	v_mul_f32_e32 v78, v78, v167
	v_mul_f32_e32 v79, v79, v167
	v_mul_f32_e32 v80, v80, v167
	v_mul_f32_e32 v81, v81, v167
	v_mul_f32_e32 v86, v86, v167
	v_mul_f32_e32 v87, v87, v167
	v_mul_f32_e32 v88, v88, v167
	v_mul_f32_e32 v89, v89, v167
	v_cvt_pk_bf16_f32 v62, v62, v63
	v_cvt_pk_bf16_f32 v63, v64, v65
	global_store_dwordx2 v48, v[62:63], s[24:25] offset:0
	v_cvt_pk_bf16_f32 v70, v70, v71
	v_cvt_pk_bf16_f32 v71, v72, v73
	global_store_dwordx2 v48, v[70:71], s[24:25] offset:32
	v_cvt_pk_bf16_f32 v78, v78, v79
	v_cvt_pk_bf16_f32 v79, v80, v81
	global_store_dwordx2 v48, v[78:79], s[24:25] offset:64
	v_cvt_pk_bf16_f32 v86, v86, v87
	v_cvt_pk_bf16_f32 v87, v88, v89
	global_store_dwordx2 v48, v[86:87], s[24:25] offset:96
	v_add_u32_e32 v48, 0x8000, v48
	s_waitcnt vmcnt(10)
; __device__ __forceinline__ unsigned cvt_pk_bf16(float lo, float hi) { unsigned r; asm volatile("v_cvt_pk_bf16_f32 %0, %1, %2" : "=v"(r) : "v"(lo), "v"(hi)); return r; }
; #define LAS __attribute__((address_space(3)))
; #define MFMA16(a, b, c) __builtin_amdgcn_mfma_f32_16x16x32_bf16((a), (b), (c), 0, 0, 0)
; __device__ __forceinline__ void unpack8(const u32x4 w, float* f) { f[0] = bf_lo(w.x); f[1] = bf_hi(w.x); f[2] = bf_lo(w.y); f[3] = bf_hi(w.y); f[4] = bf_lo(w.z); f[5] = bf_hi(w.z); f[6] = bf_lo(w.w); f[7] = bf_hi(w.w); }
; __device__ __forceinline__ void p2_block(LAS unsigned char* lds, const bf16_t* __restrict__ PROJ, bf16_t* __restrict__ ATT, bf16_t* __restrict__ SGU, const float* __restrict__ qn, const float* __restrict__ kn, ...
;     ...
;             float x1[8], x2[8]; unpack8(qa[c], x1); unpack8(qb[c], x2);
;             float ss = 0.f;
; #pragma unroll
;             for (int j = 0; j < 8; ++j) ss += x1[j] * x1[j] + x2[j] * x2[j];
;             ss += __shfl_xor(ss, 16); ss += __shfl_xor(ss, 32);
;             const float rinv = rsqrtf(ss * (1.0f / 64.0f) + pg8::EPS) * 0.125f;
;             const float* cp = COS + pos * 32 + 8 * fq; const float* sp = SIN + pos * 32 + 8 * fq;
;             float o1[8], o2[8];
; #pragma unroll
;             for (int j = 0; j < 8; ++j) { const float a1 = x1[j] * rinv * qn[8 * fq + j], a2 = x2[j] * rinv * qn[32 + 8 * fq + j], cc = cp[j], sn = sp[j]; o1[j] = a1 * cc - a2 * sn; o2[j] = a2 * cc + a1 * sn; }
;             u32x4 w0, w1;
;             w0.x = cvt_pk_bf16(o1[0], o1[1]); w0.y = cvt_pk_bf16(o1[2], o1[3]); w0.z = cvt_pk_bf16(o1[4], o1[5]); w0.w = cvt_pk_bf16(o1[6], o1[7]);
;             w1.x = cvt_pk_bf16(o2[0], o2[1]); w1.y = cvt_pk_bf16(o2[2], o2[3]); w1.z = cvt_pk_bf16(o2[4], o2[5]); w1.w = cvt_pk_bf16(o2[6], o2[7]);
;             qf0 = __builtin_bit_cast(bf16x8, w0); qf1 = __builtin_bit_cast(bf16x8, w1);
;         }
;         const int t0 = (i0 >> 4) < 6 ? (i0 >> 4) : 6;
;         f32x4 sc_[10];
;         const LAS unsigned char* kbase = KS + (16 * t0 + fr) * KS_STRIDE + 16 * fq;
; #pragma unroll
;         for (int t = 0; t < 10; ++t) { const bf16x8 k0 = *(const LAS bf16x8*)(kbase + t * 16 * KS_STRIDE), k1 = *(const LAS bf16x8*)(kbase + t * 16 * KS_STRIDE + 64);
;             f32x4 z = (f32x4){0.f, 0.f, 0.f, 0.f}; z = MFMA16(k0, qf0, z); sc_[t] = MFMA16(k1, qf1, z); }
	v_lshlrev_b32_e32 v58, 16, v218
	v_and_b32_e32 v59, 0xffff0000, v218
	v_lshlrev_b32_e32 v66, 16, v222
	v_and_b32_e32 v67, 0xffff0000, v222
	v_lshlrev_b32_e32 v60, 16, v219
	v_and_b32_e32 v61, 0xffff0000, v219
	v_lshlrev_b32_e32 v68, 16, v223
	v_and_b32_e32 v69, 0xffff0000, v223
	v_lshlrev_b32_e32 v62, 16, v220
	v_and_b32_e32 v63, 0xffff0000, v220
	v_lshlrev_b32_e32 v70, 16, v224
	v_and_b32_e32 v71, 0xffff0000, v224
	v_lshlrev_b32_e32 v64, 16, v221
	v_and_b32_e32 v65, 0xffff0000, v221
	v_lshlrev_b32_e32 v72, 16, v225
	v_and_b32_e32 v73, 0xffff0000, v225
	v_pk_mul_f32 v[74:75], v[58:59], v[58:59]
	v_pk_fma_f32 v[74:75], v[60:61], v[60:61], v[74:75]
	v_pk_fma_f32 v[74:75], v[62:63], v[62:63], v[74:75]
	v_pk_fma_f32 v[74:75], v[64:65], v[64:65], v[74:75]
	v_pk_fma_f32 v[74:75], v[66:67], v[66:67], v[74:75]
	v_pk_fma_f32 v[74:75], v[68:69], v[68:69], v[74:75]
	v_pk_fma_f32 v[74:75], v[70:71], v[70:71], v[74:75]
	v_pk_fma_f32 v[74:75], v[72:73], v[72:73], v[74:75]
	v_add_f32_e32 v74, v74, v75
	v_mov_b32_e32 v166, v74
	s_nop 1
	v_permlane16_swap_b32_e32 v74, v166
	v_add_f32_e32 v74, v74, v166
	v_mov_b32_e32 v166, v74
	s_nop 1
	v_permlane32_swap_b32_e32 v74, v166
	v_add_f32_e32 v74, v74, v166
	v_fmamk_f32 v74, v74, 0x3c800000, v209
	v_rsq_f32_e32 v76, v74
	s_nop 0
	v_mul_f32_e32 v76, 0x3e000000, v76
	v_pk_mul_f32 v[58:59], v[58:59], v[76:77] op_sel_hi:[1,0]
	v_pk_mul_f32 v[66:67], v[66:67], v[76:77] op_sel_hi:[1,0]
	v_pk_mul_f32 v[60:61], v[60:61], v[76:77] op_sel_hi:[1,0]
	v_pk_mul_f32 v[68:69], v[68:69], v[76:77] op_sel_hi:[1,0]
	v_pk_mul_f32 v[62:63], v[62:63], v[76:77] op_sel_hi:[1,0]
	v_pk_mul_f32 v[70:71], v[70:71], v[76:77] op_sel_hi:[1,0]
	v_pk_mul_f32 v[64:65], v[64:65], v[76:77] op_sel_hi:[1,0]
	v_pk_mul_f32 v[72:73], v[72:73], v[76:77] op_sel_hi:[1,0]
	v_pk_mul_f32 v[58:59], v[58:59], v[26:27]
	v_pk_mul_f32 v[66:67], v[66:67], v[34:35]
	v_pk_mul_f32 v[60:61], v[60:61], v[28:29]
	v_pk_mul_f32 v[68:69], v[68:69], v[36:37]
	v_pk_mul_f32 v[62:63], v[62:63], v[30:31]
	v_pk_mul_f32 v[70:71], v[70:71], v[38:39]
	v_pk_mul_f32 v[64:65], v[64:65], v[32:33]
	v_pk_mul_f32 v[72:73], v[72:73], v[40:41]
	v_pk_mul_f32 v[78:79], v[66:67], v[234:235]
	v_pk_mul_f32 v[86:87], v[58:59], v[234:235]
	v_pk_mul_f32 v[80:81], v[68:69], v[236:237]
	v_pk_mul_f32 v[88:89], v[60:61], v[236:237]
	v_pk_mul_f32 v[82:83], v[70:71], v[238:239]
	v_pk_mul_f32 v[90:91], v[62:63], v[238:239]
	v_pk_mul_f32 v[84:85], v[72:73], v[240:241]
	v_pk_mul_f32 v[92:93], v[64:65], v[240:241]
	v_pk_fma_f32 v[78:79], v[58:59], v[226:227], v[78:79] neg_lo:[0,0,1] neg_hi:[0,0,1]
	v_pk_fma_f32 v[86:87], v[66:67], v[226:227], v[86:87]
	v_pk_fma_f32 v[80:81], v[60:61], v[228:229], v[80:81] neg_lo:[0,0,1] neg_hi:[0,0,1]
	v_pk_fma_f32 v[88:89], v[68:69], v[228:229], v[88:89]
	v_pk_fma_f32 v[82:83], v[62:63], v[230:231], v[82:83] neg_lo:[0,0,1] neg_hi:[0,0,1]
	v_pk_fma_f32 v[90:91], v[70:71], v[230:231], v[90:91]
	v_pk_fma_f32 v[84:85], v[64:65], v[232:233], v[84:85] neg_lo:[0,0,1] neg_hi:[0,0,1]
	v_pk_fma_f32 v[92:93], v[72:73], v[232:233], v[92:93]
	v_cvt_pk_bf16_f32 v50, v78, v79
	v_cvt_pk_bf16_f32 v54, v86, v87
	v_cvt_pk_bf16_f32 v51, v80, v81
	v_cvt_pk_bf16_f32 v55, v88, v89
	v_cvt_pk_bf16_f32 v52, v82, v83
	v_cvt_pk_bf16_f32 v56, v90, v91
	v_cvt_pk_bf16_f32 v53, v84, v85
	v_cvt_pk_bf16_f32 v57, v92, v93
	global_load_dwordx4 v[218:221], v46, s[10:11]
	global_load_dwordx4 v[222:225], v46, s[10:11] offset:64
	global_load_dwordx4 v[226:229], v47, s[6:7]
	global_load_dwordx4 v[230:233], v47, s[6:7] offset:16
	global_load_dwordx4 v[234:237], v47, s[16:17]
	global_load_dwordx4 v[238:241], v47, s[16:17] offset:16
	v_add_u32_e32 v46, 0x3c000, v46
	v_add_u32_e32 v47, 0x800, v47
	s_nop 1
	s_waitcnt lgkmcnt(13)
	v_mfma_f32_16x16x32_bf16 v[58:61], v[98:101], v[50:53], 0
	s_waitcnt lgkmcnt(12)
	v_mfma_f32_16x16x32_bf16 v[58:61], v[102:105], v[54:57], v[58:61]
	ds_read_b128 v[154:157], v45 offset:27648
	ds_read_b128 v[158:161], v45 offset:27712
	s_waitcnt lgkmcnt(13)
	v_mfma_f32_16x16x32_bf16 v[62:65], v[106:109], v[50:53], 0
	s_waitcnt lgkmcnt(12)
	v_mfma_f32_16x16x32_bf16 v[62:65], v[110:113], v[54:57], v[62:65]
	ds_read_b128 v[162:165], v45 offset:29952
	ds_read_b128 v[182:185], v45 offset:30016
	s_waitcnt lgkmcnt(13)
	v_mfma_f32_16x16x32_bf16 v[66:69], v[114:117], v[50:53], 0
	s_waitcnt lgkmcnt(12)
	v_mfma_f32_16x16x32_bf16 v[66:69], v[118:121], v[54:57], v[66:69]
	s_waitcnt lgkmcnt(11)
	v_mfma_f32_16x16x32_bf16 v[70:73], v[122:125], v[50:53], 0
	s_waitcnt lgkmcnt(10)
	v_mfma_f32_16x16x32_bf16 v[70:73], v[126:129], v[54:57], v[70:73]
	s_waitcnt lgkmcnt(9)
	v_mfma_f32_16x16x32_bf16 v[74:77], v[130:133], v[50:53], 0
	s_waitcnt lgkmcnt(8)
	v_mfma_f32_16x16x32_bf16 v[74:77], v[134:137], v[54:57], v[74:77]
	s_waitcnt lgkmcnt(7)
	v_mfma_f32_16x16x32_bf16 v[78:81], v[138:141], v[50:53], 0
	s_waitcnt lgkmcnt(6)
	v_mfma_f32_16x16x32_bf16 v[78:81], v[142:145], v[54:57], v[78:81]
	s_waitcnt lgkmcnt(5)
	v_mfma_f32_16x16x32_bf16 v[82:85], v[146:149], v[50:53], 0
	s_waitcnt lgkmcnt(4)
	v_mfma_f32_16x16x32_bf16 v[82:85], v[150:153], v[54:57], v[82:85]
	s_waitcnt lgkmcnt(3)
	v_mfma_f32_16x16x32_bf16 v[86:89], v[154:157], v[50:53], 0
	s_waitcnt lgkmcnt(2)
	v_mfma_f32_16x16x32_bf16 v[86:89], v[158:161], v[54:57], v[86:89]
	s_waitcnt lgkmcnt(1)
	v_mfma_f32_16x16x32_bf16 v[90:93], v[162:165], v[50:53], 0
	s_waitcnt lgkmcnt(0)
; __device__ __forceinline__ void p2_block(LAS unsigned char* lds, const bf16_t* __restrict__ PROJ, bf16_t* __restrict__ ATT, bf16_t* __restrict__ SGU, const float* __restrict__ qn, const float* __restrict__ kn, ...
;     ...
;         float mx = -1e30f;
; #pragma unroll
;         for (int t = 0; t < 10; ++t)
; #pragma unroll
;             for (int e = 0; e < 4; ++e) { const int kx = 16 * (t0 + t) + 4 * fq + e, d = kx - irow; const bool ok = (d >= 1) && (d <= 128) && (n > 0 || kx >= 128);
;                 const float v = ok ? sc_[t][e] : -1e30f; sc_[t][e] = v; mx = fmaxf(mx, v); }
;         mx = fmaxf(mx, __shfl_xor(mx, 16)); mx = fmaxf(mx, __shfl_xor(mx, 32)); mx = fmaxf(mx, sink);
;         float sum = 0.f;
; #pragma unroll
;         for (int t = 0; t < 10; ++t)
; #pragma unroll
;             for (int e = 0; e < 4; ++e) { const float p = __builtin_amdgcn_exp2f((sc_[t][e] - mx) * LOG2E); sc_[t][e] = p; sum += p; }
;         sum += __shfl_xor(sum, 16); sum += __shfl_xor(sum, 32);
;         const float inv = 1.0f / (sum + __builtin_amdgcn_exp2f((sink - mx) * LOG2E));
	v_mfma_f32_16x16x32_bf16 v[90:93], v[182:185], v[54:57], v[90:93]
	ds_read2_b64 v[98:101], v194 offset0:20 offset1:24
	ds_read2_b64 v[102:105], v195 offset0:20 offset1:24
	ds_read2_b64 v[106:109], v196 offset0:20 offset1:24
	ds_read2_b64 v[110:113], v197 offset0:20 offset1:24
	ds_read2_b64 v[114:117], v194 offset0:28 offset1:32
	ds_read2_b64 v[118:121], v195 offset0:28 offset1:32
	ds_read2_b64 v[122:125], v196 offset0:28 offset1:32
	ds_read2_b64 v[126:129], v197 offset0:28 offset1:32
	ds_read2_b64 v[130:133], v194 offset0:36 offset1:40
	ds_read2_b64 v[134:137], v195 offset0:36 offset1:40
	ds_read2_b64 v[138:141], v196 offset0:36 offset1:40
	ds_read2_b64 v[142:145], v197 offset0:36 offset1:40
	ds_read2_b64 v[146:149], v194 offset0:44 offset1:48
	ds_read2_b64 v[150:153], v195 offset0:44 offset1:48
	ds_read2_b64 v[154:157], v196 offset0:44 offset1:48
	s_nop 4
	v_cndmask_b32_e64 v58, v49, v58, s[48:49]
	v_cndmask_b32_e64 v59, v49, v59, s[50:51]
	v_cndmask_b32_e64 v60, v49, v60, s[52:53]
	v_cndmask_b32_e64 v61, v49, v61, s[26:27]
	v_cndmask_b32_e64 v62, v49, v62, s[28:29]
	v_cndmask_b32_e64 v63, v49, v63, s[28:29]
	v_cndmask_b32_e64 v64, v49, v64, s[28:29]
	v_cndmask_b32_e64 v65, v49, v65, s[28:29]
	v_cndmask_b32_e64 v66, v49, v66, s[28:29]
	v_cndmask_b32_e64 v67, v49, v67, s[28:29]
	v_cndmask_b32_e64 v68, v49, v68, s[28:29]
	v_cndmask_b32_e64 v69, v49, v69, s[28:29]
	v_cndmask_b32_e64 v90, v90, v49, s[40:41]
	v_cndmask_b32_e64 v91, v91, v49, s[42:43]
	v_cndmask_b32_e64 v92, v92, v49, s[44:45]
	v_cndmask_b32_e64 v93, v93, v49, s[46:47]
	v_max_f32_e32 v167, v58, v59
	v_max_f32_e32 v94, v60, v61
	v_max3_f32 v167, v167, v62, v63
	v_max3_f32 v94, v94, v64, v65
	v_max3_f32 v167, v167, v66, v67
	v_max3_f32 v94, v94, v68, v69
	v_max3_f32 v167, v167, v70, v71
	v_max3_f32 v94, v94, v72, v73
	v_max3_f32 v167, v167, v74, v75
	v_max3_f32 v94, v94, v76, v77
	v_max3_f32 v167, v167, v78, v79
	v_max3_f32 v94, v94, v80, v81
	v_max3_f32 v167, v167, v82, v83
	v_max3_f32 v94, v94, v84, v85
	v_max3_f32 v167, v167, v86, v87
	v_max3_f32 v94, v94, v88, v89
	v_max3_f32 v167, v167, v90, v91
	v_max3_f32 v94, v94, v92, v93
	v_max_f32_e32 v167, v167, v94
	v_mov_b32_e32 v166, v167
	s_nop 1
	v_permlane16_swap_b32_e32 v167, v166
	v_max_f32_e32 v167, v167, v166
	v_mov_b32_e32 v166, v167
	s_nop 1
	v_permlane32_swap_b32_e32 v167, v166
	v_max_f32_e32 v167, v167, v166
	v_max_f32_e32 v167, v167, v42
	v_mul_f32_e32 v94, 0xbfb8aa3b, v167
	v_fmamk_f32 v58, v58, 0x3fb8aa3b, v94
	v_fmamk_f32 v59, v59, 0x3fb8aa3b, v94
	v_fmamk_f32 v60, v60, 0x3fb8aa3b, v94
	v_fmamk_f32 v61, v61, 0x3fb8aa3b, v94
	v_fmamk_f32 v62, v62, 0x3fb8aa3b, v94
	v_fmamk_f32 v63, v63, 0x3fb8aa3b, v94
	v_fmamk_f32 v64, v64, 0x3fb8aa3b, v94
	v_fmamk_f32 v65, v65, 0x3fb8aa3b, v94
	v_fmamk_f32 v66, v66, 0x3fb8aa3b, v94
	v_fmamk_f32 v67, v67, 0x3fb8aa3b, v94
	v_fmamk_f32 v68, v68, 0x3fb8aa3b, v94
	v_fmamk_f32 v69, v69, 0x3fb8aa3b, v94
	v_fmamk_f32 v70, v70, 0x3fb8aa3b, v94
	v_fmamk_f32 v71, v71, 0x3fb8aa3b, v94
	v_fmamk_f32 v72, v72, 0x3fb8aa3b, v94
	v_fmamk_f32 v73, v73, 0x3fb8aa3b, v94
	v_fmamk_f32 v74, v74, 0x3fb8aa3b, v94
	v_fmamk_f32 v75, v75, 0x3fb8aa3b, v94
	v_fmamk_f32 v76, v76, 0x3fb8aa3b, v94
	v_fmamk_f32 v77, v77, 0x3fb8aa3b, v94
	v_fmamk_f32 v78, v78, 0x3fb8aa3b, v94
	v_fmamk_f32 v79, v79, 0x3fb8aa3b, v94
	v_fmamk_f32 v80, v80, 0x3fb8aa3b, v94
	v_fmamk_f32 v81, v81, 0x3fb8aa3b, v94
	v_fmamk_f32 v82, v82, 0x3fb8aa3b, v94
	v_fmamk_f32 v83, v83, 0x3fb8aa3b, v94
	v_fmamk_f32 v84, v84, 0x3fb8aa3b, v94
	v_fmamk_f32 v85, v85, 0x3fb8aa3b, v94
	v_fmamk_f32 v86, v86, 0x3fb8aa3b, v94
	v_fmamk_f32 v87, v87, 0x3fb8aa3b, v94
	v_fmamk_f32 v88, v88, 0x3fb8aa3b, v94
	v_fmamk_f32 v89, v89, 0x3fb8aa3b, v94
	v_fmamk_f32 v90, v90, 0x3fb8aa3b, v94
	v_fmamk_f32 v91, v91, 0x3fb8aa3b, v94
	v_fmamk_f32 v92, v92, 0x3fb8aa3b, v94
	v_fmamk_f32 v93, v93, 0x3fb8aa3b, v94
	v_exp_f32_e32 v58, v58
	v_exp_f32_e32 v59, v59
	v_exp_f32_e32 v60, v60
	v_exp_f32_e32 v61, v61
	v_exp_f32_e32 v62, v62
	v_exp_f32_e32 v63, v63
	v_exp_f32_e32 v64, v64
	v_exp_f32_e32 v65, v65
	v_exp_f32_e32 v66, v66
	v_exp_f32_e32 v67, v67
	v_exp_f32_e32 v68, v68
	v_exp_f32_e32 v69, v69
	v_exp_f32_e32 v70, v70
	v_exp_f32_e32 v71, v71
	v_exp_f32_e32 v72, v72
	v_exp_f32_e32 v73, v73
	v_exp_f32_e32 v74, v74
	v_exp_f32_e32 v75, v75
	v_exp_f32_e32 v76, v76
	v_exp_f32_e32 v77, v77
	v_exp_f32_e32 v78, v78
	v_exp_f32_e32 v79, v79
	v_exp_f32_e32 v80, v80
	v_exp_f32_e32 v81, v81
	v_exp_f32_e32 v82, v82
	v_exp_f32_e32 v83, v83
	v_exp_f32_e32 v84, v84
	v_exp_f32_e32 v85, v85
	v_exp_f32_e32 v86, v86
	v_exp_f32_e32 v87, v87
	v_exp_f32_e32 v88, v88
	v_exp_f32_e32 v89, v89
	v_exp_f32_e32 v90, v90
	v_exp_f32_e32 v91, v91
	v_exp_f32_e32 v92, v92
	v_exp_f32_e32 v93, v93
	v_fmamk_f32 v95, v42, 0x3fb8aa3b, v94
	v_exp_f32_e32 v95, v95
	v_add_f32_e32 v167, v58, v59
	v_add_f32_e32 v94, v60, v61
	v_add_f32_e32 v167, v167, v62
	v_add_f32_e32 v94, v94, v63
	v_add_f32_e32 v167, v167, v64
	v_add_f32_e32 v94, v94, v65
	v_add_f32_e32 v167, v167, v66
	v_add_f32_e32 v94, v94, v67
	v_add_f32_e32 v167, v167, v68
	v_add_f32_e32 v94, v94, v69
	v_add_f32_e32 v167, v167, v70
	v_add_f32_e32 v94, v94, v71
	v_add_f32_e32 v167, v167, v72
	v_add_f32_e32 v94, v94, v73
	v_add_f32_e32 v167, v167, v74
	v_add_f32_e32 v94, v94, v75
	v_add_f32_e32 v167, v167, v76
	v_add_f32_e32 v94, v94, v77
	v_add_f32_e32 v167, v167, v78
	v_add_f32_e32 v94, v94, v79
	v_add_f32_e32 v167, v167, v80
	v_add_f32_e32 v94, v94, v81
	v_add_f32_e32 v167, v167, v82
	v_add_f32_e32 v94, v94, v83
	v_add_f32_e32 v167, v167, v84
	v_add_f32_e32 v94, v94, v85
	v_add_f32_e32 v167, v167, v86
	v_add_f32_e32 v94, v94, v87
	v_add_f32_e32 v167, v167, v88
	v_add_f32_e32 v94, v94, v89
	v_add_f32_e32 v167, v167, v90
	v_add_f32_e32 v94, v94, v91
	v_add_f32_e32 v167, v167, v92
	v_add_f32_e32 v94, v94, v93
	v_add_f32_e32 v167, v167, v94
	v_mov_b32_e32 v166, v167
	s_nop 1
	v_permlane16_swap_b32_e32 v167, v166
	v_add_f32_e32 v167, v167, v166
	v_mov_b32_e32 v166, v167
	s_nop 1
	v_permlane32_swap_b32_e32 v167, v166
	v_add_f32_e32 v167, v167, v166
	v_add_f32_e32 v167, v167, v95
	v_rcp_f32_e32 v167, v167
	v_mov_b32_e32 v94, 0
	v_mov_b32_e32 v95, 0
	v_mov_b32_e32 v96, 0
	v_mov_b32_e32 v97, 0
	v_cvt_pk_bf16_f32 v58, v58, v59
	v_cvt_pk_bf16_f32 v59, v60, v61
	v_cvt_pk_bf16_f32 v60, v62, v63
	v_cvt_pk_bf16_f32 v61, v64, v65
	v_cvt_pk_bf16_f32 v66, v66, v67
	v_cvt_pk_bf16_f32 v67, v68, v69
	v_cvt_pk_bf16_f32 v68, v70, v71
	v_cvt_pk_bf16_f32 v69, v72, v73
	v_cvt_pk_bf16_f32 v74, v74, v75
	v_cvt_pk_bf16_f32 v75, v76, v77
	v_cvt_pk_bf16_f32 v76, v78, v79
	v_cvt_pk_bf16_f32 v77, v80, v81
	v_cvt_pk_bf16_f32 v82, v82, v83
	v_cvt_pk_bf16_f32 v83, v84, v85
	v_cvt_pk_bf16_f32 v84, v86, v87
	v_cvt_pk_bf16_f32 v85, v88, v89
	v_cvt_pk_bf16_f32 v90, v90, v91
	v_cvt_pk_bf16_f32 v91, v92, v93
	v_cvt_pk_bf16_f32 v92, v94, v95
	v_cvt_pk_bf16_f32 v93, v96, v97
	s_nop 1
	s_waitcnt lgkmcnt(14)
; __device__ __forceinline__ void p2_block(LAS unsigned char* lds, const bf16_t* __restrict__ PROJ, bf16_t* __restrict__ ATT, bf16_t* __restrict__ SGU, const float* __restrict__ qn, const float* __restrict__ kn, ...
;     ...
;             float x1[8], x2[8]; unpack8(qa[c], x1); unpack8(qb[c], x2);
;             float ss = 0.f;
; #pragma unroll
;             for (int j = 0; j < 8; ++j) ss += x1[j] * x1[j] + x2[j] * x2[j];
;             ss += __shfl_xor(ss, 16); ss += __shfl_xor(ss, 32);
;             const float rinv = rsqrtf(ss * (1.0f / 64.0f) + pg8::EPS) * 0.125f;
;             const float* cp = COS + pos * 32 + 8 * fq; const float* sp = SIN + pos * 32 + 8 * fq;
;             float o1[8], o2[8];
; #pragma unroll
;             for (int j = 0; j < 8; ++j) { const float a1 = x1[j] * rinv * qn[8 * fq + j], a2 = x2[j] * rinv * qn[32 + 8 * fq + j], cc = cp[j], sn = sp[j]; o1[j] = a1 * cc - a2 * sn; o2[j] = a2 * cc + a1 * sn; }
;             u32x4 w0, w1;
;             w0.x = cvt_pk_bf16(o1[0], o1[1]); w0.y = cvt_pk_bf16(o1[2], o1[3]); w0.z = cvt_pk_bf16(o1[4], o1[5]); w0.w = cvt_pk_bf16(o1[6], o1[7]);
;             w1.x = cvt_pk_bf16(o2[0], o2[1]); w1.y = cvt_pk_bf16(o2[2], o2[3]); w1.z = cvt_pk_bf16(o2[4], o2[5]); w1.w = cvt_pk_bf16(o2[6], o2[7]);
;             qf0 = __builtin_bit_cast(bf16x8, w0); qf1 = __builtin_bit_cast(bf16x8, w1);
;     ...
; #pragma unroll
;         for (int j = 0; j < 5; ++j) {
;             u32x4 pw; pw.x = cvt_pk_bf16(sc_[2 * j][0], sc_[2 * j][1]); pw.y = cvt_pk_bf16(sc_[2 * j][2], sc_[2 * j][3]); pw.z = cvt_pk_bf16(sc_[2 * j + 1][0], sc_[2 * j + 1][1]); pw.w = cvt_pk_bf16(sc_[2 * j + 1][2], sc_[2 * j + 1][3]);
;             const bf16x8 pf = __builtin_bit_cast(bf16x8, pw);
; #pragma unroll
;             for (int dt = 0; dt < 4; ++dt) { const LAS unsigned char* vb = VT + (16 * dt + fr) * VT_STRIDE + (16 * (t0 + 2 * j) + 4 * fq) * 2;
;                 const u32x2 va = *(const LAS u32x2*)vb, vc = *(const LAS u32x2*)(vb + 32); u32x4 vw; vw.x = va.x; vw.y = va.y; vw.z = vc.x; vw.w = vc.y;
;                 o[dt] = MFMA16(__builtin_bit_cast(bf16x8, vw), pf, o[dt]); }
;         }
;         bf16_t* op = ATT + grow * 1024 + hq * 64 + 4 * fq;
; #pragma unroll
;         for (int dt = 0; dt < 4; ++dt) { u32x2 ow; ow.x = cvt_pk_bf16(o[dt][0] * inv, o[dt][1] * inv); ow.y = cvt_pk_bf16(o[dt][2] * inv, o[dt][3] * inv); *(u32x2*)(op + 16 * dt) = ow; }
	v_mfma_f32_16x16x32_bf16 v[62:65], v[98:101], v[58:61], 0
	ds_read2_b64 v[158:161], v197 offset0:44 offset1:48
	s_waitcnt lgkmcnt(14)
	v_mfma_f32_16x16x32_bf16 v[70:73], v[102:105], v[58:61], 0
	ds_read2_b64 v[162:165], v194 offset0:52 offset1:56
	s_waitcnt lgkmcnt(14)
	v_mfma_f32_16x16x32_bf16 v[78:81], v[106:109], v[58:61], 0
	ds_read2_b64 v[182:185], v195 offset0:52 offset1:56
	s_waitcnt lgkmcnt(14)
	v_mfma_f32_16x16x32_bf16 v[86:89], v[110:113], v[58:61], 0
	ds_read2_b64 v[186:189], v196 offset0:52 offset1:56
	s_waitcnt lgkmcnt(14)
	v_mfma_f32_16x16x32_bf16 v[62:65], v[114:117], v[66:69], v[62:65]
	ds_read2_b64 v[190:193], v197 offset0:52 offset1:56
	s_waitcnt lgkmcnt(14)
	v_mfma_f32_16x16x32_bf16 v[70:73], v[118:121], v[66:69], v[70:73]
	s_waitcnt lgkmcnt(13)
	v_mfma_f32_16x16x32_bf16 v[78:81], v[122:125], v[66:69], v[78:81]
	s_waitcnt lgkmcnt(12)
	v_mfma_f32_16x16x32_bf16 v[86:89], v[126:129], v[66:69], v[86:89]
	s_waitcnt lgkmcnt(11)
	v_mfma_f32_16x16x32_bf16 v[62:65], v[130:133], v[74:77], v[62:65]
	s_waitcnt lgkmcnt(10)
	v_mfma_f32_16x16x32_bf16 v[70:73], v[134:137], v[74:77], v[70:73]
	s_waitcnt lgkmcnt(9)
	v_mfma_f32_16x16x32_bf16 v[78:81], v[138:141], v[74:77], v[78:81]
	s_waitcnt lgkmcnt(8)
	v_mfma_f32_16x16x32_bf16 v[86:89], v[142:145], v[74:77], v[86:89]
	s_waitcnt lgkmcnt(7)
	v_mfma_f32_16x16x32_bf16 v[62:65], v[146:149], v[82:85], v[62:65]
	s_waitcnt lgkmcnt(6)
	v_mfma_f32_16x16x32_bf16 v[70:73], v[150:153], v[82:85], v[70:73]
	s_waitcnt lgkmcnt(5)
	v_mfma_f32_16x16x32_bf16 v[78:81], v[154:157], v[82:85], v[78:81]
	s_waitcnt lgkmcnt(4)
	v_mfma_f32_16x16x32_bf16 v[86:89], v[158:161], v[82:85], v[86:89]
	s_waitcnt lgkmcnt(3)
	v_mfma_f32_16x16x32_bf16 v[62:65], v[162:165], v[90:93], v[62:65]
	s_waitcnt lgkmcnt(2)
	v_mfma_f32_16x16x32_bf16 v[70:73], v[182:185], v[90:93], v[70:73]
	s_waitcnt lgkmcnt(1)
	v_mfma_f32_16x16x32_bf16 v[78:81], v[186:189], v[90:93], v[78:81]
	s_waitcnt lgkmcnt(0)
	v_mfma_f32_16x16x32_bf16 v[86:89], v[190:193], v[90:93], v[86:89]
	ds_read_b128 v[98:101], v45 offset:13824
	ds_read_b128 v[102:105], v45 offset:13888
	ds_read_b128 v[106:109], v45 offset:16128
	ds_read_b128 v[110:113], v45 offset:16192
	ds_read_b128 v[114:117], v45 offset:18432
	ds_read_b128 v[118:121], v45 offset:18496
	ds_read_b128 v[122:125], v45 offset:20736
	ds_read_b128 v[126:129], v45 offset:20800
	ds_read_b128 v[130:133], v45 offset:23040
	ds_read_b128 v[134:137], v45 offset:23104
	ds_read_b128 v[138:141], v45 offset:25344
	ds_read_b128 v[142:145], v45 offset:25408
	ds_read_b128 v[146:149], v45 offset:27648
	ds_read_b128 v[150:153], v45 offset:27712
	s_nop 7
	v_mul_f32_e32 v62, v62, v167
	v_mul_f32_e32 v63, v63, v167
	v_mul_f32_e32 v64, v64, v167
	v_mul_f32_e32 v65, v65, v167
	v_mul_f32_e32 v70, v70, v167
	v_mul_f32_e32 v71, v71, v167
	v_mul_f32_e32 v72, v72, v167
	v_mul_f32_e32 v73, v73, v167
	v_mul_f32_e32 v78, v78, v167
	v_mul_f32_e32 v79, v79, v167
	v_mul_f32_e32 v80, v80, v167
	v_mul_f32_e32 v81, v81, v167
	v_mul_f32_e32 v86, v86, v167
	v_mul_f32_e32 v87, v87, v167
	v_mul_f32_e32 v88, v88, v167
	v_mul_f32_e32 v89, v89, v167
	v_cvt_pk_bf16_f32 v62, v62, v63
	v_cvt_pk_bf16_f32 v63, v64, v65
	global_store_dwordx2 v48, v[62:63], s[24:25] offset:0
	v_cvt_pk_bf16_f32 v70, v70, v71
	v_cvt_pk_bf16_f32 v71, v72, v73
	global_store_dwordx2 v48, v[70:71], s[24:25] offset:32
	v_cvt_pk_bf16_f32 v78, v78, v79
	v_cvt_pk_bf16_f32 v79, v80, v81
	global_store_dwordx2 v48, v[78:79], s[24:25] offset:64
	v_cvt_pk_bf16_f32 v86, v86, v87
	v_cvt_pk_bf16_f32 v87, v88, v89
	global_store_dwordx2 v48, v[86:87], s[24:25] offset:96
	v_add_u32_e32 v48, 0x8000, v48
	s_waitcnt vmcnt(14)
	v_lshlrev_b32_e32 v58, 16, v2
	v_and_b32_e32 v59, 0xffff0000, v2
	v_lshlrev_b32_e32 v66, 16, v6
	v_and_b32_e32 v67, 0xffff0000, v6
	v_lshlrev_b32_e32 v60, 16, v3
	v_and_b32_e32 v61, 0xffff0000, v3
	v_lshlrev_b32_e32 v68, 16, v7
	v_and_b32_e32 v69, 0xffff0000, v7
	v_lshlrev_b32_e32 v62, 16, v4
	v_and_b32_e32 v63, 0xffff0000, v4
	v_lshlrev_b32_e32 v70, 16, v8
	v_and_b32_e32 v71, 0xffff0000, v8
	v_lshlrev_b32_e32 v64, 16, v5
	v_and_b32_e32 v65, 0xffff0000, v5
	v_lshlrev_b32_e32 v72, 16, v9
	v_and_b32_e32 v73, 0xffff0000, v9
	v_pk_mul_f32 v[74:75], v[58:59], v[58:59]
	v_pk_fma_f32 v[74:75], v[60:61], v[60:61], v[74:75]
	v_pk_fma_f32 v[74:75], v[62:63], v[62:63], v[74:75]
	v_pk_fma_f32 v[74:75], v[64:65], v[64:65], v[74:75]
	v_pk_fma_f32 v[74:75], v[66:67], v[66:67], v[74:75]
	v_pk_fma_f32 v[74:75], v[68:69], v[68:69], v[74:75]
	v_pk_fma_f32 v[74:75], v[70:71], v[70:71], v[74:75]
	v_pk_fma_f32 v[74:75], v[72:73], v[72:73], v[74:75]
	v_add_f32_e32 v74, v74, v75
	v_mov_b32_e32 v166, v74
	s_nop 1
	v_permlane16_swap_b32_e32 v74, v166
	v_add_f32_e32 v74, v74, v166
	v_mov_b32_e32 v166, v74
	s_nop 1
	v_permlane32_swap_b32_e32 v74, v166
	v_add_f32_e32 v74, v74, v166
	v_fmamk_f32 v74, v74, 0x3c800000, v209
	v_rsq_f32_e32 v76, v74
	s_nop 0
	v_mul_f32_e32 v76, 0x3e000000, v76
	v_pk_mul_f32 v[58:59], v[58:59], v[76:77] op_sel_hi:[1,0]
	v_pk_mul_f32 v[66:67], v[66:67], v[76:77] op_sel_hi:[1,0]
	v_pk_mul_f32 v[60:61], v[60:61], v[76:77] op_sel_hi:[1,0]
	v_pk_mul_f32 v[68:69], v[68:69], v[76:77] op_sel_hi:[1,0]
	v_pk_mul_f32 v[62:63], v[62:63], v[76:77] op_sel_hi:[1,0]
	v_pk_mul_f32 v[70:71], v[70:71], v[76:77] op_sel_hi:[1,0]
	v_pk_mul_f32 v[64:65], v[64:65], v[76:77] op_sel_hi:[1,0]
	v_pk_mul_f32 v[72:73], v[72:73], v[76:77] op_sel_hi:[1,0]
	v_pk_mul_f32 v[58:59], v[58:59], v[26:27]
	v_pk_mul_f32 v[66:67], v[66:67], v[34:35]
	v_pk_mul_f32 v[60:61], v[60:61], v[28:29]
	v_pk_mul_f32 v[68:69], v[68:69], v[36:37]
	v_pk_mul_f32 v[62:63], v[62:63], v[30:31]
	v_pk_mul_f32 v[70:71], v[70:71], v[38:39]
	v_pk_mul_f32 v[64:65], v[64:65], v[32:33]
	v_pk_mul_f32 v[72:73], v[72:73], v[40:41]
	v_pk_mul_f32 v[78:79], v[66:67], v[18:19]
	v_pk_mul_f32 v[86:87], v[58:59], v[18:19]
	v_pk_mul_f32 v[80:81], v[68:69], v[20:21]
	v_pk_mul_f32 v[88:89], v[60:61], v[20:21]
	v_pk_mul_f32 v[82:83], v[70:71], v[22:23]
	v_pk_mul_f32 v[90:91], v[62:63], v[22:23]
	v_pk_mul_f32 v[84:85], v[72:73], v[24:25]
	v_pk_mul_f32 v[92:93], v[64:65], v[24:25]
	v_pk_fma_f32 v[78:79], v[58:59], v[10:11], v[78:79] neg_lo:[0,0,1] neg_hi:[0,0,1]
	v_pk_fma_f32 v[86:87], v[66:67], v[10:11], v[86:87]
	v_pk_fma_f32 v[80:81], v[60:61], v[12:13], v[80:81] neg_lo:[0,0,1] neg_hi:[0,0,1]
	v_pk_fma_f32 v[88:89], v[68:69], v[12:13], v[88:89]
	v_pk_fma_f32 v[82:83], v[62:63], v[14:15], v[82:83] neg_lo:[0,0,1] neg_hi:[0,0,1]
	v_pk_fma_f32 v[90:91], v[70:71], v[14:15], v[90:91]
	v_pk_fma_f32 v[84:85], v[64:65], v[16:17], v[84:85] neg_lo:[0,0,1] neg_hi:[0,0,1]
	v_pk_fma_f32 v[92:93], v[72:73], v[16:17], v[92:93]
	v_cvt_pk_bf16_f32 v50, v78, v79
	v_cvt_pk_bf16_f32 v54, v86, v87
	v_cvt_pk_bf16_f32 v51, v80, v81
	v_cvt_pk_bf16_f32 v55, v88, v89
	v_cvt_pk_bf16_f32 v52, v82, v83
	v_cvt_pk_bf16_f32 v56, v90, v91
	v_cvt_pk_bf16_f32 v53, v84, v85
	v_cvt_pk_bf16_f32 v57, v92, v93
	s_nop 1
	s_waitcnt lgkmcnt(13)
; #define LAS __attribute__((address_space(3)))
; #define MFMA16(a, b, c) __builtin_amdgcn_mfma_f32_16x16x32_bf16((a), (b), (c), 0, 0, 0)
; __device__ __forceinline__ void p2_block(LAS unsigned char* lds, const bf16_t* __restrict__ PROJ, bf16_t* __restrict__ ATT, bf16_t* __restrict__ SGU, const float* __restrict__ qn, const float* __restrict__ kn, ...
;     ...
;         const LAS unsigned char* kbase = KS + (16 * t0 + fr) * KS_STRIDE + 16 * fq;
; #pragma unroll
;         for (int t = 0; t < 10; ++t) { const bf16x8 k0 = *(const LAS bf16x8*)(kbase + t * 16 * KS_STRIDE), k1 = *(const LAS bf16x8*)(kbase + t * 16 * KS_STRIDE + 64);
;             f32x4 z = (f32x4){0.f, 0.f, 0.f, 0.f}; z = MFMA16(k0, qf0, z); sc_[t] = MFMA16(k1, qf1, z); }
;         float mx = -1e30f;
; #pragma unroll
;         for (int t = 0; t < 10; ++t)
; #pragma unroll
;             for (int e = 0; e < 4; ++e) { const int kx = 16 * (t0 + t) + 4 * fq + e, d = kx - irow; const bool ok = (d >= 1) && (d <= 128) && (n > 0 || kx >= 128);
;                 const float v = ok ? sc_[t][e] : -1e30f; sc_[t][e] = v; mx = fmaxf(mx, v); }
;         mx = fmaxf(mx, __shfl_xor(mx, 16)); mx = fmaxf(mx, __shfl_xor(mx, 32)); mx = fmaxf(mx, sink);
;         float sum = 0.f;
; #pragma unroll
;         for (int t = 0; t < 10; ++t)
; #pragma unroll
;             for (int e = 0; e < 4; ++e) { const float p = __builtin_amdgcn_exp2f((sc_[t][e] - mx) * LOG2E); sc_[t][e] = p; sum += p; }
	v_mfma_f32_16x16x32_bf16 v[58:61], v[98:101], v[50:53], 0
	s_waitcnt lgkmcnt(12)
	v_mfma_f32_16x16x32_bf16 v[58:61], v[102:105], v[54:57], v[58:61]
	ds_read_b128 v[154:157], v45 offset:29952
	ds_read_b128 v[158:161], v45 offset:30016
	s_waitcnt lgkmcnt(13)
	v_mfma_f32_16x16x32_bf16 v[62:65], v[106:109], v[50:53], 0
	s_waitcnt lgkmcnt(12)
	v_mfma_f32_16x16x32_bf16 v[62:65], v[110:113], v[54:57], v[62:65]
	ds_read_b128 v[162:165], v45 offset:32256
	ds_read_b128 v[182:185], v45 offset:32320
	s_waitcnt lgkmcnt(13)
	v_mfma_f32_16x16x32_bf16 v[66:69], v[114:117], v[50:53], 0
	s_waitcnt lgkmcnt(12)
	v_mfma_f32_16x16x32_bf16 v[66:69], v[118:121], v[54:57], v[66:69]
	s_waitcnt lgkmcnt(11)
	v_mfma_f32_16x16x32_bf16 v[70:73], v[122:125], v[50:53], 0
	s_waitcnt lgkmcnt(10)
	v_mfma_f32_16x16x32_bf16 v[70:73], v[126:129], v[54:57], v[70:73]
	s_waitcnt lgkmcnt(9)
	v_mfma_f32_16x16x32_bf16 v[74:77], v[130:133], v[50:53], 0
	s_waitcnt lgkmcnt(8)
	v_mfma_f32_16x16x32_bf16 v[74:77], v[134:137], v[54:57], v[74:77]
	s_waitcnt lgkmcnt(7)
	v_mfma_f32_16x16x32_bf16 v[78:81], v[138:141], v[50:53], 0
	s_waitcnt lgkmcnt(6)
	v_mfma_f32_16x16x32_bf16 v[78:81], v[142:145], v[54:57], v[78:81]
	s_waitcnt lgkmcnt(5)
	v_mfma_f32_16x16x32_bf16 v[82:85], v[146:149], v[50:53], 0
	s_waitcnt lgkmcnt(4)
	v_mfma_f32_16x16x32_bf16 v[82:85], v[150:153], v[54:57], v[82:85]
	s_waitcnt lgkmcnt(3)
	v_mfma_f32_16x16x32_bf16 v[86:89], v[154:157], v[50:53], 0
	s_waitcnt lgkmcnt(2)
	v_mfma_f32_16x16x32_bf16 v[86:89], v[158:161], v[54:57], v[86:89]
	s_waitcnt lgkmcnt(1)
	v_mfma_f32_16x16x32_bf16 v[90:93], v[162:165], v[50:53], 0
	s_waitcnt lgkmcnt(0)
	v_mfma_f32_16x16x32_bf16 v[90:93], v[182:185], v[54:57], v[90:93]
	ds_read2_b64 v[98:101], v194 offset0:24 offset1:28
	ds_read2_b64 v[102:105], v195 offset0:24 offset1:28
	ds_read2_b64 v[106:109], v196 offset0:24 offset1:28
	ds_read2_b64 v[110:113], v197 offset0:24 offset1:28
	ds_read2_b64 v[114:117], v194 offset0:32 offset1:36
	ds_read2_b64 v[118:121], v195 offset0:32 offset1:36
	ds_read2_b64 v[122:125], v196 offset0:32 offset1:36
	ds_read2_b64 v[126:129], v197 offset0:32 offset1:36
	ds_read2_b64 v[130:133], v194 offset0:40 offset1:44
	ds_read2_b64 v[134:137], v195 offset0:40 offset1:44
	ds_read2_b64 v[138:141], v196 offset0:40 offset1:44
	ds_read2_b64 v[142:145], v197 offset0:40 offset1:44
	ds_read2_b64 v[146:149], v194 offset0:48 offset1:52
	ds_read2_b64 v[150:153], v195 offset0:48 offset1:52
	ds_read2_b64 v[154:157], v196 offset0:48 offset1:52
	s_nop 4
	v_cndmask_b32_e64 v58, v49, v58, s[48:49]
	v_cndmask_b32_e64 v59, v49, v59, s[50:51]
	v_cndmask_b32_e64 v60, v49, v60, s[52:53]
	v_cndmask_b32_e64 v61, v49, v61, s[26:27]
	v_cndmask_b32_e64 v62, v49, v62, s[28:29]
	v_cndmask_b32_e64 v63, v49, v63, s[28:29]
	v_cndmask_b32_e64 v64, v49, v64, s[28:29]
	v_cndmask_b32_e64 v65, v49, v65, s[28:29]
	v_cndmask_b32_e64 v90, v90, v49, s[40:41]
	v_cndmask_b32_e64 v91, v91, v49, s[42:43]
	v_cndmask_b32_e64 v92, v92, v49, s[44:45]
	v_cndmask_b32_e64 v93, v93, v49, s[46:47]
	v_max_f32_e32 v167, v58, v59
	v_max_f32_e32 v94, v60, v61
	v_max3_f32 v167, v167, v62, v63
	v_max3_f32 v94, v94, v64, v65
	v_max3_f32 v167, v167, v66, v67
	v_max3_f32 v94, v94, v68, v69
	v_max3_f32 v167, v167, v70, v71
	v_max3_f32 v94, v94, v72, v73
	v_max3_f32 v167, v167, v74, v75
	v_max3_f32 v94, v94, v76, v77
	v_max3_f32 v167, v167, v78, v79
	v_max3_f32 v94, v94, v80, v81
	v_max3_f32 v167, v167, v82, v83
	v_max3_f32 v94, v94, v84, v85
	v_max3_f32 v167, v167, v86, v87
	v_max3_f32 v94, v94, v88, v89
	v_max3_f32 v167, v167, v90, v91
	v_max3_f32 v94, v94, v92, v93
	v_max_f32_e32 v167, v167, v94
	v_mov_b32_e32 v166, v167
	s_nop 1
	v_permlane16_swap_b32_e32 v167, v166
	v_max_f32_e32 v167, v167, v166
	v_mov_b32_e32 v166, v167
	s_nop 1
	v_permlane32_swap_b32_e32 v167, v166
	v_max_f32_e32 v167, v167, v166
	v_max_f32_e32 v167, v167, v42
	v_mul_f32_e32 v94, 0xbfb8aa3b, v167
	v_fmamk_f32 v58, v58, 0x3fb8aa3b, v94
	v_fmamk_f32 v59, v59, 0x3fb8aa3b, v94
	v_fmamk_f32 v60, v60, 0x3fb8aa3b, v94
	v_fmamk_f32 v61, v61, 0x3fb8aa3b, v94
	v_fmamk_f32 v62, v62, 0x3fb8aa3b, v94
	v_fmamk_f32 v63, v63, 0x3fb8aa3b, v94
	v_fmamk_f32 v64, v64, 0x3fb8aa3b, v94
	v_fmamk_f32 v65, v65, 0x3fb8aa3b, v94
	v_fmamk_f32 v66, v66, 0x3fb8aa3b, v94
	v_fmamk_f32 v67, v67, 0x3fb8aa3b, v94
	v_fmamk_f32 v68, v68, 0x3fb8aa3b, v94
	v_fmamk_f32 v69, v69, 0x3fb8aa3b, v94
	v_fmamk_f32 v70, v70, 0x3fb8aa3b, v94
	v_fmamk_f32 v71, v71, 0x3fb8aa3b, v94
	v_fmamk_f32 v72, v72, 0x3fb8aa3b, v94
	v_fmamk_f32 v73, v73, 0x3fb8aa3b, v94
	v_fmamk_f32 v74, v74, 0x3fb8aa3b, v94
	v_fmamk_f32 v75, v75, 0x3fb8aa3b, v94
	v_fmamk_f32 v76, v76, 0x3fb8aa3b, v94
	v_fmamk_f32 v77, v77, 0x3fb8aa3b, v94
	v_fmamk_f32 v78, v78, 0x3fb8aa3b, v94
	v_fmamk_f32 v79, v79, 0x3fb8aa3b, v94
	v_fmamk_f32 v80, v80, 0x3fb8aa3b, v94
	v_fmamk_f32 v81, v81, 0x3fb8aa3b, v94
	v_fmamk_f32 v82, v82, 0x3fb8aa3b, v94
	v_fmamk_f32 v83, v83, 0x3fb8aa3b, v94
	v_fmamk_f32 v84, v84, 0x3fb8aa3b, v94
	v_fmamk_f32 v85, v85, 0x3fb8aa3b, v94
	v_fmamk_f32 v86, v86, 0x3fb8aa3b, v94
	v_fmamk_f32 v87, v87, 0x3fb8aa3b, v94
	v_fmamk_f32 v88, v88, 0x3fb8aa3b, v94
	v_fmamk_f32 v89, v89, 0x3fb8aa3b, v94
	v_fmamk_f32 v90, v90, 0x3fb8aa3b, v94
	v_fmamk_f32 v91, v91, 0x3fb8aa3b, v94
	v_fmamk_f32 v92, v92, 0x3fb8aa3b, v94
	v_fmamk_f32 v93, v93, 0x3fb8aa3b, v94
	v_exp_f32_e32 v58, v58
	v_exp_f32_e32 v59, v59
	v_exp_f32_e32 v60, v60
	v_exp_f32_e32 v61, v61
	v_exp_f32_e32 v62, v62
	v_exp_f32_e32 v63, v63
	v_exp_f32_e32 v64, v64
	v_exp_f32_e32 v65, v65
	v_exp_f32_e32 v66, v66
	v_exp_f32_e32 v67, v67
	v_exp_f32_e32 v68, v68
	v_exp_f32_e32 v69, v69
	v_exp_f32_e32 v70, v70
	v_exp_f32_e32 v71, v71
; __device__ __forceinline__ unsigned cvt_pk_bf16(float lo, float hi) { unsigned r; asm volatile("v_cvt_pk_bf16_f32 %0, %1, %2" : "=v"(r) : "v"(lo), "v"(hi)); return r; }
; #define LAS __attribute__((address_space(3)))
; #define MFMA16(a, b, c) __builtin_amdgcn_mfma_f32_16x16x32_bf16((a), (b), (c), 0, 0, 0)
; __device__ __forceinline__ void p2_block(LAS unsigned char* lds, const bf16_t* __restrict__ PROJ, bf16_t* __restrict__ ATT, bf16_t* __restrict__ SGU, const float* __restrict__ qn, const float* __restrict__ kn, ...
;     ...
;             for (int e = 0; e < 4; ++e) { const float p = __builtin_amdgcn_exp2f((sc_[t][e] - mx) * LOG2E); sc_[t][e] = p; sum += p; }
;         sum += __shfl_xor(sum, 16); sum += __shfl_xor(sum, 32);
;         const float inv = 1.0f / (sum + __builtin_amdgcn_exp2f((sink - mx) * LOG2E));
;         f32x4 o[4];
; #pragma unroll
;         for (int dt = 0; dt < 4; ++dt) o[dt] = (f32x4){0.f, 0.f, 0.f, 0.f};
; #pragma unroll
;         for (int j = 0; j < 5; ++j) {
;             u32x4 pw; pw.x = cvt_pk_bf16(sc_[2 * j][0], sc_[2 * j][1]); pw.y = cvt_pk_bf16(sc_[2 * j][2], sc_[2 * j][3]); pw.z = cvt_pk_bf16(sc_[2 * j + 1][0], sc_[2 * j + 1][1]); pw.w = cvt_pk_bf16(sc_[2 * j + 1][2], sc_[2 * j + 1][3]);
;             const bf16x8 pf = __builtin_bit_cast(bf16x8, pw);
; #pragma unroll
;             for (int dt = 0; dt < 4; ++dt) { const LAS unsigned char* vb = VT + (16 * dt + fr) * VT_STRIDE + (16 * (t0 + 2 * j) + 4 * fq) * 2;
;                 const u32x2 va = *(const LAS u32x2*)vb, vc = *(const LAS u32x2*)(vb + 32); u32x4 vw; vw.x = va.x; vw.y = va.y; vw.z = vc.x; vw.w = vc.y;
;                 o[dt] = MFMA16(__builtin_bit_cast(bf16x8, vw), pf, o[dt]); }
;         }
;         bf16_t* op = ATT + grow * 1024 + hq * 64 + 4 * fq;
; #pragma unroll
;         for (int dt = 0; dt < 4; ++dt) { u32x2 ow; ow.x = cvt_pk_bf16(o[dt][0] * inv, o[dt][1] * inv); ow.y = cvt_pk_bf16(o[dt][2] * inv, o[dt][3] * inv); *(u32x2*)(op + 16 * dt) = ow; }
	v_exp_f32_e32 v72, v72
	v_exp_f32_e32 v73, v73
	v_exp_f32_e32 v74, v74
	v_exp_f32_e32 v75, v75
	v_exp_f32_e32 v76, v76
	v_exp_f32_e32 v77, v77
	v_exp_f32_e32 v78, v78
	v_exp_f32_e32 v79, v79
	v_exp_f32_e32 v80, v80
	v_exp_f32_e32 v81, v81
	v_exp_f32_e32 v82, v82
	v_exp_f32_e32 v83, v83
	v_exp_f32_e32 v84, v84
	v_exp_f32_e32 v85, v85
	v_exp_f32_e32 v86, v86
	v_exp_f32_e32 v87, v87
	v_exp_f32_e32 v88, v88
	v_exp_f32_e32 v89, v89
	v_exp_f32_e32 v90, v90
	v_exp_f32_e32 v91, v91
	v_exp_f32_e32 v92, v92
	v_exp_f32_e32 v93, v93
	v_fmamk_f32 v95, v42, 0x3fb8aa3b, v94
	v_exp_f32_e32 v95, v95
	v_add_f32_e32 v167, v58, v59
	v_add_f32_e32 v94, v60, v61
	v_add_f32_e32 v167, v167, v62
	v_add_f32_e32 v94, v94, v63
	v_add_f32_e32 v167, v167, v64
	v_add_f32_e32 v94, v94, v65
	v_add_f32_e32 v167, v167, v66
	v_add_f32_e32 v94, v94, v67
	v_add_f32_e32 v167, v167, v68
	v_add_f32_e32 v94, v94, v69
	v_add_f32_e32 v167, v167, v70
	v_add_f32_e32 v94, v94, v71
	v_add_f32_e32 v167, v167, v72
	v_add_f32_e32 v94, v94, v73
	v_add_f32_e32 v167, v167, v74
	v_add_f32_e32 v94, v94, v75
	v_add_f32_e32 v167, v167, v76
	v_add_f32_e32 v94, v94, v77
	v_add_f32_e32 v167, v167, v78
	v_add_f32_e32 v94, v94, v79
	v_add_f32_e32 v167, v167, v80
	v_add_f32_e32 v94, v94, v81
	v_add_f32_e32 v167, v167, v82
	v_add_f32_e32 v94, v94, v83
	v_add_f32_e32 v167, v167, v84
	v_add_f32_e32 v94, v94, v85
	v_add_f32_e32 v167, v167, v86
	v_add_f32_e32 v94, v94, v87
	v_add_f32_e32 v167, v167, v88
	v_add_f32_e32 v94, v94, v89
	v_add_f32_e32 v167, v167, v90
	v_add_f32_e32 v94, v94, v91
	v_add_f32_e32 v167, v167, v92
	v_add_f32_e32 v94, v94, v93
	v_add_f32_e32 v167, v167, v94
	v_mov_b32_e32 v166, v167
	s_nop 1
	v_permlane16_swap_b32_e32 v167, v166
	v_add_f32_e32 v167, v167, v166
	v_mov_b32_e32 v166, v167
	s_nop 1
	v_permlane32_swap_b32_e32 v167, v166
	v_add_f32_e32 v167, v167, v166
	v_add_f32_e32 v167, v167, v95
	v_rcp_f32_e32 v167, v167
	v_mov_b32_e32 v94, 0
	v_mov_b32_e32 v95, 0
	v_mov_b32_e32 v96, 0
	v_mov_b32_e32 v97, 0
	v_cvt_pk_bf16_f32 v58, v58, v59
	v_cvt_pk_bf16_f32 v59, v60, v61
	v_cvt_pk_bf16_f32 v60, v62, v63
	v_cvt_pk_bf16_f32 v61, v64, v65
	v_cvt_pk_bf16_f32 v66, v66, v67
	v_cvt_pk_bf16_f32 v67, v68, v69
	v_cvt_pk_bf16_f32 v68, v70, v71
	v_cvt_pk_bf16_f32 v69, v72, v73
	v_cvt_pk_bf16_f32 v74, v74, v75
	v_cvt_pk_bf16_f32 v75, v76, v77
	v_cvt_pk_bf16_f32 v76, v78, v79
	v_cvt_pk_bf16_f32 v77, v80, v81
	v_cvt_pk_bf16_f32 v82, v82, v83
	v_cvt_pk_bf16_f32 v83, v84, v85
	v_cvt_pk_bf16_f32 v84, v86, v87
	v_cvt_pk_bf16_f32 v85, v88, v89
	v_cvt_pk_bf16_f32 v90, v90, v91
	v_cvt_pk_bf16_f32 v91, v92, v93
	v_cvt_pk_bf16_f32 v92, v94, v95
	v_cvt_pk_bf16_f32 v93, v96, v97
	s_nop 1
	s_waitcnt lgkmcnt(14)
	v_mfma_f32_16x16x32_bf16 v[62:65], v[98:101], v[58:61], 0
	ds_read2_b64 v[158:161], v197 offset0:48 offset1:52
	s_waitcnt lgkmcnt(14)
	v_mfma_f32_16x16x32_bf16 v[70:73], v[102:105], v[58:61], 0
	ds_read2_b64 v[162:165], v194 offset0:56 offset1:60
	s_waitcnt lgkmcnt(14)
	v_mfma_f32_16x16x32_bf16 v[78:81], v[106:109], v[58:61], 0
	ds_read2_b64 v[182:185], v195 offset0:56 offset1:60
	s_waitcnt lgkmcnt(14)
	v_mfma_f32_16x16x32_bf16 v[86:89], v[110:113], v[58:61], 0
	ds_read2_b64 v[186:189], v196 offset0:56 offset1:60
	s_waitcnt lgkmcnt(14)
	v_mfma_f32_16x16x32_bf16 v[62:65], v[114:117], v[66:69], v[62:65]
	ds_read2_b64 v[190:193], v197 offset0:56 offset1:60
	s_waitcnt lgkmcnt(14)
	v_mfma_f32_16x16x32_bf16 v[70:73], v[118:121], v[66:69], v[70:73]
	s_waitcnt lgkmcnt(13)
	v_mfma_f32_16x16x32_bf16 v[78:81], v[122:125], v[66:69], v[78:81]
	s_waitcnt lgkmcnt(12)
	v_mfma_f32_16x16x32_bf16 v[86:89], v[126:129], v[66:69], v[86:89]
	s_waitcnt lgkmcnt(11)
	v_mfma_f32_16x16x32_bf16 v[62:65], v[130:133], v[74:77], v[62:65]
	s_waitcnt lgkmcnt(10)
	v_mfma_f32_16x16x32_bf16 v[70:73], v[134:137], v[74:77], v[70:73]
	s_waitcnt lgkmcnt(9)
	v_mfma_f32_16x16x32_bf16 v[78:81], v[138:141], v[74:77], v[78:81]
	s_waitcnt lgkmcnt(8)
	v_mfma_f32_16x16x32_bf16 v[86:89], v[142:145], v[74:77], v[86:89]
	s_waitcnt lgkmcnt(7)
	v_mfma_f32_16x16x32_bf16 v[62:65], v[146:149], v[82:85], v[62:65]
	s_waitcnt lgkmcnt(6)
	v_mfma_f32_16x16x32_bf16 v[70:73], v[150:153], v[82:85], v[70:73]
	s_waitcnt lgkmcnt(5)
	v_mfma_f32_16x16x32_bf16 v[78:81], v[154:157], v[82:85], v[78:81]
	s_waitcnt lgkmcnt(4)
	v_mfma_f32_16x16x32_bf16 v[86:89], v[158:161], v[82:85], v[86:89]
	s_waitcnt lgkmcnt(3)
	v_mfma_f32_16x16x32_bf16 v[62:65], v[162:165], v[90:93], v[62:65]
	s_waitcnt lgkmcnt(2)
	v_mfma_f32_16x16x32_bf16 v[70:73], v[182:185], v[90:93], v[70:73]
	s_waitcnt lgkmcnt(1)
	v_mfma_f32_16x16x32_bf16 v[78:81], v[186:189], v[90:93], v[78:81]
	s_waitcnt lgkmcnt(0)
	v_mfma_f32_16x16x32_bf16 v[86:89], v[190:193], v[90:93], v[86:89]
	ds_read_b128 v[106:109], v45 offset:16128
	ds_read_b128 v[110:113], v45 offset:16192
	ds_read_b128 v[114:117], v45 offset:18432
	ds_read_b128 v[118:121], v45 offset:18496
	ds_read_b128 v[122:125], v45 offset:20736
	ds_read_b128 v[126:129], v45 offset:20800
	ds_read_b128 v[130:133], v45 offset:23040
	ds_read_b128 v[134:137], v45 offset:23104
	ds_read_b128 v[138:141], v45 offset:25344
	ds_read_b128 v[142:145], v45 offset:25408
	ds_read_b128 v[146:149], v45 offset:27648
	ds_read_b128 v[150:153], v45 offset:27712
	ds_read_b128 v[154:157], v45 offset:29952
	ds_read_b128 v[158:161], v45 offset:30016
	s_nop 7
	v_mul_f32_e32 v62, v62, v167
	v_mul_f32_e32 v63, v63, v167
	v_mul_f32_e32 v64, v64, v167
	v_mul_f32_e32 v65, v65, v167
	v_mul_f32_e32 v70, v70, v167
	v_mul_f32_e32 v71, v71, v167
	v_mul_f32_e32 v72, v72, v167
	v_mul_f32_e32 v73, v73, v167
	v_mul_f32_e32 v78, v78, v167
	v_mul_f32_e32 v79, v79, v167
	v_mul_f32_e32 v80, v80, v167
	v_mul_f32_e32 v81, v81, v167
	v_mul_f32_e32 v86, v86, v167
	v_mul_f32_e32 v87, v87, v167
	v_mul_f32_e32 v88, v88, v167
	v_mul_f32_e32 v89, v89, v167
	v_cvt_pk_bf16_f32 v62, v62, v63
	v_cvt_pk_bf16_f32 v63, v64, v65
	global_store_dwordx2 v48, v[62:63], s[24:25] offset:0
	v_cvt_pk_bf16_f32 v70, v70, v71
	v_cvt_pk_bf16_f32 v71, v72, v73
	global_store_dwordx2 v48, v[70:71], s[24:25] offset:32
	v_cvt_pk_bf16_f32 v78, v78, v79
	v_cvt_pk_bf16_f32 v79, v80, v81
	global_store_dwordx2 v48, v[78:79], s[24:25] offset:64
	v_cvt_pk_bf16_f32 v86, v86, v87
	v_cvt_pk_bf16_f32 v87, v88, v89
	global_store_dwordx2 v48, v[86:87], s[24:25] offset:96
	v_add_u32_e32 v48, 0x8000, v48
	s_waitcnt vmcnt(8)
; __device__ __forceinline__ unsigned cvt_pk_bf16(float lo, float hi) { unsigned r; asm volatile("v_cvt_pk_bf16_f32 %0, %1, %2" : "=v"(r) : "v"(lo), "v"(hi)); return r; }
; __device__ __forceinline__ void p2_block(LAS unsigned char* lds, const bf16_t* __restrict__ PROJ, bf16_t* __restrict__ ATT, bf16_t* __restrict__ SGU, const float* __restrict__ qn, const float* __restrict__ kn, ...
;     ...
;             float x1[8], x2[8]; unpack8(qa[c], x1); unpack8(qb[c], x2);
;             float ss = 0.f;
; #pragma unroll
;             for (int j = 0; j < 8; ++j) ss += x1[j] * x1[j] + x2[j] * x2[j];
;             ss += __shfl_xor(ss, 16); ss += __shfl_xor(ss, 32);
;             const float rinv = rsqrtf(ss * (1.0f / 64.0f) + pg8::EPS) * 0.125f;
;             const float* cp = COS + pos * 32 + 8 * fq; const float* sp = SIN + pos * 32 + 8 * fq;
;             float o1[8], o2[8];
; #pragma unroll
;             for (int j = 0; j < 8; ++j) { const float a1 = x1[j] * rinv * qn[8 * fq + j], a2 = x2[j] * rinv * qn[32 + 8 * fq + j], cc = cp[j], sn = sp[j]; o1[j] = a1 * cc - a2 * sn; o2[j] = a2 * cc + a1 * sn; }
;             u32x4 w0, w1;
;             w0.x = cvt_pk_bf16(o1[0], o1[1]); w0.y = cvt_pk_bf16(o1[2], o1[3]); w0.z = cvt_pk_bf16(o1[4], o1[5]); w0.w = cvt_pk_bf16(o1[6], o1[7]);
;             w1.x = cvt_pk_bf16(o2[0], o2[1]); w1.y = cvt_pk_bf16(o2[2], o2[3]); w1.z = cvt_pk_bf16(o2[4], o2[5]); w1.w = cvt_pk_bf16(o2[6], o2[7]);
;             qf0 = __builtin_bit_cast(bf16x8, w0); qf1 = __builtin_bit_cast(bf16x8, w1);
;         }
;         const int t0 = (i0 >> 4) < 6 ? (i0 >> 4) : 6;
;         f32x4 sc_[10];
;         const LAS unsigned char* kbase = KS + (16 * t0 + fr) * KS_STRIDE + 16 * fq;
; #pragma unroll
;         for (int t = 0; t < 10; ++t) { const bf16x8 k0 = *(const LAS bf16x8*)(kbase + t * 16 * KS_STRIDE), k1 = *(const LAS bf16x8*)(kbase + t * 16 * KS_STRIDE + 64);
;             f32x4 z = (f32x4){0.f, 0.f, 0.f, 0.f}; z = MFMA16(k0, qf0, z); sc_[t] = MFMA16(k1, qf1, z); }
;     ...
;         const float bias = bsp[gg * 128 + irow];
;         const size_t grow = (size_t)b * pg8::SEQ + n * 128 + irow;
;         const bf16_t* up = PROJ + grow * pg8::IN_W + pg8::C_U + gg * 128 + 4 * fq; bf16_t* op = SGU + grow * 1024 + gg * 128 + 4 * fq;
; #pragma unroll
;         for (int dt = 0; dt < 8; ++dt) { const u32x2 uw = *(const u32x2*)(up + 16 * dt);
	v_lshlrev_b32_e32 v58, 16, v218
	v_and_b32_e32 v59, 0xffff0000, v218
	v_lshlrev_b32_e32 v66, 16, v222
	v_and_b32_e32 v67, 0xffff0000, v222
	v_lshlrev_b32_e32 v60, 16, v219
	v_and_b32_e32 v61, 0xffff0000, v219
	v_lshlrev_b32_e32 v68, 16, v223
	v_and_b32_e32 v69, 0xffff0000, v223
	v_lshlrev_b32_e32 v62, 16, v220
	v_and_b32_e32 v63, 0xffff0000, v220
	v_lshlrev_b32_e32 v70, 16, v224
	v_and_b32_e32 v71, 0xffff0000, v224
	v_lshlrev_b32_e32 v64, 16, v221
	v_and_b32_e32 v65, 0xffff0000, v221
	v_lshlrev_b32_e32 v72, 16, v225
	v_and_b32_e32 v73, 0xffff0000, v225
	v_pk_mul_f32 v[74:75], v[58:59], v[58:59]
	v_pk_fma_f32 v[74:75], v[60:61], v[60:61], v[74:75]
	v_pk_fma_f32 v[74:75], v[62:63], v[62:63], v[74:75]
	v_pk_fma_f32 v[74:75], v[64:65], v[64:65], v[74:75]
	v_pk_fma_f32 v[74:75], v[66:67], v[66:67], v[74:75]
	v_pk_fma_f32 v[74:75], v[68:69], v[68:69], v[74:75]
	v_pk_fma_f32 v[74:75], v[70:71], v[70:71], v[74:75]
	v_pk_fma_f32 v[74:75], v[72:73], v[72:73], v[74:75]
	v_add_f32_e32 v74, v74, v75
	v_mov_b32_e32 v166, v74
	s_nop 1
	v_permlane16_swap_b32_e32 v74, v166
	v_add_f32_e32 v74, v74, v166
	v_mov_b32_e32 v166, v74
	s_nop 1
	v_permlane32_swap_b32_e32 v74, v166
	v_add_f32_e32 v74, v74, v166
	v_fmamk_f32 v74, v74, 0x3c800000, v209
	v_rsq_f32_e32 v76, v74
	s_nop 0
	v_mul_f32_e32 v76, 0x3e000000, v76
	v_pk_mul_f32 v[58:59], v[58:59], v[76:77] op_sel_hi:[1,0]
	v_pk_mul_f32 v[66:67], v[66:67], v[76:77] op_sel_hi:[1,0]
	v_pk_mul_f32 v[60:61], v[60:61], v[76:77] op_sel_hi:[1,0]
	v_pk_mul_f32 v[68:69], v[68:69], v[76:77] op_sel_hi:[1,0]
	v_pk_mul_f32 v[62:63], v[62:63], v[76:77] op_sel_hi:[1,0]
	v_pk_mul_f32 v[70:71], v[70:71], v[76:77] op_sel_hi:[1,0]
	v_pk_mul_f32 v[64:65], v[64:65], v[76:77] op_sel_hi:[1,0]
	v_pk_mul_f32 v[72:73], v[72:73], v[76:77] op_sel_hi:[1,0]
	v_pk_mul_f32 v[58:59], v[58:59], v[26:27]
	v_pk_mul_f32 v[66:67], v[66:67], v[34:35]
	v_pk_mul_f32 v[60:61], v[60:61], v[28:29]
	v_pk_mul_f32 v[68:69], v[68:69], v[36:37]
	v_pk_mul_f32 v[62:63], v[62:63], v[30:31]
	v_pk_mul_f32 v[70:71], v[70:71], v[38:39]
	v_pk_mul_f32 v[64:65], v[64:65], v[32:33]
	v_pk_mul_f32 v[72:73], v[72:73], v[40:41]
	v_pk_mul_f32 v[78:79], v[66:67], v[234:235]
	v_pk_mul_f32 v[86:87], v[58:59], v[234:235]
	v_pk_mul_f32 v[80:81], v[68:69], v[236:237]
	v_pk_mul_f32 v[88:89], v[60:61], v[236:237]
	v_pk_mul_f32 v[82:83], v[70:71], v[238:239]
	v_pk_mul_f32 v[90:91], v[62:63], v[238:239]
	v_pk_mul_f32 v[84:85], v[72:73], v[240:241]
	v_pk_mul_f32 v[92:93], v[64:65], v[240:241]
	v_pk_fma_f32 v[78:79], v[58:59], v[226:227], v[78:79] neg_lo:[0,0,1] neg_hi:[0,0,1]
	v_pk_fma_f32 v[86:87], v[66:67], v[226:227], v[86:87]
	v_pk_fma_f32 v[80:81], v[60:61], v[228:229], v[80:81] neg_lo:[0,0,1] neg_hi:[0,0,1]
	v_pk_fma_f32 v[88:89], v[68:69], v[228:229], v[88:89]
	v_pk_fma_f32 v[82:83], v[62:63], v[230:231], v[82:83] neg_lo:[0,0,1] neg_hi:[0,0,1]
	v_pk_fma_f32 v[90:91], v[70:71], v[230:231], v[90:91]
	v_pk_fma_f32 v[84:85], v[64:65], v[232:233], v[84:85] neg_lo:[0,0,1] neg_hi:[0,0,1]
	v_pk_fma_f32 v[92:93], v[72:73], v[232:233], v[92:93]
	v_cvt_pk_bf16_f32 v50, v78, v79
	v_cvt_pk_bf16_f32 v54, v86, v87
	v_cvt_pk_bf16_f32 v51, v80, v81
	v_cvt_pk_bf16_f32 v55, v88, v89
	v_cvt_pk_bf16_f32 v52, v82, v83
	v_cvt_pk_bf16_f32 v56, v90, v91
	v_cvt_pk_bf16_f32 v53, v84, v85
	v_cvt_pk_bf16_f32 v57, v92, v93
	v_lshrrev_b32_e32 v242, 2, v204
	v_and_b32_e32 v242, 0x70, v242
	v_and_b32_e32 v243, 15, v204
	v_or_b32_e32 v242, v242, v243
	v_lshrrev_b32_e32 v243, 1, v204
	v_and_b32_e32 v243, 24, v243
	v_and_b32_e64 v244, s2, 3
	v_lshlrev_b32_e32 v244, 9, v244
	v_and_b32_e64 v245, s2, -4
	v_lshl_add_u32 v245, v245, 5, v242
	v_mul_u32_u24_e32 v245, 0x3c00, v245
	v_add3_u32 v245, v245, v244, v243
	v_lshlrev_b32_e32 v244, 1, v244
	v_lshl_add_u32 v244, v242, 2, v244
	global_load_dword v198, v244, s[22:23]
	global_load_dword v199, v244, s[22:23] offset:512
	global_load_dwordx2 v[218:219], v245, s[10:11] offset:3072
	global_load_dwordx2 v[220:221], v245, s[10:11] offset:3104
	global_load_dwordx2 v[222:223], v245, s[10:11] offset:3136
	global_load_dwordx2 v[224:225], v245, s[10:11] offset:3168
	global_load_dwordx2 v[226:227], v245, s[10:11] offset:3200
	global_load_dwordx2 v[228:229], v245, s[10:11] offset:3232
	global_load_dwordx2 v[230:231], v245, s[10:11] offset:3264
	global_load_dwordx2 v[232:233], v245, s[10:11] offset:3296
	global_load_dwordx2 v[234:235], v245, s[10:11] offset:3328
	global_load_dwordx2 v[236:237], v245, s[10:11] offset:3360
	global_load_dwordx2 v[238:239], v245, s[10:11] offset:3392
	global_load_dwordx2 v[240:241], v245, s[10:11] offset:3424
	global_load_dwordx2 v[242:243], v245, s[10:11] offset:3456
	global_load_dwordx2 v[200:201], v245, s[10:11] offset:3520
	global_load_dwordx2 v[202:203], v245, s[10:11] offset:3552
	global_load_dwordx2 v[244:245], v245, s[10:11] offset:3488
	s_nop 1
	s_waitcnt lgkmcnt(13)
	v_mfma_f32_16x16x32_bf16 v[62:65], v[106:109], v[50:53], 0
	s_waitcnt lgkmcnt(12)
	v_mfma_f32_16x16x32_bf16 v[62:65], v[110:113], v[54:57], v[62:65]
	ds_read_b128 v[162:165], v45 offset:32256
	ds_read_b128 v[182:185], v45 offset:32320
	s_waitcnt lgkmcnt(13)
	v_mfma_f32_16x16x32_bf16 v[66:69], v[114:117], v[50:53], 0
	s_waitcnt lgkmcnt(12)
	v_mfma_f32_16x16x32_bf16 v[66:69], v[118:121], v[54:57], v[66:69]
	ds_read_b128 v[186:189], v45 offset:34560
	ds_read_b128 v[190:193], v45 offset:34624
	s_waitcnt lgkmcnt(13)
	v_mfma_f32_16x16x32_bf16 v[70:73], v[122:125], v[50:53], 0
	s_waitcnt lgkmcnt(12)
	v_mfma_f32_16x16x32_bf16 v[70:73], v[126:129], v[54:57], v[70:73]
	s_waitcnt lgkmcnt(11)
	v_mfma_f32_16x16x32_bf16 v[74:77], v[130:133], v[50:53], 0
	s_waitcnt lgkmcnt(10)
; __device__ __forceinline__ unsigned cvt_pk_bf16(float lo, float hi) { unsigned r; asm volatile("v_cvt_pk_bf16_f32 %0, %1, %2" : "=v"(r) : "v"(lo), "v"(hi)); return r; }
; #define LAS __attribute__((address_space(3)))
; __device__ __forceinline__ void p2_block(LAS unsigned char* lds, const bf16_t* __restrict__ PROJ, bf16_t* __restrict__ ATT, bf16_t* __restrict__ SGU, const float* __restrict__ qn, const float* __restrict__ kn, ...
;     ...
;         for (int t = 0; t < 10; ++t) { const bf16x8 k0 = *(const LAS bf16x8*)(kbase + t * 16 * KS_STRIDE), k1 = *(const LAS bf16x8*)(kbase + t * 16 * KS_STRIDE + 64);
;             f32x4 z = (f32x4){0.f, 0.f, 0.f, 0.f}; z = MFMA16(k0, qf0, z); sc_[t] = MFMA16(k1, qf1, z); }
;         float mx = -1e30f;
; #pragma unroll
;         for (int t = 0; t < 10; ++t)
; #pragma unroll
;             for (int e = 0; e < 4; ++e) { const int kx = 16 * (t0 + t) + 4 * fq + e, d = kx - irow; const bool ok = (d >= 1) && (d <= 128) && (n > 0 || kx >= 128);
;                 const float v = ok ? sc_[t][e] : -1e30f; sc_[t][e] = v; mx = fmaxf(mx, v); }
;         mx = fmaxf(mx, __shfl_xor(mx, 16)); mx = fmaxf(mx, __shfl_xor(mx, 32)); mx = fmaxf(mx, sink);
;         float sum = 0.f;
; #pragma unroll
;         for (int t = 0; t < 10; ++t)
; #pragma unroll
;             for (int e = 0; e < 4; ++e) { const float p = __builtin_amdgcn_exp2f((sc_[t][e] - mx) * LOG2E); sc_[t][e] = p; sum += p; }
;         sum += __shfl_xor(sum, 16); sum += __shfl_xor(sum, 32);
;         const float inv = 1.0f / (sum + __builtin_amdgcn_exp2f((sink - mx) * LOG2E));
;         f32x4 o[4];
; #pragma unroll
;         for (int dt = 0; dt < 4; ++dt) o[dt] = (f32x4){0.f, 0.f, 0.f, 0.f};
; #pragma unroll
;         for (int j = 0; j < 5; ++j) {
;             u32x4 pw; pw.x = cvt_pk_bf16(sc_[2 * j][0], sc_[2 * j][1]); pw.y = cvt_pk_bf16(sc_[2 * j][2], sc_[2 * j][3]); pw.z = cvt_pk_bf16(sc_[2 * j + 1][0], sc_[2 * j + 1][1]); pw.w = cvt_pk_bf16(sc_[2 * j + 1][2], sc_[2 * j + 1][3]);
;             const bf16x8 pf = __builtin_bit_cast(bf16x8, pw);
; #pragma unroll
;             for (int dt = 0; dt < 4; ++dt) { const LAS unsigned char* vb = VT + (16 * dt + fr) * VT_STRIDE + (16 * (t0 + 2 * j) + 4 * fq) * 2;
;                 const u32x2 va = *(const LAS u32x2*)vb, vc = *(const LAS u32x2*)(vb + 32); u32x4 vw; vw.x = va.x; vw.y = va.y; vw.z = vc.x; vw.w = vc.y;
	v_mfma_f32_16x16x32_bf16 v[74:77], v[134:137], v[54:57], v[74:77]
	s_waitcnt lgkmcnt(9)
	v_mfma_f32_16x16x32_bf16 v[78:81], v[138:141], v[50:53], 0
	s_waitcnt lgkmcnt(8)
	v_mfma_f32_16x16x32_bf16 v[78:81], v[142:145], v[54:57], v[78:81]
	s_waitcnt lgkmcnt(7)
	v_mfma_f32_16x16x32_bf16 v[82:85], v[146:149], v[50:53], 0
	s_waitcnt lgkmcnt(6)
	v_mfma_f32_16x16x32_bf16 v[82:85], v[150:153], v[54:57], v[82:85]
	s_waitcnt lgkmcnt(5)
	v_mfma_f32_16x16x32_bf16 v[86:89], v[154:157], v[50:53], 0
	s_waitcnt lgkmcnt(4)
	v_mfma_f32_16x16x32_bf16 v[86:89], v[158:161], v[54:57], v[86:89]
	s_waitcnt lgkmcnt(3)
	v_mfma_f32_16x16x32_bf16 v[90:93], v[162:165], v[50:53], 0
	s_waitcnt lgkmcnt(2)
	v_mfma_f32_16x16x32_bf16 v[90:93], v[182:185], v[54:57], v[90:93]
	s_waitcnt lgkmcnt(1)
	v_mfma_f32_16x16x32_bf16 v[94:97], v[186:189], v[50:53], 0
	s_waitcnt lgkmcnt(0)
	v_mfma_f32_16x16x32_bf16 v[94:97], v[190:193], v[54:57], v[94:97]
	ds_read2_b64 v[98:101], v194 offset0:24 offset1:28
	ds_read2_b64 v[102:105], v195 offset0:24 offset1:28
	ds_read2_b64 v[106:109], v196 offset0:24 offset1:28
	ds_read2_b64 v[110:113], v197 offset0:24 offset1:28
	ds_read2_b64 v[114:117], v194 offset0:32 offset1:36
	ds_read2_b64 v[118:121], v195 offset0:32 offset1:36
	ds_read2_b64 v[122:125], v196 offset0:32 offset1:36
	ds_read2_b64 v[126:129], v197 offset0:32 offset1:36
	ds_read2_b64 v[130:133], v194 offset0:40 offset1:44
	ds_read2_b64 v[134:137], v195 offset0:40 offset1:44
	ds_read2_b64 v[138:141], v196 offset0:40 offset1:44
	ds_read2_b64 v[142:145], v197 offset0:40 offset1:44
	ds_read2_b64 v[146:149], v194 offset0:48 offset1:52
	ds_read2_b64 v[150:153], v195 offset0:48 offset1:52
	ds_read2_b64 v[154:157], v196 offset0:48 offset1:52
	s_nop 4
	v_cndmask_b32_e64 v62, v49, v62, s[48:49]
	v_cndmask_b32_e64 v63, v49, v63, s[50:51]
	v_cndmask_b32_e64 v64, v49, v64, s[52:53]
	v_cndmask_b32_e64 v65, v49, v65, s[26:27]
	v_cndmask_b32_e64 v94, v94, v49, s[40:41]
	v_cndmask_b32_e64 v95, v95, v49, s[42:43]
	v_cndmask_b32_e64 v96, v96, v49, s[44:45]
	v_cndmask_b32_e64 v97, v97, v49, s[46:47]
	v_max_f32_e32 v167, v62, v63
	v_max_f32_e32 v58, v64, v65
	v_max3_f32 v167, v167, v66, v67
	v_max3_f32 v58, v58, v68, v69
	v_max3_f32 v167, v167, v70, v71
	v_max3_f32 v58, v58, v72, v73
	v_max3_f32 v167, v167, v74, v75
	v_max3_f32 v58, v58, v76, v77
	v_max3_f32 v167, v167, v78, v79
	v_max3_f32 v58, v58, v80, v81
	v_max3_f32 v167, v167, v82, v83
	v_max3_f32 v58, v58, v84, v85
	v_max3_f32 v167, v167, v86, v87
	v_max3_f32 v58, v58, v88, v89
	v_max3_f32 v167, v167, v90, v91
	v_max3_f32 v58, v58, v92, v93
	v_max3_f32 v167, v167, v94, v95
	v_max3_f32 v58, v58, v96, v97
	v_max_f32_e32 v167, v167, v58
	v_mov_b32_e32 v166, v167
	s_nop 1
	v_permlane16_swap_b32_e32 v167, v166
	v_max_f32_e32 v167, v167, v166
	v_mov_b32_e32 v166, v167
	s_nop 1
	v_permlane32_swap_b32_e32 v167, v166
	v_max_f32_e32 v167, v167, v166
	v_max_f32_e32 v167, v167, v42
	v_mul_f32_e32 v58, 0xbfb8aa3b, v167
	v_fmamk_f32 v62, v62, 0x3fb8aa3b, v58
	v_fmamk_f32 v63, v63, 0x3fb8aa3b, v58
	v_fmamk_f32 v64, v64, 0x3fb8aa3b, v58
	v_fmamk_f32 v65, v65, 0x3fb8aa3b, v58
	v_fmamk_f32 v66, v66, 0x3fb8aa3b, v58
	v_fmamk_f32 v67, v67, 0x3fb8aa3b, v58
	v_fmamk_f32 v68, v68, 0x3fb8aa3b, v58
	v_fmamk_f32 v69, v69, 0x3fb8aa3b, v58
	v_fmamk_f32 v70, v70, 0x3fb8aa3b, v58
	v_fmamk_f32 v71, v71, 0x3fb8aa3b, v58
	v_fmamk_f32 v72, v72, 0x3fb8aa3b, v58
	v_fmamk_f32 v73, v73, 0x3fb8aa3b, v58
	v_fmamk_f32 v74, v74, 0x3fb8aa3b, v58
	v_fmamk_f32 v75, v75, 0x3fb8aa3b, v58
	v_fmamk_f32 v76, v76, 0x3fb8aa3b, v58
	v_fmamk_f32 v77, v77, 0x3fb8aa3b, v58
	v_fmamk_f32 v78, v78, 0x3fb8aa3b, v58
	v_fmamk_f32 v79, v79, 0x3fb8aa3b, v58
	v_fmamk_f32 v80, v80, 0x3fb8aa3b, v58
	v_fmamk_f32 v81, v81, 0x3fb8aa3b, v58
	v_fmamk_f32 v82, v82, 0x3fb8aa3b, v58
	v_fmamk_f32 v83, v83, 0x3fb8aa3b, v58
	v_fmamk_f32 v84, v84, 0x3fb8aa3b, v58
	v_fmamk_f32 v85, v85, 0x3fb8aa3b, v58
	v_fmamk_f32 v86, v86, 0x3fb8aa3b, v58
	v_fmamk_f32 v87, v87, 0x3fb8aa3b, v58
	v_fmamk_f32 v88, v88, 0x3fb8aa3b, v58
	v_fmamk_f32 v89, v89, 0x3fb8aa3b, v58
	v_fmamk_f32 v90, v90, 0x3fb8aa3b, v58
	v_fmamk_f32 v91, v91, 0x3fb8aa3b, v58
	v_fmamk_f32 v92, v92, 0x3fb8aa3b, v58
	v_fmamk_f32 v93, v93, 0x3fb8aa3b, v58
	v_fmamk_f32 v94, v94, 0x3fb8aa3b, v58
	v_fmamk_f32 v95, v95, 0x3fb8aa3b, v58
	v_fmamk_f32 v96, v96, 0x3fb8aa3b, v58
	v_fmamk_f32 v97, v97, 0x3fb8aa3b, v58
	v_exp_f32_e32 v62, v62
	v_exp_f32_e32 v63, v63
	v_exp_f32_e32 v64, v64
	v_exp_f32_e32 v65, v65
	v_exp_f32_e32 v66, v66
	v_exp_f32_e32 v67, v67
	v_exp_f32_e32 v68, v68
	v_exp_f32_e32 v69, v69
	v_exp_f32_e32 v70, v70
	v_exp_f32_e32 v71, v71
	v_exp_f32_e32 v72, v72
	v_exp_f32_e32 v73, v73
	v_exp_f32_e32 v74, v74
	v_exp_f32_e32 v75, v75
	v_exp_f32_e32 v76, v76
	v_exp_f32_e32 v77, v77
	v_exp_f32_e32 v78, v78
	v_exp_f32_e32 v79, v79
	v_exp_f32_e32 v80, v80
	v_exp_f32_e32 v81, v81
	v_exp_f32_e32 v82, v82
	v_exp_f32_e32 v83, v83
	v_exp_f32_e32 v84, v84
	v_exp_f32_e32 v85, v85
	v_exp_f32_e32 v86, v86
	v_exp_f32_e32 v87, v87
	v_exp_f32_e32 v88, v88
	v_exp_f32_e32 v89, v89
	v_exp_f32_e32 v90, v90
	v_exp_f32_e32 v91, v91
	v_exp_f32_e32 v92, v92
	v_exp_f32_e32 v93, v93
	v_exp_f32_e32 v94, v94
	v_exp_f32_e32 v95, v95
	v_exp_f32_e32 v96, v96
	v_exp_f32_e32 v97, v97
	v_fmamk_f32 v59, v42, 0x3fb8aa3b, v58
	v_exp_f32_e32 v59, v59
	v_add_f32_e32 v167, v62, v63
	v_add_f32_e32 v58, v64, v65
	v_add_f32_e32 v167, v167, v66
	v_add_f32_e32 v58, v58, v67
	v_add_f32_e32 v167, v167, v68
	v_add_f32_e32 v58, v58, v69
	v_add_f32_e32 v167, v167, v70
	v_add_f32_e32 v58, v58, v71
	v_add_f32_e32 v167, v167, v72
	v_add_f32_e32 v58, v58, v73
	v_add_f32_e32 v167, v167, v74
	v_add_f32_e32 v58, v58, v75
; __device__ __forceinline__ unsigned cvt_pk_bf16(float lo, float hi) { unsigned r; asm volatile("v_cvt_pk_bf16_f32 %0, %1, %2" : "=v"(r) : "v"(lo), "v"(hi)); return r; }
; #define LAS __attribute__((address_space(3)))
; #define MFMA16(a, b, c) __builtin_amdgcn_mfma_f32_16x16x32_bf16((a), (b), (c), 0, 0, 0)
; __device__ __forceinline__ void p2_block(LAS unsigned char* lds, const bf16_t* __restrict__ PROJ, bf16_t* __restrict__ ATT, bf16_t* __restrict__ SGU, const float* __restrict__ qn, const float* __restrict__ kn, ...
;     ...
;             for (int e = 0; e < 4; ++e) { const float p = __builtin_amdgcn_exp2f((sc_[t][e] - mx) * LOG2E); sc_[t][e] = p; sum += p; }
;         sum += __shfl_xor(sum, 16); sum += __shfl_xor(sum, 32);
;         const float inv = 1.0f / (sum + __builtin_amdgcn_exp2f((sink - mx) * LOG2E));
;         f32x4 o[4];
; #pragma unroll
;         for (int dt = 0; dt < 4; ++dt) o[dt] = (f32x4){0.f, 0.f, 0.f, 0.f};
; #pragma unroll
;         for (int j = 0; j < 5; ++j) {
;             u32x4 pw; pw.x = cvt_pk_bf16(sc_[2 * j][0], sc_[2 * j][1]); pw.y = cvt_pk_bf16(sc_[2 * j][2], sc_[2 * j][3]); pw.z = cvt_pk_bf16(sc_[2 * j + 1][0], sc_[2 * j + 1][1]); pw.w = cvt_pk_bf16(sc_[2 * j + 1][2], sc_[2 * j + 1][3]);
;             const bf16x8 pf = __builtin_bit_cast(bf16x8, pw);
; #pragma unroll
;             for (int dt = 0; dt < 4; ++dt) { const LAS unsigned char* vb = VT + (16 * dt + fr) * VT_STRIDE + (16 * (t0 + 2 * j) + 4 * fq) * 2;
;                 const u32x2 va = *(const LAS u32x2*)vb, vc = *(const LAS u32x2*)(vb + 32); u32x4 vw; vw.x = va.x; vw.y = va.y; vw.z = vc.x; vw.w = vc.y;
;                 o[dt] = MFMA16(__builtin_bit_cast(bf16x8, vw), pf, o[dt]); }
;         }
;         bf16_t* op = ATT + grow * 1024 + hq * 64 + 4 * fq;
; #pragma unroll
;         for (int dt = 0; dt < 4; ++dt) { u32x2 ow; ow.x = cvt_pk_bf16(o[dt][0] * inv, o[dt][1] * inv); ow.y = cvt_pk_bf16(o[dt][2] * inv, o[dt][3] * inv); *(u32x2*)(op + 16 * dt) = ow; }
	v_add_f32_e32 v167, v167, v76
	v_add_f32_e32 v58, v58, v77
	v_add_f32_e32 v167, v167, v78
	v_add_f32_e32 v58, v58, v79
	v_add_f32_e32 v167, v167, v80
	v_add_f32_e32 v58, v58, v81
	v_add_f32_e32 v167, v167, v82
	v_add_f32_e32 v58, v58, v83
	v_add_f32_e32 v167, v167, v84
	v_add_f32_e32 v58, v58, v85
	v_add_f32_e32 v167, v167, v86
	v_add_f32_e32 v58, v58, v87
	v_add_f32_e32 v167, v167, v88
	v_add_f32_e32 v58, v58, v89
	v_add_f32_e32 v167, v167, v90
	v_add_f32_e32 v58, v58, v91
	v_add_f32_e32 v167, v167, v92
	v_add_f32_e32 v58, v58, v93
	v_add_f32_e32 v167, v167, v94
	v_add_f32_e32 v58, v58, v95
	v_add_f32_e32 v167, v167, v96
	v_add_f32_e32 v58, v58, v97
	v_add_f32_e32 v167, v167, v58
	v_mov_b32_e32 v166, v167
	s_nop 1
	v_permlane16_swap_b32_e32 v167, v166
	v_add_f32_e32 v167, v167, v166
	v_mov_b32_e32 v166, v167
	s_nop 1
	v_permlane32_swap_b32_e32 v167, v166
	v_add_f32_e32 v167, v167, v166
	v_add_f32_e32 v167, v167, v59
	v_rcp_f32_e32 v167, v167
	v_mov_b32_e32 v58, 0
	v_mov_b32_e32 v59, 0
	v_mov_b32_e32 v60, 0
	v_mov_b32_e32 v61, 0
	v_cvt_pk_bf16_f32 v58, v58, v59
	v_cvt_pk_bf16_f32 v59, v60, v61
	v_cvt_pk_bf16_f32 v60, v62, v63
	v_cvt_pk_bf16_f32 v61, v64, v65
	v_cvt_pk_bf16_f32 v66, v66, v67
	v_cvt_pk_bf16_f32 v67, v68, v69
	v_cvt_pk_bf16_f32 v68, v70, v71
	v_cvt_pk_bf16_f32 v69, v72, v73
	v_cvt_pk_bf16_f32 v74, v74, v75
	v_cvt_pk_bf16_f32 v75, v76, v77
	v_cvt_pk_bf16_f32 v76, v78, v79
	v_cvt_pk_bf16_f32 v77, v80, v81
	v_cvt_pk_bf16_f32 v82, v82, v83
	v_cvt_pk_bf16_f32 v83, v84, v85
	v_cvt_pk_bf16_f32 v84, v86, v87
	v_cvt_pk_bf16_f32 v85, v88, v89
	v_cvt_pk_bf16_f32 v90, v90, v91
	v_cvt_pk_bf16_f32 v91, v92, v93
	v_cvt_pk_bf16_f32 v92, v94, v95
	v_cvt_pk_bf16_f32 v93, v96, v97
	s_nop 1
	s_waitcnt lgkmcnt(14)
	v_mfma_f32_16x16x32_bf16 v[62:65], v[98:101], v[58:61], 0
	ds_read2_b64 v[158:161], v197 offset0:48 offset1:52
	s_waitcnt lgkmcnt(14)
	v_mfma_f32_16x16x32_bf16 v[70:73], v[102:105], v[58:61], 0
	ds_read2_b64 v[162:165], v194 offset0:56 offset1:60
	s_waitcnt lgkmcnt(14)
	v_mfma_f32_16x16x32_bf16 v[78:81], v[106:109], v[58:61], 0
	ds_read2_b64 v[182:185], v195 offset0:56 offset1:60
	s_waitcnt lgkmcnt(14)
	v_mfma_f32_16x16x32_bf16 v[86:89], v[110:113], v[58:61], 0
	ds_read2_b64 v[186:189], v196 offset0:56 offset1:60
	s_waitcnt lgkmcnt(14)
	v_mfma_f32_16x16x32_bf16 v[62:65], v[114:117], v[66:69], v[62:65]
	ds_read2_b64 v[190:193], v197 offset0:56 offset1:60
	s_waitcnt lgkmcnt(14)
	v_mfma_f32_16x16x32_bf16 v[70:73], v[118:121], v[66:69], v[70:73]
	s_waitcnt lgkmcnt(13)
	v_mfma_f32_16x16x32_bf16 v[78:81], v[122:125], v[66:69], v[78:81]
	s_waitcnt lgkmcnt(12)
	v_mfma_f32_16x16x32_bf16 v[86:89], v[126:129], v[66:69], v[86:89]
	s_waitcnt lgkmcnt(11)
	v_mfma_f32_16x16x32_bf16 v[62:65], v[130:133], v[74:77], v[62:65]
	s_waitcnt lgkmcnt(10)
	v_mfma_f32_16x16x32_bf16 v[70:73], v[134:137], v[74:77], v[70:73]
	s_waitcnt lgkmcnt(9)
	v_mfma_f32_16x16x32_bf16 v[78:81], v[138:141], v[74:77], v[78:81]
	s_waitcnt lgkmcnt(8)
	v_mfma_f32_16x16x32_bf16 v[86:89], v[142:145], v[74:77], v[86:89]
	s_waitcnt lgkmcnt(7)
	v_mfma_f32_16x16x32_bf16 v[62:65], v[146:149], v[82:85], v[62:65]
	s_waitcnt lgkmcnt(6)
	v_mfma_f32_16x16x32_bf16 v[70:73], v[150:153], v[82:85], v[70:73]
	s_waitcnt lgkmcnt(5)
	v_mfma_f32_16x16x32_bf16 v[78:81], v[154:157], v[82:85], v[78:81]
	s_waitcnt lgkmcnt(4)
	v_mfma_f32_16x16x32_bf16 v[86:89], v[158:161], v[82:85], v[86:89]
	s_waitcnt lgkmcnt(3)
	v_mfma_f32_16x16x32_bf16 v[62:65], v[162:165], v[90:93], v[62:65]
	s_waitcnt lgkmcnt(2)
	v_mfma_f32_16x16x32_bf16 v[70:73], v[182:185], v[90:93], v[70:73]
	s_waitcnt lgkmcnt(1)
	v_mfma_f32_16x16x32_bf16 v[78:81], v[186:189], v[90:93], v[78:81]
	s_waitcnt lgkmcnt(0)
	v_mfma_f32_16x16x32_bf16 v[86:89], v[190:193], v[90:93], v[86:89]
	s_nop 7
	v_mul_f32_e32 v62, v62, v167
	v_mul_f32_e32 v63, v63, v167
	v_mul_f32_e32 v64, v64, v167
	v_mul_f32_e32 v65, v65, v167
	v_mul_f32_e32 v70, v70, v167
	v_mul_f32_e32 v71, v71, v167
	v_mul_f32_e32 v72, v72, v167
	v_mul_f32_e32 v73, v73, v167
	v_mul_f32_e32 v78, v78, v167
	v_mul_f32_e32 v79, v79, v167
	v_mul_f32_e32 v80, v80, v167
	v_mul_f32_e32 v81, v81, v167
	v_mul_f32_e32 v86, v86, v167
	v_mul_f32_e32 v87, v87, v167
	v_mul_f32_e32 v88, v88, v167
	v_mul_f32_e32 v89, v89, v167
	v_cvt_pk_bf16_f32 v62, v62, v63
	v_cvt_pk_bf16_f32 v63, v64, v65
	global_store_dwordx2 v48, v[62:63], s[24:25] offset:0
	v_cvt_pk_bf16_f32 v70, v70, v71
	v_cvt_pk_bf16_f32 v71, v72, v73
	global_store_dwordx2 v48, v[70:71], s[24:25] offset:32
	v_cvt_pk_bf16_f32 v78, v78, v79
	v_cvt_pk_bf16_f32 v79, v80, v81
	global_store_dwordx2 v48, v[78:79], s[24:25] offset:64
	v_cvt_pk_bf16_f32 v86, v86, v87
	v_cvt_pk_bf16_f32 v87, v88, v89
	global_store_dwordx2 v48, v[86:87], s[24:25] offset:96
	v_add_u32_e32 v48, 0x8000, v48
	s_branch .Latt_done
; __device__ __forceinline__ unsigned cvt_pk_bf16(float lo, float hi) { unsigned r; asm volatile("v_cvt_pk_bf16_f32 %0, %1, %2" : "=v"(r) : "v"(lo), "v"(hi)); return r; }
; #define LAS __attribute__((address_space(3)))
; #define MFMA16(a, b, c) __builtin_amdgcn_mfma_f32_16x16x32_bf16((a), (b), (c), 0, 0, 0)
; __device__ __forceinline__ void p2_block(LAS unsigned char* lds, const bf16_t* __restrict__ PROJ, bf16_t* __restrict__ ATT, bf16_t* __restrict__ SGU, const float* __restrict__ qn, const float* __restrict__ kn, ...
;     ...
;         const int i0 = rbase + 16 * c, irow = i0 + fr, pos = n * 128 + irow; const size_t grow = (size_t)b * pg8::SEQ + pos;
;         bf16x8 qf0, qf1;
;         {
;             float x1[8], x2[8]; unpack8(qa[c], x1); unpack8(qb[c], x2);
;             float ss = 0.f;
; #pragma unroll
;             for (int j = 0; j < 8; ++j) ss += x1[j] * x1[j] + x2[j] * x2[j];
;             ss += __shfl_xor(ss, 16); ss += __shfl_xor(ss, 32);
;             const float rinv = rsqrtf(ss * (1.0f / 64.0f) + pg8::EPS) * 0.125f;
;             const float* cp = COS + pos * 32 + 8 * fq; const float* sp = SIN + pos * 32 + 8 * fq;
;             float o1[8], o2[8];
; #pragma unroll
;             for (int j = 0; j < 8; ++j) { const float a1 = x1[j] * rinv * qn[8 * fq + j], a2 = x2[j] * rinv * qn[32 + 8 * fq + j], cc = cp[j], sn = sp[j]; o1[j] = a1 * cc - a2 * sn; o2[j] = a2 * cc + a1 * sn; }
;             u32x4 w0, w1;
;             w0.x = cvt_pk_bf16(o1[0], o1[1]); w0.y = cvt_pk_bf16(o1[2], o1[3]); w0.z = cvt_pk_bf16(o1[4], o1[5]); w0.w = cvt_pk_bf16(o1[6], o1[7]);
;             w1.x = cvt_pk_bf16(o2[0], o2[1]); w1.y = cvt_pk_bf16(o2[2], o2[3]); w1.z = cvt_pk_bf16(o2[4], o2[5]); w1.w = cvt_pk_bf16(o2[6], o2[7]);
;             qf0 = __builtin_bit_cast(bf16x8, w0); qf1 = __builtin_bit_cast(bf16x8, w1);
;         }
;         const int t0 = (i0 >> 4) < 6 ? (i0 >> 4) : 6;
;         f32x4 sc_[10];
;         const LAS unsigned char* kbase = KS + (16 * t0 + fr) * KS_STRIDE + 16 * fq;
; #pragma unroll
;         for (int t = 0; t < 10; ++t) { const bf16x8 k0 = *(const LAS bf16x8*)(kbase + t * 16 * KS_STRIDE), k1 = *(const LAS bf16x8*)(kbase + t * 16 * KS_STRIDE + 64);
;             f32x4 z = (f32x4){0.f, 0.f, 0.f, 0.f}; z = MFMA16(k0, qf0, z); sc_[t] = MFMA16(k1, qf1, z); }
.Latt_r0:
	ds_read_b128 v[98:101], v45 offset:0
	ds_read_b128 v[102:105], v45 offset:64
	ds_read_b128 v[106:109], v45 offset:2304
	ds_read_b128 v[110:113], v45 offset:2368
	ds_read_b128 v[114:117], v45 offset:4608
	ds_read_b128 v[118:121], v45 offset:4672
	ds_read_b128 v[122:125], v45 offset:6912
	ds_read_b128 v[126:129], v45 offset:6976
	ds_read_b128 v[130:133], v45 offset:9216
	ds_read_b128 v[134:137], v45 offset:9280
	ds_read_b128 v[138:141], v45 offset:11520
	ds_read_b128 v[142:145], v45 offset:11584
	ds_read_b128 v[146:149], v45 offset:13824
	ds_read_b128 v[150:153], v45 offset:13888
	s_waitcnt vmcnt(6)
	v_lshlrev_b32_e32 v58, 16, v2
	v_and_b32_e32 v59, 0xffff0000, v2
	v_lshlrev_b32_e32 v66, 16, v6
	v_and_b32_e32 v67, 0xffff0000, v6
	v_lshlrev_b32_e32 v60, 16, v3
	v_and_b32_e32 v61, 0xffff0000, v3
	v_lshlrev_b32_e32 v68, 16, v7
	v_and_b32_e32 v69, 0xffff0000, v7
	v_lshlrev_b32_e32 v62, 16, v4
	v_and_b32_e32 v63, 0xffff0000, v4
	v_lshlrev_b32_e32 v70, 16, v8
	v_and_b32_e32 v71, 0xffff0000, v8
	v_lshlrev_b32_e32 v64, 16, v5
	v_and_b32_e32 v65, 0xffff0000, v5
	v_lshlrev_b32_e32 v72, 16, v9
	v_and_b32_e32 v73, 0xffff0000, v9
	v_pk_mul_f32 v[74:75], v[58:59], v[58:59]
	v_pk_fma_f32 v[74:75], v[60:61], v[60:61], v[74:75]
	v_pk_fma_f32 v[74:75], v[62:63], v[62:63], v[74:75]
	v_pk_fma_f32 v[74:75], v[64:65], v[64:65], v[74:75]
	v_pk_fma_f32 v[74:75], v[66:67], v[66:67], v[74:75]
	v_pk_fma_f32 v[74:75], v[68:69], v[68:69], v[74:75]
	v_pk_fma_f32 v[74:75], v[70:71], v[70:71], v[74:75]
	v_pk_fma_f32 v[74:75], v[72:73], v[72:73], v[74:75]
	v_add_f32_e32 v74, v74, v75
	v_mov_b32_e32 v166, v74
	s_nop 1
	v_permlane16_swap_b32_e32 v74, v166
	v_add_f32_e32 v74, v74, v166
	v_mov_b32_e32 v166, v74
	s_nop 1
	v_permlane32_swap_b32_e32 v74, v166
	v_add_f32_e32 v74, v74, v166
	v_fmamk_f32 v74, v74, 0x3c800000, v209
	v_rsq_f32_e32 v76, v74
	s_nop 0
	v_mul_f32_e32 v76, 0x3e000000, v76
	v_pk_mul_f32 v[58:59], v[58:59], v[76:77] op_sel_hi:[1,0]
	v_pk_mul_f32 v[66:67], v[66:67], v[76:77] op_sel_hi:[1,0]
	v_pk_mul_f32 v[60:61], v[60:61], v[76:77] op_sel_hi:[1,0]
	v_pk_mul_f32 v[68:69], v[68:69], v[76:77] op_sel_hi:[1,0]
	v_pk_mul_f32 v[62:63], v[62:63], v[76:77] op_sel_hi:[1,0]
	v_pk_mul_f32 v[70:71], v[70:71], v[76:77] op_sel_hi:[1,0]
	v_pk_mul_f32 v[64:65], v[64:65], v[76:77] op_sel_hi:[1,0]
	v_pk_mul_f32 v[72:73], v[72:73], v[76:77] op_sel_hi:[1,0]
	v_pk_mul_f32 v[58:59], v[58:59], v[26:27]
	v_pk_mul_f32 v[66:67], v[66:67], v[34:35]
	v_pk_mul_f32 v[60:61], v[60:61], v[28:29]
	v_pk_mul_f32 v[68:69], v[68:69], v[36:37]
	v_pk_mul_f32 v[62:63], v[62:63], v[30:31]
	v_pk_mul_f32 v[70:71], v[70:71], v[38:39]
	v_pk_mul_f32 v[64:65], v[64:65], v[32:33]
	v_pk_mul_f32 v[72:73], v[72:73], v[40:41]
	v_pk_mul_f32 v[78:79], v[66:67], v[18:19]
	v_pk_mul_f32 v[86:87], v[58:59], v[18:19]
	v_pk_mul_f32 v[80:81], v[68:69], v[20:21]
	v_pk_mul_f32 v[88:89], v[60:61], v[20:21]
	v_pk_mul_f32 v[82:83], v[70:71], v[22:23]
	v_pk_mul_f32 v[90:91], v[62:63], v[22:23]
	v_pk_mul_f32 v[84:85], v[72:73], v[24:25]
	v_pk_mul_f32 v[92:93], v[64:65], v[24:25]
	v_pk_fma_f32 v[78:79], v[58:59], v[10:11], v[78:79] neg_lo:[0,0,1] neg_hi:[0,0,1]
	v_pk_fma_f32 v[86:87], v[66:67], v[10:11], v[86:87]
	v_pk_fma_f32 v[80:81], v[60:61], v[12:13], v[80:81] neg_lo:[0,0,1] neg_hi:[0,0,1]
	v_pk_fma_f32 v[88:89], v[68:69], v[12:13], v[88:89]
	v_pk_fma_f32 v[82:83], v[62:63], v[14:15], v[82:83] neg_lo:[0,0,1] neg_hi:[0,0,1]
	v_pk_fma_f32 v[90:91], v[70:71], v[14:15], v[90:91]
	v_pk_fma_f32 v[84:85], v[64:65], v[16:17], v[84:85] neg_lo:[0,0,1] neg_hi:[0,0,1]
	v_pk_fma_f32 v[92:93], v[72:73], v[16:17], v[92:93]
	v_cvt_pk_bf16_f32 v50, v78, v79
	v_cvt_pk_bf16_f32 v54, v86, v87
	v_cvt_pk_bf16_f32 v51, v80, v81
	v_cvt_pk_bf16_f32 v55, v88, v89
	v_cvt_pk_bf16_f32 v52, v82, v83
	v_cvt_pk_bf16_f32 v56, v90, v91
	v_cvt_pk_bf16_f32 v53, v84, v85
	v_cvt_pk_bf16_f32 v57, v92, v93
	global_load_dwordx4 v[2:5], v46, s[10:11]
	global_load_dwordx4 v[6:9], v46, s[10:11] offset:64
	global_load_dwordx4 v[10:13], v47, s[6:7]
	global_load_dwordx4 v[14:17], v47, s[6:7] offset:16
	global_load_dwordx4 v[18:21], v47, s[16:17]
	global_load_dwordx4 v[22:25], v47, s[16:17] offset:16
	v_add_u32_e32 v46, 0x3c000, v46
	v_add_u32_e32 v47, 0x800, v47
	s_nop 1
	s_waitcnt lgkmcnt(13)
	v_mfma_f32_16x16x32_bf16 v[58:61], v[98:101], v[50:53], 0
	s_waitcnt lgkmcnt(12)
	v_mfma_f32_16x16x32_bf16 v[58:61], v[102:105], v[54:57], v[58:61]
	ds_read_b128 v[154:157], v45 offset:16128
	ds_read_b128 v[158:161], v45 offset:16192
	s_waitcnt lgkmcnt(13)
	v_mfma_f32_16x16x32_bf16 v[62:65], v[106:109], v[50:53], 0
	s_waitcnt lgkmcnt(12)
	v_mfma_f32_16x16x32_bf16 v[62:65], v[110:113], v[54:57], v[62:65]
	ds_read_b128 v[162:165], v45 offset:18432
	ds_read_b128 v[182:185], v45 offset:18496
	s_waitcnt lgkmcnt(13)
	v_mfma_f32_16x16x32_bf16 v[66:69], v[114:117], v[50:53], 0
	s_waitcnt lgkmcnt(12)
	v_mfma_f32_16x16x32_bf16 v[66:69], v[118:121], v[54:57], v[66:69]
	s_waitcnt lgkmcnt(11)
	v_mfma_f32_16x16x32_bf16 v[70:73], v[122:125], v[50:53], 0
	s_waitcnt lgkmcnt(10)
	v_mfma_f32_16x16x32_bf16 v[70:73], v[126:129], v[54:57], v[70:73]
	s_waitcnt lgkmcnt(9)
	v_mfma_f32_16x16x32_bf16 v[74:77], v[130:133], v[50:53], 0
	s_waitcnt lgkmcnt(8)
	v_mfma_f32_16x16x32_bf16 v[74:77], v[134:137], v[54:57], v[74:77]
	s_waitcnt lgkmcnt(7)
	v_mfma_f32_16x16x32_bf16 v[78:81], v[138:141], v[50:53], 0
	s_waitcnt lgkmcnt(6)
	v_mfma_f32_16x16x32_bf16 v[78:81], v[142:145], v[54:57], v[78:81]
	s_waitcnt lgkmcnt(5)
	v_mfma_f32_16x16x32_bf16 v[82:85], v[146:149], v[50:53], 0
	s_waitcnt lgkmcnt(4)
	v_mfma_f32_16x16x32_bf16 v[82:85], v[150:153], v[54:57], v[82:85]
	s_waitcnt lgkmcnt(3)
; #define LAS __attribute__((address_space(3)))
; #define MFMA16(a, b, c) __builtin_amdgcn_mfma_f32_16x16x32_bf16((a), (b), (c), 0, 0, 0)
; __device__ __forceinline__ void p2_block(LAS unsigned char* lds, const bf16_t* __restrict__ PROJ, bf16_t* __restrict__ ATT, bf16_t* __restrict__ SGU, const float* __restrict__ qn, const float* __restrict__ kn, ...
;     ...
;         for (int t = 0; t < 10; ++t) { const bf16x8 k0 = *(const LAS bf16x8*)(kbase + t * 16 * KS_STRIDE), k1 = *(const LAS bf16x8*)(kbase + t * 16 * KS_STRIDE + 64);
;             f32x4 z = (f32x4){0.f, 0.f, 0.f, 0.f}; z = MFMA16(k0, qf0, z); sc_[t] = MFMA16(k1, qf1, z); }
;         float mx = -1e30f;
; #pragma unroll
;         for (int t = 0; t < 10; ++t)
; #pragma unroll
;             for (int e = 0; e < 4; ++e) { const int kx = 16 * (t0 + t) + 4 * fq + e, d = kx - irow; const bool ok = (d >= 1) && (d <= 128) && (n > 0 || kx >= 128);
;                 const float v = ok ? sc_[t][e] : -1e30f; sc_[t][e] = v; mx = fmaxf(mx, v); }
;         mx = fmaxf(mx, __shfl_xor(mx, 16)); mx = fmaxf(mx, __shfl_xor(mx, 32)); mx = fmaxf(mx, sink);
;         float sum = 0.f;
; #pragma unroll
;         for (int t = 0; t < 10; ++t)
; #pragma unroll
;             for (int e = 0; e < 4; ++e) { const float p = __builtin_amdgcn_exp2f((sc_[t][e] - mx) * LOG2E); sc_[t][e] = p; sum += p; }
	v_mfma_f32_16x16x32_bf16 v[86:89], v[154:157], v[50:53], 0
	s_waitcnt lgkmcnt(2)
	v_mfma_f32_16x16x32_bf16 v[86:89], v[158:161], v[54:57], v[86:89]
	s_waitcnt lgkmcnt(1)
	v_mfma_f32_16x16x32_bf16 v[90:93], v[162:165], v[50:53], 0
	s_waitcnt lgkmcnt(0)
	v_mfma_f32_16x16x32_bf16 v[90:93], v[182:185], v[54:57], v[90:93]
	ds_read2_b64 v[98:101], v194 offset0:0 offset1:4
	ds_read2_b64 v[102:105], v195 offset0:0 offset1:4
	ds_read2_b64 v[106:109], v196 offset0:0 offset1:4
	ds_read2_b64 v[110:113], v197 offset0:0 offset1:4
	ds_read2_b64 v[114:117], v194 offset0:8 offset1:12
	ds_read2_b64 v[118:121], v195 offset0:8 offset1:12
	ds_read2_b64 v[122:125], v196 offset0:8 offset1:12
	ds_read2_b64 v[126:129], v197 offset0:8 offset1:12
	ds_read2_b64 v[130:133], v194 offset0:16 offset1:20
	ds_read2_b64 v[134:137], v195 offset0:16 offset1:20
	ds_read2_b64 v[138:141], v196 offset0:16 offset1:20
	ds_read2_b64 v[142:145], v197 offset0:16 offset1:20
	ds_read2_b64 v[146:149], v194 offset0:24 offset1:28
	ds_read2_b64 v[150:153], v195 offset0:24 offset1:28
	ds_read2_b64 v[154:157], v196 offset0:24 offset1:28
	s_nop 4
	v_cndmask_b32_e64 v58, v49, v58, s[48:49]
	v_cndmask_b32_e64 v59, v49, v59, s[50:51]
	v_cndmask_b32_e64 v60, v49, v60, s[52:53]
	v_cndmask_b32_e64 v61, v49, v61, s[26:27]
	v_cndmask_b32_e64 v62, v49, v62, s[28:29]
	v_cndmask_b32_e64 v63, v49, v63, s[28:29]
	v_cndmask_b32_e64 v64, v49, v64, s[28:29]
	v_cndmask_b32_e64 v65, v49, v65, s[28:29]
	v_cndmask_b32_e64 v66, v49, v66, s[28:29]
	v_cndmask_b32_e64 v67, v49, v67, s[28:29]
	v_cndmask_b32_e64 v68, v49, v68, s[28:29]
	v_cndmask_b32_e64 v69, v49, v69, s[28:29]
	v_cndmask_b32_e64 v70, v49, v70, s[28:29]
	v_cndmask_b32_e64 v71, v49, v71, s[28:29]
	v_cndmask_b32_e64 v72, v49, v72, s[28:29]
	v_cndmask_b32_e64 v73, v49, v73, s[28:29]
	v_cndmask_b32_e64 v74, v49, v74, s[28:29]
	v_cndmask_b32_e64 v75, v49, v75, s[28:29]
	v_cndmask_b32_e64 v76, v49, v76, s[28:29]
	v_cndmask_b32_e64 v77, v49, v77, s[28:29]
	v_cndmask_b32_e64 v78, v49, v78, s[28:29]
	v_cndmask_b32_e64 v79, v49, v79, s[28:29]
	v_cndmask_b32_e64 v80, v49, v80, s[28:29]
	v_cndmask_b32_e64 v81, v49, v81, s[28:29]
	v_cndmask_b32_e64 v82, v49, v82, s[28:29]
	v_cndmask_b32_e64 v83, v49, v83, s[28:29]
	v_cndmask_b32_e64 v84, v49, v84, s[28:29]
	v_cndmask_b32_e64 v85, v49, v85, s[28:29]
	v_cndmask_b32_e64 v86, v49, v86, s[28:29]
	v_cndmask_b32_e64 v87, v49, v87, s[28:29]
	v_cndmask_b32_e64 v88, v49, v88, s[28:29]
	v_cndmask_b32_e64 v89, v49, v89, s[28:29]
	v_cndmask_b32_e64 v90, v90, v49, s[40:41]
	v_cndmask_b32_e64 v91, v91, v49, s[42:43]
	v_cndmask_b32_e64 v92, v92, v49, s[44:45]
	v_cndmask_b32_e64 v93, v93, v49, s[46:47]
	v_max_f32_e32 v167, v58, v59
	v_max_f32_e32 v94, v60, v61
	v_max3_f32 v167, v167, v62, v63
	v_max3_f32 v94, v94, v64, v65
	v_max3_f32 v167, v167, v66, v67
	v_max3_f32 v94, v94, v68, v69
	v_max3_f32 v167, v167, v70, v71
	v_max3_f32 v94, v94, v72, v73
	v_max3_f32 v167, v167, v74, v75
	v_max3_f32 v94, v94, v76, v77
	v_max3_f32 v167, v167, v78, v79
	v_max3_f32 v94, v94, v80, v81
	v_max3_f32 v167, v167, v82, v83
	v_max3_f32 v94, v94, v84, v85
	v_max3_f32 v167, v167, v86, v87
	v_max3_f32 v94, v94, v88, v89
	v_max3_f32 v167, v167, v90, v91
	v_max3_f32 v94, v94, v92, v93
	v_max_f32_e32 v167, v167, v94
	v_mov_b32_e32 v166, v167
	s_nop 1
	v_permlane16_swap_b32_e32 v167, v166
	v_max_f32_e32 v167, v167, v166
	v_mov_b32_e32 v166, v167
	s_nop 1
	v_permlane32_swap_b32_e32 v167, v166
	v_max_f32_e32 v167, v167, v166
	v_max_f32_e32 v167, v167, v42
	v_mul_f32_e32 v94, 0xbfb8aa3b, v167
	v_fmamk_f32 v58, v58, 0x3fb8aa3b, v94
	v_fmamk_f32 v59, v59, 0x3fb8aa3b, v94
	v_fmamk_f32 v60, v60, 0x3fb8aa3b, v94
	v_fmamk_f32 v61, v61, 0x3fb8aa3b, v94
	v_fmamk_f32 v62, v62, 0x3fb8aa3b, v94
	v_fmamk_f32 v63, v63, 0x3fb8aa3b, v94
	v_fmamk_f32 v64, v64, 0x3fb8aa3b, v94
	v_fmamk_f32 v65, v65, 0x3fb8aa3b, v94
	v_fmamk_f32 v66, v66, 0x3fb8aa3b, v94
	v_fmamk_f32 v67, v67, 0x3fb8aa3b, v94
	v_fmamk_f32 v68, v68, 0x3fb8aa3b, v94
	v_fmamk_f32 v69, v69, 0x3fb8aa3b, v94
	v_fmamk_f32 v70, v70, 0x3fb8aa3b, v94
	v_fmamk_f32 v71, v71, 0x3fb8aa3b, v94
	v_fmamk_f32 v72, v72, 0x3fb8aa3b, v94
	v_fmamk_f32 v73, v73, 0x3fb8aa3b, v94
	v_fmamk_f32 v74, v74, 0x3fb8aa3b, v94
	v_fmamk_f32 v75, v75, 0x3fb8aa3b, v94
	v_fmamk_f32 v76, v76, 0x3fb8aa3b, v94
	v_fmamk_f32 v77, v77, 0x3fb8aa3b, v94
	v_fmamk_f32 v78, v78, 0x3fb8aa3b, v94
	v_fmamk_f32 v79, v79, 0x3fb8aa3b, v94
	v_fmamk_f32 v80, v80, 0x3fb8aa3b, v94
	v_fmamk_f32 v81, v81, 0x3fb8aa3b, v94
	v_fmamk_f32 v82, v82, 0x3fb8aa3b, v94
	v_fmamk_f32 v83, v83, 0x3fb8aa3b, v94
	v_fmamk_f32 v84, v84, 0x3fb8aa3b, v94
	v_fmamk_f32 v85, v85, 0x3fb8aa3b, v94
	v_fmamk_f32 v86, v86, 0x3fb8aa3b, v94
	v_fmamk_f32 v87, v87, 0x3fb8aa3b, v94
	v_fmamk_f32 v88, v88, 0x3fb8aa3b, v94
	v_fmamk_f32 v89, v89, 0x3fb8aa3b, v94
	v_fmamk_f32 v90, v90, 0x3fb8aa3b, v94
	v_fmamk_f32 v91, v91, 0x3fb8aa3b, v94
	v_fmamk_f32 v92, v92, 0x3fb8aa3b, v94
	v_fmamk_f32 v93, v93, 0x3fb8aa3b, v94
	v_exp_f32_e32 v58, v58
	v_exp_f32_e32 v59, v59
	v_exp_f32_e32 v60, v60
	v_exp_f32_e32 v61, v61
	v_exp_f32_e32 v62, v62
	v_exp_f32_e32 v63, v63
	v_exp_f32_e32 v64, v64
	v_exp_f32_e32 v65, v65
	v_exp_f32_e32 v66, v66
	v_exp_f32_e32 v67, v67
	v_exp_f32_e32 v68, v68
	v_exp_f32_e32 v69, v69
	v_exp_f32_e32 v70, v70
	v_exp_f32_e32 v71, v71
	v_exp_f32_e32 v72, v72
	v_exp_f32_e32 v73, v73
	v_exp_f32_e32 v74, v74
	v_exp_f32_e32 v75, v75
	v_exp_f32_e32 v76, v76
	v_exp_f32_e32 v77, v77
	v_exp_f32_e32 v78, v78
	v_exp_f32_e32 v79, v79
	v_exp_f32_e32 v80, v80
	v_exp_f32_e32 v81, v81
	v_exp_f32_e32 v82, v82
	v_exp_f32_e32 v83, v83
	v_exp_f32_e32 v84, v84
	v_exp_f32_e32 v85, v85
	v_exp_f32_e32 v86, v86
; __device__ __forceinline__ unsigned cvt_pk_bf16(float lo, float hi) { unsigned r; asm volatile("v_cvt_pk_bf16_f32 %0, %1, %2" : "=v"(r) : "v"(lo), "v"(hi)); return r; }
; #define LAS __attribute__((address_space(3)))
; #define MFMA16(a, b, c) __builtin_amdgcn_mfma_f32_16x16x32_bf16((a), (b), (c), 0, 0, 0)
; __device__ __forceinline__ void p2_block(LAS unsigned char* lds, const bf16_t* __restrict__ PROJ, bf16_t* __restrict__ ATT, bf16_t* __restrict__ SGU, const float* __restrict__ qn, const float* __restrict__ kn, ...
;     ...
;             for (int e = 0; e < 4; ++e) { const float p = __builtin_amdgcn_exp2f((sc_[t][e] - mx) * LOG2E); sc_[t][e] = p; sum += p; }
;         sum += __shfl_xor(sum, 16); sum += __shfl_xor(sum, 32);
;         const float inv = 1.0f / (sum + __builtin_amdgcn_exp2f((sink - mx) * LOG2E));
;         f32x4 o[4];
; #pragma unroll
;         for (int dt = 0; dt < 4; ++dt) o[dt] = (f32x4){0.f, 0.f, 0.f, 0.f};
; #pragma unroll
;         for (int j = 0; j < 5; ++j) {
;             u32x4 pw; pw.x = cvt_pk_bf16(sc_[2 * j][0], sc_[2 * j][1]); pw.y = cvt_pk_bf16(sc_[2 * j][2], sc_[2 * j][3]); pw.z = cvt_pk_bf16(sc_[2 * j + 1][0], sc_[2 * j + 1][1]); pw.w = cvt_pk_bf16(sc_[2 * j + 1][2], sc_[2 * j + 1][3]);
;             const bf16x8 pf = __builtin_bit_cast(bf16x8, pw);
; #pragma unroll
;             for (int dt = 0; dt < 4; ++dt) { const LAS unsigned char* vb = VT + (16 * dt + fr) * VT_STRIDE + (16 * (t0 + 2 * j) + 4 * fq) * 2;
;                 const u32x2 va = *(const LAS u32x2*)vb, vc = *(const LAS u32x2*)(vb + 32); u32x4 vw; vw.x = va.x; vw.y = va.y; vw.z = vc.x; vw.w = vc.y;
;                 o[dt] = MFMA16(__builtin_bit_cast(bf16x8, vw), pf, o[dt]); }
;         }
;         bf16_t* op = ATT + grow * 1024 + hq * 64 + 4 * fq;
; #pragma unroll
;         for (int dt = 0; dt < 4; ++dt) { u32x2 ow; ow.x = cvt_pk_bf16(o[dt][0] * inv, o[dt][1] * inv); ow.y = cvt_pk_bf16(o[dt][2] * inv, o[dt][3] * inv); *(u32x2*)(op + 16 * dt) = ow; }
	v_exp_f32_e32 v87, v87
	v_exp_f32_e32 v88, v88
	v_exp_f32_e32 v89, v89
	v_exp_f32_e32 v90, v90
	v_exp_f32_e32 v91, v91
	v_exp_f32_e32 v92, v92
	v_exp_f32_e32 v93, v93
	v_fmamk_f32 v95, v42, 0x3fb8aa3b, v94
	v_exp_f32_e32 v95, v95
	v_add_f32_e32 v167, v58, v59
	v_add_f32_e32 v94, v60, v61
	v_add_f32_e32 v167, v167, v62
	v_add_f32_e32 v94, v94, v63
	v_add_f32_e32 v167, v167, v64
	v_add_f32_e32 v94, v94, v65
	v_add_f32_e32 v167, v167, v66
	v_add_f32_e32 v94, v94, v67
	v_add_f32_e32 v167, v167, v68
	v_add_f32_e32 v94, v94, v69
	v_add_f32_e32 v167, v167, v70
	v_add_f32_e32 v94, v94, v71
	v_add_f32_e32 v167, v167, v72
	v_add_f32_e32 v94, v94, v73
	v_add_f32_e32 v167, v167, v74
	v_add_f32_e32 v94, v94, v75
	v_add_f32_e32 v167, v167, v76
	v_add_f32_e32 v94, v94, v77
	v_add_f32_e32 v167, v167, v78
	v_add_f32_e32 v94, v94, v79
	v_add_f32_e32 v167, v167, v80
	v_add_f32_e32 v94, v94, v81
	v_add_f32_e32 v167, v167, v82
	v_add_f32_e32 v94, v94, v83
	v_add_f32_e32 v167, v167, v84
	v_add_f32_e32 v94, v94, v85
	v_add_f32_e32 v167, v167, v86
	v_add_f32_e32 v94, v94, v87
	v_add_f32_e32 v167, v167, v88
	v_add_f32_e32 v94, v94, v89
	v_add_f32_e32 v167, v167, v90
	v_add_f32_e32 v94, v94, v91
	v_add_f32_e32 v167, v167, v92
	v_add_f32_e32 v94, v94, v93
	v_add_f32_e32 v167, v167, v94
	v_mov_b32_e32 v166, v167
	s_nop 1
	v_permlane16_swap_b32_e32 v167, v166
	v_add_f32_e32 v167, v167, v166
	v_mov_b32_e32 v166, v167
	s_nop 1
	v_permlane32_swap_b32_e32 v167, v166
	v_add_f32_e32 v167, v167, v166
	v_add_f32_e32 v167, v167, v95
	v_rcp_f32_e32 v167, v167
	v_mov_b32_e32 v94, 0
	v_mov_b32_e32 v95, 0
	v_mov_b32_e32 v96, 0
	v_mov_b32_e32 v97, 0
	v_cvt_pk_bf16_f32 v58, v58, v59
	v_cvt_pk_bf16_f32 v59, v60, v61
	v_cvt_pk_bf16_f32 v60, v62, v63
	v_cvt_pk_bf16_f32 v61, v64, v65
	v_cvt_pk_bf16_f32 v66, v66, v67
	v_cvt_pk_bf16_f32 v67, v68, v69
	v_cvt_pk_bf16_f32 v68, v70, v71
	v_cvt_pk_bf16_f32 v69, v72, v73
	v_cvt_pk_bf16_f32 v74, v74, v75
	v_cvt_pk_bf16_f32 v75, v76, v77
	v_cvt_pk_bf16_f32 v76, v78, v79
	v_cvt_pk_bf16_f32 v77, v80, v81
	v_cvt_pk_bf16_f32 v82, v82, v83
	v_cvt_pk_bf16_f32 v83, v84, v85
	v_cvt_pk_bf16_f32 v84, v86, v87
	v_cvt_pk_bf16_f32 v85, v88, v89
	v_cvt_pk_bf16_f32 v90, v90, v91
	v_cvt_pk_bf16_f32 v91, v92, v93
	v_cvt_pk_bf16_f32 v92, v94, v95
	v_cvt_pk_bf16_f32 v93, v96, v97
	s_nop 1
	s_waitcnt lgkmcnt(14)
	v_mfma_f32_16x16x32_bf16 v[62:65], v[98:101], v[58:61], 0
	ds_read2_b64 v[158:161], v197 offset0:24 offset1:28
	s_waitcnt lgkmcnt(14)
	v_mfma_f32_16x16x32_bf16 v[70:73], v[102:105], v[58:61], 0
	ds_read2_b64 v[162:165], v194 offset0:32 offset1:36
	s_waitcnt lgkmcnt(14)
	v_mfma_f32_16x16x32_bf16 v[78:81], v[106:109], v[58:61], 0
	ds_read2_b64 v[182:185], v195 offset0:32 offset1:36
	s_waitcnt lgkmcnt(14)
	v_mfma_f32_16x16x32_bf16 v[86:89], v[110:113], v[58:61], 0
	ds_read2_b64 v[186:189], v196 offset0:32 offset1:36
	s_waitcnt lgkmcnt(14)
	v_mfma_f32_16x16x32_bf16 v[62:65], v[114:117], v[66:69], v[62:65]
	ds_read2_b64 v[190:193], v197 offset0:32 offset1:36
	s_waitcnt lgkmcnt(14)
	v_mfma_f32_16x16x32_bf16 v[70:73], v[118:121], v[66:69], v[70:73]
	s_waitcnt lgkmcnt(13)
	v_mfma_f32_16x16x32_bf16 v[78:81], v[122:125], v[66:69], v[78:81]
	s_waitcnt lgkmcnt(12)
	v_mfma_f32_16x16x32_bf16 v[86:89], v[126:129], v[66:69], v[86:89]
	s_waitcnt lgkmcnt(11)
	v_mfma_f32_16x16x32_bf16 v[62:65], v[130:133], v[74:77], v[62:65]
	s_waitcnt lgkmcnt(10)
	v_mfma_f32_16x16x32_bf16 v[70:73], v[134:137], v[74:77], v[70:73]
	s_waitcnt lgkmcnt(9)
	v_mfma_f32_16x16x32_bf16 v[78:81], v[138:141], v[74:77], v[78:81]
	s_waitcnt lgkmcnt(8)
	v_mfma_f32_16x16x32_bf16 v[86:89], v[142:145], v[74:77], v[86:89]
	s_waitcnt lgkmcnt(7)
	v_mfma_f32_16x16x32_bf16 v[62:65], v[146:149], v[82:85], v[62:65]
	s_waitcnt lgkmcnt(6)
	v_mfma_f32_16x16x32_bf16 v[70:73], v[150:153], v[82:85], v[70:73]
	s_waitcnt lgkmcnt(5)
	v_mfma_f32_16x16x32_bf16 v[78:81], v[154:157], v[82:85], v[78:81]
	s_waitcnt lgkmcnt(4)
	v_mfma_f32_16x16x32_bf16 v[86:89], v[158:161], v[82:85], v[86:89]
	s_waitcnt lgkmcnt(3)
	v_mfma_f32_16x16x32_bf16 v[62:65], v[162:165], v[90:93], v[62:65]
	s_waitcnt lgkmcnt(2)
	v_mfma_f32_16x16x32_bf16 v[70:73], v[182:185], v[90:93], v[70:73]
	s_waitcnt lgkmcnt(1)
	v_mfma_f32_16x16x32_bf16 v[78:81], v[186:189], v[90:93], v[78:81]
	s_waitcnt lgkmcnt(0)
	v_mfma_f32_16x16x32_bf16 v[86:89], v[190:193], v[90:93], v[86:89]
	ds_read_b128 v[98:101], v45 offset:2304
	ds_read_b128 v[102:105], v45 offset:2368
	ds_read_b128 v[106:109], v45 offset:4608
	ds_read_b128 v[110:113], v45 offset:4672
	ds_read_b128 v[114:117], v45 offset:6912
	ds_read_b128 v[118:121], v45 offset:6976
	ds_read_b128 v[122:125], v45 offset:9216
	ds_read_b128 v[126:129], v45 offset:9280
	ds_read_b128 v[130:133], v45 offset:11520
	ds_read_b128 v[134:137], v45 offset:11584
	ds_read_b128 v[138:141], v45 offset:13824
	ds_read_b128 v[142:145], v45 offset:13888
	ds_read_b128 v[146:149], v45 offset:16128
	ds_read_b128 v[150:153], v45 offset:16192
	s_nop 7
	v_mul_f32_e32 v62, v62, v167
	v_mul_f32_e32 v63, v63, v167
	v_mul_f32_e32 v64, v64, v167
	v_mul_f32_e32 v65, v65, v167
	v_mul_f32_e32 v70, v70, v167
	v_mul_f32_e32 v71, v71, v167
	v_mul_f32_e32 v72, v72, v167
	v_mul_f32_e32 v73, v73, v167
	v_mul_f32_e32 v78, v78, v167
	v_mul_f32_e32 v79, v79, v167
	v_mul_f32_e32 v80, v80, v167
	v_mul_f32_e32 v81, v81, v167
	v_mul_f32_e32 v86, v86, v167
	v_mul_f32_e32 v87, v87, v167
	v_mul_f32_e32 v88, v88, v167
	v_mul_f32_e32 v89, v89, v167
	v_cvt_pk_bf16_f32 v62, v62, v63
	v_cvt_pk_bf16_f32 v63, v64, v65
	global_store_dwordx2 v48, v[62:63], s[24:25] offset:0
	v_cvt_pk_bf16_f32 v70, v70, v71
	v_cvt_pk_bf16_f32 v71, v72, v73
	global_store_dwordx2 v48, v[70:71], s[24:25] offset:32
	v_cvt_pk_bf16_f32 v78, v78, v79
	v_cvt_pk_bf16_f32 v79, v80, v81
	global_store_dwordx2 v48, v[78:79], s[24:25] offset:64
	v_cvt_pk_bf16_f32 v86, v86, v87
	v_cvt_pk_bf16_f32 v87, v88, v89
	global_store_dwordx2 v48, v[86:87], s[24:25] offset:96
	v_add_u32_e32 v48, 0x8000, v48
	s_waitcnt vmcnt(10)
; __device__ __forceinline__ unsigned cvt_pk_bf16(float lo, float hi) { unsigned r; asm volatile("v_cvt_pk_bf16_f32 %0, %1, %2" : "=v"(r) : "v"(lo), "v"(hi)); return r; }
; #define LAS __attribute__((address_space(3)))
; #define MFMA16(a, b, c) __builtin_amdgcn_mfma_f32_16x16x32_bf16((a), (b), (c), 0, 0, 0)
; __device__ __forceinline__ void p2_block(LAS unsigned char* lds, const bf16_t* __restrict__ PROJ, bf16_t* __restrict__ ATT, bf16_t* __restrict__ SGU, const float* __restrict__ qn, const float* __restrict__ kn, ...
;     ...
;         const int i0 = rbase + 16 * c, irow = i0 + fr, pos = n * 128 + irow; const size_t grow = (size_t)b * pg8::SEQ + pos;
;         bf16x8 qf0, qf1;
;         {
;             float x1[8], x2[8]; unpack8(qa[c], x1); unpack8(qb[c], x2);
;             float ss = 0.f;
; #pragma unroll
;             for (int j = 0; j < 8; ++j) ss += x1[j] * x1[j] + x2[j] * x2[j];
;             ss += __shfl_xor(ss, 16); ss += __shfl_xor(ss, 32);
;             const float rinv = rsqrtf(ss * (1.0f / 64.0f) + pg8::EPS) * 0.125f;
;             const float* cp = COS + pos * 32 + 8 * fq; const float* sp = SIN + pos * 32 + 8 * fq;
;             float o1[8], o2[8];
; #pragma unroll
;             for (int j = 0; j < 8; ++j) { const float a1 = x1[j] * rinv * qn[8 * fq + j], a2 = x2[j] * rinv * qn[32 + 8 * fq + j], cc = cp[j], sn = sp[j]; o1[j] = a1 * cc - a2 * sn; o2[j] = a2 * cc + a1 * sn; }
;             u32x4 w0, w1;
;             w0.x = cvt_pk_bf16(o1[0], o1[1]); w0.y = cvt_pk_bf16(o1[2], o1[3]); w0.z = cvt_pk_bf16(o1[4], o1[5]); w0.w = cvt_pk_bf16(o1[6], o1[7]);
;             w1.x = cvt_pk_bf16(o2[0], o2[1]); w1.y = cvt_pk_bf16(o2[2], o2[3]); w1.z = cvt_pk_bf16(o2[4], o2[5]); w1.w = cvt_pk_bf16(o2[6], o2[7]);
;             qf0 = __builtin_bit_cast(bf16x8, w0); qf1 = __builtin_bit_cast(bf16x8, w1);
;         }
;         const int t0 = (i0 >> 4) < 6 ? (i0 >> 4) : 6;
;         f32x4 sc_[10];
;         const LAS unsigned char* kbase = KS + (16 * t0 + fr) * KS_STRIDE + 16 * fq;
; #pragma unroll
;         for (int t = 0; t < 10; ++t) { const bf16x8 k0 = *(const LAS bf16x8*)(kbase + t * 16 * KS_STRIDE), k1 = *(const LAS bf16x8*)(kbase + t * 16 * KS_STRIDE + 64);
;             f32x4 z = (f32x4){0.f, 0.f, 0.f, 0.f}; z = MFMA16(k0, qf0, z); sc_[t] = MFMA16(k1, qf1, z); }
	v_lshlrev_b32_e32 v58, 16, v218
	v_and_b32_e32 v59, 0xffff0000, v218
	v_lshlrev_b32_e32 v66, 16, v222
	v_and_b32_e32 v67, 0xffff0000, v222
	v_lshlrev_b32_e32 v60, 16, v219
	v_and_b32_e32 v61, 0xffff0000, v219
	v_lshlrev_b32_e32 v68, 16, v223
	v_and_b32_e32 v69, 0xffff0000, v223
	v_lshlrev_b32_e32 v62, 16, v220
	v_and_b32_e32 v63, 0xffff0000, v220
	v_lshlrev_b32_e32 v70, 16, v224
	v_and_b32_e32 v71, 0xffff0000, v224
	v_lshlrev_b32_e32 v64, 16, v221
	v_and_b32_e32 v65, 0xffff0000, v221
	v_lshlrev_b32_e32 v72, 16, v225
	v_and_b32_e32 v73, 0xffff0000, v225
	v_pk_mul_f32 v[74:75], v[58:59], v[58:59]
	v_pk_fma_f32 v[74:75], v[60:61], v[60:61], v[74:75]
	v_pk_fma_f32 v[74:75], v[62:63], v[62:63], v[74:75]
	v_pk_fma_f32 v[74:75], v[64:65], v[64:65], v[74:75]
	v_pk_fma_f32 v[74:75], v[66:67], v[66:67], v[74:75]
	v_pk_fma_f32 v[74:75], v[68:69], v[68:69], v[74:75]
	v_pk_fma_f32 v[74:75], v[70:71], v[70:71], v[74:75]
	v_pk_fma_f32 v[74:75], v[72:73], v[72:73], v[74:75]
	v_add_f32_e32 v74, v74, v75
	v_mov_b32_e32 v166, v74
	s_nop 1
	v_permlane16_swap_b32_e32 v74, v166
	v_add_f32_e32 v74, v74, v166
	v_mov_b32_e32 v166, v74
	s_nop 1
	v_permlane32_swap_b32_e32 v74, v166
	v_add_f32_e32 v74, v74, v166
	v_fmamk_f32 v74, v74, 0x3c800000, v209
	v_rsq_f32_e32 v76, v74
	s_nop 0
	v_mul_f32_e32 v76, 0x3e000000, v76
	v_pk_mul_f32 v[58:59], v[58:59], v[76:77] op_sel_hi:[1,0]
	v_pk_mul_f32 v[66:67], v[66:67], v[76:77] op_sel_hi:[1,0]
	v_pk_mul_f32 v[60:61], v[60:61], v[76:77] op_sel_hi:[1,0]
	v_pk_mul_f32 v[68:69], v[68:69], v[76:77] op_sel_hi:[1,0]
	v_pk_mul_f32 v[62:63], v[62:63], v[76:77] op_sel_hi:[1,0]
	v_pk_mul_f32 v[70:71], v[70:71], v[76:77] op_sel_hi:[1,0]
	v_pk_mul_f32 v[64:65], v[64:65], v[76:77] op_sel_hi:[1,0]
	v_pk_mul_f32 v[72:73], v[72:73], v[76:77] op_sel_hi:[1,0]
	v_pk_mul_f32 v[58:59], v[58:59], v[26:27]
	v_pk_mul_f32 v[66:67], v[66:67], v[34:35]
	v_pk_mul_f32 v[60:61], v[60:61], v[28:29]
	v_pk_mul_f32 v[68:69], v[68:69], v[36:37]
	v_pk_mul_f32 v[62:63], v[62:63], v[30:31]
	v_pk_mul_f32 v[70:71], v[70:71], v[38:39]
	v_pk_mul_f32 v[64:65], v[64:65], v[32:33]
	v_pk_mul_f32 v[72:73], v[72:73], v[40:41]
	v_pk_mul_f32 v[78:79], v[66:67], v[234:235]
	v_pk_mul_f32 v[86:87], v[58:59], v[234:235]
	v_pk_mul_f32 v[80:81], v[68:69], v[236:237]
	v_pk_mul_f32 v[88:89], v[60:61], v[236:237]
	v_pk_mul_f32 v[82:83], v[70:71], v[238:239]
	v_pk_mul_f32 v[90:91], v[62:63], v[238:239]
	v_pk_mul_f32 v[84:85], v[72:73], v[240:241]
	v_pk_mul_f32 v[92:93], v[64:65], v[240:241]
	v_pk_fma_f32 v[78:79], v[58:59], v[226:227], v[78:79] neg_lo:[0,0,1] neg_hi:[0,0,1]
	v_pk_fma_f32 v[86:87], v[66:67], v[226:227], v[86:87]
	v_pk_fma_f32 v[80:81], v[60:61], v[228:229], v[80:81] neg_lo:[0,0,1] neg_hi:[0,0,1]
	v_pk_fma_f32 v[88:89], v[68:69], v[228:229], v[88:89]
	v_pk_fma_f32 v[82:83], v[62:63], v[230:231], v[82:83] neg_lo:[0,0,1] neg_hi:[0,0,1]
	v_pk_fma_f32 v[90:91], v[70:71], v[230:231], v[90:91]
	v_pk_fma_f32 v[84:85], v[64:65], v[232:233], v[84:85] neg_lo:[0,0,1] neg_hi:[0,0,1]
	v_pk_fma_f32 v[92:93], v[72:73], v[232:233], v[92:93]
	v_cvt_pk_bf16_f32 v50, v78, v79
	v_cvt_pk_bf16_f32 v54, v86, v87
	v_cvt_pk_bf16_f32 v51, v80, v81
	v_cvt_pk_bf16_f32 v55, v88, v89
	v_cvt_pk_bf16_f32 v52, v82, v83
	v_cvt_pk_bf16_f32 v56, v90, v91
	v_cvt_pk_bf16_f32 v53, v84, v85
	v_cvt_pk_bf16_f32 v57, v92, v93
	global_load_dwordx4 v[218:221], v46, s[10:11]
	global_load_dwordx4 v[222:225], v46, s[10:11] offset:64
	global_load_dwordx4 v[226:229], v47, s[6:7]
	global_load_dwordx4 v[230:233], v47, s[6:7] offset:16
	global_load_dwordx4 v[234:237], v47, s[16:17]
	global_load_dwordx4 v[238:241], v47, s[16:17] offset:16
	v_add_u32_e32 v46, 0x3c000, v46
	v_add_u32_e32 v47, 0x800, v47
	s_nop 1
	s_waitcnt lgkmcnt(13)
	v_mfma_f32_16x16x32_bf16 v[58:61], v[98:101], v[50:53], 0
	s_waitcnt lgkmcnt(12)
	v_mfma_f32_16x16x32_bf16 v[58:61], v[102:105], v[54:57], v[58:61]
	ds_read_b128 v[154:157], v45 offset:18432
	ds_read_b128 v[158:161], v45 offset:18496
	s_waitcnt lgkmcnt(13)
	v_mfma_f32_16x16x32_bf16 v[62:65], v[106:109], v[50:53], 0
	s_waitcnt lgkmcnt(12)
	v_mfma_f32_16x16x32_bf16 v[62:65], v[110:113], v[54:57], v[62:65]
	ds_read_b128 v[162:165], v45 offset:20736
	ds_read_b128 v[182:185], v45 offset:20800
	s_waitcnt lgkmcnt(13)
	v_mfma_f32_16x16x32_bf16 v[66:69], v[114:117], v[50:53], 0
	s_waitcnt lgkmcnt(12)
	v_mfma_f32_16x16x32_bf16 v[66:69], v[118:121], v[54:57], v[66:69]
	s_waitcnt lgkmcnt(11)
	v_mfma_f32_16x16x32_bf16 v[70:73], v[122:125], v[50:53], 0
	s_waitcnt lgkmcnt(10)
	v_mfma_f32_16x16x32_bf16 v[70:73], v[126:129], v[54:57], v[70:73]
	s_waitcnt lgkmcnt(9)
	v_mfma_f32_16x16x32_bf16 v[74:77], v[130:133], v[50:53], 0
	s_waitcnt lgkmcnt(8)
	v_mfma_f32_16x16x32_bf16 v[74:77], v[134:137], v[54:57], v[74:77]
	s_waitcnt lgkmcnt(7)
	v_mfma_f32_16x16x32_bf16 v[78:81], v[138:141], v[50:53], 0
	s_waitcnt lgkmcnt(6)
	v_mfma_f32_16x16x32_bf16 v[78:81], v[142:145], v[54:57], v[78:81]
	s_waitcnt lgkmcnt(5)
	v_mfma_f32_16x16x32_bf16 v[82:85], v[146:149], v[50:53], 0
	s_waitcnt lgkmcnt(4)
	v_mfma_f32_16x16x32_bf16 v[82:85], v[150:153], v[54:57], v[82:85]
	s_waitcnt lgkmcnt(3)
	v_mfma_f32_16x16x32_bf16 v[86:89], v[154:157], v[50:53], 0
	s_waitcnt lgkmcnt(2)
	v_mfma_f32_16x16x32_bf16 v[86:89], v[158:161], v[54:57], v[86:89]
	s_waitcnt lgkmcnt(1)
	v_mfma_f32_16x16x32_bf16 v[90:93], v[162:165], v[50:53], 0
	s_waitcnt lgkmcnt(0)
; #define LAS __attribute__((address_space(3)))
; #define MFMA16(a, b, c) __builtin_amdgcn_mfma_f32_16x16x32_bf16((a), (b), (c), 0, 0, 0)
; __device__ __forceinline__ void p2_block(LAS unsigned char* lds, const bf16_t* __restrict__ PROJ, bf16_t* __restrict__ ATT, bf16_t* __restrict__ SGU, const float* __restrict__ qn, const float* __restrict__ kn, ...
;     ...
;         for (int t = 0; t < 10; ++t) { const bf16x8 k0 = *(const LAS bf16x8*)(kbase + t * 16 * KS_STRIDE), k1 = *(const LAS bf16x8*)(kbase + t * 16 * KS_STRIDE + 64);
;             f32x4 z = (f32x4){0.f, 0.f, 0.f, 0.f}; z = MFMA16(k0, qf0, z); sc_[t] = MFMA16(k1, qf1, z); }
;         float mx = -1e30f;
; #pragma unroll
;         for (int t = 0; t < 10; ++t)
; #pragma unroll
;             for (int e = 0; e < 4; ++e) { const int kx = 16 * (t0 + t) + 4 * fq + e, d = kx - irow; const bool ok = (d >= 1) && (d <= 128) && (n > 0 || kx >= 128);
;                 const float v = ok ? sc_[t][e] : -1e30f; sc_[t][e] = v; mx = fmaxf(mx, v); }
;         mx = fmaxf(mx, __shfl_xor(mx, 16)); mx = fmaxf(mx, __shfl_xor(mx, 32)); mx = fmaxf(mx, sink);
;         float sum = 0.f;
; #pragma unroll
;         for (int t = 0; t < 10; ++t)
; #pragma unroll
;             for (int e = 0; e < 4; ++e) { const float p = __builtin_amdgcn_exp2f((sc_[t][e] - mx) * LOG2E); sc_[t][e] = p; sum += p; }
	v_mfma_f32_16x16x32_bf16 v[90:93], v[182:185], v[54:57], v[90:93]
	ds_read2_b64 v[98:101], v194 offset0:4 offset1:8
	ds_read2_b64 v[102:105], v195 offset0:4 offset1:8
	ds_read2_b64 v[106:109], v196 offset0:4 offset1:8
	ds_read2_b64 v[110:113], v197 offset0:4 offset1:8
	ds_read2_b64 v[114:117], v194 offset0:12 offset1:16
	ds_read2_b64 v[118:121], v195 offset0:12 offset1:16
	ds_read2_b64 v[122:125], v196 offset0:12 offset1:16
	ds_read2_b64 v[126:129], v197 offset0:12 offset1:16
	ds_read2_b64 v[130:133], v194 offset0:20 offset1:24
	ds_read2_b64 v[134:137], v195 offset0:20 offset1:24
	ds_read2_b64 v[138:141], v196 offset0:20 offset1:24
	ds_read2_b64 v[142:145], v197 offset0:20 offset1:24
	ds_read2_b64 v[146:149], v194 offset0:28 offset1:32
	ds_read2_b64 v[150:153], v195 offset0:28 offset1:32
	ds_read2_b64 v[154:157], v196 offset0:28 offset1:32
	s_nop 4
	v_cndmask_b32_e64 v58, v49, v58, s[48:49]
	v_cndmask_b32_e64 v59, v49, v59, s[50:51]
	v_cndmask_b32_e64 v60, v49, v60, s[52:53]
	v_cndmask_b32_e64 v61, v49, v61, s[26:27]
	v_cndmask_b32_e64 v62, v49, v62, s[28:29]
	v_cndmask_b32_e64 v63, v49, v63, s[28:29]
	v_cndmask_b32_e64 v64, v49, v64, s[28:29]
	v_cndmask_b32_e64 v65, v49, v65, s[28:29]
	v_cndmask_b32_e64 v66, v49, v66, s[28:29]
	v_cndmask_b32_e64 v67, v49, v67, s[28:29]
	v_cndmask_b32_e64 v68, v49, v68, s[28:29]
	v_cndmask_b32_e64 v69, v49, v69, s[28:29]
	v_cndmask_b32_e64 v70, v49, v70, s[28:29]
	v_cndmask_b32_e64 v71, v49, v71, s[28:29]
	v_cndmask_b32_e64 v72, v49, v72, s[28:29]
	v_cndmask_b32_e64 v73, v49, v73, s[28:29]
	v_cndmask_b32_e64 v74, v49, v74, s[28:29]
	v_cndmask_b32_e64 v75, v49, v75, s[28:29]
	v_cndmask_b32_e64 v76, v49, v76, s[28:29]
	v_cndmask_b32_e64 v77, v49, v77, s[28:29]
	v_cndmask_b32_e64 v78, v49, v78, s[28:29]
	v_cndmask_b32_e64 v79, v49, v79, s[28:29]
	v_cndmask_b32_e64 v80, v49, v80, s[28:29]
	v_cndmask_b32_e64 v81, v49, v81, s[28:29]
	v_cndmask_b32_e64 v82, v49, v82, s[28:29]
	v_cndmask_b32_e64 v83, v49, v83, s[28:29]
	v_cndmask_b32_e64 v84, v49, v84, s[28:29]
	v_cndmask_b32_e64 v85, v49, v85, s[28:29]
	v_cndmask_b32_e64 v90, v90, v49, s[40:41]
	v_cndmask_b32_e64 v91, v91, v49, s[42:43]
	v_cndmask_b32_e64 v92, v92, v49, s[44:45]
	v_cndmask_b32_e64 v93, v93, v49, s[46:47]
	v_max_f32_e32 v167, v58, v59
	v_max_f32_e32 v94, v60, v61
	v_max3_f32 v167, v167, v62, v63
	v_max3_f32 v94, v94, v64, v65
	v_max3_f32 v167, v167, v66, v67
	v_max3_f32 v94, v94, v68, v69
	v_max3_f32 v167, v167, v70, v71
	v_max3_f32 v94, v94, v72, v73
	v_max3_f32 v167, v167, v74, v75
	v_max3_f32 v94, v94, v76, v77
	v_max3_f32 v167, v167, v78, v79
	v_max3_f32 v94, v94, v80, v81
	v_max3_f32 v167, v167, v82, v83
	v_max3_f32 v94, v94, v84, v85
	v_max3_f32 v167, v167, v86, v87
	v_max3_f32 v94, v94, v88, v89
	v_max3_f32 v167, v167, v90, v91
	v_max3_f32 v94, v94, v92, v93
	v_max_f32_e32 v167, v167, v94
	v_mov_b32_e32 v166, v167
	s_nop 1
	v_permlane16_swap_b32_e32 v167, v166
	v_max_f32_e32 v167, v167, v166
	v_mov_b32_e32 v166, v167
	s_nop 1
	v_permlane32_swap_b32_e32 v167, v166
	v_max_f32_e32 v167, v167, v166
	v_max_f32_e32 v167, v167, v42
	v_mul_f32_e32 v94, 0xbfb8aa3b, v167
	v_fmamk_f32 v58, v58, 0x3fb8aa3b, v94
	v_fmamk_f32 v59, v59, 0x3fb8aa3b, v94
	v_fmamk_f32 v60, v60, 0x3fb8aa3b, v94
	v_fmamk_f32 v61, v61, 0x3fb8aa3b, v94
	v_fmamk_f32 v62, v62, 0x3fb8aa3b, v94
	v_fmamk_f32 v63, v63, 0x3fb8aa3b, v94
	v_fmamk_f32 v64, v64, 0x3fb8aa3b, v94
	v_fmamk_f32 v65, v65, 0x3fb8aa3b, v94
	v_fmamk_f32 v66, v66, 0x3fb8aa3b, v94
	v_fmamk_f32 v67, v67, 0x3fb8aa3b, v94
	v_fmamk_f32 v68, v68, 0x3fb8aa3b, v94
	v_fmamk_f32 v69, v69, 0x3fb8aa3b, v94
	v_fmamk_f32 v70, v70, 0x3fb8aa3b, v94
	v_fmamk_f32 v71, v71, 0x3fb8aa3b, v94
	v_fmamk_f32 v72, v72, 0x3fb8aa3b, v94
	v_fmamk_f32 v73, v73, 0x3fb8aa3b, v94
	v_fmamk_f32 v74, v74, 0x3fb8aa3b, v94
	v_fmamk_f32 v75, v75, 0x3fb8aa3b, v94
	v_fmamk_f32 v76, v76, 0x3fb8aa3b, v94
	v_fmamk_f32 v77, v77, 0x3fb8aa3b, v94
	v_fmamk_f32 v78, v78, 0x3fb8aa3b, v94
	v_fmamk_f32 v79, v79, 0x3fb8aa3b, v94
	v_fmamk_f32 v80, v80, 0x3fb8aa3b, v94
	v_fmamk_f32 v81, v81, 0x3fb8aa3b, v94
	v_fmamk_f32 v82, v82, 0x3fb8aa3b, v94
	v_fmamk_f32 v83, v83, 0x3fb8aa3b, v94
	v_fmamk_f32 v84, v84, 0x3fb8aa3b, v94
	v_fmamk_f32 v85, v85, 0x3fb8aa3b, v94
	v_fmamk_f32 v86, v86, 0x3fb8aa3b, v94
	v_fmamk_f32 v87, v87, 0x3fb8aa3b, v94
	v_fmamk_f32 v88, v88, 0x3fb8aa3b, v94
	v_fmamk_f32 v89, v89, 0x3fb8aa3b, v94
	v_fmamk_f32 v90, v90, 0x3fb8aa3b, v94
	v_fmamk_f32 v91, v91, 0x3fb8aa3b, v94
	v_fmamk_f32 v92, v92, 0x3fb8aa3b, v94
	v_fmamk_f32 v93, v93, 0x3fb8aa3b, v94
	v_exp_f32_e32 v58, v58
	v_exp_f32_e32 v59, v59
	v_exp_f32_e32 v60, v60
	v_exp_f32_e32 v61, v61
	v_exp_f32_e32 v62, v62
	v_exp_f32_e32 v63, v63
	v_exp_f32_e32 v64, v64
	v_exp_f32_e32 v65, v65
	v_exp_f32_e32 v66, v66
	v_exp_f32_e32 v67, v67
	v_exp_f32_e32 v68, v68
	v_exp_f32_e32 v69, v69
	v_exp_f32_e32 v70, v70
	v_exp_f32_e32 v71, v71
	v_exp_f32_e32 v72, v72
	v_exp_f32_e32 v73, v73
	v_exp_f32_e32 v74, v74
	v_exp_f32_e32 v75, v75
	v_exp_f32_e32 v76, v76
	v_exp_f32_e32 v77, v77
	v_exp_f32_e32 v78, v78
	v_exp_f32_e32 v79, v79
	v_exp_f32_e32 v80, v80
	v_exp_f32_e32 v81, v81
	v_exp_f32_e32 v82, v82
	v_exp_f32_e32 v83, v83
	v_exp_f32_e32 v84, v84
	v_exp_f32_e32 v85, v85
	v_exp_f32_e32 v86, v86
	v_exp_f32_e32 v87, v87
	v_exp_f32_e32 v88, v88
	v_exp_f32_e32 v89, v89
	v_exp_f32_e32 v90, v90
	v_exp_f32_e32 v91, v91
	v_exp_f32_e32 v92, v92
	v_exp_f32_e32 v93, v93
	v_fmamk_f32 v95, v42, 0x3fb8aa3b, v94
	v_exp_f32_e32 v95, v95
	v_add_f32_e32 v167, v58, v59
	v_add_f32_e32 v94, v60, v61
	v_add_f32_e32 v167, v167, v62
	v_add_f32_e32 v94, v94, v63
	v_add_f32_e32 v167, v167, v64
	v_add_f32_e32 v94, v94, v65
; __device__ __forceinline__ unsigned cvt_pk_bf16(float lo, float hi) { unsigned r; asm volatile("v_cvt_pk_bf16_f32 %0, %1, %2" : "=v"(r) : "v"(lo), "v"(hi)); return r; }
; #define LAS __attribute__((address_space(3)))
; #define MFMA16(a, b, c) __builtin_amdgcn_mfma_f32_16x16x32_bf16((a), (b), (c), 0, 0, 0)
; __device__ __forceinline__ void p2_block(LAS unsigned char* lds, const bf16_t* __restrict__ PROJ, bf16_t* __restrict__ ATT, bf16_t* __restrict__ SGU, const float* __restrict__ qn, const float* __restrict__ kn, ...
;     ...
;             for (int e = 0; e < 4; ++e) { const float p = __builtin_amdgcn_exp2f((sc_[t][e] - mx) * LOG2E); sc_[t][e] = p; sum += p; }
;         sum += __shfl_xor(sum, 16); sum += __shfl_xor(sum, 32);
;         const float inv = 1.0f / (sum + __builtin_amdgcn_exp2f((sink - mx) * LOG2E));
;         f32x4 o[4];
; #pragma unroll
;         for (int dt = 0; dt < 4; ++dt) o[dt] = (f32x4){0.f, 0.f, 0.f, 0.f};
; #pragma unroll
;         for (int j = 0; j < 5; ++j) {
;             u32x4 pw; pw.x = cvt_pk_bf16(sc_[2 * j][0], sc_[2 * j][1]); pw.y = cvt_pk_bf16(sc_[2 * j][2], sc_[2 * j][3]); pw.z = cvt_pk_bf16(sc_[2 * j + 1][0], sc_[2 * j + 1][1]); pw.w = cvt_pk_bf16(sc_[2 * j + 1][2], sc_[2 * j + 1][3]);
;             const bf16x8 pf = __builtin_bit_cast(bf16x8, pw);
; #pragma unroll
;             for (int dt = 0; dt < 4; ++dt) { const LAS unsigned char* vb = VT + (16 * dt + fr) * VT_STRIDE + (16 * (t0 + 2 * j) + 4 * fq) * 2;
;                 const u32x2 va = *(const LAS u32x2*)vb, vc = *(const LAS u32x2*)(vb + 32); u32x4 vw; vw.x = va.x; vw.y = va.y; vw.z = vc.x; vw.w = vc.y;
;                 o[dt] = MFMA16(__builtin_bit_cast(bf16x8, vw), pf, o[dt]); }
;         }
;         bf16_t* op = ATT + grow * 1024 + hq * 64 + 4 * fq;
; #pragma unroll
;         for (int dt = 0; dt < 4; ++dt) { u32x2 ow; ow.x = cvt_pk_bf16(o[dt][0] * inv, o[dt][1] * inv); ow.y = cvt_pk_bf16(o[dt][2] * inv, o[dt][3] * inv); *(u32x2*)(op + 16 * dt) = ow; }
	v_add_f32_e32 v167, v167, v66
	v_add_f32_e32 v94, v94, v67
	v_add_f32_e32 v167, v167, v68
	v_add_f32_e32 v94, v94, v69
	v_add_f32_e32 v167, v167, v70
	v_add_f32_e32 v94, v94, v71
	v_add_f32_e32 v167, v167, v72
	v_add_f32_e32 v94, v94, v73
	v_add_f32_e32 v167, v167, v74
	v_add_f32_e32 v94, v94, v75
	v_add_f32_e32 v167, v167, v76
	v_add_f32_e32 v94, v94, v77
	v_add_f32_e32 v167, v167, v78
	v_add_f32_e32 v94, v94, v79
	v_add_f32_e32 v167, v167, v80
	v_add_f32_e32 v94, v94, v81
	v_add_f32_e32 v167, v167, v82
	v_add_f32_e32 v94, v94, v83
	v_add_f32_e32 v167, v167, v84
	v_add_f32_e32 v94, v94, v85
	v_add_f32_e32 v167, v167, v86
	v_add_f32_e32 v94, v94, v87
	v_add_f32_e32 v167, v167, v88
	v_add_f32_e32 v94, v94, v89
	v_add_f32_e32 v167, v167, v90
	v_add_f32_e32 v94, v94, v91
	v_add_f32_e32 v167, v167, v92
	v_add_f32_e32 v94, v94, v93
	v_add_f32_e32 v167, v167, v94
	v_mov_b32_e32 v166, v167
	s_nop 1
	v_permlane16_swap_b32_e32 v167, v166
	v_add_f32_e32 v167, v167, v166
	v_mov_b32_e32 v166, v167
	s_nop 1
	v_permlane32_swap_b32_e32 v167, v166
	v_add_f32_e32 v167, v167, v166
	v_add_f32_e32 v167, v167, v95
	v_rcp_f32_e32 v167, v167
	v_mov_b32_e32 v94, 0
	v_mov_b32_e32 v95, 0
	v_mov_b32_e32 v96, 0
	v_mov_b32_e32 v97, 0
	v_cvt_pk_bf16_f32 v58, v58, v59
	v_cvt_pk_bf16_f32 v59, v60, v61
	v_cvt_pk_bf16_f32 v60, v62, v63
	v_cvt_pk_bf16_f32 v61, v64, v65
	v_cvt_pk_bf16_f32 v66, v66, v67
	v_cvt_pk_bf16_f32 v67, v68, v69
	v_cvt_pk_bf16_f32 v68, v70, v71
	v_cvt_pk_bf16_f32 v69, v72, v73
	v_cvt_pk_bf16_f32 v74, v74, v75
	v_cvt_pk_bf16_f32 v75, v76, v77
	v_cvt_pk_bf16_f32 v76, v78, v79
	v_cvt_pk_bf16_f32 v77, v80, v81
	v_cvt_pk_bf16_f32 v82, v82, v83
	v_cvt_pk_bf16_f32 v83, v84, v85
	v_cvt_pk_bf16_f32 v84, v86, v87
	v_cvt_pk_bf16_f32 v85, v88, v89
	v_cvt_pk_bf16_f32 v90, v90, v91
	v_cvt_pk_bf16_f32 v91, v92, v93
	v_cvt_pk_bf16_f32 v92, v94, v95
	v_cvt_pk_bf16_f32 v93, v96, v97
	s_nop 1
	s_waitcnt lgkmcnt(14)
	v_mfma_f32_16x16x32_bf16 v[62:65], v[98:101], v[58:61], 0
	ds_read2_b64 v[158:161], v197 offset0:28 offset1:32
	s_waitcnt lgkmcnt(14)
	v_mfma_f32_16x16x32_bf16 v[70:73], v[102:105], v[58:61], 0
	ds_read2_b64 v[162:165], v194 offset0:36 offset1:40
	s_waitcnt lgkmcnt(14)
	v_mfma_f32_16x16x32_bf16 v[78:81], v[106:109], v[58:61], 0
	ds_read2_b64 v[182:185], v195 offset0:36 offset1:40
	s_waitcnt lgkmcnt(14)
	v_mfma_f32_16x16x32_bf16 v[86:89], v[110:113], v[58:61], 0
	ds_read2_b64 v[186:189], v196 offset0:36 offset1:40
	s_waitcnt lgkmcnt(14)
	v_mfma_f32_16x16x32_bf16 v[62:65], v[114:117], v[66:69], v[62:65]
	ds_read2_b64 v[190:193], v197 offset0:36 offset1:40
	s_waitcnt lgkmcnt(14)
	v_mfma_f32_16x16x32_bf16 v[70:73], v[118:121], v[66:69], v[70:73]
	s_waitcnt lgkmcnt(13)
	v_mfma_f32_16x16x32_bf16 v[78:81], v[122:125], v[66:69], v[78:81]
	s_waitcnt lgkmcnt(12)
	v_mfma_f32_16x16x32_bf16 v[86:89], v[126:129], v[66:69], v[86:89]
	s_waitcnt lgkmcnt(11)
	v_mfma_f32_16x16x32_bf16 v[62:65], v[130:133], v[74:77], v[62:65]
	s_waitcnt lgkmcnt(10)
	v_mfma_f32_16x16x32_bf16 v[70:73], v[134:137], v[74:77], v[70:73]
	s_waitcnt lgkmcnt(9)
	v_mfma_f32_16x16x32_bf16 v[78:81], v[138:141], v[74:77], v[78:81]
	s_waitcnt lgkmcnt(8)
	v_mfma_f32_16x16x32_bf16 v[86:89], v[142:145], v[74:77], v[86:89]
	s_waitcnt lgkmcnt(7)
	v_mfma_f32_16x16x32_bf16 v[62:65], v[146:149], v[82:85], v[62:65]
	s_waitcnt lgkmcnt(6)
	v_mfma_f32_16x16x32_bf16 v[70:73], v[150:153], v[82:85], v[70:73]
	s_waitcnt lgkmcnt(5)
	v_mfma_f32_16x16x32_bf16 v[78:81], v[154:157], v[82:85], v[78:81]
	s_waitcnt lgkmcnt(4)
	v_mfma_f32_16x16x32_bf16 v[86:89], v[158:161], v[82:85], v[86:89]
	s_waitcnt lgkmcnt(3)
	v_mfma_f32_16x16x32_bf16 v[62:65], v[162:165], v[90:93], v[62:65]
	s_waitcnt lgkmcnt(2)
	v_mfma_f32_16x16x32_bf16 v[70:73], v[182:185], v[90:93], v[70:73]
	s_waitcnt lgkmcnt(1)
	v_mfma_f32_16x16x32_bf16 v[78:81], v[186:189], v[90:93], v[78:81]
	s_waitcnt lgkmcnt(0)
	v_mfma_f32_16x16x32_bf16 v[86:89], v[190:193], v[90:93], v[86:89]
	ds_read_b128 v[98:101], v45 offset:4608
	ds_read_b128 v[102:105], v45 offset:4672
	ds_read_b128 v[106:109], v45 offset:6912
	ds_read_b128 v[110:113], v45 offset:6976
	ds_read_b128 v[114:117], v45 offset:9216
	ds_read_b128 v[118:121], v45 offset:9280
	ds_read_b128 v[122:125], v45 offset:11520
	ds_read_b128 v[126:129], v45 offset:11584
	ds_read_b128 v[130:133], v45 offset:13824
	ds_read_b128 v[134:137], v45 offset:13888
	ds_read_b128 v[138:141], v45 offset:16128
	ds_read_b128 v[142:145], v45 offset:16192
	ds_read_b128 v[146:149], v45 offset:18432
	ds_read_b128 v[150:153], v45 offset:18496
	s_nop 7
	v_mul_f32_e32 v62, v62, v167
	v_mul_f32_e32 v63, v63, v167
	v_mul_f32_e32 v64, v64, v167
	v_mul_f32_e32 v65, v65, v167
	v_mul_f32_e32 v70, v70, v167
	v_mul_f32_e32 v71, v71, v167
	v_mul_f32_e32 v72, v72, v167
	v_mul_f32_e32 v73, v73, v167
	v_mul_f32_e32 v78, v78, v167
	v_mul_f32_e32 v79, v79, v167
	v_mul_f32_e32 v80, v80, v167
	v_mul_f32_e32 v81, v81, v167
	v_mul_f32_e32 v86, v86, v167
	v_mul_f32_e32 v87, v87, v167
	v_mul_f32_e32 v88, v88, v167
	v_mul_f32_e32 v89, v89, v167
	v_cvt_pk_bf16_f32 v62, v62, v63
	v_cvt_pk_bf16_f32 v63, v64, v65
	global_store_dwordx2 v48, v[62:63], s[24:25] offset:0
	v_cvt_pk_bf16_f32 v70, v70, v71
	v_cvt_pk_bf16_f32 v71, v72, v73
	global_store_dwordx2 v48, v[70:71], s[24:25] offset:32
	v_cvt_pk_bf16_f32 v78, v78, v79
	v_cvt_pk_bf16_f32 v79, v80, v81
	global_store_dwordx2 v48, v[78:79], s[24:25] offset:64
	v_cvt_pk_bf16_f32 v86, v86, v87
	v_cvt_pk_bf16_f32 v87, v88, v89
	global_store_dwordx2 v48, v[86:87], s[24:25] offset:96
	v_add_u32_e32 v48, 0x8000, v48
	s_waitcnt vmcnt(14)
; __device__ __forceinline__ unsigned cvt_pk_bf16(float lo, float hi) { unsigned r; asm volatile("v_cvt_pk_bf16_f32 %0, %1, %2" : "=v"(r) : "v"(lo), "v"(hi)); return r; }
; #define LAS __attribute__((address_space(3)))
; #define MFMA16(a, b, c) __builtin_amdgcn_mfma_f32_16x16x32_bf16((a), (b), (c), 0, 0, 0)
; __device__ __forceinline__ void p2_block(LAS unsigned char* lds, const bf16_t* __restrict__ PROJ, bf16_t* __restrict__ ATT, bf16_t* __restrict__ SGU, const float* __restrict__ qn, const float* __restrict__ kn, ...
;     ...
;         const int i0 = rbase + 16 * c, irow = i0 + fr, pos = n * 128 + irow; const size_t grow = (size_t)b * pg8::SEQ + pos;
;         bf16x8 qf0, qf1;
;         {
;             float x1[8], x2[8]; unpack8(qa[c], x1); unpack8(qb[c], x2);
;             float ss = 0.f;
; #pragma unroll
;             for (int j = 0; j < 8; ++j) ss += x1[j] * x1[j] + x2[j] * x2[j];
;             ss += __shfl_xor(ss, 16); ss += __shfl_xor(ss, 32);
;             const float rinv = rsqrtf(ss * (1.0f / 64.0f) + pg8::EPS) * 0.125f;
;             const float* cp = COS + pos * 32 + 8 * fq; const float* sp = SIN + pos * 32 + 8 * fq;
;             float o1[8], o2[8];
; #pragma unroll
;             for (int j = 0; j < 8; ++j) { const float a1 = x1[j] * rinv * qn[8 * fq + j], a2 = x2[j] * rinv * qn[32 + 8 * fq + j], cc = cp[j], sn = sp[j]; o1[j] = a1 * cc - a2 * sn; o2[j] = a2 * cc + a1 * sn; }
;             u32x4 w0, w1;
;             w0.x = cvt_pk_bf16(o1[0], o1[1]); w0.y = cvt_pk_bf16(o1[2], o1[3]); w0.z = cvt_pk_bf16(o1[4], o1[5]); w0.w = cvt_pk_bf16(o1[6], o1[7]);
;             w1.x = cvt_pk_bf16(o2[0], o2[1]); w1.y = cvt_pk_bf16(o2[2], o2[3]); w1.z = cvt_pk_bf16(o2[4], o2[5]); w1.w = cvt_pk_bf16(o2[6], o2[7]);
;             qf0 = __builtin_bit_cast(bf16x8, w0); qf1 = __builtin_bit_cast(bf16x8, w1);
;         }
;         const int t0 = (i0 >> 4) < 6 ? (i0 >> 4) : 6;
;         f32x4 sc_[10];
;         const LAS unsigned char* kbase = KS + (16 * t0 + fr) * KS_STRIDE + 16 * fq;
; #pragma unroll
;         for (int t = 0; t < 10; ++t) { const bf16x8 k0 = *(const LAS bf16x8*)(kbase + t * 16 * KS_STRIDE), k1 = *(const LAS bf16x8*)(kbase + t * 16 * KS_STRIDE + 64);
;             f32x4 z = (f32x4){0.f, 0.f, 0.f, 0.f}; z = MFMA16(k0, qf0, z); sc_[t] = MFMA16(k1, qf1, z); }
	v_lshlrev_b32_e32 v58, 16, v2
	v_and_b32_e32 v59, 0xffff0000, v2
	v_lshlrev_b32_e32 v66, 16, v6
	v_and_b32_e32 v67, 0xffff0000, v6
	v_lshlrev_b32_e32 v60, 16, v3
	v_and_b32_e32 v61, 0xffff0000, v3
	v_lshlrev_b32_e32 v68, 16, v7
	v_and_b32_e32 v69, 0xffff0000, v7
	v_lshlrev_b32_e32 v62, 16, v4
	v_and_b32_e32 v63, 0xffff0000, v4
	v_lshlrev_b32_e32 v70, 16, v8
	v_and_b32_e32 v71, 0xffff0000, v8
	v_lshlrev_b32_e32 v64, 16, v5
	v_and_b32_e32 v65, 0xffff0000, v5
	v_lshlrev_b32_e32 v72, 16, v9
	v_and_b32_e32 v73, 0xffff0000, v9
	v_pk_mul_f32 v[74:75], v[58:59], v[58:59]
	v_pk_fma_f32 v[74:75], v[60:61], v[60:61], v[74:75]
	v_pk_fma_f32 v[74:75], v[62:63], v[62:63], v[74:75]
	v_pk_fma_f32 v[74:75], v[64:65], v[64:65], v[74:75]
	v_pk_fma_f32 v[74:75], v[66:67], v[66:67], v[74:75]
	v_pk_fma_f32 v[74:75], v[68:69], v[68:69], v[74:75]
	v_pk_fma_f32 v[74:75], v[70:71], v[70:71], v[74:75]
	v_pk_fma_f32 v[74:75], v[72:73], v[72:73], v[74:75]
	v_add_f32_e32 v74, v74, v75
	v_mov_b32_e32 v166, v74
	s_nop 1
	v_permlane16_swap_b32_e32 v74, v166
	v_add_f32_e32 v74, v74, v166
	v_mov_b32_e32 v166, v74
	s_nop 1
	v_permlane32_swap_b32_e32 v74, v166
	v_add_f32_e32 v74, v74, v166
	v_fmamk_f32 v74, v74, 0x3c800000, v209
	v_rsq_f32_e32 v76, v74
	s_nop 0
	v_mul_f32_e32 v76, 0x3e000000, v76
	v_pk_mul_f32 v[58:59], v[58:59], v[76:77] op_sel_hi:[1,0]
	v_pk_mul_f32 v[66:67], v[66:67], v[76:77] op_sel_hi:[1,0]
	v_pk_mul_f32 v[60:61], v[60:61], v[76:77] op_sel_hi:[1,0]
	v_pk_mul_f32 v[68:69], v[68:69], v[76:77] op_sel_hi:[1,0]
	v_pk_mul_f32 v[62:63], v[62:63], v[76:77] op_sel_hi:[1,0]
	v_pk_mul_f32 v[70:71], v[70:71], v[76:77] op_sel_hi:[1,0]
	v_pk_mul_f32 v[64:65], v[64:65], v[76:77] op_sel_hi:[1,0]
	v_pk_mul_f32 v[72:73], v[72:73], v[76:77] op_sel_hi:[1,0]
	v_pk_mul_f32 v[58:59], v[58:59], v[26:27]
	v_pk_mul_f32 v[66:67], v[66:67], v[34:35]
	v_pk_mul_f32 v[60:61], v[60:61], v[28:29]
	v_pk_mul_f32 v[68:69], v[68:69], v[36:37]
	v_pk_mul_f32 v[62:63], v[62:63], v[30:31]
	v_pk_mul_f32 v[70:71], v[70:71], v[38:39]
	v_pk_mul_f32 v[64:65], v[64:65], v[32:33]
	v_pk_mul_f32 v[72:73], v[72:73], v[40:41]
	v_pk_mul_f32 v[78:79], v[66:67], v[18:19]
	v_pk_mul_f32 v[86:87], v[58:59], v[18:19]
	v_pk_mul_f32 v[80:81], v[68:69], v[20:21]
	v_pk_mul_f32 v[88:89], v[60:61], v[20:21]
	v_pk_mul_f32 v[82:83], v[70:71], v[22:23]
	v_pk_mul_f32 v[90:91], v[62:63], v[22:23]
	v_pk_mul_f32 v[84:85], v[72:73], v[24:25]
	v_pk_mul_f32 v[92:93], v[64:65], v[24:25]
	v_pk_fma_f32 v[78:79], v[58:59], v[10:11], v[78:79] neg_lo:[0,0,1] neg_hi:[0,0,1]
	v_pk_fma_f32 v[86:87], v[66:67], v[10:11], v[86:87]
	v_pk_fma_f32 v[80:81], v[60:61], v[12:13], v[80:81] neg_lo:[0,0,1] neg_hi:[0,0,1]
	v_pk_fma_f32 v[88:89], v[68:69], v[12:13], v[88:89]
	v_pk_fma_f32 v[82:83], v[62:63], v[14:15], v[82:83] neg_lo:[0,0,1] neg_hi:[0,0,1]
	v_pk_fma_f32 v[90:91], v[70:71], v[14:15], v[90:91]
	v_pk_fma_f32 v[84:85], v[64:65], v[16:17], v[84:85] neg_lo:[0,0,1] neg_hi:[0,0,1]
	v_pk_fma_f32 v[92:93], v[72:73], v[16:17], v[92:93]
	v_cvt_pk_bf16_f32 v50, v78, v79
	v_cvt_pk_bf16_f32 v54, v86, v87
	v_cvt_pk_bf16_f32 v51, v80, v81
	v_cvt_pk_bf16_f32 v55, v88, v89
	v_cvt_pk_bf16_f32 v52, v82, v83
	v_cvt_pk_bf16_f32 v56, v90, v91
	v_cvt_pk_bf16_f32 v53, v84, v85
	v_cvt_pk_bf16_f32 v57, v92, v93
	s_nop 1
	s_waitcnt lgkmcnt(13)
	v_mfma_f32_16x16x32_bf16 v[58:61], v[98:101], v[50:53], 0
	s_waitcnt lgkmcnt(12)
	v_mfma_f32_16x16x32_bf16 v[58:61], v[102:105], v[54:57], v[58:61]
	ds_read_b128 v[154:157], v45 offset:20736
	ds_read_b128 v[158:161], v45 offset:20800
	s_waitcnt lgkmcnt(13)
	v_mfma_f32_16x16x32_bf16 v[62:65], v[106:109], v[50:53], 0
	s_waitcnt lgkmcnt(12)
	v_mfma_f32_16x16x32_bf16 v[62:65], v[110:113], v[54:57], v[62:65]
	ds_read_b128 v[162:165], v45 offset:23040
	ds_read_b128 v[182:185], v45 offset:23104
	s_waitcnt lgkmcnt(13)
	v_mfma_f32_16x16x32_bf16 v[66:69], v[114:117], v[50:53], 0
	s_waitcnt lgkmcnt(12)
	v_mfma_f32_16x16x32_bf16 v[66:69], v[118:121], v[54:57], v[66:69]
	s_waitcnt lgkmcnt(11)
	v_mfma_f32_16x16x32_bf16 v[70:73], v[122:125], v[50:53], 0
	s_waitcnt lgkmcnt(10)
	v_mfma_f32_16x16x32_bf16 v[70:73], v[126:129], v[54:57], v[70:73]
	s_waitcnt lgkmcnt(9)
	v_mfma_f32_16x16x32_bf16 v[74:77], v[130:133], v[50:53], 0
	s_waitcnt lgkmcnt(8)
	v_mfma_f32_16x16x32_bf16 v[74:77], v[134:137], v[54:57], v[74:77]
	s_waitcnt lgkmcnt(7)
	v_mfma_f32_16x16x32_bf16 v[78:81], v[138:141], v[50:53], 0
	s_waitcnt lgkmcnt(6)
	v_mfma_f32_16x16x32_bf16 v[78:81], v[142:145], v[54:57], v[78:81]
	s_waitcnt lgkmcnt(5)
	v_mfma_f32_16x16x32_bf16 v[82:85], v[146:149], v[50:53], 0
	s_waitcnt lgkmcnt(4)
	v_mfma_f32_16x16x32_bf16 v[82:85], v[150:153], v[54:57], v[82:85]
	s_waitcnt lgkmcnt(3)
	v_mfma_f32_16x16x32_bf16 v[86:89], v[154:157], v[50:53], 0
	s_waitcnt lgkmcnt(2)
	v_mfma_f32_16x16x32_bf16 v[86:89], v[158:161], v[54:57], v[86:89]
	s_waitcnt lgkmcnt(1)
	v_mfma_f32_16x16x32_bf16 v[90:93], v[162:165], v[50:53], 0
	s_waitcnt lgkmcnt(0)
; #define LAS __attribute__((address_space(3)))
; #define MFMA16(a, b, c) __builtin_amdgcn_mfma_f32_16x16x32_bf16((a), (b), (c), 0, 0, 0)
; __device__ __forceinline__ void p2_block(LAS unsigned char* lds, const bf16_t* __restrict__ PROJ, bf16_t* __restrict__ ATT, bf16_t* __restrict__ SGU, const float* __restrict__ qn, const float* __restrict__ kn, ...
;     ...
;         for (int t = 0; t < 10; ++t) { const bf16x8 k0 = *(const LAS bf16x8*)(kbase + t * 16 * KS_STRIDE), k1 = *(const LAS bf16x8*)(kbase + t * 16 * KS_STRIDE + 64);
;             f32x4 z = (f32x4){0.f, 0.f, 0.f, 0.f}; z = MFMA16(k0, qf0, z); sc_[t] = MFMA16(k1, qf1, z); }
;         float mx = -1e30f;
; #pragma unroll
;         for (int t = 0; t < 10; ++t)
; #pragma unroll
;             for (int e = 0; e < 4; ++e) { const int kx = 16 * (t0 + t) + 4 * fq + e, d = kx - irow; const bool ok = (d >= 1) && (d <= 128) && (n > 0 || kx >= 128);
;                 const float v = ok ? sc_[t][e] : -1e30f; sc_[t][e] = v; mx = fmaxf(mx, v); }
;         mx = fmaxf(mx, __shfl_xor(mx, 16)); mx = fmaxf(mx, __shfl_xor(mx, 32)); mx = fmaxf(mx, sink);
;         float sum = 0.f;
; #pragma unroll
;         for (int t = 0; t < 10; ++t)
; #pragma unroll
;             for (int e = 0; e < 4; ++e) { const float p = __builtin_amdgcn_exp2f((sc_[t][e] - mx) * LOG2E); sc_[t][e] = p; sum += p; }
;         sum += __shfl_xor(sum, 16); sum += __shfl_xor(sum, 32);
	v_mfma_f32_16x16x32_bf16 v[90:93], v[182:185], v[54:57], v[90:93]
	ds_read2_b64 v[98:101], v194 offset0:8 offset1:12
	ds_read2_b64 v[102:105], v195 offset0:8 offset1:12
	ds_read2_b64 v[106:109], v196 offset0:8 offset1:12
	ds_read2_b64 v[110:113], v197 offset0:8 offset1:12
	ds_read2_b64 v[114:117], v194 offset0:16 offset1:20
	ds_read2_b64 v[118:121], v195 offset0:16 offset1:20
	ds_read2_b64 v[122:125], v196 offset0:16 offset1:20
	ds_read2_b64 v[126:129], v197 offset0:16 offset1:20
	ds_read2_b64 v[130:133], v194 offset0:24 offset1:28
	ds_read2_b64 v[134:137], v195 offset0:24 offset1:28
	ds_read2_b64 v[138:141], v196 offset0:24 offset1:28
	ds_read2_b64 v[142:145], v197 offset0:24 offset1:28
	ds_read2_b64 v[146:149], v194 offset0:32 offset1:36
	ds_read2_b64 v[150:153], v195 offset0:32 offset1:36
	ds_read2_b64 v[154:157], v196 offset0:32 offset1:36
	s_nop 4
	v_cndmask_b32_e64 v58, v49, v58, s[48:49]
	v_cndmask_b32_e64 v59, v49, v59, s[50:51]
	v_cndmask_b32_e64 v60, v49, v60, s[52:53]
	v_cndmask_b32_e64 v61, v49, v61, s[26:27]
	v_cndmask_b32_e64 v62, v49, v62, s[28:29]
	v_cndmask_b32_e64 v63, v49, v63, s[28:29]
	v_cndmask_b32_e64 v64, v49, v64, s[28:29]
	v_cndmask_b32_e64 v65, v49, v65, s[28:29]
	v_cndmask_b32_e64 v66, v49, v66, s[28:29]
	v_cndmask_b32_e64 v67, v49, v67, s[28:29]
	v_cndmask_b32_e64 v68, v49, v68, s[28:29]
	v_cndmask_b32_e64 v69, v49, v69, s[28:29]
	v_cndmask_b32_e64 v70, v49, v70, s[28:29]
	v_cndmask_b32_e64 v71, v49, v71, s[28:29]
	v_cndmask_b32_e64 v72, v49, v72, s[28:29]
	v_cndmask_b32_e64 v73, v49, v73, s[28:29]
	v_cndmask_b32_e64 v74, v49, v74, s[28:29]
	v_cndmask_b32_e64 v75, v49, v75, s[28:29]
	v_cndmask_b32_e64 v76, v49, v76, s[28:29]
	v_cndmask_b32_e64 v77, v49, v77, s[28:29]
	v_cndmask_b32_e64 v78, v49, v78, s[28:29]
	v_cndmask_b32_e64 v79, v49, v79, s[28:29]
	v_cndmask_b32_e64 v80, v49, v80, s[28:29]
	v_cndmask_b32_e64 v81, v49, v81, s[28:29]
	v_cndmask_b32_e64 v90, v90, v49, s[40:41]
	v_cndmask_b32_e64 v91, v91, v49, s[42:43]
	v_cndmask_b32_e64 v92, v92, v49, s[44:45]
	v_cndmask_b32_e64 v93, v93, v49, s[46:47]
	v_max_f32_e32 v167, v58, v59
	v_max_f32_e32 v94, v60, v61
	v_max3_f32 v167, v167, v62, v63
	v_max3_f32 v94, v94, v64, v65
	v_max3_f32 v167, v167, v66, v67
	v_max3_f32 v94, v94, v68, v69
	v_max3_f32 v167, v167, v70, v71
	v_max3_f32 v94, v94, v72, v73
	v_max3_f32 v167, v167, v74, v75
	v_max3_f32 v94, v94, v76, v77
	v_max3_f32 v167, v167, v78, v79
	v_max3_f32 v94, v94, v80, v81
	v_max3_f32 v167, v167, v82, v83
	v_max3_f32 v94, v94, v84, v85
	v_max3_f32 v167, v167, v86, v87
	v_max3_f32 v94, v94, v88, v89
	v_max3_f32 v167, v167, v90, v91
	v_max3_f32 v94, v94, v92, v93
	v_max_f32_e32 v167, v167, v94
	v_mov_b32_e32 v166, v167
	s_nop 1
	v_permlane16_swap_b32_e32 v167, v166
	v_max_f32_e32 v167, v167, v166
	v_mov_b32_e32 v166, v167
	s_nop 1
	v_permlane32_swap_b32_e32 v167, v166
	v_max_f32_e32 v167, v167, v166
	v_max_f32_e32 v167, v167, v42
	v_mul_f32_e32 v94, 0xbfb8aa3b, v167
	v_fmamk_f32 v58, v58, 0x3fb8aa3b, v94
	v_fmamk_f32 v59, v59, 0x3fb8aa3b, v94
	v_fmamk_f32 v60, v60, 0x3fb8aa3b, v94
	v_fmamk_f32 v61, v61, 0x3fb8aa3b, v94
	v_fmamk_f32 v62, v62, 0x3fb8aa3b, v94
	v_fmamk_f32 v63, v63, 0x3fb8aa3b, v94
	v_fmamk_f32 v64, v64, 0x3fb8aa3b, v94
	v_fmamk_f32 v65, v65, 0x3fb8aa3b, v94
	v_fmamk_f32 v66, v66, 0x3fb8aa3b, v94
	v_fmamk_f32 v67, v67, 0x3fb8aa3b, v94
	v_fmamk_f32 v68, v68, 0x3fb8aa3b, v94
	v_fmamk_f32 v69, v69, 0x3fb8aa3b, v94
	v_fmamk_f32 v70, v70, 0x3fb8aa3b, v94
	v_fmamk_f32 v71, v71, 0x3fb8aa3b, v94
	v_fmamk_f32 v72, v72, 0x3fb8aa3b, v94
	v_fmamk_f32 v73, v73, 0x3fb8aa3b, v94
	v_fmamk_f32 v74, v74, 0x3fb8aa3b, v94
	v_fmamk_f32 v75, v75, 0x3fb8aa3b, v94
	v_fmamk_f32 v76, v76, 0x3fb8aa3b, v94
	v_fmamk_f32 v77, v77, 0x3fb8aa3b, v94
	v_fmamk_f32 v78, v78, 0x3fb8aa3b, v94
	v_fmamk_f32 v79, v79, 0x3fb8aa3b, v94
	v_fmamk_f32 v80, v80, 0x3fb8aa3b, v94
	v_fmamk_f32 v81, v81, 0x3fb8aa3b, v94
	v_fmamk_f32 v82, v82, 0x3fb8aa3b, v94
	v_fmamk_f32 v83, v83, 0x3fb8aa3b, v94
	v_fmamk_f32 v84, v84, 0x3fb8aa3b, v94
	v_fmamk_f32 v85, v85, 0x3fb8aa3b, v94
	v_fmamk_f32 v86, v86, 0x3fb8aa3b, v94
	v_fmamk_f32 v87, v87, 0x3fb8aa3b, v94
	v_fmamk_f32 v88, v88, 0x3fb8aa3b, v94
	v_fmamk_f32 v89, v89, 0x3fb8aa3b, v94
	v_fmamk_f32 v90, v90, 0x3fb8aa3b, v94
	v_fmamk_f32 v91, v91, 0x3fb8aa3b, v94
	v_fmamk_f32 v92, v92, 0x3fb8aa3b, v94
	v_fmamk_f32 v93, v93, 0x3fb8aa3b, v94
	v_exp_f32_e32 v58, v58
	v_exp_f32_e32 v59, v59
	v_exp_f32_e32 v60, v60
	v_exp_f32_e32 v61, v61
	v_exp_f32_e32 v62, v62
	v_exp_f32_e32 v63, v63
	v_exp_f32_e32 v64, v64
	v_exp_f32_e32 v65, v65
	v_exp_f32_e32 v66, v66
	v_exp_f32_e32 v67, v67
	v_exp_f32_e32 v68, v68
	v_exp_f32_e32 v69, v69
	v_exp_f32_e32 v70, v70
	v_exp_f32_e32 v71, v71
	v_exp_f32_e32 v72, v72
	v_exp_f32_e32 v73, v73
	v_exp_f32_e32 v74, v74
	v_exp_f32_e32 v75, v75
	v_exp_f32_e32 v76, v76
	v_exp_f32_e32 v77, v77
	v_exp_f32_e32 v78, v78
	v_exp_f32_e32 v79, v79
	v_exp_f32_e32 v80, v80
	v_exp_f32_e32 v81, v81
	v_exp_f32_e32 v82, v82
	v_exp_f32_e32 v83, v83
	v_exp_f32_e32 v84, v84
	v_exp_f32_e32 v85, v85
	v_exp_f32_e32 v86, v86
	v_exp_f32_e32 v87, v87
	v_exp_f32_e32 v88, v88
	v_exp_f32_e32 v89, v89
	v_exp_f32_e32 v90, v90
	v_exp_f32_e32 v91, v91
	v_exp_f32_e32 v92, v92
	v_exp_f32_e32 v93, v93
	v_fmamk_f32 v95, v42, 0x3fb8aa3b, v94
	v_exp_f32_e32 v95, v95
	v_add_f32_e32 v167, v58, v59
	v_add_f32_e32 v94, v60, v61
	v_add_f32_e32 v167, v167, v62
	v_add_f32_e32 v94, v94, v63
	v_add_f32_e32 v167, v167, v64
	v_add_f32_e32 v94, v94, v65
	v_add_f32_e32 v167, v167, v66
	v_add_f32_e32 v94, v94, v67
	v_add_f32_e32 v167, v167, v68
	v_add_f32_e32 v94, v94, v69
	v_add_f32_e32 v167, v167, v70
	v_add_f32_e32 v94, v94, v71
; __device__ __forceinline__ unsigned cvt_pk_bf16(float lo, float hi) { unsigned r; asm volatile("v_cvt_pk_bf16_f32 %0, %1, %2" : "=v"(r) : "v"(lo), "v"(hi)); return r; }
; #define LAS __attribute__((address_space(3)))
; #define MFMA16(a, b, c) __builtin_amdgcn_mfma_f32_16x16x32_bf16((a), (b), (c), 0, 0, 0)
; __device__ __forceinline__ void p2_block(LAS unsigned char* lds, const bf16_t* __restrict__ PROJ, bf16_t* __restrict__ ATT, bf16_t* __restrict__ SGU, const float* __restrict__ qn, const float* __restrict__ kn, ...
;     ...
;             for (int e = 0; e < 4; ++e) { const float p = __builtin_amdgcn_exp2f((sc_[t][e] - mx) * LOG2E); sc_[t][e] = p; sum += p; }
;         sum += __shfl_xor(sum, 16); sum += __shfl_xor(sum, 32);
;         const float inv = 1.0f / (sum + __builtin_amdgcn_exp2f((sink - mx) * LOG2E));
;         f32x4 o[4];
; #pragma unroll
;         for (int dt = 0; dt < 4; ++dt) o[dt] = (f32x4){0.f, 0.f, 0.f, 0.f};
; #pragma unroll
;         for (int j = 0; j < 5; ++j) {
;             u32x4 pw; pw.x = cvt_pk_bf16(sc_[2 * j][0], sc_[2 * j][1]); pw.y = cvt_pk_bf16(sc_[2 * j][2], sc_[2 * j][3]); pw.z = cvt_pk_bf16(sc_[2 * j + 1][0], sc_[2 * j + 1][1]); pw.w = cvt_pk_bf16(sc_[2 * j + 1][2], sc_[2 * j + 1][3]);
;             const bf16x8 pf = __builtin_bit_cast(bf16x8, pw);
; #pragma unroll
;             for (int dt = 0; dt < 4; ++dt) { const LAS unsigned char* vb = VT + (16 * dt + fr) * VT_STRIDE + (16 * (t0 + 2 * j) + 4 * fq) * 2;
;                 const u32x2 va = *(const LAS u32x2*)vb, vc = *(const LAS u32x2*)(vb + 32); u32x4 vw; vw.x = va.x; vw.y = va.y; vw.z = vc.x; vw.w = vc.y;
;                 o[dt] = MFMA16(__builtin_bit_cast(bf16x8, vw), pf, o[dt]); }
;         }
;         bf16_t* op = ATT + grow * 1024 + hq * 64 + 4 * fq;
; #pragma unroll
;         for (int dt = 0; dt < 4; ++dt) { u32x2 ow; ow.x = cvt_pk_bf16(o[dt][0] * inv, o[dt][1] * inv); ow.y = cvt_pk_bf16(o[dt][2] * inv, o[dt][3] * inv); *(u32x2*)(op + 16 * dt) = ow; }
	v_add_f32_e32 v167, v167, v72
	v_add_f32_e32 v94, v94, v73
	v_add_f32_e32 v167, v167, v74
	v_add_f32_e32 v94, v94, v75
	v_add_f32_e32 v167, v167, v76
	v_add_f32_e32 v94, v94, v77
	v_add_f32_e32 v167, v167, v78
	v_add_f32_e32 v94, v94, v79
	v_add_f32_e32 v167, v167, v80
	v_add_f32_e32 v94, v94, v81
	v_add_f32_e32 v167, v167, v82
	v_add_f32_e32 v94, v94, v83
	v_add_f32_e32 v167, v167, v84
	v_add_f32_e32 v94, v94, v85
	v_add_f32_e32 v167, v167, v86
	v_add_f32_e32 v94, v94, v87
	v_add_f32_e32 v167, v167, v88
	v_add_f32_e32 v94, v94, v89
	v_add_f32_e32 v167, v167, v90
	v_add_f32_e32 v94, v94, v91
	v_add_f32_e32 v167, v167, v92
	v_add_f32_e32 v94, v94, v93
	v_add_f32_e32 v167, v167, v94
	v_mov_b32_e32 v166, v167
	s_nop 1
	v_permlane16_swap_b32_e32 v167, v166
	v_add_f32_e32 v167, v167, v166
	v_mov_b32_e32 v166, v167
	s_nop 1
	v_permlane32_swap_b32_e32 v167, v166
	v_add_f32_e32 v167, v167, v166
	v_add_f32_e32 v167, v167, v95
	v_rcp_f32_e32 v167, v167
	v_mov_b32_e32 v94, 0
	v_mov_b32_e32 v95, 0
	v_mov_b32_e32 v96, 0
	v_mov_b32_e32 v97, 0
	v_cvt_pk_bf16_f32 v58, v58, v59
	v_cvt_pk_bf16_f32 v59, v60, v61
	v_cvt_pk_bf16_f32 v60, v62, v63
	v_cvt_pk_bf16_f32 v61, v64, v65
	v_cvt_pk_bf16_f32 v66, v66, v67
	v_cvt_pk_bf16_f32 v67, v68, v69
	v_cvt_pk_bf16_f32 v68, v70, v71
	v_cvt_pk_bf16_f32 v69, v72, v73
	v_cvt_pk_bf16_f32 v74, v74, v75
	v_cvt_pk_bf16_f32 v75, v76, v77
	v_cvt_pk_bf16_f32 v76, v78, v79
	v_cvt_pk_bf16_f32 v77, v80, v81
	v_cvt_pk_bf16_f32 v82, v82, v83
	v_cvt_pk_bf16_f32 v83, v84, v85
	v_cvt_pk_bf16_f32 v84, v86, v87
	v_cvt_pk_bf16_f32 v85, v88, v89
	v_cvt_pk_bf16_f32 v90, v90, v91
	v_cvt_pk_bf16_f32 v91, v92, v93
	v_cvt_pk_bf16_f32 v92, v94, v95
	v_cvt_pk_bf16_f32 v93, v96, v97
	s_nop 1
	s_waitcnt lgkmcnt(14)
	v_mfma_f32_16x16x32_bf16 v[62:65], v[98:101], v[58:61], 0
	ds_read2_b64 v[158:161], v197 offset0:32 offset1:36
	s_waitcnt lgkmcnt(14)
	v_mfma_f32_16x16x32_bf16 v[70:73], v[102:105], v[58:61], 0
	ds_read2_b64 v[162:165], v194 offset0:40 offset1:44
	s_waitcnt lgkmcnt(14)
	v_mfma_f32_16x16x32_bf16 v[78:81], v[106:109], v[58:61], 0
	ds_read2_b64 v[182:185], v195 offset0:40 offset1:44
	s_waitcnt lgkmcnt(14)
	v_mfma_f32_16x16x32_bf16 v[86:89], v[110:113], v[58:61], 0
	ds_read2_b64 v[186:189], v196 offset0:40 offset1:44
	s_waitcnt lgkmcnt(14)
	v_mfma_f32_16x16x32_bf16 v[62:65], v[114:117], v[66:69], v[62:65]
	ds_read2_b64 v[190:193], v197 offset0:40 offset1:44
	s_waitcnt lgkmcnt(14)
	v_mfma_f32_16x16x32_bf16 v[70:73], v[118:121], v[66:69], v[70:73]
	s_waitcnt lgkmcnt(13)
	v_mfma_f32_16x16x32_bf16 v[78:81], v[122:125], v[66:69], v[78:81]
	s_waitcnt lgkmcnt(12)
	v_mfma_f32_16x16x32_bf16 v[86:89], v[126:129], v[66:69], v[86:89]
	s_waitcnt lgkmcnt(11)
	v_mfma_f32_16x16x32_bf16 v[62:65], v[130:133], v[74:77], v[62:65]
	s_waitcnt lgkmcnt(10)
	v_mfma_f32_16x16x32_bf16 v[70:73], v[134:137], v[74:77], v[70:73]
	s_waitcnt lgkmcnt(9)
	v_mfma_f32_16x16x32_bf16 v[78:81], v[138:141], v[74:77], v[78:81]
	s_waitcnt lgkmcnt(8)
	v_mfma_f32_16x16x32_bf16 v[86:89], v[142:145], v[74:77], v[86:89]
	s_waitcnt lgkmcnt(7)
	v_mfma_f32_16x16x32_bf16 v[62:65], v[146:149], v[82:85], v[62:65]
	s_waitcnt lgkmcnt(6)
	v_mfma_f32_16x16x32_bf16 v[70:73], v[150:153], v[82:85], v[70:73]
	s_waitcnt lgkmcnt(5)
	v_mfma_f32_16x16x32_bf16 v[78:81], v[154:157], v[82:85], v[78:81]
	s_waitcnt lgkmcnt(4)
	v_mfma_f32_16x16x32_bf16 v[86:89], v[158:161], v[82:85], v[86:89]
	s_waitcnt lgkmcnt(3)
	v_mfma_f32_16x16x32_bf16 v[62:65], v[162:165], v[90:93], v[62:65]
	s_waitcnt lgkmcnt(2)
	v_mfma_f32_16x16x32_bf16 v[70:73], v[182:185], v[90:93], v[70:73]
	s_waitcnt lgkmcnt(1)
	v_mfma_f32_16x16x32_bf16 v[78:81], v[186:189], v[90:93], v[78:81]
	s_waitcnt lgkmcnt(0)
	v_mfma_f32_16x16x32_bf16 v[86:89], v[190:193], v[90:93], v[86:89]
	ds_read_b128 v[98:101], v45 offset:6912
	ds_read_b128 v[102:105], v45 offset:6976
	ds_read_b128 v[106:109], v45 offset:9216
	ds_read_b128 v[110:113], v45 offset:9280
	ds_read_b128 v[114:117], v45 offset:11520
	ds_read_b128 v[118:121], v45 offset:11584
	ds_read_b128 v[122:125], v45 offset:13824
	ds_read_b128 v[126:129], v45 offset:13888
	ds_read_b128 v[130:133], v45 offset:16128
	ds_read_b128 v[134:137], v45 offset:16192
	ds_read_b128 v[138:141], v45 offset:18432
	ds_read_b128 v[142:145], v45 offset:18496
	ds_read_b128 v[146:149], v45 offset:20736
	ds_read_b128 v[150:153], v45 offset:20800
	s_nop 7
	v_mul_f32_e32 v62, v62, v167
	v_mul_f32_e32 v63, v63, v167
	v_mul_f32_e32 v64, v64, v167
	v_mul_f32_e32 v65, v65, v167
	v_mul_f32_e32 v70, v70, v167
	v_mul_f32_e32 v71, v71, v167
	v_mul_f32_e32 v72, v72, v167
	v_mul_f32_e32 v73, v73, v167
	v_mul_f32_e32 v78, v78, v167
	v_mul_f32_e32 v79, v79, v167
	v_mul_f32_e32 v80, v80, v167
	v_mul_f32_e32 v81, v81, v167
	v_mul_f32_e32 v86, v86, v167
	v_mul_f32_e32 v87, v87, v167
	v_mul_f32_e32 v88, v88, v167
	v_mul_f32_e32 v89, v89, v167
	v_cvt_pk_bf16_f32 v62, v62, v63
	v_cvt_pk_bf16_f32 v63, v64, v65
	global_store_dwordx2 v48, v[62:63], s[24:25] offset:0
	v_cvt_pk_bf16_f32 v70, v70, v71
	v_cvt_pk_bf16_f32 v71, v72, v73
	global_store_dwordx2 v48, v[70:71], s[24:25] offset:32
	v_cvt_pk_bf16_f32 v78, v78, v79
	v_cvt_pk_bf16_f32 v79, v80, v81
	global_store_dwordx2 v48, v[78:79], s[24:25] offset:64
	v_cvt_pk_bf16_f32 v86, v86, v87
	v_cvt_pk_bf16_f32 v87, v88, v89
	global_store_dwordx2 v48, v[86:87], s[24:25] offset:96
	v_add_u32_e32 v48, 0x8000, v48
	s_waitcnt vmcnt(8)
; #define LAS __attribute__((address_space(3)))
; __device__ __forceinline__ void p2_block(LAS unsigned char* lds, const bf16_t* __restrict__ PROJ, bf16_t* __restrict__ ATT, bf16_t* __restrict__ SGU, const float* __restrict__ qn, const float* __restrict__ kn, ...
;     ...
;         const int i0 = rbase + 16 * c, irow = i0 + fr, pos = n * 128 + irow; const size_t grow = (size_t)b * pg8::SEQ + pos;
;         bf16x8 qf0, qf1;
;         {
;             float x1[8], x2[8]; unpack8(qa[c], x1); unpack8(qb[c], x2);
;             float ss = 0.f;
; #pragma unroll
;             for (int j = 0; j < 8; ++j) ss += x1[j] * x1[j] + x2[j] * x2[j];
;             ss += __shfl_xor(ss, 16); ss += __shfl_xor(ss, 32);
;             const float rinv = rsqrtf(ss * (1.0f / 64.0f) + pg8::EPS) * 0.125f;
;             const float* cp = COS + pos * 32 + 8 * fq; const float* sp = SIN + pos * 32 + 8 * fq;
;             float o1[8], o2[8];
; #pragma unroll
;             for (int j = 0; j < 8; ++j) { const float a1 = x1[j] * rinv * qn[8 * fq + j], a2 = x2[j] * rinv * qn[32 + 8 * fq + j], cc = cp[j], sn = sp[j]; o1[j] = a1 * cc - a2 * sn; o2[j] = a2 * cc + a1 * sn; }
;             u32x4 w0, w1;
;             w0.x = cvt_pk_bf16(o1[0], o1[1]); w0.y = cvt_pk_bf16(o1[2], o1[3]); w0.z = cvt_pk_bf16(o1[4], o1[5]); w0.w = cvt_pk_bf16(o1[6], o1[7]);
;             w1.x = cvt_pk_bf16(o2[0], o2[1]); w1.y = cvt_pk_bf16(o2[2], o2[3]); w1.z = cvt_pk_bf16(o2[4], o2[5]); w1.w = cvt_pk_bf16(o2[6], o2[7]);
;             qf0 = __builtin_bit_cast(bf16x8, w0); qf1 = __builtin_bit_cast(bf16x8, w1);
;         }
;         const int t0 = (i0 >> 4) < 6 ? (i0 >> 4) : 6;
;         f32x4 sc_[10];
;         const LAS unsigned char* kbase = KS + (16 * t0 + fr) * KS_STRIDE + 16 * fq;
; #pragma unroll
;         for (int t = 0; t < 10; ++t) { const bf16x8 k0 = *(const LAS bf16x8*)(kbase + t * 16 * KS_STRIDE), k1 = *(const LAS bf16x8*)(kbase + t * 16 * KS_STRIDE + 64);
;             f32x4 z = (f32x4){0.f, 0.f, 0.f, 0.f}; z = MFMA16(k0, qf0, z); sc_[t] = MFMA16(k1, qf1, z); }
;     ...
;         const float bias = bsp[gg * 128 + irow];
;         const size_t grow = (size_t)b * pg8::SEQ + n * 128 + irow;
;         const bf16_t* up = PROJ + grow * pg8::IN_W + pg8::C_U + gg * 128 + 4 * fq; bf16_t* op = SGU + grow * 1024 + gg * 128 + 4 * fq;
; #pragma unroll
;         for (int dt = 0; dt < 8; ++dt) { const u32x2 uw = *(const u32x2*)(up + 16 * dt);
	v_lshlrev_b32_e32 v58, 16, v218
	v_and_b32_e32 v59, 0xffff0000, v218
	v_lshlrev_b32_e32 v66, 16, v222
	v_and_b32_e32 v67, 0xffff0000, v222
	v_lshlrev_b32_e32 v60, 16, v219
	v_and_b32_e32 v61, 0xffff0000, v219
	v_lshlrev_b32_e32 v68, 16, v223
	v_and_b32_e32 v69, 0xffff0000, v223
	v_lshlrev_b32_e32 v62, 16, v220
	v_and_b32_e32 v63, 0xffff0000, v220
	v_lshlrev_b32_e32 v70, 16, v224
	v_and_b32_e32 v71, 0xffff0000, v224
	v_lshlrev_b32_e32 v64, 16, v221
	v_and_b32_e32 v65, 0xffff0000, v221
	v_lshlrev_b32_e32 v72, 16, v225
	v_and_b32_e32 v73, 0xffff0000, v225
	v_pk_mul_f32 v[74:75], v[58:59], v[58:59]
	v_pk_fma_f32 v[74:75], v[60:61], v[60:61], v[74:75]
	v_pk_fma_f32 v[74:75], v[62:63], v[62:63], v[74:75]
	v_pk_fma_f32 v[74:75], v[64:65], v[64:65], v[74:75]
	v_pk_fma_f32 v[74:75], v[66:67], v[66:67], v[74:75]
	v_pk_fma_f32 v[74:75], v[68:69], v[68:69], v[74:75]
	v_pk_fma_f32 v[74:75], v[70:71], v[70:71], v[74:75]
	v_pk_fma_f32 v[74:75], v[72:73], v[72:73], v[74:75]
	v_add_f32_e32 v74, v74, v75
	v_mov_b32_e32 v166, v74
	s_nop 1
	v_permlane16_swap_b32_e32 v74, v166
	v_add_f32_e32 v74, v74, v166
	v_mov_b32_e32 v166, v74
	s_nop 1
	v_permlane32_swap_b32_e32 v74, v166
	v_add_f32_e32 v74, v74, v166
	v_fmamk_f32 v74, v74, 0x3c800000, v209
	v_rsq_f32_e32 v76, v74
	s_nop 0
	v_mul_f32_e32 v76, 0x3e000000, v76
	v_pk_mul_f32 v[58:59], v[58:59], v[76:77] op_sel_hi:[1,0]
	v_pk_mul_f32 v[66:67], v[66:67], v[76:77] op_sel_hi:[1,0]
	v_pk_mul_f32 v[60:61], v[60:61], v[76:77] op_sel_hi:[1,0]
	v_pk_mul_f32 v[68:69], v[68:69], v[76:77] op_sel_hi:[1,0]
	v_pk_mul_f32 v[62:63], v[62:63], v[76:77] op_sel_hi:[1,0]
	v_pk_mul_f32 v[70:71], v[70:71], v[76:77] op_sel_hi:[1,0]
	v_pk_mul_f32 v[64:65], v[64:65], v[76:77] op_sel_hi:[1,0]
	v_pk_mul_f32 v[72:73], v[72:73], v[76:77] op_sel_hi:[1,0]
	v_pk_mul_f32 v[58:59], v[58:59], v[26:27]
	v_pk_mul_f32 v[66:67], v[66:67], v[34:35]
	v_pk_mul_f32 v[60:61], v[60:61], v[28:29]
	v_pk_mul_f32 v[68:69], v[68:69], v[36:37]
	v_pk_mul_f32 v[62:63], v[62:63], v[30:31]
	v_pk_mul_f32 v[70:71], v[70:71], v[38:39]
	v_pk_mul_f32 v[64:65], v[64:65], v[32:33]
	v_pk_mul_f32 v[72:73], v[72:73], v[40:41]
	v_pk_mul_f32 v[78:79], v[66:67], v[234:235]
	v_pk_mul_f32 v[86:87], v[58:59], v[234:235]
	v_pk_mul_f32 v[80:81], v[68:69], v[236:237]
	v_pk_mul_f32 v[88:89], v[60:61], v[236:237]
	v_pk_mul_f32 v[82:83], v[70:71], v[238:239]
	v_pk_mul_f32 v[90:91], v[62:63], v[238:239]
	v_pk_mul_f32 v[84:85], v[72:73], v[240:241]
	v_pk_mul_f32 v[92:93], v[64:65], v[240:241]
	v_pk_fma_f32 v[78:79], v[58:59], v[226:227], v[78:79] neg_lo:[0,0,1] neg_hi:[0,0,1]
	v_pk_fma_f32 v[86:87], v[66:67], v[226:227], v[86:87]
	v_pk_fma_f32 v[80:81], v[60:61], v[228:229], v[80:81] neg_lo:[0,0,1] neg_hi:[0,0,1]
	v_pk_fma_f32 v[88:89], v[68:69], v[228:229], v[88:89]
	v_pk_fma_f32 v[82:83], v[62:63], v[230:231], v[82:83] neg_lo:[0,0,1] neg_hi:[0,0,1]
	v_pk_fma_f32 v[90:91], v[70:71], v[230:231], v[90:91]
	v_pk_fma_f32 v[84:85], v[64:65], v[232:233], v[84:85] neg_lo:[0,0,1] neg_hi:[0,0,1]
	v_pk_fma_f32 v[92:93], v[72:73], v[232:233], v[92:93]
	v_cvt_pk_bf16_f32 v50, v78, v79
	v_cvt_pk_bf16_f32 v54, v86, v87
	v_cvt_pk_bf16_f32 v51, v80, v81
	v_cvt_pk_bf16_f32 v55, v88, v89
	v_cvt_pk_bf16_f32 v52, v82, v83
	v_cvt_pk_bf16_f32 v56, v90, v91
	v_cvt_pk_bf16_f32 v53, v84, v85
	v_cvt_pk_bf16_f32 v57, v92, v93
	v_lshrrev_b32_e32 v242, 2, v204
	v_and_b32_e32 v242, 0x70, v242
	v_and_b32_e32 v243, 15, v204
	v_or_b32_e32 v242, v242, v243
	v_lshrrev_b32_e32 v243, 1, v204
	v_and_b32_e32 v243, 24, v243
	v_and_b32_e64 v244, s2, 3
	v_lshlrev_b32_e32 v244, 9, v244
	v_and_b32_e64 v245, s2, -4
	v_lshl_add_u32 v245, v245, 5, v242
	v_mul_u32_u24_e32 v245, 0x3c00, v245
	v_add3_u32 v245, v245, v244, v243
	v_lshlrev_b32_e32 v244, 1, v244
	v_lshl_add_u32 v244, v242, 2, v244
	global_load_dword v198, v244, s[22:23]
	global_load_dword v199, v244, s[22:23] offset:512
	global_load_dwordx2 v[218:219], v245, s[10:11] offset:3072
	global_load_dwordx2 v[220:221], v245, s[10:11] offset:3104
	global_load_dwordx2 v[222:223], v245, s[10:11] offset:3136
	global_load_dwordx2 v[224:225], v245, s[10:11] offset:3168
	global_load_dwordx2 v[226:227], v245, s[10:11] offset:3200
	global_load_dwordx2 v[228:229], v245, s[10:11] offset:3232
	global_load_dwordx2 v[230:231], v245, s[10:11] offset:3264
	global_load_dwordx2 v[232:233], v245, s[10:11] offset:3296
	global_load_dwordx2 v[234:235], v245, s[10:11] offset:3328
	global_load_dwordx2 v[236:237], v245, s[10:11] offset:3360
	global_load_dwordx2 v[238:239], v245, s[10:11] offset:3392
	global_load_dwordx2 v[240:241], v245, s[10:11] offset:3424
	global_load_dwordx2 v[242:243], v245, s[10:11] offset:3456
	global_load_dwordx2 v[200:201], v245, s[10:11] offset:3520
	global_load_dwordx2 v[202:203], v245, s[10:11] offset:3552
	global_load_dwordx2 v[244:245], v245, s[10:11] offset:3488
	s_nop 1
	s_waitcnt lgkmcnt(13)
	v_mfma_f32_16x16x32_bf16 v[58:61], v[98:101], v[50:53], 0
	s_waitcnt lgkmcnt(12)
	v_mfma_f32_16x16x32_bf16 v[58:61], v[102:105], v[54:57], v[58:61]
	ds_read_b128 v[154:157], v45 offset:23040
	ds_read_b128 v[158:161], v45 offset:23104
	s_waitcnt lgkmcnt(13)
	v_mfma_f32_16x16x32_bf16 v[62:65], v[106:109], v[50:53], 0
	s_waitcnt lgkmcnt(12)
	v_mfma_f32_16x16x32_bf16 v[62:65], v[110:113], v[54:57], v[62:65]
	ds_read_b128 v[162:165], v45 offset:25344
	ds_read_b128 v[182:185], v45 offset:25408
	s_waitcnt lgkmcnt(13)
	v_mfma_f32_16x16x32_bf16 v[66:69], v[114:117], v[50:53], 0
	s_waitcnt lgkmcnt(12)
	v_mfma_f32_16x16x32_bf16 v[66:69], v[118:121], v[54:57], v[66:69]
	s_waitcnt lgkmcnt(11)
	v_mfma_f32_16x16x32_bf16 v[70:73], v[122:125], v[50:53], 0
	s_waitcnt lgkmcnt(10)
; #define LAS __attribute__((address_space(3)))
; #define MFMA16(a, b, c) __builtin_amdgcn_mfma_f32_16x16x32_bf16((a), (b), (c), 0, 0, 0)
; __device__ __forceinline__ void p2_block(LAS unsigned char* lds, const bf16_t* __restrict__ PROJ, bf16_t* __restrict__ ATT, bf16_t* __restrict__ SGU, const float* __restrict__ qn, const float* __restrict__ kn, ...
;     ...
;         for (int t = 0; t < 10; ++t) { const bf16x8 k0 = *(const LAS bf16x8*)(kbase + t * 16 * KS_STRIDE), k1 = *(const LAS bf16x8*)(kbase + t * 16 * KS_STRIDE + 64);
;             f32x4 z = (f32x4){0.f, 0.f, 0.f, 0.f}; z = MFMA16(k0, qf0, z); sc_[t] = MFMA16(k1, qf1, z); }
;         float mx = -1e30f;
; #pragma unroll
;         for (int t = 0; t < 10; ++t)
; #pragma unroll
;             for (int e = 0; e < 4; ++e) { const int kx = 16 * (t0 + t) + 4 * fq + e, d = kx - irow; const bool ok = (d >= 1) && (d <= 128) && (n > 0 || kx >= 128);
;                 const float v = ok ? sc_[t][e] : -1e30f; sc_[t][e] = v; mx = fmaxf(mx, v); }
;         mx = fmaxf(mx, __shfl_xor(mx, 16)); mx = fmaxf(mx, __shfl_xor(mx, 32)); mx = fmaxf(mx, sink);
;         float sum = 0.f;
; #pragma unroll
;         for (int t = 0; t < 10; ++t)
; #pragma unroll
;             for (int e = 0; e < 4; ++e) { const float p = __builtin_amdgcn_exp2f((sc_[t][e] - mx) * LOG2E); sc_[t][e] = p; sum += p; }
	v_mfma_f32_16x16x32_bf16 v[70:73], v[126:129], v[54:57], v[70:73]
	s_waitcnt lgkmcnt(9)
	v_mfma_f32_16x16x32_bf16 v[74:77], v[130:133], v[50:53], 0
	s_waitcnt lgkmcnt(8)
	v_mfma_f32_16x16x32_bf16 v[74:77], v[134:137], v[54:57], v[74:77]
	s_waitcnt lgkmcnt(7)
	v_mfma_f32_16x16x32_bf16 v[78:81], v[138:141], v[50:53], 0
	s_waitcnt lgkmcnt(6)
	v_mfma_f32_16x16x32_bf16 v[78:81], v[142:145], v[54:57], v[78:81]
	s_waitcnt lgkmcnt(5)
	v_mfma_f32_16x16x32_bf16 v[82:85], v[146:149], v[50:53], 0
	s_waitcnt lgkmcnt(4)
	v_mfma_f32_16x16x32_bf16 v[82:85], v[150:153], v[54:57], v[82:85]
	s_waitcnt lgkmcnt(3)
	v_mfma_f32_16x16x32_bf16 v[86:89], v[154:157], v[50:53], 0
	s_waitcnt lgkmcnt(2)
	v_mfma_f32_16x16x32_bf16 v[86:89], v[158:161], v[54:57], v[86:89]
	s_waitcnt lgkmcnt(1)
	v_mfma_f32_16x16x32_bf16 v[90:93], v[162:165], v[50:53], 0
	s_waitcnt lgkmcnt(0)
	v_mfma_f32_16x16x32_bf16 v[90:93], v[182:185], v[54:57], v[90:93]
	ds_read2_b64 v[98:101], v194 offset0:12 offset1:16
	ds_read2_b64 v[102:105], v195 offset0:12 offset1:16
	ds_read2_b64 v[106:109], v196 offset0:12 offset1:16
	ds_read2_b64 v[110:113], v197 offset0:12 offset1:16
	ds_read2_b64 v[114:117], v194 offset0:20 offset1:24
	ds_read2_b64 v[118:121], v195 offset0:20 offset1:24
	ds_read2_b64 v[122:125], v196 offset0:20 offset1:24
	ds_read2_b64 v[126:129], v197 offset0:20 offset1:24
	ds_read2_b64 v[130:133], v194 offset0:28 offset1:32
	ds_read2_b64 v[134:137], v195 offset0:28 offset1:32
	ds_read2_b64 v[138:141], v196 offset0:28 offset1:32
	ds_read2_b64 v[142:145], v197 offset0:28 offset1:32
	ds_read2_b64 v[146:149], v194 offset0:36 offset1:40
	ds_read2_b64 v[150:153], v195 offset0:36 offset1:40
	ds_read2_b64 v[154:157], v196 offset0:36 offset1:40
	s_nop 4
	v_cndmask_b32_e64 v58, v49, v58, s[48:49]
	v_cndmask_b32_e64 v59, v49, v59, s[50:51]
	v_cndmask_b32_e64 v60, v49, v60, s[52:53]
	v_cndmask_b32_e64 v61, v49, v61, s[26:27]
	v_cndmask_b32_e64 v62, v49, v62, s[28:29]
	v_cndmask_b32_e64 v63, v49, v63, s[28:29]
	v_cndmask_b32_e64 v64, v49, v64, s[28:29]
	v_cndmask_b32_e64 v65, v49, v65, s[28:29]
	v_cndmask_b32_e64 v66, v49, v66, s[28:29]
	v_cndmask_b32_e64 v67, v49, v67, s[28:29]
	v_cndmask_b32_e64 v68, v49, v68, s[28:29]
	v_cndmask_b32_e64 v69, v49, v69, s[28:29]
	v_cndmask_b32_e64 v70, v49, v70, s[28:29]
	v_cndmask_b32_e64 v71, v49, v71, s[28:29]
	v_cndmask_b32_e64 v72, v49, v72, s[28:29]
	v_cndmask_b32_e64 v73, v49, v73, s[28:29]
	v_cndmask_b32_e64 v74, v49, v74, s[28:29]
	v_cndmask_b32_e64 v75, v49, v75, s[28:29]
	v_cndmask_b32_e64 v76, v49, v76, s[28:29]
	v_cndmask_b32_e64 v77, v49, v77, s[28:29]
	v_cndmask_b32_e64 v90, v90, v49, s[40:41]
	v_cndmask_b32_e64 v91, v91, v49, s[42:43]
	v_cndmask_b32_e64 v92, v92, v49, s[44:45]
	v_cndmask_b32_e64 v93, v93, v49, s[46:47]
	v_max_f32_e32 v167, v58, v59
	v_max_f32_e32 v94, v60, v61
	v_max3_f32 v167, v167, v62, v63
	v_max3_f32 v94, v94, v64, v65
	v_max3_f32 v167, v167, v66, v67
	v_max3_f32 v94, v94, v68, v69
	v_max3_f32 v167, v167, v70, v71
	v_max3_f32 v94, v94, v72, v73
	v_max3_f32 v167, v167, v74, v75
	v_max3_f32 v94, v94, v76, v77
	v_max3_f32 v167, v167, v78, v79
	v_max3_f32 v94, v94, v80, v81
	v_max3_f32 v167, v167, v82, v83
	v_max3_f32 v94, v94, v84, v85
	v_max3_f32 v167, v167, v86, v87
	v_max3_f32 v94, v94, v88, v89
	v_max3_f32 v167, v167, v90, v91
	v_max3_f32 v94, v94, v92, v93
	v_max_f32_e32 v167, v167, v94
	v_mov_b32_e32 v166, v167
	s_nop 1
	v_permlane16_swap_b32_e32 v167, v166
	v_max_f32_e32 v167, v167, v166
	v_mov_b32_e32 v166, v167
	s_nop 1
	v_permlane32_swap_b32_e32 v167, v166
	v_max_f32_e32 v167, v167, v166
	v_max_f32_e32 v167, v167, v42
	v_mul_f32_e32 v94, 0xbfb8aa3b, v167
	v_fmamk_f32 v58, v58, 0x3fb8aa3b, v94
	v_fmamk_f32 v59, v59, 0x3fb8aa3b, v94
	v_fmamk_f32 v60, v60, 0x3fb8aa3b, v94
	v_fmamk_f32 v61, v61, 0x3fb8aa3b, v94
	v_fmamk_f32 v62, v62, 0x3fb8aa3b, v94
	v_fmamk_f32 v63, v63, 0x3fb8aa3b, v94
	v_fmamk_f32 v64, v64, 0x3fb8aa3b, v94
	v_fmamk_f32 v65, v65, 0x3fb8aa3b, v94
	v_fmamk_f32 v66, v66, 0x3fb8aa3b, v94
	v_fmamk_f32 v67, v67, 0x3fb8aa3b, v94
	v_fmamk_f32 v68, v68, 0x3fb8aa3b, v94
	v_fmamk_f32 v69, v69, 0x3fb8aa3b, v94
	v_fmamk_f32 v70, v70, 0x3fb8aa3b, v94
	v_fmamk_f32 v71, v71, 0x3fb8aa3b, v94
	v_fmamk_f32 v72, v72, 0x3fb8aa3b, v94
	v_fmamk_f32 v73, v73, 0x3fb8aa3b, v94
	v_fmamk_f32 v74, v74, 0x3fb8aa3b, v94
	v_fmamk_f32 v75, v75, 0x3fb8aa3b, v94
	v_fmamk_f32 v76, v76, 0x3fb8aa3b, v94
	v_fmamk_f32 v77, v77, 0x3fb8aa3b, v94
	v_fmamk_f32 v78, v78, 0x3fb8aa3b, v94
	v_fmamk_f32 v79, v79, 0x3fb8aa3b, v94
	v_fmamk_f32 v80, v80, 0x3fb8aa3b, v94
	v_fmamk_f32 v81, v81, 0x3fb8aa3b, v94
	v_fmamk_f32 v82, v82, 0x3fb8aa3b, v94
	v_fmamk_f32 v83, v83, 0x3fb8aa3b, v94
	v_fmamk_f32 v84, v84, 0x3fb8aa3b, v94
	v_fmamk_f32 v85, v85, 0x3fb8aa3b, v94
	v_fmamk_f32 v86, v86, 0x3fb8aa3b, v94
	v_fmamk_f32 v87, v87, 0x3fb8aa3b, v94
	v_fmamk_f32 v88, v88, 0x3fb8aa3b, v94
	v_fmamk_f32 v89, v89, 0x3fb8aa3b, v94
	v_fmamk_f32 v90, v90, 0x3fb8aa3b, v94
	v_fmamk_f32 v91, v91, 0x3fb8aa3b, v94
	v_fmamk_f32 v92, v92, 0x3fb8aa3b, v94
	v_fmamk_f32 v93, v93, 0x3fb8aa3b, v94
	v_exp_f32_e32 v58, v58
	v_exp_f32_e32 v59, v59
	v_exp_f32_e32 v60, v60
	v_exp_f32_e32 v61, v61
	v_exp_f32_e32 v62, v62
	v_exp_f32_e32 v63, v63
	v_exp_f32_e32 v64, v64
	v_exp_f32_e32 v65, v65
	v_exp_f32_e32 v66, v66
	v_exp_f32_e32 v67, v67
	v_exp_f32_e32 v68, v68
	v_exp_f32_e32 v69, v69
	v_exp_f32_e32 v70, v70
	v_exp_f32_e32 v71, v71
	v_exp_f32_e32 v72, v72
	v_exp_f32_e32 v73, v73
	v_exp_f32_e32 v74, v74
	v_exp_f32_e32 v75, v75
	v_exp_f32_e32 v76, v76
	v_exp_f32_e32 v77, v77
	v_exp_f32_e32 v78, v78
	v_exp_f32_e32 v79, v79
	v_exp_f32_e32 v80, v80
	v_exp_f32_e32 v81, v81
	v_exp_f32_e32 v82, v82
; __device__ __forceinline__ unsigned cvt_pk_bf16(float lo, float hi) { unsigned r; asm volatile("v_cvt_pk_bf16_f32 %0, %1, %2" : "=v"(r) : "v"(lo), "v"(hi)); return r; }
; #define LAS __attribute__((address_space(3)))
; #define MFMA16(a, b, c) __builtin_amdgcn_mfma_f32_16x16x32_bf16((a), (b), (c), 0, 0, 0)
; __device__ __forceinline__ void p2_block(LAS unsigned char* lds, const bf16_t* __restrict__ PROJ, bf16_t* __restrict__ ATT, bf16_t* __restrict__ SGU, const float* __restrict__ qn, const float* __restrict__ kn, ...
;     ...
;             for (int e = 0; e < 4; ++e) { const float p = __builtin_amdgcn_exp2f((sc_[t][e] - mx) * LOG2E); sc_[t][e] = p; sum += p; }
;         sum += __shfl_xor(sum, 16); sum += __shfl_xor(sum, 32);
;         const float inv = 1.0f / (sum + __builtin_amdgcn_exp2f((sink - mx) * LOG2E));
;         f32x4 o[4];
; #pragma unroll
;         for (int dt = 0; dt < 4; ++dt) o[dt] = (f32x4){0.f, 0.f, 0.f, 0.f};
; #pragma unroll
;         for (int j = 0; j < 5; ++j) {
;             u32x4 pw; pw.x = cvt_pk_bf16(sc_[2 * j][0], sc_[2 * j][1]); pw.y = cvt_pk_bf16(sc_[2 * j][2], sc_[2 * j][3]); pw.z = cvt_pk_bf16(sc_[2 * j + 1][0], sc_[2 * j + 1][1]); pw.w = cvt_pk_bf16(sc_[2 * j + 1][2], sc_[2 * j + 1][3]);
;             const bf16x8 pf = __builtin_bit_cast(bf16x8, pw);
; #pragma unroll
;             for (int dt = 0; dt < 4; ++dt) { const LAS unsigned char* vb = VT + (16 * dt + fr) * VT_STRIDE + (16 * (t0 + 2 * j) + 4 * fq) * 2;
;                 const u32x2 va = *(const LAS u32x2*)vb, vc = *(const LAS u32x2*)(vb + 32); u32x4 vw; vw.x = va.x; vw.y = va.y; vw.z = vc.x; vw.w = vc.y;
;                 o[dt] = MFMA16(__builtin_bit_cast(bf16x8, vw), pf, o[dt]); }
;         }
;         bf16_t* op = ATT + grow * 1024 + hq * 64 + 4 * fq;
; #pragma unroll
;         for (int dt = 0; dt < 4; ++dt) { u32x2 ow; ow.x = cvt_pk_bf16(o[dt][0] * inv, o[dt][1] * inv); ow.y = cvt_pk_bf16(o[dt][2] * inv, o[dt][3] * inv); *(u32x2*)(op + 16 * dt) = ow; }
	v_exp_f32_e32 v83, v83
	v_exp_f32_e32 v84, v84
	v_exp_f32_e32 v85, v85
	v_exp_f32_e32 v86, v86
	v_exp_f32_e32 v87, v87
	v_exp_f32_e32 v88, v88
	v_exp_f32_e32 v89, v89
	v_exp_f32_e32 v90, v90
	v_exp_f32_e32 v91, v91
	v_exp_f32_e32 v92, v92
	v_exp_f32_e32 v93, v93
	v_fmamk_f32 v95, v42, 0x3fb8aa3b, v94
	v_exp_f32_e32 v95, v95
	v_add_f32_e32 v167, v58, v59
	v_add_f32_e32 v94, v60, v61
	v_add_f32_e32 v167, v167, v62
	v_add_f32_e32 v94, v94, v63
	v_add_f32_e32 v167, v167, v64
	v_add_f32_e32 v94, v94, v65
	v_add_f32_e32 v167, v167, v66
	v_add_f32_e32 v94, v94, v67
	v_add_f32_e32 v167, v167, v68
	v_add_f32_e32 v94, v94, v69
	v_add_f32_e32 v167, v167, v70
	v_add_f32_e32 v94, v94, v71
	v_add_f32_e32 v167, v167, v72
	v_add_f32_e32 v94, v94, v73
	v_add_f32_e32 v167, v167, v74
	v_add_f32_e32 v94, v94, v75
	v_add_f32_e32 v167, v167, v76
	v_add_f32_e32 v94, v94, v77
	v_add_f32_e32 v167, v167, v78
	v_add_f32_e32 v94, v94, v79
	v_add_f32_e32 v167, v167, v80
	v_add_f32_e32 v94, v94, v81
	v_add_f32_e32 v167, v167, v82
	v_add_f32_e32 v94, v94, v83
	v_add_f32_e32 v167, v167, v84
	v_add_f32_e32 v94, v94, v85
	v_add_f32_e32 v167, v167, v86
	v_add_f32_e32 v94, v94, v87
	v_add_f32_e32 v167, v167, v88
	v_add_f32_e32 v94, v94, v89
	v_add_f32_e32 v167, v167, v90
	v_add_f32_e32 v94, v94, v91
	v_add_f32_e32 v167, v167, v92
	v_add_f32_e32 v94, v94, v93
	v_add_f32_e32 v167, v167, v94
	v_mov_b32_e32 v166, v167
	s_nop 1
	v_permlane16_swap_b32_e32 v167, v166
	v_add_f32_e32 v167, v167, v166
	v_mov_b32_e32 v166, v167
	s_nop 1
	v_permlane32_swap_b32_e32 v167, v166
	v_add_f32_e32 v167, v167, v166
	v_add_f32_e32 v167, v167, v95
	v_rcp_f32_e32 v167, v167
	v_mov_b32_e32 v94, 0
	v_mov_b32_e32 v95, 0
	v_mov_b32_e32 v96, 0
	v_mov_b32_e32 v97, 0
	v_cvt_pk_bf16_f32 v58, v58, v59
	v_cvt_pk_bf16_f32 v59, v60, v61
	v_cvt_pk_bf16_f32 v60, v62, v63
	v_cvt_pk_bf16_f32 v61, v64, v65
	v_cvt_pk_bf16_f32 v66, v66, v67
	v_cvt_pk_bf16_f32 v67, v68, v69
	v_cvt_pk_bf16_f32 v68, v70, v71
	v_cvt_pk_bf16_f32 v69, v72, v73
	v_cvt_pk_bf16_f32 v74, v74, v75
	v_cvt_pk_bf16_f32 v75, v76, v77
	v_cvt_pk_bf16_f32 v76, v78, v79
	v_cvt_pk_bf16_f32 v77, v80, v81
	v_cvt_pk_bf16_f32 v82, v82, v83
	v_cvt_pk_bf16_f32 v83, v84, v85
	v_cvt_pk_bf16_f32 v84, v86, v87
	v_cvt_pk_bf16_f32 v85, v88, v89
	v_cvt_pk_bf16_f32 v90, v90, v91
	v_cvt_pk_bf16_f32 v91, v92, v93
	v_cvt_pk_bf16_f32 v92, v94, v95
	v_cvt_pk_bf16_f32 v93, v96, v97
	s_nop 1
	s_waitcnt lgkmcnt(14)
	v_mfma_f32_16x16x32_bf16 v[62:65], v[98:101], v[58:61], 0
	ds_read2_b64 v[158:161], v197 offset0:36 offset1:40
	s_waitcnt lgkmcnt(14)
	v_mfma_f32_16x16x32_bf16 v[70:73], v[102:105], v[58:61], 0
	ds_read2_b64 v[162:165], v194 offset0:44 offset1:48
	s_waitcnt lgkmcnt(14)
	v_mfma_f32_16x16x32_bf16 v[78:81], v[106:109], v[58:61], 0
	ds_read2_b64 v[182:185], v195 offset0:44 offset1:48
	s_waitcnt lgkmcnt(14)
	v_mfma_f32_16x16x32_bf16 v[86:89], v[110:113], v[58:61], 0
	ds_read2_b64 v[186:189], v196 offset0:44 offset1:48
	s_waitcnt lgkmcnt(14)
	v_mfma_f32_16x16x32_bf16 v[62:65], v[114:117], v[66:69], v[62:65]
	ds_read2_b64 v[190:193], v197 offset0:44 offset1:48
	s_waitcnt lgkmcnt(14)
	v_mfma_f32_16x16x32_bf16 v[70:73], v[118:121], v[66:69], v[70:73]
	s_waitcnt lgkmcnt(13)
	v_mfma_f32_16x16x32_bf16 v[78:81], v[122:125], v[66:69], v[78:81]
	s_waitcnt lgkmcnt(12)
	v_mfma_f32_16x16x32_bf16 v[86:89], v[126:129], v[66:69], v[86:89]
	s_waitcnt lgkmcnt(11)
	v_mfma_f32_16x16x32_bf16 v[62:65], v[130:133], v[74:77], v[62:65]
	s_waitcnt lgkmcnt(10)
	v_mfma_f32_16x16x32_bf16 v[70:73], v[134:137], v[74:77], v[70:73]
	s_waitcnt lgkmcnt(9)
	v_mfma_f32_16x16x32_bf16 v[78:81], v[138:141], v[74:77], v[78:81]
	s_waitcnt lgkmcnt(8)
	v_mfma_f32_16x16x32_bf16 v[86:89], v[142:145], v[74:77], v[86:89]
	s_waitcnt lgkmcnt(7)
	v_mfma_f32_16x16x32_bf16 v[62:65], v[146:149], v[82:85], v[62:65]
	s_waitcnt lgkmcnt(6)
	v_mfma_f32_16x16x32_bf16 v[70:73], v[150:153], v[82:85], v[70:73]
	s_waitcnt lgkmcnt(5)
	v_mfma_f32_16x16x32_bf16 v[78:81], v[154:157], v[82:85], v[78:81]
	s_waitcnt lgkmcnt(4)
	v_mfma_f32_16x16x32_bf16 v[86:89], v[158:161], v[82:85], v[86:89]
	s_waitcnt lgkmcnt(3)
	v_mfma_f32_16x16x32_bf16 v[62:65], v[162:165], v[90:93], v[62:65]
	s_waitcnt lgkmcnt(2)
	v_mfma_f32_16x16x32_bf16 v[70:73], v[182:185], v[90:93], v[70:73]
	s_waitcnt lgkmcnt(1)
	v_mfma_f32_16x16x32_bf16 v[78:81], v[186:189], v[90:93], v[78:81]
	s_waitcnt lgkmcnt(0)
	v_mfma_f32_16x16x32_bf16 v[86:89], v[190:193], v[90:93], v[86:89]
	s_nop 7
	v_mul_f32_e32 v62, v62, v167
	v_mul_f32_e32 v63, v63, v167
	v_mul_f32_e32 v64, v64, v167
	v_mul_f32_e32 v65, v65, v167
	v_mul_f32_e32 v70, v70, v167
	v_mul_f32_e32 v71, v71, v167
	v_mul_f32_e32 v72, v72, v167
	v_mul_f32_e32 v73, v73, v167
	v_mul_f32_e32 v78, v78, v167
	v_mul_f32_e32 v79, v79, v167
	v_mul_f32_e32 v80, v80, v167
	v_mul_f32_e32 v81, v81, v167
	v_mul_f32_e32 v86, v86, v167
	v_mul_f32_e32 v87, v87, v167
	v_mul_f32_e32 v88, v88, v167
	v_mul_f32_e32 v89, v89, v167
	v_cvt_pk_bf16_f32 v62, v62, v63
	v_cvt_pk_bf16_f32 v63, v64, v65
	global_store_dwordx2 v48, v[62:63], s[24:25] offset:0
	v_cvt_pk_bf16_f32 v70, v70, v71
	v_cvt_pk_bf16_f32 v71, v72, v73
	global_store_dwordx2 v48, v[70:71], s[24:25] offset:32
	v_cvt_pk_bf16_f32 v78, v78, v79
	v_cvt_pk_bf16_f32 v79, v80, v81
	global_store_dwordx2 v48, v[78:79], s[24:25] offset:64
	v_cvt_pk_bf16_f32 v86, v86, v87
	v_cvt_pk_bf16_f32 v87, v88, v89
	global_store_dwordx2 v48, v[86:87], s[24:25] offset:96
	v_add_u32_e32 v48, 0x8000, v48
	s_branch .Latt_done
; __device__ __forceinline__ unsigned cvt_pk_bf16(float lo, float hi) { unsigned r; asm volatile("v_cvt_pk_bf16_f32 %0, %1, %2" : "=v"(r) : "v"(lo), "v"(hi)); return r; }
; #define LAS __attribute__((address_space(3)))
; #define MFMA16(a, b, c) __builtin_amdgcn_mfma_f32_16x16x32_bf16((a), (b), (c), 0, 0, 0)
; __device__ __forceinline__ void p2_block(LAS unsigned char* lds, const bf16_t* __restrict__ PROJ, bf16_t* __restrict__ ATT, bf16_t* __restrict__ SGU, const float* __restrict__ qn, const float* __restrict__ kn, ...
;     ...
;     for (int gi = 0; gi < 2; ++gi) {
;         const int gg = 2 * kvh + gi, irow = 16 * w + fr, nks = (w >> 1) + 1;
;         const LAS unsigned char* VNT = lds + (gi ? VN_OFF1 : VN_OFF0);
;         f32x4 acc[8];
; #pragma unroll
;         for (int dt = 0; dt < 8; ++dt) acc[dt] = (f32x4){0.f, 0.f, 0.f, 0.f};
;         const float* wrow = wsp + (size_t)gg * 16384 + irow * 128 + 8 * fq;
; #pragma unroll
;         for (int ks = 0; ks < 4; ++ks) if (ks < nks) {
;             const f32x4 wa = *(const f32x4*)(wrow + 32 * ks), wb = *(const f32x4*)(wrow + 32 * ks + 4);
;             const int j0 = 32 * ks + 8 * fq; float wv[8];
; #pragma unroll
;             for (int e = 0; e < 4; ++e) { wv[e] = (j0 + e <= irow) ? wa[e] : 0.f; wv[4 + e] = (j0 + 4 + e <= irow) ? wb[e] : 0.f; }
;             u32x4 ww; ww.x = cvt_pk_bf16(wv[0], wv[1]); ww.y = cvt_pk_bf16(wv[2], wv[3]); ww.z = cvt_pk_bf16(wv[4], wv[5]); ww.w = cvt_pk_bf16(wv[6], wv[7]);
;             const bf16x8 wf = __builtin_bit_cast(bf16x8, ww);
; #pragma unroll
;             for (int dt = 0; dt < 8; ++dt) { const bf16x8 af = *(const LAS bf16x8*)(VNT + (16 * dt + fr) * VN_STRIDE + (32 * ks + 8 * fq) * 2); acc[dt] = MFMA16(af, wf, acc[dt]); }
;         }
;         const float bias = bsp[gg * 128 + irow];
;         const size_t grow = (size_t)b * pg8::SEQ + n * 128 + irow;
;         const bf16_t* up = PROJ + grow * pg8::IN_W + pg8::C_U + gg * 128 + 4 * fq; bf16_t* op = SGU + grow * 1024 + gg * 128 + 4 * fq;
.Latt_done:
	v_readfirstlane_b32 s16, v204
	v_and_b32_e32 v184, 15, v204
	v_bfe_u32 v185, v204, 4, 2
	s_and_b32 s24, s2, 3
	s_lshr_b32 s16, s16, 6
	s_lshl_b32 s4, s24, 17
	s_lshr_b32 s17, s16, 1
	v_lshl_add_u32 v191, s16, 4, v184
	v_lshlrev_b32_e32 v186, 9, v191
	v_lshl_add_u32 v186, v185, 5, v186
	v_add_u32_e32 v186, s4, v186
	v_add_u32_e32 v187, 0x10000, v186
	global_load_dwordx4 v[98:101], v186, s[20:21] offset:0
	global_load_dwordx4 v[102:105], v186, s[20:21] offset:16
	global_load_dwordx4 v[106:109], v186, s[20:21] offset:128
	global_load_dwordx4 v[110:113], v186, s[20:21] offset:144
	global_load_dwordx4 v[114:117], v186, s[20:21] offset:256
	global_load_dwordx4 v[118:121], v186, s[20:21] offset:272
	global_load_dwordx4 v[122:125], v186, s[20:21] offset:384
	global_load_dwordx4 v[126:129], v186, s[20:21] offset:400
	global_load_dwordx4 v[66:69], v187, s[20:21] offset:0
	global_load_dwordx4 v[70:73], v187, s[20:21] offset:16
	global_load_dwordx4 v[74:77], v187, s[20:21] offset:128
	global_load_dwordx4 v[78:81], v187, s[20:21] offset:144
	global_load_dwordx4 v[82:85], v187, s[20:21] offset:256
	global_load_dwordx4 v[86:89], v187, s[20:21] offset:272
	global_load_dwordx4 v[90:93], v187, s[20:21] offset:384
	global_load_dwordx4 v[94:97], v187, s[20:21] offset:400
	v_mul_u32_u24_e32 v194, 0x110, v184
	v_lshl_add_u32 v194, v185, 4, v194
	v_add_u32_e32 v194, 0x11800, v194
	v_lshlrev_b32_e32 v195, 3, v185
	v_sub_u32_e32 v195, v191, v195
	s_and_b32 s25, s2, -4
	s_lshl_b32 s25, s25, 5
	v_add_u32_e32 v192, s25, v191
	s_lshl_b32 s4, s24, 9
	v_lshl_add_u32 v193, v185, 3, s4
	v_lshl_add_u32 v189, v192, 11, v193
	s_cmp_eq_u32 s17, 0
	s_cbranch_scc1 .Lsgu_n1
	s_cmp_eq_u32 s17, 1
	s_cbranch_scc1 .Lsgu_n2
	s_cmp_eq_u32 s17, 2
	s_cbranch_scc1 .Lsgu_n3
	s_branch .Lsgu_n4
